# PEER part a rewritten by hand: both heads scored per wave, permlane32_swap so each half-wave finalises its own head (candidate phase once, not twice), network top-16 of the 50 candidates, LDS byte-tab
# speedup vs baseline: 1.0415x; 1.0294x over previous
; #define MFMA32(a, b, c) __builtin_amdgcn_mfma_f32_32x32x16_bf16((a), (b), (c), 0, 0, 0)
; DI int my_tid() { int t = threadIdx.x & 255; asm volatile("" : "+v"(t)); return t; }
; DI void hsync() { hsync_impl(false); }
; DI void peer_top16(const u16* __restrict__ PQrow, const u16* __restrict__ SK, unsigned (&top)[16], int lr, int hh) {
;   bf16x8 qf[8];
; #pragma unroll
;   for (int ks = 0; ks < 8; ++ks) qf[ks] = *(const bf16x8*)(PQrow + ks * 16 + hh * 8);
;   unsigned g[4][16];
; #pragma unroll
;   for (int kt = 0; kt < 4; ++kt) {
;     f32x16 acc;
; #pragma unroll
;     for (int e = 0; e < 16; ++e) acc[e] = 0.f;
; #pragma unroll
;     for (int ks = 0; ks < 8; ++ks) {
;       bf16x8 a = *(const bf16x8*)(SK + (size_t)(kt * 32 + lr) * 128 + ks * 16 + hh * 8);
;       acc = MFMA32(a, qf[ks], acc);
; template <bool STORE>
; DI void peer_item(const Params& p, int item, char* smem) {
;     ...
;   const int tid = my_tid(), lane = tid & 63, wave = tid >> 6;
;   const int lr = lane & 31, hh = lane >> 5;
;   const int tok0 = item * 32;
;   hsync();
;   for (int hq = 0; hq < 2; ++hq) {
;     const int hd = wave * 2 + hq;
;     unsigned top1[16], top2[16];
;     const u16* pqrow = PQ + (size_t)(tok0 + lr) * 2048 + hd * 256;
;     peer_top16(pqrow, SUBK + (size_t)(hd * 2 + 0) * 128 * 128, top1, lr, hh);
;     peer_top16(pqrow + 128, SUBK + (size_t)(hd * 2 + 1) * 128 * 128, top2, lr, hh);
.LBB0_1045:
	s_or_b64 exec, exec, s[0:1]
	v_writelane_b32 v254, s6, 0
	v_writelane_b32 v254, s7, 1
	v_writelane_b32 v254, s12, 2
	v_writelane_b32 v254, s13, 3
	v_writelane_b32 v254, s14, 4
	v_writelane_b32 v254, s15, 5
	v_writelane_b32 v254, s16, 6
	v_writelane_b32 v254, s17, 7
	v_writelane_b32 v254, s18, 8
	v_writelane_b32 v254, s19, 9
	v_writelane_b32 v254, s20, 10
	v_writelane_b32 v254, s21, 11
	v_writelane_b32 v254, s22, 12
	v_writelane_b32 v254, s23, 13
	v_writelane_b32 v254, s24, 14
	v_writelane_b32 v254, s25, 15
	v_writelane_b32 v254, s26, 16
	v_writelane_b32 v254, s27, 17
	v_writelane_b32 v254, s28, 18
	v_writelane_b32 v254, s29, 19
	v_writelane_b32 v254, s30, 20
	v_writelane_b32 v254, s31, 21
	v_writelane_b32 v254, s33, 22
	v_writelane_b32 v254, s34, 23
	v_writelane_b32 v254, s35, 24
	v_writelane_b32 v254, s36, 25
	v_writelane_b32 v254, s37, 26
	v_writelane_b32 v254, s38, 27
	v_writelane_b32 v254, s39, 28
	v_writelane_b32 v254, s40, 29
	v_writelane_b32 v254, s41, 30
	v_writelane_b32 v254, s42, 31
	v_writelane_b32 v254, s44, 32
	v_writelane_b32 v254, s45, 33
	v_writelane_b32 v254, s48, 34
	v_writelane_b32 v254, s49, 35
	v_writelane_b32 v254, s50, 36
	v_writelane_b32 v254, s51, 37
	v_writelane_b32 v254, s52, 38
	v_writelane_b32 v254, s53, 39
	v_writelane_b32 v254, s55, 40
	v_writelane_b32 v254, s60, 41
	v_writelane_b32 v254, s61, 42
	v_writelane_b32 v254, s62, 43
	v_writelane_b32 v254, s63, 44
	v_writelane_b32 v254, s66, 45
	v_writelane_b32 v254, s67, 46
	v_writelane_b32 v254, s68, 47
	v_writelane_b32 v254, s69, 48
	v_writelane_b32 v254, s74, 49
	v_writelane_b32 v254, s75, 50
	v_writelane_b32 v254, s76, 51
	v_writelane_b32 v254, s77, 52
	v_writelane_b32 v254, s78, 53
	v_writelane_b32 v254, s79, 54
	v_writelane_b32 v254, s88, 55
	s_mov_b32 s16, s33
	s_lshl_b32 s19, s6, 5
	v_readlane_b32 s56, v253, 48
	v_readlane_b32 s57, v253, 49
	v_readfirstlane_b32 s13, v211
	v_mbcnt_lo_u32_b32 v235, -1, 0
	v_mbcnt_hi_u32_b32 v235, -1, v235
	s_nop 3
	s_bfe_u32 s17, s13, 0x20006
	s_add_u32 s0, s56, 0x1180000
	s_addc_u32 s1, s57, 0
	s_add_u32 s2, s56, 0xac80200
	s_addc_u32 s3, s57, 0
	s_lshl_b32 s15, s19, 12
	s_add_u32 s2, s2, s15
	s_addc_u32 s3, s3, 0
	s_lshl_b32 s15, s17, 10
	s_add_u32 s2, s2, s15
	s_addc_u32 s3, s3, 0
	s_lshl_b32 s15, s17, 17
	s_add_u32 s0, s0, s15
	s_addc_u32 s1, s1, 0
	s_mul_i32 s18, s17, 7168
	s_add_u32 s18, s18, s16
	s_add_u32 s18, s18, 49152
	v_and_b32_e32 v236, 31, v235
	v_lshrrev_b32_e32 v237, 5, v235
	v_lshlrev_b32_e32 v243, 2, v235
	v_add_u32_e32 v240, s18, v243
	ds_write_b32 v240, v3 offset:512
	ds_write_b32 v240, v53 offset:768
	ds_write_b32 v240, v64 offset:1024
	ds_write_b32 v240, v65 offset:1280
	ds_write_b32 v240, v66 offset:1536
	ds_write_b32 v240, v67 offset:1792
	ds_write_b32 v240, v68 offset:2048
	ds_write_b32 v240, v69 offset:2304
	ds_write_b32 v240, v70 offset:2560
	ds_write_b32 v240, v71 offset:2816
	ds_write_b32 v240, v72 offset:3072
	ds_write_b32 v240, v73 offset:3328
	ds_write_b32 v240, v74 offset:3584
	ds_write_b32 v240, v75 offset:3840
	ds_write_b32 v240, v76 offset:4096
	ds_write_b32 v240, v77 offset:4352
	ds_write_b32 v240, v78 offset:4608
	ds_write_b32 v240, v79 offset:4864
	ds_write_b32 v240, v80 offset:5120
	ds_write_b32 v240, v81 offset:5376
	ds_write_b32 v240, v82 offset:5632
	ds_write_b32 v240, v83 offset:5888
	ds_write_b32 v240, v84 offset:6144
	ds_write_b32 v240, v96 offset:6400
	v_lshlrev_b32_e32 v244, 4, v237
	v_lshl_add_u32 v238, v236, 8, v244
	v_lshl_add_u32 v239, v236, 12, v244
	s_lshl_b32 s15, s17, 11
	s_add_u32 s15, s15, s16
	s_add_u32 s15, s15, 32768
	v_lshl_add_u32 v241, v235, 5, s15
	s_lshl_b32 s15, s17, 7
	s_add_u32 s15, s15, s16
	v_lshl_add_u32 v242, v236, 9, s15
	v_lshl_add_u32 v242, v237, 6, v242
	s_waitcnt lgkmcnt(0)
	global_load_dwordx4 v[176:179], v239, s[2:3] offset:0
	global_load_dwordx4 v[180:183], v239, s[2:3] offset:32
	global_load_dwordx4 v[184:187], v239, s[2:3] offset:64
	global_load_dwordx4 v[188:191], v239, s[2:3] offset:96
	global_load_dwordx4 v[192:195], v239, s[2:3] offset:128
	global_load_dwordx4 v[196:199], v239, s[2:3] offset:160
	global_load_dwordx4 v[200:203], v239, s[2:3] offset:192
	global_load_dwordx4 v[204:207], v239, s[2:3] offset:224
	s_add_u32 s4, s0, 0
	s_addc_u32 s5, s1, 0
	global_load_dwordx4 v[144:147], v238, s[4:5] offset:0
	global_load_dwordx4 v[148:151], v238, s[4:5] offset:32
	global_load_dwordx4 v[152:155], v238, s[4:5] offset:64
	global_load_dwordx4 v[156:159], v238, s[4:5] offset:96
	global_load_dwordx4 v[160:163], v238, s[4:5] offset:128
	global_load_dwordx4 v[164:167], v238, s[4:5] offset:160
	global_load_dwordx4 v[168:171], v238, s[4:5] offset:192
	global_load_dwordx4 v[172:175], v238, s[4:5] offset:224
	v_lshlrev_b32_e32 v245, 2, v237
	v_sub_u32_e32 v213, 127, v245
	v_sub_u32_e32 v214, 126, v245
	v_sub_u32_e32 v215, 125, v245
	v_sub_u32_e32 v216, 124, v245
	v_sub_u32_e32 v217, 119, v245
	v_sub_u32_e32 v218, 118, v245
	v_sub_u32_e32 v219, 117, v245
	v_sub_u32_e32 v220, 116, v245
	v_sub_u32_e32 v221, 111, v245
	v_sub_u32_e32 v222, 110, v245
	v_sub_u32_e32 v223, 109, v245
	v_sub_u32_e32 v224, 108, v245
	v_sub_u32_e32 v225, 103, v245
	v_sub_u32_e32 v226, 102, v245
	v_sub_u32_e32 v227, 101, v245
	v_sub_u32_e32 v228, 100, v245
	s_waitcnt vmcnt(7)
	v_mfma_f32_32x32x16_bf16 v[128:143], v[144:147], v[176:179], 0
	s_waitcnt vmcnt(6)
	v_mfma_f32_32x32x16_bf16 v[128:143], v[148:151], v[180:183], v[128:143]
	s_waitcnt vmcnt(5)
	v_mfma_f32_32x32x16_bf16 v[128:143], v[152:155], v[184:187], v[128:143]
	s_waitcnt vmcnt(4)
	v_mfma_f32_32x32x16_bf16 v[128:143], v[156:159], v[188:191], v[128:143]
	s_waitcnt vmcnt(3)
; #define MFMA32(a, b, c) __builtin_amdgcn_mfma_f32_32x32x16_bf16((a), (b), (c), 0, 0, 0)
; DI int crow(int i, int hh) { return (i & 3) + 8 * (i >> 2) + 4 * hh; }
; template <int LOGN>
; DI void bitonic_sort_desc(unsigned (&a)[1 << LOGN]) {
;   constexpr int N = 1 << LOGN;
; #pragma unroll
;   for (int ks = 1; ks <= LOGN; ++ks)
; #pragma unroll
;     ...
; #pragma unroll
;       for (int i = 0; i < N; ++i) {
;         const int k = 1 << ks, j = 1 << js, l = i ^ j;
;         if (l > i) {
;           const bool desc = ((i & k) == 0) || (ks == LOGN);
;           const unsigned x = a[i], y = a[l];
;           const unsigned hi = max(x, y), lo = min(x, y);
;           a[i] = desc ? hi : lo;
;           a[l] = desc ? lo : hi;
;         }
;       }
; }
; DI void peer_top16(const u16* __restrict__ PQrow, const u16* __restrict__ SK, unsigned (&top)[16], int lr, int hh) {
;     ...
;     for (int ks = 0; ks < 8; ++ks) {
;       bf16x8 a = *(const bf16x8*)(SK + (size_t)(kt * 32 + lr) * 128 + ks * 16 + hh * 8);
;       acc = MFMA32(a, qf[ks], acc);
;     }
; #pragma unroll
;     for (int e = 0; e < 16; ++e) {
;       int kidx = kt * 32 + crow(e, hh);
;       g[kt][e] = (f2ord(acc[e]) & ~127u) | (unsigned)(127 - kidx);
;     }
;     bitonic_sort_desc<4>(g[kt]);
;   }
	v_mfma_f32_32x32x16_bf16 v[128:143], v[160:163], v[192:195], v[128:143]
	s_waitcnt vmcnt(2)
	v_mfma_f32_32x32x16_bf16 v[128:143], v[164:167], v[196:199], v[128:143]
	s_waitcnt vmcnt(1)
	v_mfma_f32_32x32x16_bf16 v[128:143], v[168:171], v[200:203], v[128:143]
	s_waitcnt vmcnt(0)
	v_mfma_f32_32x32x16_bf16 v[128:143], v[172:175], v[204:207], v[128:143]
	s_add_u32 s4, s0, 8192
	s_addc_u32 s5, s1, 0
	global_load_dwordx4 v[144:147], v238, s[4:5] offset:0
	global_load_dwordx4 v[148:151], v238, s[4:5] offset:32
	global_load_dwordx4 v[152:155], v238, s[4:5] offset:64
	global_load_dwordx4 v[156:159], v238, s[4:5] offset:96
	global_load_dwordx4 v[160:163], v238, s[4:5] offset:128
	global_load_dwordx4 v[164:167], v238, s[4:5] offset:160
	global_load_dwordx4 v[168:171], v238, s[4:5] offset:192
	global_load_dwordx4 v[172:175], v238, s[4:5] offset:224
	s_nop 7
	v_ashrrev_i32_e32 v230, 31, v128
	v_or_b32_e32 v230, 0x80000000, v230
	v_xor_b32_e32 v229, v230, v128
	v_and_b32_e32 v229, 0xffffff80, v229
	v_or_b32_e32 v117, v229, v213
	v_ashrrev_i32_e32 v230, 31, v129
	v_or_b32_e32 v230, 0x80000000, v230
	v_xor_b32_e32 v229, v230, v129
	v_and_b32_e32 v229, 0xffffff80, v229
	v_or_b32_e32 v116, v229, v214
	v_ashrrev_i32_e32 v230, 31, v130
	v_or_b32_e32 v230, 0x80000000, v230
	v_xor_b32_e32 v229, v230, v130
	v_and_b32_e32 v229, 0xffffff80, v229
	v_or_b32_e32 v115, v229, v215
	v_ashrrev_i32_e32 v230, 31, v131
	v_or_b32_e32 v230, 0x80000000, v230
	v_xor_b32_e32 v229, v230, v131
	v_and_b32_e32 v229, 0xffffff80, v229
	v_or_b32_e32 v114, v229, v216
	v_ashrrev_i32_e32 v230, 31, v132
	v_or_b32_e32 v230, 0x80000000, v230
	v_xor_b32_e32 v229, v230, v132
	v_and_b32_e32 v229, 0xffffff80, v229
	v_or_b32_e32 v113, v229, v217
	v_ashrrev_i32_e32 v230, 31, v133
	v_or_b32_e32 v230, 0x80000000, v230
	v_xor_b32_e32 v229, v230, v133
	v_and_b32_e32 v229, 0xffffff80, v229
	v_or_b32_e32 v112, v229, v218
	v_ashrrev_i32_e32 v230, 31, v134
	v_or_b32_e32 v230, 0x80000000, v230
	v_xor_b32_e32 v229, v230, v134
	v_and_b32_e32 v229, 0xffffff80, v229
	v_or_b32_e32 v111, v229, v219
	v_ashrrev_i32_e32 v230, 31, v135
	v_or_b32_e32 v230, 0x80000000, v230
	v_xor_b32_e32 v229, v230, v135
	v_and_b32_e32 v229, 0xffffff80, v229
	v_or_b32_e32 v110, v229, v220
	v_ashrrev_i32_e32 v230, 31, v136
	v_or_b32_e32 v230, 0x80000000, v230
	v_xor_b32_e32 v229, v230, v136
	v_and_b32_e32 v229, 0xffffff80, v229
	v_or_b32_e32 v109, v229, v221
	v_ashrrev_i32_e32 v230, 31, v137
	v_or_b32_e32 v230, 0x80000000, v230
	v_xor_b32_e32 v229, v230, v137
	v_and_b32_e32 v229, 0xffffff80, v229
	v_or_b32_e32 v108, v229, v222
	v_ashrrev_i32_e32 v230, 31, v138
	v_or_b32_e32 v230, 0x80000000, v230
	v_xor_b32_e32 v229, v230, v138
	v_and_b32_e32 v229, 0xffffff80, v229
	v_or_b32_e32 v107, v229, v223
	v_ashrrev_i32_e32 v230, 31, v139
	v_or_b32_e32 v230, 0x80000000, v230
	v_xor_b32_e32 v229, v230, v139
	v_and_b32_e32 v229, 0xffffff80, v229
	v_or_b32_e32 v106, v229, v224
	v_ashrrev_i32_e32 v230, 31, v140
	v_or_b32_e32 v230, 0x80000000, v230
	v_xor_b32_e32 v229, v230, v140
	v_and_b32_e32 v229, 0xffffff80, v229
	v_or_b32_e32 v105, v229, v225
	v_ashrrev_i32_e32 v230, 31, v141
	v_or_b32_e32 v230, 0x80000000, v230
	v_xor_b32_e32 v229, v230, v141
	v_and_b32_e32 v229, 0xffffff80, v229
	v_or_b32_e32 v104, v229, v226
	v_ashrrev_i32_e32 v230, 31, v142
	v_or_b32_e32 v230, 0x80000000, v230
	v_xor_b32_e32 v229, v230, v142
	v_and_b32_e32 v229, 0xffffff80, v229
	v_or_b32_e32 v103, v229, v227
	v_ashrrev_i32_e32 v230, 31, v143
	v_or_b32_e32 v230, 0x80000000, v230
	v_xor_b32_e32 v229, v230, v143
	v_and_b32_e32 v229, 0xffffff80, v229
	v_or_b32_e32 v102, v229, v228
	v_subrev_u32_e32 v213, 32, v213
	v_subrev_u32_e32 v214, 32, v214
	v_subrev_u32_e32 v215, 32, v215
	v_subrev_u32_e32 v216, 32, v216
	v_subrev_u32_e32 v217, 32, v217
	v_subrev_u32_e32 v218, 32, v218
	v_subrev_u32_e32 v219, 32, v219
	v_subrev_u32_e32 v220, 32, v220
	v_subrev_u32_e32 v221, 32, v221
	v_subrev_u32_e32 v222, 32, v222
	v_subrev_u32_e32 v223, 32, v223
	v_subrev_u32_e32 v224, 32, v224
	v_subrev_u32_e32 v225, 32, v225
	v_subrev_u32_e32 v226, 32, v226
	v_subrev_u32_e32 v227, 32, v227
	v_subrev_u32_e32 v228, 32, v228
	v_max_u32_e32 v101, v117, v116
	v_min_u32_e32 v116, v117, v116
	v_min_u32_e32 v117, v115, v114
	v_max_u32_e32 v114, v115, v114
	v_max_u32_e32 v115, v113, v112
	v_min_u32_e32 v112, v113, v112
	v_min_u32_e32 v113, v111, v110
	v_max_u32_e32 v110, v111, v110
	v_max_u32_e32 v111, v109, v108
	v_min_u32_e32 v108, v109, v108
	v_min_u32_e32 v109, v107, v106
	v_max_u32_e32 v106, v107, v106
	v_max_u32_e32 v107, v105, v104
	v_min_u32_e32 v104, v105, v104
	v_min_u32_e32 v105, v103, v102
	v_max_u32_e32 v102, v103, v102
	v_max_u32_e32 v103, v101, v117
	v_min_u32_e32 v117, v101, v117
	v_max_u32_e32 v101, v116, v114
	v_min_u32_e32 v114, v116, v114
	v_min_u32_e32 v116, v115, v113
	v_max_u32_e32 v113, v115, v113
	v_min_u32_e32 v115, v112, v110
	v_max_u32_e32 v110, v112, v110
	v_max_u32_e32 v112, v111, v109
	v_min_u32_e32 v109, v111, v109
	v_max_u32_e32 v111, v108, v106
	v_min_u32_e32 v106, v108, v106
	v_min_u32_e32 v108, v107, v105
	v_max_u32_e32 v105, v107, v105
	v_min_u32_e32 v107, v104, v102
	v_max_u32_e32 v102, v104, v102
	v_max_u32_e32 v104, v103, v101
	v_min_u32_e32 v101, v103, v101
	v_max_u32_e32 v103, v117, v114
	v_min_u32_e32 v114, v117, v114
	v_min_u32_e32 v117, v116, v115
	v_max_u32_e32 v115, v116, v115
	v_min_u32_e32 v116, v113, v110
	v_max_u32_e32 v110, v113, v110
	v_max_u32_e32 v113, v112, v111
	v_min_u32_e32 v111, v112, v111
	v_max_u32_e32 v112, v109, v106
	v_min_u32_e32 v106, v109, v106
	v_min_u32_e32 v109, v108, v107
	v_max_u32_e32 v107, v108, v107
	v_min_u32_e32 v108, v105, v102
; #define MFMA32(a, b, c) __builtin_amdgcn_mfma_f32_32x32x16_bf16((a), (b), (c), 0, 0, 0)
; template <int LOGN>
; DI void bitonic_sort_desc(unsigned (&a)[1 << LOGN]) {
;   constexpr int N = 1 << LOGN;
; #pragma unroll
;   for (int ks = 1; ks <= LOGN; ++ks)
; #pragma unroll
;     ...
; #pragma unroll
;       for (int i = 0; i < N; ++i) {
;         const int k = 1 << ks, j = 1 << js, l = i ^ j;
;         if (l > i) {
;           const bool desc = ((i & k) == 0) || (ks == LOGN);
;           const unsigned x = a[i], y = a[l];
;           const unsigned hi = max(x, y), lo = min(x, y);
;           a[i] = desc ? hi : lo;
;           a[l] = desc ? lo : hi;
;         }
;       }
; }
; DI void peer_top16(const u16* __restrict__ PQrow, const u16* __restrict__ SK, unsigned (&top)[16], int lr, int hh) {
;     ...
; #pragma unroll
;     for (int ks = 0; ks < 8; ++ks) {
;       bf16x8 a = *(const bf16x8*)(SK + (size_t)(kt * 32 + lr) * 128 + ks * 16 + hh * 8);
;       acc = MFMA32(a, qf[ks], acc);
;     }
	v_max_u32_e32 v102, v105, v102
	v_max_u32_e32 v105, v104, v117
	v_min_u32_e32 v117, v104, v117
	v_max_u32_e32 v104, v101, v115
	v_min_u32_e32 v115, v101, v115
	v_max_u32_e32 v101, v103, v116
	v_min_u32_e32 v116, v103, v116
	v_max_u32_e32 v103, v114, v110
	v_min_u32_e32 v110, v114, v110
	v_min_u32_e32 v114, v113, v109
	v_max_u32_e32 v109, v113, v109
	v_min_u32_e32 v113, v111, v107
	v_max_u32_e32 v107, v111, v107
	v_min_u32_e32 v111, v112, v108
	v_max_u32_e32 v108, v112, v108
	v_min_u32_e32 v112, v106, v102
	v_max_u32_e32 v102, v106, v102
	v_max_u32_e32 v106, v105, v101
	v_min_u32_e32 v101, v105, v101
	v_max_u32_e32 v105, v104, v103
	v_min_u32_e32 v103, v104, v103
	v_max_u32_e32 v104, v117, v116
	v_min_u32_e32 v116, v117, v116
	v_max_u32_e32 v117, v115, v110
	v_min_u32_e32 v110, v115, v110
	v_min_u32_e32 v115, v114, v111
	v_max_u32_e32 v111, v114, v111
	v_min_u32_e32 v114, v113, v112
	v_max_u32_e32 v112, v113, v112
	v_min_u32_e32 v113, v109, v108
	v_max_u32_e32 v108, v109, v108
	v_min_u32_e32 v109, v107, v102
	v_max_u32_e32 v102, v107, v102
	v_max_u32_e32 v107, v106, v105
	v_min_u32_e32 v105, v106, v105
	v_max_u32_e32 v106, v101, v103
	v_min_u32_e32 v103, v101, v103
	v_max_u32_e32 v101, v104, v117
	v_min_u32_e32 v117, v104, v117
	v_max_u32_e32 v104, v116, v110
	v_min_u32_e32 v110, v116, v110
	v_min_u32_e32 v116, v115, v114
	v_max_u32_e32 v114, v115, v114
	v_min_u32_e32 v115, v111, v112
	v_max_u32_e32 v112, v111, v112
	v_min_u32_e32 v111, v113, v109
	v_max_u32_e32 v109, v113, v109
	v_min_u32_e32 v113, v108, v102
	v_max_u32_e32 v102, v108, v102
	v_max_u32_e32 v108, v107, v116
	v_min_u32_e32 v116, v107, v116
	v_max_u32_e32 v107, v105, v114
	v_min_u32_e32 v114, v105, v114
	v_max_u32_e32 v105, v106, v115
	v_min_u32_e32 v115, v106, v115
	v_max_u32_e32 v106, v103, v112
	v_min_u32_e32 v112, v103, v112
	v_max_u32_e32 v103, v101, v111
	v_min_u32_e32 v111, v101, v111
	v_max_u32_e32 v101, v117, v109
	v_min_u32_e32 v109, v117, v109
	v_max_u32_e32 v117, v104, v113
	v_min_u32_e32 v113, v104, v113
	v_max_u32_e32 v104, v110, v102
	v_min_u32_e32 v102, v110, v102
	v_max_u32_e32 v110, v108, v103
	v_min_u32_e32 v103, v108, v103
	v_max_u32_e32 v108, v107, v101
	v_min_u32_e32 v101, v107, v101
	v_max_u32_e32 v107, v105, v117
	v_min_u32_e32 v117, v105, v117
	v_max_u32_e32 v105, v106, v104
	v_min_u32_e32 v104, v106, v104
	v_max_u32_e32 v106, v116, v111
	v_min_u32_e32 v111, v116, v111
	v_max_u32_e32 v116, v114, v109
	v_min_u32_e32 v109, v114, v109
	v_max_u32_e32 v114, v115, v113
	v_min_u32_e32 v113, v115, v113
	v_max_u32_e32 v115, v112, v102
	v_min_u32_e32 v102, v112, v102
	v_max_u32_e32 v112, v110, v107
	v_min_u32_e32 v107, v110, v107
	v_max_u32_e32 v110, v108, v105
	v_min_u32_e32 v105, v108, v105
	v_max_u32_e32 v108, v103, v117
	v_min_u32_e32 v117, v103, v117
	v_max_u32_e32 v103, v101, v104
	v_min_u32_e32 v104, v101, v104
	v_max_u32_e32 v101, v106, v114
	v_min_u32_e32 v114, v106, v114
	v_max_u32_e32 v106, v116, v115
	v_min_u32_e32 v115, v116, v115
	v_max_u32_e32 v116, v111, v113
	v_min_u32_e32 v113, v111, v113
	v_max_u32_e32 v111, v109, v102
	v_min_u32_e32 v102, v109, v102
	v_max_u32_e32 v109, v112, v110
	v_min_u32_e32 v110, v112, v110
	v_max_u32_e32 v112, v107, v105
	v_min_u32_e32 v105, v107, v105
	v_max_u32_e32 v107, v108, v103
	v_min_u32_e32 v103, v108, v103
	v_max_u32_e32 v108, v117, v104
	v_min_u32_e32 v104, v117, v104
	v_max_u32_e32 v117, v101, v106
	v_min_u32_e32 v106, v101, v106
	v_max_u32_e32 v101, v114, v115
	v_min_u32_e32 v115, v114, v115
	v_max_u32_e32 v114, v116, v111
	v_min_u32_e32 v111, v116, v111
	v_max_u32_e32 v116, v113, v102
	v_min_u32_e32 v102, v113, v102
	s_waitcnt vmcnt(7)
	v_mfma_f32_32x32x16_bf16 v[128:143], v[144:147], v[176:179], 0
	s_waitcnt vmcnt(6)
	v_mfma_f32_32x32x16_bf16 v[128:143], v[148:151], v[180:183], v[128:143]
	s_waitcnt vmcnt(5)
	v_mfma_f32_32x32x16_bf16 v[128:143], v[152:155], v[184:187], v[128:143]
	s_waitcnt vmcnt(4)
	v_mfma_f32_32x32x16_bf16 v[128:143], v[156:159], v[188:191], v[128:143]
	s_waitcnt vmcnt(3)
	v_mfma_f32_32x32x16_bf16 v[128:143], v[160:163], v[192:195], v[128:143]
	s_waitcnt vmcnt(2)
	v_mfma_f32_32x32x16_bf16 v[128:143], v[164:167], v[196:199], v[128:143]
	s_waitcnt vmcnt(1)
	v_mfma_f32_32x32x16_bf16 v[128:143], v[168:171], v[200:203], v[128:143]
	s_waitcnt vmcnt(0)
; #define MFMA32(a, b, c) __builtin_amdgcn_mfma_f32_32x32x16_bf16((a), (b), (c), 0, 0, 0)
; DI int crow(int i, int hh) { return (i & 3) + 8 * (i >> 2) + 4 * hh; }
; template <int LOGN>
; DI void bitonic_sort_desc(unsigned (&a)[1 << LOGN]) {
;   constexpr int N = 1 << LOGN;
; #pragma unroll
;   for (int ks = 1; ks <= LOGN; ++ks)
; #pragma unroll
;     ...
; #pragma unroll
;       for (int i = 0; i < N; ++i) {
;         const int k = 1 << ks, j = 1 << js, l = i ^ j;
;         if (l > i) {
;           const bool desc = ((i & k) == 0) || (ks == LOGN);
;           const unsigned x = a[i], y = a[l];
;           const unsigned hi = max(x, y), lo = min(x, y);
;           a[i] = desc ? hi : lo;
;           a[l] = desc ? lo : hi;
;         }
;       }
; }
; DI void peer_top16(const u16* __restrict__ PQrow, const u16* __restrict__ SK, unsigned (&top)[16], int lr, int hh) {
;     ...
;     for (int ks = 0; ks < 8; ++ks) {
;       bf16x8 a = *(const bf16x8*)(SK + (size_t)(kt * 32 + lr) * 128 + ks * 16 + hh * 8);
;       acc = MFMA32(a, qf[ks], acc);
;     }
; #pragma unroll
;     for (int e = 0; e < 16; ++e) {
;       int kidx = kt * 32 + crow(e, hh);
;       g[kt][e] = (f2ord(acc[e]) & ~127u) | (unsigned)(127 - kidx);
;     }
;     bitonic_sort_desc<4>(g[kt]);
;   }
	v_mfma_f32_32x32x16_bf16 v[128:143], v[172:175], v[204:207], v[128:143]
	s_add_u32 s4, s0, 16384
	s_addc_u32 s5, s1, 0
	global_load_dwordx4 v[144:147], v238, s[4:5] offset:0
	global_load_dwordx4 v[148:151], v238, s[4:5] offset:32
	global_load_dwordx4 v[152:155], v238, s[4:5] offset:64
	global_load_dwordx4 v[156:159], v238, s[4:5] offset:96
	global_load_dwordx4 v[160:163], v238, s[4:5] offset:128
	global_load_dwordx4 v[164:167], v238, s[4:5] offset:160
	global_load_dwordx4 v[168:171], v238, s[4:5] offset:192
	global_load_dwordx4 v[172:175], v238, s[4:5] offset:224
	s_nop 7
	v_ashrrev_i32_e32 v230, 31, v128
	v_or_b32_e32 v230, 0x80000000, v230
	v_xor_b32_e32 v229, v230, v128
	v_and_b32_e32 v229, 0xffffff80, v229
	v_or_b32_e32 v113, v229, v213
	v_ashrrev_i32_e32 v230, 31, v129
	v_or_b32_e32 v230, 0x80000000, v230
	v_xor_b32_e32 v229, v230, v129
	v_and_b32_e32 v229, 0xffffff80, v229
	v_or_b32_e32 v100, v229, v214
	v_ashrrev_i32_e32 v230, 31, v130
	v_or_b32_e32 v230, 0x80000000, v230
	v_xor_b32_e32 v229, v230, v130
	v_and_b32_e32 v229, 0xffffff80, v229
	v_or_b32_e32 v99, v229, v215
	v_ashrrev_i32_e32 v230, 31, v131
	v_or_b32_e32 v230, 0x80000000, v230
	v_xor_b32_e32 v229, v230, v131
	v_and_b32_e32 v229, 0xffffff80, v229
	v_or_b32_e32 v98, v229, v216
	v_ashrrev_i32_e32 v230, 31, v132
	v_or_b32_e32 v230, 0x80000000, v230
	v_xor_b32_e32 v229, v230, v132
	v_and_b32_e32 v229, 0xffffff80, v229
	v_or_b32_e32 v97, v229, v217
	v_ashrrev_i32_e32 v230, 31, v133
	v_or_b32_e32 v230, 0x80000000, v230
	v_xor_b32_e32 v229, v230, v133
	v_and_b32_e32 v229, 0xffffff80, v229
	v_or_b32_e32 v96, v229, v218
	v_ashrrev_i32_e32 v230, 31, v134
	v_or_b32_e32 v230, 0x80000000, v230
	v_xor_b32_e32 v229, v230, v134
	v_and_b32_e32 v229, 0xffffff80, v229
	v_or_b32_e32 v95, v229, v219
	v_ashrrev_i32_e32 v230, 31, v135
	v_or_b32_e32 v230, 0x80000000, v230
	v_xor_b32_e32 v229, v230, v135
	v_and_b32_e32 v229, 0xffffff80, v229
	v_or_b32_e32 v94, v229, v220
	v_ashrrev_i32_e32 v230, 31, v136
	v_or_b32_e32 v230, 0x80000000, v230
	v_xor_b32_e32 v229, v230, v136
	v_and_b32_e32 v229, 0xffffff80, v229
	v_or_b32_e32 v93, v229, v221
	v_ashrrev_i32_e32 v230, 31, v137
	v_or_b32_e32 v230, 0x80000000, v230
	v_xor_b32_e32 v229, v230, v137
	v_and_b32_e32 v229, 0xffffff80, v229
	v_or_b32_e32 v92, v229, v222
	v_ashrrev_i32_e32 v230, 31, v138
	v_or_b32_e32 v230, 0x80000000, v230
	v_xor_b32_e32 v229, v230, v138
	v_and_b32_e32 v229, 0xffffff80, v229
	v_or_b32_e32 v91, v229, v223
	v_ashrrev_i32_e32 v230, 31, v139
	v_or_b32_e32 v230, 0x80000000, v230
	v_xor_b32_e32 v229, v230, v139
	v_and_b32_e32 v229, 0xffffff80, v229
	v_or_b32_e32 v90, v229, v224
	v_ashrrev_i32_e32 v230, 31, v140
	v_or_b32_e32 v230, 0x80000000, v230
	v_xor_b32_e32 v229, v230, v140
	v_and_b32_e32 v229, 0xffffff80, v229
	v_or_b32_e32 v89, v229, v225
	v_ashrrev_i32_e32 v230, 31, v141
	v_or_b32_e32 v230, 0x80000000, v230
	v_xor_b32_e32 v229, v230, v141
	v_and_b32_e32 v229, 0xffffff80, v229
	v_or_b32_e32 v88, v229, v226
	v_ashrrev_i32_e32 v230, 31, v142
	v_or_b32_e32 v230, 0x80000000, v230
	v_xor_b32_e32 v229, v230, v142
	v_and_b32_e32 v229, 0xffffff80, v229
	v_or_b32_e32 v87, v229, v227
	v_ashrrev_i32_e32 v230, 31, v143
	v_or_b32_e32 v230, 0x80000000, v230
	v_xor_b32_e32 v229, v230, v143
	v_and_b32_e32 v229, 0xffffff80, v229
	v_or_b32_e32 v86, v229, v228
	v_subrev_u32_e32 v213, 32, v213
	v_subrev_u32_e32 v214, 32, v214
	v_subrev_u32_e32 v215, 32, v215
	v_subrev_u32_e32 v216, 32, v216
	v_subrev_u32_e32 v217, 32, v217
	v_subrev_u32_e32 v218, 32, v218
	v_subrev_u32_e32 v219, 32, v219
	v_subrev_u32_e32 v220, 32, v220
	v_subrev_u32_e32 v221, 32, v221
	v_subrev_u32_e32 v222, 32, v222
	v_subrev_u32_e32 v223, 32, v223
	v_subrev_u32_e32 v224, 32, v224
	v_subrev_u32_e32 v225, 32, v225
	v_subrev_u32_e32 v226, 32, v226
	v_subrev_u32_e32 v227, 32, v227
	v_subrev_u32_e32 v228, 32, v228
	v_max_u32_e32 v85, v113, v100
	v_min_u32_e32 v100, v113, v100
	v_min_u32_e32 v113, v99, v98
	v_max_u32_e32 v98, v99, v98
	v_max_u32_e32 v99, v97, v96
	v_min_u32_e32 v96, v97, v96
	v_min_u32_e32 v97, v95, v94
	v_max_u32_e32 v94, v95, v94
	v_max_u32_e32 v95, v93, v92
	v_min_u32_e32 v92, v93, v92
	v_min_u32_e32 v93, v91, v90
	v_max_u32_e32 v90, v91, v90
	v_max_u32_e32 v91, v89, v88
	v_min_u32_e32 v88, v89, v88
	v_min_u32_e32 v89, v87, v86
	v_max_u32_e32 v86, v87, v86
	v_max_u32_e32 v87, v85, v113
	v_min_u32_e32 v113, v85, v113
	v_max_u32_e32 v85, v100, v98
	v_min_u32_e32 v98, v100, v98
	v_min_u32_e32 v100, v99, v97
	v_max_u32_e32 v97, v99, v97
	v_min_u32_e32 v99, v96, v94
	v_max_u32_e32 v94, v96, v94
	v_max_u32_e32 v96, v95, v93
	v_min_u32_e32 v93, v95, v93
	v_max_u32_e32 v95, v92, v90
	v_min_u32_e32 v90, v92, v90
	v_min_u32_e32 v92, v91, v89
	v_max_u32_e32 v89, v91, v89
	v_min_u32_e32 v91, v88, v86
	v_max_u32_e32 v86, v88, v86
	v_max_u32_e32 v88, v87, v85
	v_min_u32_e32 v85, v87, v85
	v_max_u32_e32 v87, v113, v98
	v_min_u32_e32 v98, v113, v98
	v_min_u32_e32 v113, v100, v99
	v_max_u32_e32 v99, v100, v99
	v_min_u32_e32 v100, v97, v94
	v_max_u32_e32 v94, v97, v94
	v_max_u32_e32 v97, v96, v95
	v_min_u32_e32 v95, v96, v95
	v_max_u32_e32 v96, v93, v90
	v_min_u32_e32 v90, v93, v90
	v_min_u32_e32 v93, v92, v91
	v_max_u32_e32 v91, v92, v91
	v_min_u32_e32 v92, v89, v86
	v_max_u32_e32 v86, v89, v86
	v_max_u32_e32 v89, v88, v113
	v_min_u32_e32 v113, v88, v113
	v_max_u32_e32 v88, v85, v99
	v_min_u32_e32 v99, v85, v99
	v_max_u32_e32 v85, v87, v100
	v_min_u32_e32 v100, v87, v100
	v_max_u32_e32 v87, v98, v94
	v_min_u32_e32 v94, v98, v94
	v_min_u32_e32 v98, v97, v93
	v_max_u32_e32 v93, v97, v93
	v_min_u32_e32 v97, v95, v91
	v_max_u32_e32 v91, v95, v91
	v_min_u32_e32 v95, v96, v92
; #define MFMA32(a, b, c) __builtin_amdgcn_mfma_f32_32x32x16_bf16((a), (b), (c), 0, 0, 0)
; template <int LOGN>
; DI void bitonic_sort_desc(unsigned (&a)[1 << LOGN]) {
;   constexpr int N = 1 << LOGN;
; #pragma unroll
;   for (int ks = 1; ks <= LOGN; ++ks)
; #pragma unroll
;     ...
; #pragma unroll
;       for (int i = 0; i < N; ++i) {
;         const int k = 1 << ks, j = 1 << js, l = i ^ j;
;         if (l > i) {
;           const bool desc = ((i & k) == 0) || (ks == LOGN);
;           const unsigned x = a[i], y = a[l];
;           const unsigned hi = max(x, y), lo = min(x, y);
;           a[i] = desc ? hi : lo;
;           a[l] = desc ? lo : hi;
;         }
;       }
; }
; DI void merge_top16(unsigned (&a)[16], const unsigned (&b)[16]) {
; #pragma unroll
;   for (int i = 0; i < 16; ++i) a[i] = max(a[i], b[15 - i]);
; #pragma unroll
;     ...
; #pragma unroll
;     for (int i = 0; i < 16; ++i) {
;       const int j = 1 << js, l = i ^ j;
;       if (l > i) {
;         const unsigned x = a[i], y = a[l];
;         a[i] = max(x, y);
;         a[l] = min(x, y);
;       }
;     }
; }
; DI void peer_top16(const u16* __restrict__ PQrow, const u16* __restrict__ SK, unsigned (&top)[16], int lr, int hh) {
;     ...
; #pragma unroll
;     for (int ks = 0; ks < 8; ++ks) {
;       bf16x8 a = *(const bf16x8*)(SK + (size_t)(kt * 32 + lr) * 128 + ks * 16 + hh * 8);
;       acc = MFMA32(a, qf[ks], acc);
;     }
	v_max_u32_e32 v92, v96, v92
	v_min_u32_e32 v96, v90, v86
	v_max_u32_e32 v86, v90, v86
	v_max_u32_e32 v90, v89, v85
	v_min_u32_e32 v85, v89, v85
	v_max_u32_e32 v89, v88, v87
	v_min_u32_e32 v87, v88, v87
	v_max_u32_e32 v88, v113, v100
	v_min_u32_e32 v100, v113, v100
	v_max_u32_e32 v113, v99, v94
	v_min_u32_e32 v94, v99, v94
	v_min_u32_e32 v99, v98, v95
	v_max_u32_e32 v95, v98, v95
	v_min_u32_e32 v98, v97, v96
	v_max_u32_e32 v96, v97, v96
	v_min_u32_e32 v97, v93, v92
	v_max_u32_e32 v92, v93, v92
	v_min_u32_e32 v93, v91, v86
	v_max_u32_e32 v86, v91, v86
	v_max_u32_e32 v91, v90, v89
	v_min_u32_e32 v89, v90, v89
	v_max_u32_e32 v90, v85, v87
	v_min_u32_e32 v87, v85, v87
	v_max_u32_e32 v85, v88, v113
	v_min_u32_e32 v113, v88, v113
	v_max_u32_e32 v88, v100, v94
	v_min_u32_e32 v94, v100, v94
	v_min_u32_e32 v100, v99, v98
	v_max_u32_e32 v98, v99, v98
	v_min_u32_e32 v99, v95, v96
	v_max_u32_e32 v96, v95, v96
	v_min_u32_e32 v95, v97, v93
	v_max_u32_e32 v93, v97, v93
	v_min_u32_e32 v97, v92, v86
	v_max_u32_e32 v86, v92, v86
	v_max_u32_e32 v92, v91, v100
	v_min_u32_e32 v100, v91, v100
	v_max_u32_e32 v91, v89, v98
	v_min_u32_e32 v98, v89, v98
	v_max_u32_e32 v89, v90, v99
	v_min_u32_e32 v99, v90, v99
	v_max_u32_e32 v90, v87, v96
	v_min_u32_e32 v96, v87, v96
	v_max_u32_e32 v87, v85, v95
	v_min_u32_e32 v95, v85, v95
	v_max_u32_e32 v85, v113, v93
	v_min_u32_e32 v93, v113, v93
	v_max_u32_e32 v113, v88, v97
	v_min_u32_e32 v97, v88, v97
	v_max_u32_e32 v88, v94, v86
	v_min_u32_e32 v86, v94, v86
	v_max_u32_e32 v94, v92, v87
	v_min_u32_e32 v87, v92, v87
	v_max_u32_e32 v92, v91, v85
	v_min_u32_e32 v85, v91, v85
	v_max_u32_e32 v91, v89, v113
	v_min_u32_e32 v113, v89, v113
	v_max_u32_e32 v89, v90, v88
	v_min_u32_e32 v88, v90, v88
	v_max_u32_e32 v90, v100, v95
	v_min_u32_e32 v95, v100, v95
	v_max_u32_e32 v100, v98, v93
	v_min_u32_e32 v93, v98, v93
	v_max_u32_e32 v98, v99, v97
	v_min_u32_e32 v97, v99, v97
	v_max_u32_e32 v99, v96, v86
	v_min_u32_e32 v86, v96, v86
	v_max_u32_e32 v96, v94, v91
	v_min_u32_e32 v91, v94, v91
	v_max_u32_e32 v94, v92, v89
	v_min_u32_e32 v89, v92, v89
	v_max_u32_e32 v92, v87, v113
	v_min_u32_e32 v113, v87, v113
	v_max_u32_e32 v87, v85, v88
	v_min_u32_e32 v88, v85, v88
	v_max_u32_e32 v85, v90, v98
	v_min_u32_e32 v98, v90, v98
	v_max_u32_e32 v90, v100, v99
	v_min_u32_e32 v99, v100, v99
	v_max_u32_e32 v100, v95, v97
	v_min_u32_e32 v97, v95, v97
	v_max_u32_e32 v95, v93, v86
	v_min_u32_e32 v86, v93, v86
	v_max_u32_e32 v93, v96, v94
	v_min_u32_e32 v94, v96, v94
	v_max_u32_e32 v96, v91, v89
	v_min_u32_e32 v89, v91, v89
	v_max_u32_e32 v91, v92, v87
	v_min_u32_e32 v87, v92, v87
	v_max_u32_e32 v92, v113, v88
	v_min_u32_e32 v88, v113, v88
	v_max_u32_e32 v113, v85, v90
	v_min_u32_e32 v90, v85, v90
	v_max_u32_e32 v85, v98, v99
	v_min_u32_e32 v99, v98, v99
	v_max_u32_e32 v98, v100, v95
	v_min_u32_e32 v95, v100, v95
	v_max_u32_e32 v100, v97, v86
	v_min_u32_e32 v86, v97, v86
	v_max_u32_e32 v97, v109, v86
	v_max_u32_e32 v109, v110, v100
	v_max_u32_e32 v110, v112, v95
	v_max_u32_e32 v112, v105, v98
	v_max_u32_e32 v105, v107, v99
	v_max_u32_e32 v107, v103, v85
	v_max_u32_e32 v103, v108, v90
	v_max_u32_e32 v108, v104, v113
	v_max_u32_e32 v104, v117, v88
	v_max_u32_e32 v117, v106, v92
	v_max_u32_e32 v106, v101, v87
	v_max_u32_e32 v101, v115, v91
	v_max_u32_e32 v115, v114, v89
	v_max_u32_e32 v114, v111, v96
	v_max_u32_e32 v111, v116, v94
	v_max_u32_e32 v116, v102, v93
	v_max_u32_e32 v86, v97, v104
	v_min_u32_e32 v104, v97, v104
	v_max_u32_e32 v97, v109, v117
	v_min_u32_e32 v117, v109, v117
	v_max_u32_e32 v109, v110, v106
	v_min_u32_e32 v106, v110, v106
	v_max_u32_e32 v110, v112, v101
	v_min_u32_e32 v101, v112, v101
	v_max_u32_e32 v112, v105, v115
	v_min_u32_e32 v115, v105, v115
	v_max_u32_e32 v105, v107, v114
	v_min_u32_e32 v114, v107, v114
	v_max_u32_e32 v107, v103, v111
	v_min_u32_e32 v111, v103, v111
	v_max_u32_e32 v103, v108, v116
	v_min_u32_e32 v116, v108, v116
	v_max_u32_e32 v108, v86, v112
	v_min_u32_e32 v112, v86, v112
	v_max_u32_e32 v86, v97, v105
	v_min_u32_e32 v105, v97, v105
	v_max_u32_e32 v97, v109, v107
	v_min_u32_e32 v107, v109, v107
	v_max_u32_e32 v109, v110, v103
	v_min_u32_e32 v103, v110, v103
	v_max_u32_e32 v110, v104, v115
	v_min_u32_e32 v115, v104, v115
	v_max_u32_e32 v104, v117, v114
	v_min_u32_e32 v114, v117, v114
	v_max_u32_e32 v117, v106, v111
	v_min_u32_e32 v111, v106, v111
	v_max_u32_e32 v106, v101, v116
	v_min_u32_e32 v116, v101, v116
	v_max_u32_e32 v101, v108, v97
	v_min_u32_e32 v97, v108, v97
	v_max_u32_e32 v108, v86, v109
	v_min_u32_e32 v109, v86, v109
	v_max_u32_e32 v86, v112, v107
	v_min_u32_e32 v107, v112, v107
	v_max_u32_e32 v112, v105, v103
	v_min_u32_e32 v103, v105, v103
	v_max_u32_e32 v105, v110, v117
	v_min_u32_e32 v117, v110, v117
	v_max_u32_e32 v110, v104, v106
	v_min_u32_e32 v106, v104, v106
	v_max_u32_e32 v104, v115, v111
	v_min_u32_e32 v111, v115, v111
	v_max_u32_e32 v115, v114, v116
	v_min_u32_e32 v116, v114, v116
	v_max_u32_e32 v114, v101, v108
	v_min_u32_e32 v108, v101, v108
	v_max_u32_e32 v101, v97, v109
	v_min_u32_e32 v109, v97, v109
	v_max_u32_e32 v97, v86, v112
	v_min_u32_e32 v112, v86, v112
	v_max_u32_e32 v86, v107, v103
	v_min_u32_e32 v103, v107, v103
	v_max_u32_e32 v107, v105, v110
	v_min_u32_e32 v110, v105, v110
	v_max_u32_e32 v105, v117, v106
	v_min_u32_e32 v106, v117, v106
	v_max_u32_e32 v117, v104, v115
	v_min_u32_e32 v115, v104, v115
	v_max_u32_e32 v104, v111, v116
	v_min_u32_e32 v116, v111, v116
	s_waitcnt vmcnt(7)
	v_mfma_f32_32x32x16_bf16 v[128:143], v[144:147], v[176:179], 0
	s_waitcnt vmcnt(6)
	v_mfma_f32_32x32x16_bf16 v[128:143], v[148:151], v[180:183], v[128:143]
	s_waitcnt vmcnt(5)
; #define MFMA32(a, b, c) __builtin_amdgcn_mfma_f32_32x32x16_bf16((a), (b), (c), 0, 0, 0)
; DI int crow(int i, int hh) { return (i & 3) + 8 * (i >> 2) + 4 * hh; }
; template <int LOGN>
; DI void bitonic_sort_desc(unsigned (&a)[1 << LOGN]) {
;   constexpr int N = 1 << LOGN;
; #pragma unroll
;   for (int ks = 1; ks <= LOGN; ++ks)
; #pragma unroll
;     ...
; #pragma unroll
;       for (int i = 0; i < N; ++i) {
;         const int k = 1 << ks, j = 1 << js, l = i ^ j;
;         if (l > i) {
;           const bool desc = ((i & k) == 0) || (ks == LOGN);
;           const unsigned x = a[i], y = a[l];
;           const unsigned hi = max(x, y), lo = min(x, y);
;           a[i] = desc ? hi : lo;
;           a[l] = desc ? lo : hi;
;         }
;       }
; }
; DI void peer_top16(const u16* __restrict__ PQrow, const u16* __restrict__ SK, unsigned (&top)[16], int lr, int hh) {
;     ...
;     for (int ks = 0; ks < 8; ++ks) {
;       bf16x8 a = *(const bf16x8*)(SK + (size_t)(kt * 32 + lr) * 128 + ks * 16 + hh * 8);
;       acc = MFMA32(a, qf[ks], acc);
;     }
; #pragma unroll
;     for (int e = 0; e < 16; ++e) {
;       int kidx = kt * 32 + crow(e, hh);
;       g[kt][e] = (f2ord(acc[e]) & ~127u) | (unsigned)(127 - kidx);
;     }
;     bitonic_sort_desc<4>(g[kt]);
;   }
	v_mfma_f32_32x32x16_bf16 v[128:143], v[152:155], v[184:187], v[128:143]
	s_waitcnt vmcnt(4)
	v_mfma_f32_32x32x16_bf16 v[128:143], v[156:159], v[188:191], v[128:143]
	s_waitcnt vmcnt(3)
	v_mfma_f32_32x32x16_bf16 v[128:143], v[160:163], v[192:195], v[128:143]
	s_waitcnt vmcnt(2)
	v_mfma_f32_32x32x16_bf16 v[128:143], v[164:167], v[196:199], v[128:143]
	s_waitcnt vmcnt(1)
	v_mfma_f32_32x32x16_bf16 v[128:143], v[168:171], v[200:203], v[128:143]
	s_waitcnt vmcnt(0)
	v_mfma_f32_32x32x16_bf16 v[128:143], v[172:175], v[204:207], v[128:143]
	s_add_u32 s4, s0, 24576
	s_addc_u32 s5, s1, 0
	global_load_dwordx4 v[144:147], v238, s[4:5] offset:0
	global_load_dwordx4 v[148:151], v238, s[4:5] offset:32
	global_load_dwordx4 v[152:155], v238, s[4:5] offset:64
	global_load_dwordx4 v[156:159], v238, s[4:5] offset:96
	global_load_dwordx4 v[160:163], v238, s[4:5] offset:128
	global_load_dwordx4 v[164:167], v238, s[4:5] offset:160
	global_load_dwordx4 v[168:171], v238, s[4:5] offset:192
	global_load_dwordx4 v[172:175], v238, s[4:5] offset:224
	s_nop 7
	v_ashrrev_i32_e32 v230, 31, v128
	v_or_b32_e32 v230, 0x80000000, v230
	v_xor_b32_e32 v229, v230, v128
	v_and_b32_e32 v229, 0xffffff80, v229
	v_or_b32_e32 v111, v229, v213
	v_ashrrev_i32_e32 v230, 31, v129
	v_or_b32_e32 v230, 0x80000000, v230
	v_xor_b32_e32 v229, v230, v129
	v_and_b32_e32 v229, 0xffffff80, v229
	v_or_b32_e32 v100, v229, v214
	v_ashrrev_i32_e32 v230, 31, v130
	v_or_b32_e32 v230, 0x80000000, v230
	v_xor_b32_e32 v229, v230, v130
	v_and_b32_e32 v229, 0xffffff80, v229
	v_or_b32_e32 v95, v229, v215
	v_ashrrev_i32_e32 v230, 31, v131
	v_or_b32_e32 v230, 0x80000000, v230
	v_xor_b32_e32 v229, v230, v131
	v_and_b32_e32 v229, 0xffffff80, v229
	v_or_b32_e32 v98, v229, v216
	v_ashrrev_i32_e32 v230, 31, v132
	v_or_b32_e32 v230, 0x80000000, v230
	v_xor_b32_e32 v229, v230, v132
	v_and_b32_e32 v229, 0xffffff80, v229
	v_or_b32_e32 v99, v229, v217
	v_ashrrev_i32_e32 v230, 31, v133
	v_or_b32_e32 v230, 0x80000000, v230
	v_xor_b32_e32 v229, v230, v133
	v_and_b32_e32 v229, 0xffffff80, v229
	v_or_b32_e32 v85, v229, v218
	v_ashrrev_i32_e32 v230, 31, v134
	v_or_b32_e32 v230, 0x80000000, v230
	v_xor_b32_e32 v229, v230, v134
	v_and_b32_e32 v229, 0xffffff80, v229
	v_or_b32_e32 v90, v229, v219
	v_ashrrev_i32_e32 v230, 31, v135
	v_or_b32_e32 v230, 0x80000000, v230
	v_xor_b32_e32 v229, v230, v135
	v_and_b32_e32 v229, 0xffffff80, v229
	v_or_b32_e32 v113, v229, v220
	v_ashrrev_i32_e32 v230, 31, v136
	v_or_b32_e32 v230, 0x80000000, v230
	v_xor_b32_e32 v229, v230, v136
	v_and_b32_e32 v229, 0xffffff80, v229
	v_or_b32_e32 v88, v229, v221
	v_ashrrev_i32_e32 v230, 31, v137
	v_or_b32_e32 v230, 0x80000000, v230
	v_xor_b32_e32 v229, v230, v137
	v_and_b32_e32 v229, 0xffffff80, v229
	v_or_b32_e32 v92, v229, v222
	v_ashrrev_i32_e32 v230, 31, v138
	v_or_b32_e32 v230, 0x80000000, v230
	v_xor_b32_e32 v229, v230, v138
	v_and_b32_e32 v229, 0xffffff80, v229
	v_or_b32_e32 v87, v229, v223
	v_ashrrev_i32_e32 v230, 31, v139
	v_or_b32_e32 v230, 0x80000000, v230
	v_xor_b32_e32 v229, v230, v139
	v_and_b32_e32 v229, 0xffffff80, v229
	v_or_b32_e32 v91, v229, v224
	v_ashrrev_i32_e32 v230, 31, v140
	v_or_b32_e32 v230, 0x80000000, v230
	v_xor_b32_e32 v229, v230, v140
	v_and_b32_e32 v229, 0xffffff80, v229
	v_or_b32_e32 v89, v229, v225
	v_ashrrev_i32_e32 v230, 31, v141
	v_or_b32_e32 v230, 0x80000000, v230
	v_xor_b32_e32 v229, v230, v141
	v_and_b32_e32 v229, 0xffffff80, v229
	v_or_b32_e32 v96, v229, v226
	v_ashrrev_i32_e32 v230, 31, v142
	v_or_b32_e32 v230, 0x80000000, v230
	v_xor_b32_e32 v229, v230, v142
	v_and_b32_e32 v229, 0xffffff80, v229
	v_or_b32_e32 v94, v229, v227
	v_ashrrev_i32_e32 v230, 31, v143
	v_or_b32_e32 v230, 0x80000000, v230
	v_xor_b32_e32 v229, v230, v143
	v_and_b32_e32 v229, 0xffffff80, v229
	v_or_b32_e32 v93, v229, v228
	v_subrev_u32_e32 v213, 32, v213
	v_subrev_u32_e32 v214, 32, v214
	v_subrev_u32_e32 v215, 32, v215
	v_subrev_u32_e32 v216, 32, v216
	v_subrev_u32_e32 v217, 32, v217
	v_subrev_u32_e32 v218, 32, v218
	v_subrev_u32_e32 v219, 32, v219
	v_subrev_u32_e32 v220, 32, v220
	v_subrev_u32_e32 v221, 32, v221
	v_subrev_u32_e32 v222, 32, v222
	v_subrev_u32_e32 v223, 32, v223
	v_subrev_u32_e32 v224, 32, v224
	v_subrev_u32_e32 v225, 32, v225
	v_subrev_u32_e32 v226, 32, v226
	v_subrev_u32_e32 v227, 32, v227
	v_subrev_u32_e32 v228, 32, v228
	v_max_u32_e32 v102, v111, v100
	v_min_u32_e32 v100, v111, v100
	v_min_u32_e32 v111, v95, v98
	v_max_u32_e32 v98, v95, v98
	v_max_u32_e32 v95, v99, v85
	v_min_u32_e32 v85, v99, v85
	v_min_u32_e32 v99, v90, v113
	v_max_u32_e32 v113, v90, v113
	v_max_u32_e32 v90, v88, v92
	v_min_u32_e32 v92, v88, v92
	v_min_u32_e32 v88, v87, v91
	v_max_u32_e32 v91, v87, v91
	v_max_u32_e32 v87, v89, v96
	v_min_u32_e32 v96, v89, v96
	v_min_u32_e32 v89, v94, v93
	v_max_u32_e32 v93, v94, v93
	v_max_u32_e32 v94, v102, v111
	v_min_u32_e32 v111, v102, v111
	v_max_u32_e32 v102, v100, v98
	v_min_u32_e32 v98, v100, v98
	v_min_u32_e32 v100, v95, v99
	v_max_u32_e32 v99, v95, v99
	v_min_u32_e32 v95, v85, v113
	v_max_u32_e32 v113, v85, v113
	v_max_u32_e32 v85, v90, v88
	v_min_u32_e32 v88, v90, v88
	v_max_u32_e32 v90, v92, v91
	v_min_u32_e32 v91, v92, v91
	v_min_u32_e32 v92, v87, v89
	v_max_u32_e32 v89, v87, v89
	v_min_u32_e32 v87, v96, v93
	v_max_u32_e32 v93, v96, v93
	v_max_u32_e32 v96, v94, v102
	v_min_u32_e32 v102, v94, v102
	v_max_u32_e32 v94, v111, v98
	v_min_u32_e32 v98, v111, v98
	v_min_u32_e32 v111, v100, v95
	v_max_u32_e32 v95, v100, v95
	v_min_u32_e32 v100, v99, v113
	v_max_u32_e32 v113, v99, v113
	v_max_u32_e32 v99, v85, v90
	v_min_u32_e32 v90, v85, v90
	v_max_u32_e32 v85, v88, v91
	v_min_u32_e32 v91, v88, v91
	v_min_u32_e32 v88, v92, v87
; #define MFMA32(a, b, c) __builtin_amdgcn_mfma_f32_32x32x16_bf16((a), (b), (c), 0, 0, 0)
; DI int crow(int i, int hh) { return (i & 3) + 8 * (i >> 2) + 4 * hh; }
; template <int LOGN>
; DI void bitonic_sort_desc(unsigned (&a)[1 << LOGN]) {
;   constexpr int N = 1 << LOGN;
; #pragma unroll
;   for (int ks = 1; ks <= LOGN; ++ks)
; #pragma unroll
;     ...
; #pragma unroll
;       for (int i = 0; i < N; ++i) {
;         const int k = 1 << ks, j = 1 << js, l = i ^ j;
;         if (l > i) {
;           const bool desc = ((i & k) == 0) || (ks == LOGN);
;           const unsigned x = a[i], y = a[l];
;           const unsigned hi = max(x, y), lo = min(x, y);
;           a[i] = desc ? hi : lo;
;           a[l] = desc ? lo : hi;
;         }
;       }
; }
; DI void peer_top16(const u16* __restrict__ PQrow, const u16* __restrict__ SK, unsigned (&top)[16], int lr, int hh) {
;   bf16x8 qf[8];
; #pragma unroll
;   for (int ks = 0; ks < 8; ++ks) qf[ks] = *(const bf16x8*)(PQrow + ks * 16 + hh * 8);
;   unsigned g[4][16];
; #pragma unroll
;   for (int kt = 0; kt < 4; ++kt) {
;     f32x16 acc;
; #pragma unroll
;     for (int e = 0; e < 16; ++e) acc[e] = 0.f;
; #pragma unroll
;     for (int ks = 0; ks < 8; ++ks) {
;       bf16x8 a = *(const bf16x8*)(SK + (size_t)(kt * 32 + lr) * 128 + ks * 16 + hh * 8);
;       acc = MFMA32(a, qf[ks], acc);
;     }
; #pragma unroll
;     for (int e = 0; e < 16; ++e) {
;       int kidx = kt * 32 + crow(e, hh);
;       g[kt][e] = (f2ord(acc[e]) & ~127u) | (unsigned)(127 - kidx);
	v_max_u32_e32 v87, v92, v87
	v_min_u32_e32 v92, v89, v93
	v_max_u32_e32 v93, v89, v93
	v_max_u32_e32 v89, v96, v111
	v_min_u32_e32 v111, v96, v111
	v_max_u32_e32 v96, v102, v95
	v_min_u32_e32 v95, v102, v95
	v_max_u32_e32 v102, v94, v100
	v_min_u32_e32 v100, v94, v100
	v_max_u32_e32 v94, v98, v113
	v_min_u32_e32 v113, v98, v113
	v_min_u32_e32 v98, v99, v88
	v_max_u32_e32 v88, v99, v88
	v_min_u32_e32 v99, v90, v87
	v_max_u32_e32 v87, v90, v87
	v_min_u32_e32 v90, v85, v92
	v_max_u32_e32 v92, v85, v92
	v_min_u32_e32 v85, v91, v93
	v_max_u32_e32 v93, v91, v93
	v_max_u32_e32 v91, v89, v102
	v_min_u32_e32 v102, v89, v102
	v_max_u32_e32 v89, v96, v94
	v_min_u32_e32 v94, v96, v94
	v_max_u32_e32 v96, v111, v100
	v_min_u32_e32 v100, v111, v100
	v_max_u32_e32 v111, v95, v113
	v_min_u32_e32 v113, v95, v113
	v_min_u32_e32 v95, v98, v90
	v_max_u32_e32 v90, v98, v90
	v_min_u32_e32 v98, v99, v85
	v_max_u32_e32 v85, v99, v85
	v_min_u32_e32 v99, v88, v92
	v_max_u32_e32 v92, v88, v92
	v_min_u32_e32 v88, v87, v93
	v_max_u32_e32 v93, v87, v93
	v_max_u32_e32 v87, v91, v89
	v_min_u32_e32 v89, v91, v89
	v_max_u32_e32 v91, v102, v94
	v_min_u32_e32 v94, v102, v94
	v_max_u32_e32 v102, v96, v111
	v_min_u32_e32 v111, v96, v111
	v_max_u32_e32 v96, v100, v113
	v_min_u32_e32 v113, v100, v113
	v_min_u32_e32 v100, v95, v98
	v_max_u32_e32 v98, v95, v98
	v_min_u32_e32 v95, v90, v85
	v_max_u32_e32 v85, v90, v85
	v_min_u32_e32 v90, v99, v88
	v_max_u32_e32 v88, v99, v88
	v_min_u32_e32 v99, v92, v93
	v_max_u32_e32 v93, v92, v93
	v_max_u32_e32 v92, v87, v100
	v_min_u32_e32 v100, v87, v100
	v_max_u32_e32 v87, v89, v98
	v_min_u32_e32 v98, v89, v98
	v_max_u32_e32 v89, v91, v95
	v_min_u32_e32 v95, v91, v95
	v_max_u32_e32 v91, v94, v85
	v_min_u32_e32 v85, v94, v85
	v_max_u32_e32 v94, v102, v90
	v_min_u32_e32 v90, v102, v90
	v_max_u32_e32 v102, v111, v88
	v_min_u32_e32 v88, v111, v88
	v_max_u32_e32 v111, v96, v99
	v_min_u32_e32 v99, v96, v99
	v_max_u32_e32 v96, v113, v93
	v_min_u32_e32 v93, v113, v93
	v_max_u32_e32 v113, v92, v94
	v_min_u32_e32 v94, v92, v94
	v_max_u32_e32 v92, v87, v102
	v_min_u32_e32 v102, v87, v102
	v_max_u32_e32 v87, v89, v111
	v_min_u32_e32 v111, v89, v111
	v_max_u32_e32 v89, v91, v96
	v_min_u32_e32 v96, v91, v96
	v_max_u32_e32 v91, v100, v90
	v_min_u32_e32 v90, v100, v90
	v_max_u32_e32 v100, v98, v88
	v_min_u32_e32 v88, v98, v88
	v_max_u32_e32 v98, v95, v99
	v_min_u32_e32 v99, v95, v99
	v_max_u32_e32 v95, v85, v93
	v_min_u32_e32 v93, v85, v93
	v_max_u32_e32 v85, v113, v87
	v_min_u32_e32 v87, v113, v87
	v_max_u32_e32 v113, v92, v89
	v_min_u32_e32 v89, v92, v89
	v_max_u32_e32 v92, v94, v111
	v_min_u32_e32 v111, v94, v111
	v_max_u32_e32 v94, v102, v96
	v_min_u32_e32 v96, v102, v96
	v_max_u32_e32 v102, v91, v98
	v_min_u32_e32 v98, v91, v98
	v_max_u32_e32 v91, v100, v95
	v_min_u32_e32 v95, v100, v95
	v_max_u32_e32 v100, v90, v99
	v_min_u32_e32 v99, v90, v99
	v_max_u32_e32 v90, v88, v93
	v_min_u32_e32 v93, v88, v93
	v_max_u32_e32 v88, v85, v113
	v_min_u32_e32 v113, v85, v113
	v_max_u32_e32 v85, v87, v89
	v_min_u32_e32 v89, v87, v89
	v_max_u32_e32 v87, v92, v94
	v_min_u32_e32 v94, v92, v94
	v_max_u32_e32 v92, v111, v96
	v_min_u32_e32 v96, v111, v96
	v_max_u32_e32 v111, v102, v91
	v_min_u32_e32 v91, v102, v91
	v_max_u32_e32 v102, v98, v95
	v_min_u32_e32 v95, v98, v95
	v_max_u32_e32 v98, v100, v90
	v_min_u32_e32 v90, v100, v90
	v_max_u32_e32 v100, v99, v93
	v_min_u32_e32 v93, v99, v93
	s_waitcnt vmcnt(7)
	v_mfma_f32_32x32x16_bf16 v[128:143], v[144:147], v[176:179], 0
	s_waitcnt vmcnt(6)
	v_mfma_f32_32x32x16_bf16 v[128:143], v[148:151], v[180:183], v[128:143]
	s_waitcnt vmcnt(5)
	v_mfma_f32_32x32x16_bf16 v[128:143], v[152:155], v[184:187], v[128:143]
	s_waitcnt vmcnt(4)
	v_mfma_f32_32x32x16_bf16 v[128:143], v[156:159], v[188:191], v[128:143]
	s_waitcnt vmcnt(3)
	v_mfma_f32_32x32x16_bf16 v[128:143], v[160:163], v[192:195], v[128:143]
	s_waitcnt vmcnt(2)
	v_mfma_f32_32x32x16_bf16 v[128:143], v[164:167], v[196:199], v[128:143]
	s_waitcnt vmcnt(1)
	v_mfma_f32_32x32x16_bf16 v[128:143], v[168:171], v[200:203], v[128:143]
	s_waitcnt vmcnt(0)
	v_mfma_f32_32x32x16_bf16 v[128:143], v[172:175], v[204:207], v[128:143]
	global_load_dwordx4 v[176:179], v239, s[2:3] offset:256
	global_load_dwordx4 v[180:183], v239, s[2:3] offset:288
	global_load_dwordx4 v[184:187], v239, s[2:3] offset:320
	global_load_dwordx4 v[188:191], v239, s[2:3] offset:352
	global_load_dwordx4 v[192:195], v239, s[2:3] offset:384
	global_load_dwordx4 v[196:199], v239, s[2:3] offset:416
	global_load_dwordx4 v[200:203], v239, s[2:3] offset:448
	global_load_dwordx4 v[204:207], v239, s[2:3] offset:480
	s_add_u32 s4, s0, 32768
	s_addc_u32 s5, s1, 0
	global_load_dwordx4 v[144:147], v238, s[4:5] offset:0
	global_load_dwordx4 v[148:151], v238, s[4:5] offset:32
	global_load_dwordx4 v[152:155], v238, s[4:5] offset:64
	global_load_dwordx4 v[156:159], v238, s[4:5] offset:96
	global_load_dwordx4 v[160:163], v238, s[4:5] offset:128
	global_load_dwordx4 v[164:167], v238, s[4:5] offset:160
	global_load_dwordx4 v[168:171], v238, s[4:5] offset:192
	global_load_dwordx4 v[172:175], v238, s[4:5] offset:224
	s_nop 7
	v_ashrrev_i32_e32 v230, 31, v128
	v_or_b32_e32 v230, 0x80000000, v230
	v_xor_b32_e32 v229, v230, v128
	v_and_b32_e32 v229, 0xffffff80, v229
	v_or_b32_e32 v99, v229, v213
	v_ashrrev_i32_e32 v230, 31, v129
	v_or_b32_e32 v230, 0x80000000, v230
	v_xor_b32_e32 v229, v230, v129
	v_and_b32_e32 v229, 0xffffff80, v229
	v_or_b32_e32 v84, v229, v214
	v_ashrrev_i32_e32 v230, 31, v130
	v_or_b32_e32 v230, 0x80000000, v230
	v_xor_b32_e32 v229, v230, v130
	v_and_b32_e32 v229, 0xffffff80, v229
	v_or_b32_e32 v83, v229, v215
; DI int crow(int i, int hh) { return (i & 3) + 8 * (i >> 2) + 4 * hh; }
; template <int LOGN>
; DI void bitonic_sort_desc(unsigned (&a)[1 << LOGN]) {
;   constexpr int N = 1 << LOGN;
; #pragma unroll
;   for (int ks = 1; ks <= LOGN; ++ks)
; #pragma unroll
;     ...
; #pragma unroll
;       for (int i = 0; i < N; ++i) {
;         const int k = 1 << ks, j = 1 << js, l = i ^ j;
;         if (l > i) {
;           const bool desc = ((i & k) == 0) || (ks == LOGN);
;           const unsigned x = a[i], y = a[l];
;           const unsigned hi = max(x, y), lo = min(x, y);
;           a[i] = desc ? hi : lo;
;           a[l] = desc ? lo : hi;
;         }
;       }
; }
; DI void peer_top16(const u16* __restrict__ PQrow, const u16* __restrict__ SK, unsigned (&top)[16], int lr, int hh) {
;     ...
;     for (int e = 0; e < 16; ++e) {
;       int kidx = kt * 32 + crow(e, hh);
;       g[kt][e] = (f2ord(acc[e]) & ~127u) | (unsigned)(127 - kidx);
;     }
;     bitonic_sort_desc<4>(g[kt]);
	v_ashrrev_i32_e32 v230, 31, v131
	v_or_b32_e32 v230, 0x80000000, v230
	v_xor_b32_e32 v229, v230, v131
	v_and_b32_e32 v229, 0xffffff80, v229
	v_or_b32_e32 v82, v229, v216
	v_ashrrev_i32_e32 v230, 31, v132
	v_or_b32_e32 v230, 0x80000000, v230
	v_xor_b32_e32 v229, v230, v132
	v_and_b32_e32 v229, 0xffffff80, v229
	v_or_b32_e32 v81, v229, v217
	v_ashrrev_i32_e32 v230, 31, v133
	v_or_b32_e32 v230, 0x80000000, v230
	v_xor_b32_e32 v229, v230, v133
	v_and_b32_e32 v229, 0xffffff80, v229
	v_or_b32_e32 v80, v229, v218
	v_ashrrev_i32_e32 v230, 31, v134
	v_or_b32_e32 v230, 0x80000000, v230
	v_xor_b32_e32 v229, v230, v134
	v_and_b32_e32 v229, 0xffffff80, v229
	v_or_b32_e32 v79, v229, v219
	v_ashrrev_i32_e32 v230, 31, v135
	v_or_b32_e32 v230, 0x80000000, v230
	v_xor_b32_e32 v229, v230, v135
	v_and_b32_e32 v229, 0xffffff80, v229
	v_or_b32_e32 v78, v229, v220
	v_ashrrev_i32_e32 v230, 31, v136
	v_or_b32_e32 v230, 0x80000000, v230
	v_xor_b32_e32 v229, v230, v136
	v_and_b32_e32 v229, 0xffffff80, v229
	v_or_b32_e32 v77, v229, v221
	v_ashrrev_i32_e32 v230, 31, v137
	v_or_b32_e32 v230, 0x80000000, v230
	v_xor_b32_e32 v229, v230, v137
	v_and_b32_e32 v229, 0xffffff80, v229
	v_or_b32_e32 v76, v229, v222
	v_ashrrev_i32_e32 v230, 31, v138
	v_or_b32_e32 v230, 0x80000000, v230
	v_xor_b32_e32 v229, v230, v138
	v_and_b32_e32 v229, 0xffffff80, v229
	v_or_b32_e32 v75, v229, v223
	v_ashrrev_i32_e32 v230, 31, v139
	v_or_b32_e32 v230, 0x80000000, v230
	v_xor_b32_e32 v229, v230, v139
	v_and_b32_e32 v229, 0xffffff80, v229
	v_or_b32_e32 v74, v229, v224
	v_ashrrev_i32_e32 v230, 31, v140
	v_or_b32_e32 v230, 0x80000000, v230
	v_xor_b32_e32 v229, v230, v140
	v_and_b32_e32 v229, 0xffffff80, v229
	v_or_b32_e32 v73, v229, v225
	v_ashrrev_i32_e32 v230, 31, v141
	v_or_b32_e32 v230, 0x80000000, v230
	v_xor_b32_e32 v229, v230, v141
	v_and_b32_e32 v229, 0xffffff80, v229
	v_or_b32_e32 v72, v229, v226
	v_ashrrev_i32_e32 v230, 31, v142
	v_or_b32_e32 v230, 0x80000000, v230
	v_xor_b32_e32 v229, v230, v142
	v_and_b32_e32 v229, 0xffffff80, v229
	v_or_b32_e32 v71, v229, v227
	v_ashrrev_i32_e32 v230, 31, v143
	v_or_b32_e32 v230, 0x80000000, v230
	v_xor_b32_e32 v229, v230, v143
	v_and_b32_e32 v229, 0xffffff80, v229
	v_or_b32_e32 v70, v229, v228
	v_max_u32_e32 v69, v99, v84
	v_min_u32_e32 v84, v99, v84
	v_min_u32_e32 v99, v83, v82
	v_max_u32_e32 v82, v83, v82
	v_max_u32_e32 v83, v81, v80
	v_min_u32_e32 v80, v81, v80
	v_min_u32_e32 v81, v79, v78
	v_max_u32_e32 v78, v79, v78
	v_max_u32_e32 v79, v77, v76
	v_min_u32_e32 v76, v77, v76
	v_min_u32_e32 v77, v75, v74
	v_max_u32_e32 v74, v75, v74
	v_max_u32_e32 v75, v73, v72
	v_min_u32_e32 v72, v73, v72
	v_min_u32_e32 v73, v71, v70
	v_max_u32_e32 v70, v71, v70
	v_max_u32_e32 v71, v69, v99
	v_min_u32_e32 v99, v69, v99
	v_max_u32_e32 v69, v84, v82
	v_min_u32_e32 v82, v84, v82
	v_min_u32_e32 v84, v83, v81
	v_max_u32_e32 v81, v83, v81
	v_min_u32_e32 v83, v80, v78
	v_max_u32_e32 v78, v80, v78
	v_max_u32_e32 v80, v79, v77
	v_min_u32_e32 v77, v79, v77
	v_max_u32_e32 v79, v76, v74
	v_min_u32_e32 v74, v76, v74
	v_min_u32_e32 v76, v75, v73
	v_max_u32_e32 v73, v75, v73
	v_min_u32_e32 v75, v72, v70
	v_max_u32_e32 v70, v72, v70
	v_max_u32_e32 v72, v71, v69
	v_min_u32_e32 v69, v71, v69
	v_max_u32_e32 v71, v99, v82
	v_min_u32_e32 v82, v99, v82
	v_min_u32_e32 v99, v84, v83
	v_max_u32_e32 v83, v84, v83
	v_min_u32_e32 v84, v81, v78
	v_max_u32_e32 v78, v81, v78
	v_max_u32_e32 v81, v80, v79
	v_min_u32_e32 v79, v80, v79
	v_max_u32_e32 v80, v77, v74
	v_min_u32_e32 v74, v77, v74
	v_min_u32_e32 v77, v76, v75
	v_max_u32_e32 v75, v76, v75
	v_min_u32_e32 v76, v73, v70
	v_max_u32_e32 v70, v73, v70
	v_max_u32_e32 v73, v72, v99
	v_min_u32_e32 v99, v72, v99
	v_max_u32_e32 v72, v69, v83
	v_min_u32_e32 v83, v69, v83
	v_max_u32_e32 v69, v71, v84
	v_min_u32_e32 v84, v71, v84
	v_max_u32_e32 v71, v82, v78
	v_min_u32_e32 v78, v82, v78
	v_min_u32_e32 v82, v81, v77
	v_max_u32_e32 v77, v81, v77
	v_min_u32_e32 v81, v79, v75
	v_max_u32_e32 v75, v79, v75
	v_min_u32_e32 v79, v80, v76
	v_max_u32_e32 v76, v80, v76
	v_min_u32_e32 v80, v74, v70
	v_max_u32_e32 v70, v74, v70
	v_max_u32_e32 v74, v73, v69
	v_min_u32_e32 v69, v73, v69
	v_max_u32_e32 v73, v72, v71
	v_min_u32_e32 v71, v72, v71
	v_max_u32_e32 v72, v99, v84
	v_min_u32_e32 v84, v99, v84
	v_max_u32_e32 v99, v83, v78
	v_min_u32_e32 v78, v83, v78
	v_min_u32_e32 v83, v82, v79
	v_max_u32_e32 v79, v82, v79
	v_min_u32_e32 v82, v81, v80
	v_max_u32_e32 v80, v81, v80
	v_min_u32_e32 v81, v77, v76
	v_max_u32_e32 v76, v77, v76
	v_min_u32_e32 v77, v75, v70
	v_max_u32_e32 v70, v75, v70
	v_max_u32_e32 v75, v74, v73
	v_min_u32_e32 v73, v74, v73
	v_max_u32_e32 v74, v69, v71
	v_min_u32_e32 v71, v69, v71
	v_max_u32_e32 v69, v72, v99
	v_min_u32_e32 v99, v72, v99
	v_max_u32_e32 v72, v84, v78
	v_min_u32_e32 v78, v84, v78
	v_min_u32_e32 v84, v83, v82
	v_max_u32_e32 v82, v83, v82
	v_min_u32_e32 v83, v79, v80
	v_max_u32_e32 v80, v79, v80
	v_min_u32_e32 v79, v81, v77
	v_max_u32_e32 v77, v81, v77
	v_min_u32_e32 v81, v76, v70
	v_max_u32_e32 v70, v76, v70
	v_max_u32_e32 v76, v75, v84
	v_min_u32_e32 v84, v75, v84
	v_max_u32_e32 v75, v73, v82
	v_min_u32_e32 v82, v73, v82
	v_max_u32_e32 v73, v74, v83
	v_min_u32_e32 v83, v74, v83
	v_max_u32_e32 v74, v71, v80
	v_min_u32_e32 v80, v71, v80
	v_max_u32_e32 v71, v69, v79
	v_min_u32_e32 v79, v69, v79
	v_max_u32_e32 v69, v99, v77
	v_min_u32_e32 v77, v99, v77
	v_max_u32_e32 v99, v72, v81
	v_min_u32_e32 v81, v72, v81
	v_max_u32_e32 v72, v78, v70
	v_min_u32_e32 v70, v78, v70
	v_max_u32_e32 v78, v76, v71
	v_min_u32_e32 v71, v76, v71
	v_max_u32_e32 v76, v75, v69
	v_min_u32_e32 v69, v75, v69
	v_max_u32_e32 v75, v73, v99
	v_min_u32_e32 v99, v73, v99
; DI void merge_top16(unsigned (&a)[16], const unsigned (&b)[16]) {
; #pragma unroll
;   for (int i = 0; i < 16; ++i) a[i] = max(a[i], b[15 - i]);
; #pragma unroll
;     ...
; #pragma unroll
;     for (int i = 0; i < 16; ++i) {
;       const int j = 1 << js, l = i ^ j;
;       if (l > i) {
;         const unsigned x = a[i], y = a[l];
;         a[i] = max(x, y);
;         a[l] = min(x, y);
;       }
;     }
; }
; DI void peer_top16(const u16* __restrict__ PQrow, const u16* __restrict__ SK, unsigned (&top)[16], int lr, int hh) {
;     ...
;   merge_top16(g[0], g[1]);
;   merge_top16(g[2], g[3]);
;   merge_top16(g[0], g[2]);
;   unsigned other[16];
; #pragma unroll
;   for (int i = 0; i < 16; ++i) other[i] = (unsigned)__shfl_xor((int)g[0][i], 32);
;   merge_top16(g[0], other);
; #pragma unroll
;   for (int i = 0; i < 16; ++i) top[i] = g[0][i];
	v_max_u32_e32 v73, v74, v72
	v_min_u32_e32 v72, v74, v72
	v_max_u32_e32 v74, v84, v79
	v_min_u32_e32 v79, v84, v79
	v_max_u32_e32 v84, v82, v77
	v_min_u32_e32 v77, v82, v77
	v_max_u32_e32 v82, v83, v81
	v_min_u32_e32 v81, v83, v81
	v_max_u32_e32 v83, v80, v70
	v_min_u32_e32 v70, v80, v70
	v_max_u32_e32 v80, v78, v75
	v_min_u32_e32 v75, v78, v75
	v_max_u32_e32 v78, v76, v73
	v_min_u32_e32 v73, v76, v73
	v_max_u32_e32 v76, v71, v99
	v_min_u32_e32 v99, v71, v99
	v_max_u32_e32 v71, v69, v72
	v_min_u32_e32 v72, v69, v72
	v_max_u32_e32 v69, v74, v82
	v_min_u32_e32 v82, v74, v82
	v_max_u32_e32 v74, v84, v83
	v_min_u32_e32 v83, v84, v83
	v_max_u32_e32 v84, v79, v81
	v_min_u32_e32 v81, v79, v81
	v_max_u32_e32 v79, v77, v70
	v_min_u32_e32 v70, v77, v70
	v_max_u32_e32 v77, v80, v78
	v_min_u32_e32 v78, v80, v78
	v_max_u32_e32 v80, v75, v73
	v_min_u32_e32 v73, v75, v73
	v_max_u32_e32 v75, v76, v71
	v_min_u32_e32 v71, v76, v71
	v_max_u32_e32 v76, v99, v72
	v_min_u32_e32 v72, v99, v72
	v_max_u32_e32 v99, v69, v74
	v_min_u32_e32 v74, v69, v74
	v_max_u32_e32 v69, v82, v83
	v_min_u32_e32 v83, v82, v83
	v_max_u32_e32 v82, v84, v79
	v_min_u32_e32 v79, v84, v79
	v_max_u32_e32 v84, v81, v70
	v_min_u32_e32 v70, v81, v70
	v_max_u32_e32 v81, v88, v70
	v_max_u32_e32 v88, v113, v84
	v_max_u32_e32 v113, v85, v79
	v_max_u32_e32 v85, v89, v82
	v_max_u32_e32 v89, v87, v83
	v_max_u32_e32 v87, v94, v69
	v_max_u32_e32 v94, v92, v74
	v_max_u32_e32 v92, v96, v99
	v_max_u32_e32 v96, v111, v72
	v_max_u32_e32 v111, v91, v76
	v_max_u32_e32 v91, v102, v71
	v_max_u32_e32 v102, v95, v75
	v_max_u32_e32 v95, v98, v73
	v_max_u32_e32 v98, v90, v80
	v_max_u32_e32 v90, v100, v78
	v_max_u32_e32 v100, v93, v77
	v_max_u32_e32 v70, v81, v96
	v_min_u32_e32 v96, v81, v96
	v_max_u32_e32 v81, v88, v111
	v_min_u32_e32 v111, v88, v111
	v_max_u32_e32 v88, v113, v91
	v_min_u32_e32 v91, v113, v91
	v_max_u32_e32 v113, v85, v102
	v_min_u32_e32 v102, v85, v102
	v_max_u32_e32 v85, v89, v95
	v_min_u32_e32 v95, v89, v95
	v_max_u32_e32 v89, v87, v98
	v_min_u32_e32 v98, v87, v98
	v_max_u32_e32 v87, v94, v90
	v_min_u32_e32 v90, v94, v90
	v_max_u32_e32 v94, v92, v100
	v_min_u32_e32 v100, v92, v100
	v_max_u32_e32 v92, v70, v85
	v_min_u32_e32 v85, v70, v85
	v_max_u32_e32 v70, v81, v89
	v_min_u32_e32 v89, v81, v89
	v_max_u32_e32 v81, v88, v87
	v_min_u32_e32 v87, v88, v87
	v_max_u32_e32 v88, v113, v94
	v_min_u32_e32 v94, v113, v94
	v_max_u32_e32 v113, v96, v95
	v_min_u32_e32 v95, v96, v95
	v_max_u32_e32 v96, v111, v98
	v_min_u32_e32 v98, v111, v98
	v_max_u32_e32 v111, v91, v90
	v_min_u32_e32 v90, v91, v90
	v_max_u32_e32 v91, v102, v100
	v_min_u32_e32 v100, v102, v100
	v_max_u32_e32 v102, v92, v81
	v_min_u32_e32 v81, v92, v81
	v_max_u32_e32 v92, v70, v88
	v_min_u32_e32 v88, v70, v88
	v_max_u32_e32 v70, v85, v87
	v_min_u32_e32 v87, v85, v87
	v_max_u32_e32 v85, v89, v94
	v_min_u32_e32 v94, v89, v94
	v_max_u32_e32 v89, v113, v111
	v_min_u32_e32 v111, v113, v111
	v_max_u32_e32 v113, v96, v91
	v_min_u32_e32 v91, v96, v91
	v_max_u32_e32 v96, v95, v90
	v_min_u32_e32 v90, v95, v90
	v_max_u32_e32 v95, v98, v100
	v_min_u32_e32 v100, v98, v100
	v_max_u32_e32 v98, v102, v92
	v_min_u32_e32 v92, v102, v92
	v_max_u32_e32 v102, v81, v88
	v_min_u32_e32 v88, v81, v88
	v_max_u32_e32 v81, v70, v85
	v_min_u32_e32 v85, v70, v85
	v_max_u32_e32 v70, v87, v94
	v_min_u32_e32 v94, v87, v94
	v_max_u32_e32 v87, v89, v113
	v_min_u32_e32 v113, v89, v113
	v_max_u32_e32 v89, v111, v91
	v_min_u32_e32 v91, v111, v91
	v_max_u32_e32 v111, v96, v95
	v_min_u32_e32 v95, v96, v95
	v_max_u32_e32 v96, v90, v100
	v_min_u32_e32 v100, v90, v100
	v_max_u32_e32 v90, v114, v100
	v_max_u32_e32 v114, v108, v96
	v_max_u32_e32 v108, v101, v95
	v_max_u32_e32 v101, v109, v111
	v_max_u32_e32 v109, v97, v91
	v_max_u32_e32 v97, v112, v89
	v_max_u32_e32 v112, v86, v113
	v_max_u32_e32 v86, v103, v87
	v_max_u32_e32 v103, v107, v94
	v_max_u32_e32 v107, v110, v70
	v_max_u32_e32 v110, v105, v85
	v_max_u32_e32 v105, v106, v81
	v_max_u32_e32 v106, v117, v88
	v_max_u32_e32 v117, v115, v102
	v_max_u32_e32 v115, v104, v92
	v_max_u32_e32 v104, v116, v98
	v_max_u32_e32 v100, v90, v103
	v_min_u32_e32 v103, v90, v103
	v_max_u32_e32 v90, v114, v107
	v_min_u32_e32 v107, v114, v107
	v_max_u32_e32 v114, v108, v110
	v_min_u32_e32 v110, v108, v110
	v_max_u32_e32 v108, v101, v105
	v_min_u32_e32 v105, v101, v105
	v_max_u32_e32 v101, v109, v106
	v_min_u32_e32 v106, v109, v106
	v_max_u32_e32 v109, v97, v117
	v_min_u32_e32 v117, v97, v117
	v_max_u32_e32 v97, v112, v115
	v_min_u32_e32 v115, v112, v115
	v_max_u32_e32 v112, v86, v104
	v_min_u32_e32 v104, v86, v104
	v_max_u32_e32 v86, v100, v101
	v_min_u32_e32 v101, v100, v101
	v_max_u32_e32 v100, v90, v109
	v_min_u32_e32 v109, v90, v109
	v_max_u32_e32 v90, v114, v97
	v_min_u32_e32 v97, v114, v97
	v_max_u32_e32 v114, v108, v112
	v_min_u32_e32 v112, v108, v112
	v_max_u32_e32 v108, v103, v106
	v_min_u32_e32 v106, v103, v106
	v_max_u32_e32 v103, v107, v117
	v_min_u32_e32 v117, v107, v117
	v_max_u32_e32 v107, v110, v115
	v_min_u32_e32 v115, v110, v115
	v_max_u32_e32 v110, v105, v104
	v_min_u32_e32 v104, v105, v104
	v_max_u32_e32 v105, v86, v90
	v_min_u32_e32 v90, v86, v90
	v_max_u32_e32 v86, v100, v114
	v_min_u32_e32 v114, v100, v114
	v_max_u32_e32 v100, v101, v97
	v_min_u32_e32 v97, v101, v97
	v_max_u32_e32 v101, v109, v112
	v_min_u32_e32 v112, v109, v112
	v_max_u32_e32 v109, v108, v107
	v_min_u32_e32 v107, v108, v107
	v_max_u32_e32 v108, v103, v110
	v_min_u32_e32 v110, v103, v110
	v_max_u32_e32 v103, v106, v115
	v_min_u32_e32 v115, v106, v115
	v_max_u32_e32 v106, v117, v104
	v_min_u32_e32 v104, v117, v104
	v_max_u32_e32 v117, v105, v86
	v_min_u32_e32 v86, v105, v86
	v_max_u32_e32 v105, v90, v114
	v_min_u32_e32 v114, v90, v114
	v_max_u32_e32 v90, v100, v101
	v_min_u32_e32 v101, v100, v101
	v_max_u32_e32 v100, v97, v112
	v_min_u32_e32 v112, v97, v112
	v_max_u32_e32 v97, v109, v108
	v_min_u32_e32 v108, v109, v108
	v_max_u32_e32 v109, v107, v110
	v_min_u32_e32 v110, v107, v110
	v_max_u32_e32 v107, v103, v106
	v_min_u32_e32 v106, v103, v106
	v_max_u32_e32 v103, v115, v104
	v_min_u32_e32 v104, v115, v104
	v_mov_b32_e32 v0, v117
	v_mov_b32_e32 v1, v86
	v_mov_b32_e32 v2, v105
	v_mov_b32_e32 v3, v114
	v_mov_b32_e32 v4, v90
	v_mov_b32_e32 v5, v101
	v_mov_b32_e32 v6, v100
	v_mov_b32_e32 v7, v112
	v_mov_b32_e32 v8, v97
	v_mov_b32_e32 v9, v108
	v_mov_b32_e32 v10, v109
	v_mov_b32_e32 v11, v110
	v_mov_b32_e32 v12, v107
	v_mov_b32_e32 v13, v106
	v_mov_b32_e32 v14, v103
	v_mov_b32_e32 v15, v104
	v_sub_u32_e32 v213, 127, v245
	v_sub_u32_e32 v214, 126, v245
	v_sub_u32_e32 v215, 125, v245
	v_sub_u32_e32 v216, 124, v245
	v_sub_u32_e32 v217, 119, v245
	v_sub_u32_e32 v218, 118, v245
	v_sub_u32_e32 v219, 117, v245
	v_sub_u32_e32 v220, 116, v245
	v_sub_u32_e32 v221, 111, v245
	v_sub_u32_e32 v222, 110, v245
	v_sub_u32_e32 v223, 109, v245
	v_sub_u32_e32 v224, 108, v245
	v_sub_u32_e32 v225, 103, v245
	v_sub_u32_e32 v226, 102, v245
	v_sub_u32_e32 v227, 101, v245
	v_sub_u32_e32 v228, 100, v245
	s_waitcnt vmcnt(7)
; #define MFMA32(a, b, c) __builtin_amdgcn_mfma_f32_32x32x16_bf16((a), (b), (c), 0, 0, 0)
; DI int crow(int i, int hh) { return (i & 3) + 8 * (i >> 2) + 4 * hh; }
; template <int LOGN>
; DI void bitonic_sort_desc(unsigned (&a)[1 << LOGN]) {
;   constexpr int N = 1 << LOGN;
; #pragma unroll
;   for (int ks = 1; ks <= LOGN; ++ks)
; #pragma unroll
;     ...
; #pragma unroll
;       for (int i = 0; i < N; ++i) {
;         const int k = 1 << ks, j = 1 << js, l = i ^ j;
;         if (l > i) {
;           const bool desc = ((i & k) == 0) || (ks == LOGN);
;           const unsigned x = a[i], y = a[l];
;           const unsigned hi = max(x, y), lo = min(x, y);
;           a[i] = desc ? hi : lo;
;           a[l] = desc ? lo : hi;
;         }
;       }
; }
; DI void peer_top16(const u16* __restrict__ PQrow, const u16* __restrict__ SK, unsigned (&top)[16], int lr, int hh) {
;     ...
;     for (int ks = 0; ks < 8; ++ks) {
;       bf16x8 a = *(const bf16x8*)(SK + (size_t)(kt * 32 + lr) * 128 + ks * 16 + hh * 8);
;       acc = MFMA32(a, qf[ks], acc);
;     }
; #pragma unroll
;     for (int e = 0; e < 16; ++e) {
;       int kidx = kt * 32 + crow(e, hh);
;       g[kt][e] = (f2ord(acc[e]) & ~127u) | (unsigned)(127 - kidx);
;     }
;     bitonic_sort_desc<4>(g[kt]);
;   }
	v_mfma_f32_32x32x16_bf16 v[128:143], v[144:147], v[176:179], 0
	s_waitcnt vmcnt(6)
	v_mfma_f32_32x32x16_bf16 v[128:143], v[148:151], v[180:183], v[128:143]
	s_waitcnt vmcnt(5)
	v_mfma_f32_32x32x16_bf16 v[128:143], v[152:155], v[184:187], v[128:143]
	s_waitcnt vmcnt(4)
	v_mfma_f32_32x32x16_bf16 v[128:143], v[156:159], v[188:191], v[128:143]
	s_waitcnt vmcnt(3)
	v_mfma_f32_32x32x16_bf16 v[128:143], v[160:163], v[192:195], v[128:143]
	s_waitcnt vmcnt(2)
	v_mfma_f32_32x32x16_bf16 v[128:143], v[164:167], v[196:199], v[128:143]
	s_waitcnt vmcnt(1)
	v_mfma_f32_32x32x16_bf16 v[128:143], v[168:171], v[200:203], v[128:143]
	s_waitcnt vmcnt(0)
	v_mfma_f32_32x32x16_bf16 v[128:143], v[172:175], v[204:207], v[128:143]
	s_add_u32 s4, s0, 40960
	s_addc_u32 s5, s1, 0
	global_load_dwordx4 v[144:147], v238, s[4:5] offset:0
	global_load_dwordx4 v[148:151], v238, s[4:5] offset:32
	global_load_dwordx4 v[152:155], v238, s[4:5] offset:64
	global_load_dwordx4 v[156:159], v238, s[4:5] offset:96
	global_load_dwordx4 v[160:163], v238, s[4:5] offset:128
	global_load_dwordx4 v[164:167], v238, s[4:5] offset:160
	global_load_dwordx4 v[168:171], v238, s[4:5] offset:192
	global_load_dwordx4 v[172:175], v238, s[4:5] offset:224
	s_nop 7
	v_ashrrev_i32_e32 v230, 31, v128
	v_or_b32_e32 v230, 0x80000000, v230
	v_xor_b32_e32 v229, v230, v128
	v_and_b32_e32 v229, 0xffffff80, v229
	v_or_b32_e32 v104, v229, v213
	v_ashrrev_i32_e32 v230, 31, v129
	v_or_b32_e32 v230, 0x80000000, v230
	v_xor_b32_e32 v229, v230, v129
	v_and_b32_e32 v229, 0xffffff80, v229
	v_or_b32_e32 v103, v229, v214
	v_ashrrev_i32_e32 v230, 31, v130
	v_or_b32_e32 v230, 0x80000000, v230
	v_xor_b32_e32 v229, v230, v130
	v_and_b32_e32 v229, 0xffffff80, v229
	v_or_b32_e32 v106, v229, v215
	v_ashrrev_i32_e32 v230, 31, v131
	v_or_b32_e32 v230, 0x80000000, v230
	v_xor_b32_e32 v229, v230, v131
	v_and_b32_e32 v229, 0xffffff80, v229
	v_or_b32_e32 v107, v229, v216
	v_ashrrev_i32_e32 v230, 31, v132
	v_or_b32_e32 v230, 0x80000000, v230
	v_xor_b32_e32 v229, v230, v132
	v_and_b32_e32 v229, 0xffffff80, v229
	v_or_b32_e32 v110, v229, v217
	v_ashrrev_i32_e32 v230, 31, v133
	v_or_b32_e32 v230, 0x80000000, v230
	v_xor_b32_e32 v229, v230, v133
	v_and_b32_e32 v229, 0xffffff80, v229
	v_or_b32_e32 v109, v229, v218
	v_ashrrev_i32_e32 v230, 31, v134
	v_or_b32_e32 v230, 0x80000000, v230
	v_xor_b32_e32 v229, v230, v134
	v_and_b32_e32 v229, 0xffffff80, v229
	v_or_b32_e32 v108, v229, v219
	v_ashrrev_i32_e32 v230, 31, v135
	v_or_b32_e32 v230, 0x80000000, v230
	v_xor_b32_e32 v229, v230, v135
	v_and_b32_e32 v229, 0xffffff80, v229
	v_or_b32_e32 v97, v229, v220
	v_ashrrev_i32_e32 v230, 31, v136
	v_or_b32_e32 v230, 0x80000000, v230
	v_xor_b32_e32 v229, v230, v136
	v_and_b32_e32 v229, 0xffffff80, v229
	v_or_b32_e32 v112, v229, v221
	v_ashrrev_i32_e32 v230, 31, v137
	v_or_b32_e32 v230, 0x80000000, v230
	v_xor_b32_e32 v229, v230, v137
	v_and_b32_e32 v229, 0xffffff80, v229
	v_or_b32_e32 v100, v229, v222
	v_ashrrev_i32_e32 v230, 31, v138
	v_or_b32_e32 v230, 0x80000000, v230
	v_xor_b32_e32 v229, v230, v138
	v_and_b32_e32 v229, 0xffffff80, v229
	v_or_b32_e32 v101, v229, v223
	v_ashrrev_i32_e32 v230, 31, v139
	v_or_b32_e32 v230, 0x80000000, v230
	v_xor_b32_e32 v229, v230, v139
	v_and_b32_e32 v229, 0xffffff80, v229
	v_or_b32_e32 v90, v229, v224
	v_ashrrev_i32_e32 v230, 31, v140
	v_or_b32_e32 v230, 0x80000000, v230
	v_xor_b32_e32 v229, v230, v140
	v_and_b32_e32 v229, 0xffffff80, v229
	v_or_b32_e32 v114, v229, v225
	v_ashrrev_i32_e32 v230, 31, v141
	v_or_b32_e32 v230, 0x80000000, v230
	v_xor_b32_e32 v229, v230, v141
	v_and_b32_e32 v229, 0xffffff80, v229
	v_or_b32_e32 v105, v229, v226
	v_ashrrev_i32_e32 v230, 31, v142
	v_or_b32_e32 v230, 0x80000000, v230
	v_xor_b32_e32 v229, v230, v142
	v_and_b32_e32 v229, 0xffffff80, v229
	v_or_b32_e32 v86, v229, v227
	v_ashrrev_i32_e32 v230, 31, v143
	v_or_b32_e32 v230, 0x80000000, v230
	v_xor_b32_e32 v229, v230, v143
	v_and_b32_e32 v229, 0xffffff80, v229
	v_or_b32_e32 v117, v229, v228
	v_subrev_u32_e32 v213, 32, v213
	v_subrev_u32_e32 v214, 32, v214
	v_subrev_u32_e32 v215, 32, v215
	v_subrev_u32_e32 v216, 32, v216
	v_subrev_u32_e32 v217, 32, v217
	v_subrev_u32_e32 v218, 32, v218
	v_subrev_u32_e32 v219, 32, v219
	v_subrev_u32_e32 v220, 32, v220
	v_subrev_u32_e32 v221, 32, v221
	v_subrev_u32_e32 v222, 32, v222
	v_subrev_u32_e32 v223, 32, v223
	v_subrev_u32_e32 v224, 32, v224
	v_subrev_u32_e32 v225, 32, v225
	v_subrev_u32_e32 v226, 32, v226
	v_subrev_u32_e32 v227, 32, v227
	v_subrev_u32_e32 v228, 32, v228
	v_max_u32_e32 v115, v104, v103
	v_min_u32_e32 v103, v104, v103
	v_min_u32_e32 v104, v106, v107
	v_max_u32_e32 v107, v106, v107
	v_max_u32_e32 v106, v110, v109
	v_min_u32_e32 v109, v110, v109
	v_min_u32_e32 v110, v108, v97
	v_max_u32_e32 v97, v108, v97
	v_max_u32_e32 v108, v112, v100
	v_min_u32_e32 v100, v112, v100
	v_min_u32_e32 v112, v101, v90
	v_max_u32_e32 v90, v101, v90
	v_max_u32_e32 v101, v114, v105
	v_min_u32_e32 v105, v114, v105
	v_min_u32_e32 v114, v86, v117
	v_max_u32_e32 v117, v86, v117
	v_max_u32_e32 v86, v115, v104
	v_min_u32_e32 v104, v115, v104
	v_max_u32_e32 v115, v103, v107
	v_min_u32_e32 v107, v103, v107
	v_min_u32_e32 v103, v106, v110
	v_max_u32_e32 v110, v106, v110
	v_min_u32_e32 v106, v109, v97
	v_max_u32_e32 v97, v109, v97
	v_max_u32_e32 v109, v108, v112
	v_min_u32_e32 v112, v108, v112
	v_max_u32_e32 v108, v100, v90
	v_min_u32_e32 v90, v100, v90
	v_min_u32_e32 v100, v101, v114
	v_max_u32_e32 v114, v101, v114
	v_min_u32_e32 v101, v105, v117
	v_max_u32_e32 v117, v105, v117
	v_max_u32_e32 v105, v86, v115
	v_min_u32_e32 v115, v86, v115
	v_max_u32_e32 v86, v104, v107
	v_min_u32_e32 v107, v104, v107
; #define MFMA32(a, b, c) __builtin_amdgcn_mfma_f32_32x32x16_bf16((a), (b), (c), 0, 0, 0)
; template <int LOGN>
; DI void bitonic_sort_desc(unsigned (&a)[1 << LOGN]) {
;   constexpr int N = 1 << LOGN;
; #pragma unroll
;   for (int ks = 1; ks <= LOGN; ++ks)
; #pragma unroll
;     ...
; #pragma unroll
;       for (int i = 0; i < N; ++i) {
;         const int k = 1 << ks, j = 1 << js, l = i ^ j;
;         if (l > i) {
;           const bool desc = ((i & k) == 0) || (ks == LOGN);
;           const unsigned x = a[i], y = a[l];
;           const unsigned hi = max(x, y), lo = min(x, y);
;           a[i] = desc ? hi : lo;
;           a[l] = desc ? lo : hi;
;         }
;       }
; }
; DI void peer_top16(const u16* __restrict__ PQrow, const u16* __restrict__ SK, unsigned (&top)[16], int lr, int hh) {
;     ...
; #pragma unroll
;     for (int ks = 0; ks < 8; ++ks) {
;       bf16x8 a = *(const bf16x8*)(SK + (size_t)(kt * 32 + lr) * 128 + ks * 16 + hh * 8);
;       acc = MFMA32(a, qf[ks], acc);
;     }
	v_min_u32_e32 v104, v103, v106
	v_max_u32_e32 v106, v103, v106
	v_min_u32_e32 v103, v110, v97
	v_max_u32_e32 v97, v110, v97
	v_max_u32_e32 v110, v109, v108
	v_min_u32_e32 v108, v109, v108
	v_max_u32_e32 v109, v112, v90
	v_min_u32_e32 v90, v112, v90
	v_min_u32_e32 v112, v100, v101
	v_max_u32_e32 v101, v100, v101
	v_min_u32_e32 v100, v114, v117
	v_max_u32_e32 v117, v114, v117
	v_max_u32_e32 v114, v105, v104
	v_min_u32_e32 v104, v105, v104
	v_max_u32_e32 v105, v115, v106
	v_min_u32_e32 v106, v115, v106
	v_max_u32_e32 v115, v86, v103
	v_min_u32_e32 v103, v86, v103
	v_max_u32_e32 v86, v107, v97
	v_min_u32_e32 v97, v107, v97
	v_min_u32_e32 v107, v110, v112
	v_max_u32_e32 v112, v110, v112
	v_min_u32_e32 v110, v108, v101
	v_max_u32_e32 v101, v108, v101
	v_min_u32_e32 v108, v109, v100
	v_max_u32_e32 v100, v109, v100
	v_min_u32_e32 v109, v90, v117
	v_max_u32_e32 v117, v90, v117
	v_max_u32_e32 v90, v114, v115
	v_min_u32_e32 v115, v114, v115
	v_max_u32_e32 v114, v105, v86
	v_min_u32_e32 v86, v105, v86
	v_max_u32_e32 v105, v104, v103
	v_min_u32_e32 v103, v104, v103
	v_max_u32_e32 v104, v106, v97
	v_min_u32_e32 v97, v106, v97
	v_min_u32_e32 v106, v107, v108
	v_max_u32_e32 v108, v107, v108
	v_min_u32_e32 v107, v110, v109
	v_max_u32_e32 v109, v110, v109
	v_min_u32_e32 v110, v112, v100
	v_max_u32_e32 v100, v112, v100
	v_min_u32_e32 v112, v101, v117
	v_max_u32_e32 v117, v101, v117
	v_max_u32_e32 v101, v90, v114
	v_min_u32_e32 v114, v90, v114
	v_max_u32_e32 v90, v115, v86
	v_min_u32_e32 v86, v115, v86
	v_max_u32_e32 v115, v105, v104
	v_min_u32_e32 v104, v105, v104
	v_max_u32_e32 v105, v103, v97
	v_min_u32_e32 v97, v103, v97
	v_min_u32_e32 v103, v106, v107
	v_max_u32_e32 v107, v106, v107
	v_min_u32_e32 v106, v108, v109
	v_max_u32_e32 v109, v108, v109
	v_min_u32_e32 v108, v110, v112
	v_max_u32_e32 v112, v110, v112
	v_min_u32_e32 v110, v100, v117
	v_max_u32_e32 v117, v100, v117
	v_max_u32_e32 v100, v101, v103
	v_min_u32_e32 v103, v101, v103
	v_max_u32_e32 v101, v114, v107
	v_min_u32_e32 v107, v114, v107
	v_max_u32_e32 v114, v90, v106
	v_min_u32_e32 v106, v90, v106
	v_max_u32_e32 v90, v86, v109
	v_min_u32_e32 v109, v86, v109
	v_max_u32_e32 v86, v115, v108
	v_min_u32_e32 v108, v115, v108
	v_max_u32_e32 v115, v104, v112
	v_min_u32_e32 v112, v104, v112
	v_max_u32_e32 v104, v105, v110
	v_min_u32_e32 v110, v105, v110
	v_max_u32_e32 v105, v97, v117
	v_min_u32_e32 v117, v97, v117
	v_max_u32_e32 v97, v100, v86
	v_min_u32_e32 v86, v100, v86
	v_max_u32_e32 v100, v101, v115
	v_min_u32_e32 v115, v101, v115
	v_max_u32_e32 v101, v114, v104
	v_min_u32_e32 v104, v114, v104
	v_max_u32_e32 v114, v90, v105
	v_min_u32_e32 v105, v90, v105
	v_max_u32_e32 v90, v103, v108
	v_min_u32_e32 v108, v103, v108
	v_max_u32_e32 v103, v107, v112
	v_min_u32_e32 v112, v107, v112
	v_max_u32_e32 v107, v106, v110
	v_min_u32_e32 v110, v106, v110
	v_max_u32_e32 v106, v109, v117
	v_min_u32_e32 v117, v109, v117
	v_max_u32_e32 v109, v97, v101
	v_min_u32_e32 v101, v97, v101
	v_max_u32_e32 v97, v100, v114
	v_min_u32_e32 v114, v100, v114
	v_max_u32_e32 v100, v86, v104
	v_min_u32_e32 v104, v86, v104
	v_max_u32_e32 v86, v115, v105
	v_min_u32_e32 v105, v115, v105
	v_max_u32_e32 v115, v90, v107
	v_min_u32_e32 v107, v90, v107
	v_max_u32_e32 v90, v103, v106
	v_min_u32_e32 v106, v103, v106
	v_max_u32_e32 v103, v108, v110
	v_min_u32_e32 v110, v108, v110
	v_max_u32_e32 v108, v112, v117
	v_min_u32_e32 v117, v112, v117
	v_max_u32_e32 v112, v109, v97
	v_min_u32_e32 v97, v109, v97
	v_max_u32_e32 v109, v101, v114
	v_min_u32_e32 v114, v101, v114
	v_max_u32_e32 v101, v100, v86
	v_min_u32_e32 v86, v100, v86
	v_max_u32_e32 v100, v104, v105
	v_min_u32_e32 v105, v104, v105
	v_max_u32_e32 v104, v115, v90
	v_min_u32_e32 v90, v115, v90
	v_max_u32_e32 v115, v107, v106
	v_min_u32_e32 v106, v107, v106
	v_max_u32_e32 v107, v103, v108
	v_min_u32_e32 v108, v103, v108
	v_max_u32_e32 v103, v110, v117
	v_min_u32_e32 v117, v110, v117
	s_waitcnt vmcnt(7)
	v_mfma_f32_32x32x16_bf16 v[128:143], v[144:147], v[176:179], 0
	s_waitcnt vmcnt(6)
	v_mfma_f32_32x32x16_bf16 v[128:143], v[148:151], v[180:183], v[128:143]
	s_waitcnt vmcnt(5)
	v_mfma_f32_32x32x16_bf16 v[128:143], v[152:155], v[184:187], v[128:143]
	s_waitcnt vmcnt(4)
	v_mfma_f32_32x32x16_bf16 v[128:143], v[156:159], v[188:191], v[128:143]
	s_waitcnt vmcnt(3)
	v_mfma_f32_32x32x16_bf16 v[128:143], v[160:163], v[192:195], v[128:143]
	s_waitcnt vmcnt(2)
	v_mfma_f32_32x32x16_bf16 v[128:143], v[164:167], v[196:199], v[128:143]
	s_waitcnt vmcnt(1)
	v_mfma_f32_32x32x16_bf16 v[128:143], v[168:171], v[200:203], v[128:143]
	s_waitcnt vmcnt(0)
; #define MFMA32(a, b, c) __builtin_amdgcn_mfma_f32_32x32x16_bf16((a), (b), (c), 0, 0, 0)
; DI int crow(int i, int hh) { return (i & 3) + 8 * (i >> 2) + 4 * hh; }
; template <int LOGN>
; DI void bitonic_sort_desc(unsigned (&a)[1 << LOGN]) {
;   constexpr int N = 1 << LOGN;
; #pragma unroll
;   for (int ks = 1; ks <= LOGN; ++ks)
; #pragma unroll
;     ...
; #pragma unroll
;       for (int i = 0; i < N; ++i) {
;         const int k = 1 << ks, j = 1 << js, l = i ^ j;
;         if (l > i) {
;           const bool desc = ((i & k) == 0) || (ks == LOGN);
;           const unsigned x = a[i], y = a[l];
;           const unsigned hi = max(x, y), lo = min(x, y);
;           a[i] = desc ? hi : lo;
;           a[l] = desc ? lo : hi;
;         }
;       }
; }
; DI void peer_top16(const u16* __restrict__ PQrow, const u16* __restrict__ SK, unsigned (&top)[16], int lr, int hh) {
;     ...
;     for (int ks = 0; ks < 8; ++ks) {
;       bf16x8 a = *(const bf16x8*)(SK + (size_t)(kt * 32 + lr) * 128 + ks * 16 + hh * 8);
;       acc = MFMA32(a, qf[ks], acc);
;     }
; #pragma unroll
;     for (int e = 0; e < 16; ++e) {
;       int kidx = kt * 32 + crow(e, hh);
;       g[kt][e] = (f2ord(acc[e]) & ~127u) | (unsigned)(127 - kidx);
;     }
;     bitonic_sort_desc<4>(g[kt]);
;   }
	v_mfma_f32_32x32x16_bf16 v[128:143], v[172:175], v[204:207], v[128:143]
	s_add_u32 s4, s0, 49152
	s_addc_u32 s5, s1, 0
	global_load_dwordx4 v[144:147], v238, s[4:5] offset:0
	global_load_dwordx4 v[148:151], v238, s[4:5] offset:32
	global_load_dwordx4 v[152:155], v238, s[4:5] offset:64
	global_load_dwordx4 v[156:159], v238, s[4:5] offset:96
	global_load_dwordx4 v[160:163], v238, s[4:5] offset:128
	global_load_dwordx4 v[164:167], v238, s[4:5] offset:160
	global_load_dwordx4 v[168:171], v238, s[4:5] offset:192
	global_load_dwordx4 v[172:175], v238, s[4:5] offset:224
	s_nop 7
	v_ashrrev_i32_e32 v230, 31, v128
	v_or_b32_e32 v230, 0x80000000, v230
	v_xor_b32_e32 v229, v230, v128
	v_and_b32_e32 v229, 0xffffff80, v229
	v_or_b32_e32 v110, v229, v213
	v_ashrrev_i32_e32 v230, 31, v129
	v_or_b32_e32 v230, 0x80000000, v230
	v_xor_b32_e32 v229, v230, v129
	v_and_b32_e32 v229, 0xffffff80, v229
	v_or_b32_e32 v96, v229, v214
	v_ashrrev_i32_e32 v230, 31, v130
	v_or_b32_e32 v230, 0x80000000, v230
	v_xor_b32_e32 v229, v230, v130
	v_and_b32_e32 v229, 0xffffff80, v229
	v_or_b32_e32 v95, v229, v215
	v_ashrrev_i32_e32 v230, 31, v131
	v_or_b32_e32 v230, 0x80000000, v230
	v_xor_b32_e32 v229, v230, v131
	v_and_b32_e32 v229, 0xffffff80, v229
	v_or_b32_e32 v111, v229, v216
	v_ashrrev_i32_e32 v230, 31, v132
	v_or_b32_e32 v230, 0x80000000, v230
	v_xor_b32_e32 v229, v230, v132
	v_and_b32_e32 v229, 0xffffff80, v229
	v_or_b32_e32 v91, v229, v217
	v_ashrrev_i32_e32 v230, 31, v133
	v_or_b32_e32 v230, 0x80000000, v230
	v_xor_b32_e32 v229, v230, v133
	v_and_b32_e32 v229, 0xffffff80, v229
	v_or_b32_e32 v89, v229, v218
	v_ashrrev_i32_e32 v230, 31, v134
	v_or_b32_e32 v230, 0x80000000, v230
	v_xor_b32_e32 v229, v230, v134
	v_and_b32_e32 v229, 0xffffff80, v229
	v_or_b32_e32 v113, v229, v219
	v_ashrrev_i32_e32 v230, 31, v135
	v_or_b32_e32 v230, 0x80000000, v230
	v_xor_b32_e32 v229, v230, v135
	v_and_b32_e32 v229, 0xffffff80, v229
	v_or_b32_e32 v87, v229, v220
	v_ashrrev_i32_e32 v230, 31, v136
	v_or_b32_e32 v230, 0x80000000, v230
	v_xor_b32_e32 v229, v230, v136
	v_and_b32_e32 v229, 0xffffff80, v229
	v_or_b32_e32 v94, v229, v221
	v_ashrrev_i32_e32 v230, 31, v137
	v_or_b32_e32 v230, 0x80000000, v230
	v_xor_b32_e32 v229, v230, v137
	v_and_b32_e32 v229, 0xffffff80, v229
	v_or_b32_e32 v70, v229, v222
	v_ashrrev_i32_e32 v230, 31, v138
	v_or_b32_e32 v230, 0x80000000, v230
	v_xor_b32_e32 v229, v230, v138
	v_and_b32_e32 v229, 0xffffff80, v229
	v_or_b32_e32 v85, v229, v223
	v_ashrrev_i32_e32 v230, 31, v139
	v_or_b32_e32 v230, 0x80000000, v230
	v_xor_b32_e32 v229, v230, v139
	v_and_b32_e32 v229, 0xffffff80, v229
	v_or_b32_e32 v81, v229, v224
	v_ashrrev_i32_e32 v230, 31, v140
	v_or_b32_e32 v230, 0x80000000, v230
	v_xor_b32_e32 v229, v230, v140
	v_and_b32_e32 v229, 0xffffff80, v229
	v_or_b32_e32 v88, v229, v225
	v_ashrrev_i32_e32 v230, 31, v141
	v_or_b32_e32 v230, 0x80000000, v230
	v_xor_b32_e32 v229, v230, v141
	v_and_b32_e32 v229, 0xffffff80, v229
	v_or_b32_e32 v102, v229, v226
	v_ashrrev_i32_e32 v230, 31, v142
	v_or_b32_e32 v230, 0x80000000, v230
	v_xor_b32_e32 v229, v230, v142
	v_and_b32_e32 v229, 0xffffff80, v229
	v_or_b32_e32 v92, v229, v227
	v_ashrrev_i32_e32 v230, 31, v143
	v_or_b32_e32 v230, 0x80000000, v230
	v_xor_b32_e32 v229, v230, v143
	v_and_b32_e32 v229, 0xffffff80, v229
	v_or_b32_e32 v98, v229, v228
	v_subrev_u32_e32 v213, 32, v213
	v_subrev_u32_e32 v214, 32, v214
	v_subrev_u32_e32 v215, 32, v215
	v_subrev_u32_e32 v216, 32, v216
	v_subrev_u32_e32 v217, 32, v217
	v_subrev_u32_e32 v218, 32, v218
	v_subrev_u32_e32 v219, 32, v219
	v_subrev_u32_e32 v220, 32, v220
	v_subrev_u32_e32 v221, 32, v221
	v_subrev_u32_e32 v222, 32, v222
	v_subrev_u32_e32 v223, 32, v223
	v_subrev_u32_e32 v224, 32, v224
	v_subrev_u32_e32 v225, 32, v225
	v_subrev_u32_e32 v226, 32, v226
	v_subrev_u32_e32 v227, 32, v227
	v_subrev_u32_e32 v228, 32, v228
	v_max_u32_e32 v116, v110, v96
	v_min_u32_e32 v96, v110, v96
	v_min_u32_e32 v110, v95, v111
	v_max_u32_e32 v111, v95, v111
	v_max_u32_e32 v95, v91, v89
	v_min_u32_e32 v89, v91, v89
	v_min_u32_e32 v91, v113, v87
	v_max_u32_e32 v87, v113, v87
	v_max_u32_e32 v113, v94, v70
	v_min_u32_e32 v70, v94, v70
	v_min_u32_e32 v94, v85, v81
	v_max_u32_e32 v81, v85, v81
	v_max_u32_e32 v85, v88, v102
	v_min_u32_e32 v102, v88, v102
	v_min_u32_e32 v88, v92, v98
	v_max_u32_e32 v98, v92, v98
	v_max_u32_e32 v92, v116, v110
	v_min_u32_e32 v110, v116, v110
	v_max_u32_e32 v116, v96, v111
	v_min_u32_e32 v111, v96, v111
	v_min_u32_e32 v96, v95, v91
	v_max_u32_e32 v91, v95, v91
	v_min_u32_e32 v95, v89, v87
	v_max_u32_e32 v87, v89, v87
	v_max_u32_e32 v89, v113, v94
	v_min_u32_e32 v94, v113, v94
	v_max_u32_e32 v113, v70, v81
	v_min_u32_e32 v81, v70, v81
	v_min_u32_e32 v70, v85, v88
	v_max_u32_e32 v88, v85, v88
	v_min_u32_e32 v85, v102, v98
	v_max_u32_e32 v98, v102, v98
	v_max_u32_e32 v102, v92, v116
	v_min_u32_e32 v116, v92, v116
	v_max_u32_e32 v92, v110, v111
	v_min_u32_e32 v111, v110, v111
	v_min_u32_e32 v110, v96, v95
	v_max_u32_e32 v95, v96, v95
	v_min_u32_e32 v96, v91, v87
	v_max_u32_e32 v87, v91, v87
	v_max_u32_e32 v91, v89, v113
	v_min_u32_e32 v113, v89, v113
	v_max_u32_e32 v89, v94, v81
	v_min_u32_e32 v81, v94, v81
	v_min_u32_e32 v94, v70, v85
	v_max_u32_e32 v85, v70, v85
	v_min_u32_e32 v70, v88, v98
	v_max_u32_e32 v98, v88, v98
	v_max_u32_e32 v88, v102, v110
	v_min_u32_e32 v110, v102, v110
	v_max_u32_e32 v102, v116, v95
	v_min_u32_e32 v95, v116, v95
	v_max_u32_e32 v116, v92, v96
	v_min_u32_e32 v96, v92, v96
	v_max_u32_e32 v92, v111, v87
	v_min_u32_e32 v87, v111, v87
	v_min_u32_e32 v111, v91, v94
	v_max_u32_e32 v94, v91, v94
	v_min_u32_e32 v91, v113, v85
	v_max_u32_e32 v85, v113, v85
; template <int LOGN>
; DI void bitonic_sort_desc(unsigned (&a)[1 << LOGN]) {
;   constexpr int N = 1 << LOGN;
; #pragma unroll
;   for (int ks = 1; ks <= LOGN; ++ks)
; #pragma unroll
;     ...
; #pragma unroll
;       for (int i = 0; i < N; ++i) {
;         const int k = 1 << ks, j = 1 << js, l = i ^ j;
;         if (l > i) {
;           const bool desc = ((i & k) == 0) || (ks == LOGN);
;           const unsigned x = a[i], y = a[l];
;           const unsigned hi = max(x, y), lo = min(x, y);
;           a[i] = desc ? hi : lo;
;           a[l] = desc ? lo : hi;
;         }
;       }
; }
; DI void merge_top16(unsigned (&a)[16], const unsigned (&b)[16]) {
; #pragma unroll
;   for (int i = 0; i < 16; ++i) a[i] = max(a[i], b[15 - i]);
; #pragma unroll
;     ...
; #pragma unroll
;     for (int i = 0; i < 16; ++i) {
;       const int j = 1 << js, l = i ^ j;
;       if (l > i) {
;         const unsigned x = a[i], y = a[l];
;         a[i] = max(x, y);
;         a[l] = min(x, y);
;       }
;     }
; }
	v_min_u32_e32 v113, v89, v70
	v_max_u32_e32 v70, v89, v70
	v_min_u32_e32 v89, v81, v98
	v_max_u32_e32 v98, v81, v98
	v_max_u32_e32 v81, v88, v116
	v_min_u32_e32 v116, v88, v116
	v_max_u32_e32 v88, v102, v92
	v_min_u32_e32 v92, v102, v92
	v_max_u32_e32 v102, v110, v96
	v_min_u32_e32 v96, v110, v96
	v_max_u32_e32 v110, v95, v87
	v_min_u32_e32 v87, v95, v87
	v_min_u32_e32 v95, v111, v113
	v_max_u32_e32 v113, v111, v113
	v_min_u32_e32 v111, v91, v89
	v_max_u32_e32 v89, v91, v89
	v_min_u32_e32 v91, v94, v70
	v_max_u32_e32 v70, v94, v70
	v_min_u32_e32 v94, v85, v98
	v_max_u32_e32 v98, v85, v98
	v_max_u32_e32 v85, v81, v88
	v_min_u32_e32 v88, v81, v88
	v_max_u32_e32 v81, v116, v92
	v_min_u32_e32 v92, v116, v92
	v_max_u32_e32 v116, v102, v110
	v_min_u32_e32 v110, v102, v110
	v_max_u32_e32 v102, v96, v87
	v_min_u32_e32 v87, v96, v87
	v_min_u32_e32 v96, v95, v111
	v_max_u32_e32 v111, v95, v111
	v_min_u32_e32 v95, v113, v89
	v_max_u32_e32 v89, v113, v89
	v_min_u32_e32 v113, v91, v94
	v_max_u32_e32 v94, v91, v94
	v_min_u32_e32 v91, v70, v98
	v_max_u32_e32 v98, v70, v98
	v_max_u32_e32 v70, v85, v96
	v_min_u32_e32 v96, v85, v96
	v_max_u32_e32 v85, v88, v111
	v_min_u32_e32 v111, v88, v111
	v_max_u32_e32 v88, v81, v95
	v_min_u32_e32 v95, v81, v95
	v_max_u32_e32 v81, v92, v89
	v_min_u32_e32 v89, v92, v89
	v_max_u32_e32 v92, v116, v113
	v_min_u32_e32 v113, v116, v113
	v_max_u32_e32 v116, v110, v94
	v_min_u32_e32 v94, v110, v94
	v_max_u32_e32 v110, v102, v91
	v_min_u32_e32 v91, v102, v91
	v_max_u32_e32 v102, v87, v98
	v_min_u32_e32 v98, v87, v98
	v_max_u32_e32 v87, v70, v92
	v_min_u32_e32 v92, v70, v92
	v_max_u32_e32 v70, v85, v116
	v_min_u32_e32 v116, v85, v116
	v_max_u32_e32 v85, v88, v110
	v_min_u32_e32 v110, v88, v110
	v_max_u32_e32 v88, v81, v102
	v_min_u32_e32 v102, v81, v102
	v_max_u32_e32 v81, v96, v113
	v_min_u32_e32 v113, v96, v113
	v_max_u32_e32 v96, v111, v94
	v_min_u32_e32 v94, v111, v94
	v_max_u32_e32 v111, v95, v91
	v_min_u32_e32 v91, v95, v91
	v_max_u32_e32 v95, v89, v98
	v_min_u32_e32 v98, v89, v98
	v_max_u32_e32 v89, v87, v85
	v_min_u32_e32 v85, v87, v85
	v_max_u32_e32 v87, v70, v88
	v_min_u32_e32 v88, v70, v88
	v_max_u32_e32 v70, v92, v110
	v_min_u32_e32 v110, v92, v110
	v_max_u32_e32 v92, v116, v102
	v_min_u32_e32 v102, v116, v102
	v_max_u32_e32 v116, v81, v111
	v_min_u32_e32 v111, v81, v111
	v_max_u32_e32 v81, v96, v95
	v_min_u32_e32 v95, v96, v95
	v_max_u32_e32 v96, v113, v91
	v_min_u32_e32 v91, v113, v91
	v_max_u32_e32 v113, v94, v98
	v_min_u32_e32 v98, v94, v98
	v_max_u32_e32 v94, v89, v87
	v_min_u32_e32 v87, v89, v87
	v_max_u32_e32 v89, v85, v88
	v_min_u32_e32 v88, v85, v88
	v_max_u32_e32 v85, v70, v92
	v_min_u32_e32 v92, v70, v92
	v_max_u32_e32 v70, v110, v102
	v_min_u32_e32 v102, v110, v102
	v_max_u32_e32 v110, v116, v81
	v_min_u32_e32 v81, v116, v81
	v_max_u32_e32 v116, v111, v95
	v_min_u32_e32 v95, v111, v95
	v_max_u32_e32 v111, v96, v113
	v_min_u32_e32 v113, v96, v113
	v_max_u32_e32 v96, v91, v98
	v_min_u32_e32 v98, v91, v98
	v_max_u32_e32 v91, v112, v98
	v_max_u32_e32 v112, v97, v96
	v_max_u32_e32 v97, v109, v113
	v_max_u32_e32 v109, v114, v111
	v_max_u32_e32 v114, v101, v95
	v_max_u32_e32 v101, v86, v116
	v_max_u32_e32 v86, v100, v81
	v_max_u32_e32 v100, v105, v110
	v_max_u32_e32 v105, v104, v102
	v_max_u32_e32 v104, v90, v70
	v_max_u32_e32 v90, v115, v92
	v_max_u32_e32 v115, v106, v85
	v_max_u32_e32 v106, v107, v88
	v_max_u32_e32 v107, v108, v89
	v_max_u32_e32 v108, v103, v87
	v_max_u32_e32 v103, v117, v94
	v_max_u32_e32 v98, v91, v105
	v_min_u32_e32 v105, v91, v105
	v_max_u32_e32 v91, v112, v104
	v_min_u32_e32 v104, v112, v104
	v_max_u32_e32 v112, v97, v90
	v_min_u32_e32 v90, v97, v90
	v_max_u32_e32 v97, v109, v115
	v_min_u32_e32 v115, v109, v115
	v_max_u32_e32 v109, v114, v106
	v_min_u32_e32 v106, v114, v106
	v_max_u32_e32 v114, v101, v107
	v_min_u32_e32 v107, v101, v107
	v_max_u32_e32 v101, v86, v108
	v_min_u32_e32 v108, v86, v108
	v_max_u32_e32 v86, v100, v103
	v_min_u32_e32 v103, v100, v103
	v_max_u32_e32 v100, v98, v109
	v_min_u32_e32 v109, v98, v109
	v_max_u32_e32 v98, v91, v114
	v_min_u32_e32 v114, v91, v114
	v_max_u32_e32 v91, v112, v101
	v_min_u32_e32 v101, v112, v101
	v_max_u32_e32 v112, v97, v86
	v_min_u32_e32 v86, v97, v86
	v_max_u32_e32 v97, v105, v106
	v_min_u32_e32 v106, v105, v106
	v_max_u32_e32 v105, v104, v107
	v_min_u32_e32 v107, v104, v107
	v_max_u32_e32 v104, v90, v108
	v_min_u32_e32 v108, v90, v108
	v_max_u32_e32 v90, v115, v103
	v_min_u32_e32 v103, v115, v103
	v_max_u32_e32 v115, v100, v91
	v_min_u32_e32 v91, v100, v91
	v_max_u32_e32 v100, v98, v112
	v_min_u32_e32 v112, v98, v112
	v_max_u32_e32 v98, v109, v101
	v_min_u32_e32 v101, v109, v101
	v_max_u32_e32 v109, v114, v86
	v_min_u32_e32 v86, v114, v86
	v_max_u32_e32 v114, v97, v104
	v_min_u32_e32 v104, v97, v104
	v_max_u32_e32 v97, v105, v90
	v_min_u32_e32 v90, v105, v90
	v_max_u32_e32 v105, v106, v108
	v_min_u32_e32 v108, v106, v108
	v_max_u32_e32 v106, v107, v103
	v_min_u32_e32 v103, v107, v103
	v_max_u32_e32 v107, v115, v100
	v_min_u32_e32 v100, v115, v100
	v_max_u32_e32 v115, v91, v112
	v_min_u32_e32 v112, v91, v112
	v_max_u32_e32 v91, v98, v109
	v_min_u32_e32 v109, v98, v109
	v_max_u32_e32 v98, v101, v86
	v_min_u32_e32 v86, v101, v86
	v_max_u32_e32 v101, v114, v97
	v_min_u32_e32 v97, v114, v97
	v_max_u32_e32 v114, v104, v90
	v_min_u32_e32 v90, v104, v90
	v_max_u32_e32 v104, v105, v106
	v_min_u32_e32 v106, v105, v106
	v_max_u32_e32 v105, v108, v103
	v_min_u32_e32 v103, v108, v103
	s_waitcnt vmcnt(7)
	v_mfma_f32_32x32x16_bf16 v[128:143], v[144:147], v[176:179], 0
	s_waitcnt vmcnt(6)
	v_mfma_f32_32x32x16_bf16 v[128:143], v[148:151], v[180:183], v[128:143]
	s_waitcnt vmcnt(5)
; #define MFMA32(a, b, c) __builtin_amdgcn_mfma_f32_32x32x16_bf16((a), (b), (c), 0, 0, 0)
; DI int crow(int i, int hh) { return (i & 3) + 8 * (i >> 2) + 4 * hh; }
; template <int LOGN>
; DI void bitonic_sort_desc(unsigned (&a)[1 << LOGN]) {
;   constexpr int N = 1 << LOGN;
; #pragma unroll
;   for (int ks = 1; ks <= LOGN; ++ks)
; #pragma unroll
;     ...
; #pragma unroll
;       for (int i = 0; i < N; ++i) {
;         const int k = 1 << ks, j = 1 << js, l = i ^ j;
;         if (l > i) {
;           const bool desc = ((i & k) == 0) || (ks == LOGN);
;           const unsigned x = a[i], y = a[l];
;           const unsigned hi = max(x, y), lo = min(x, y);
;           a[i] = desc ? hi : lo;
;           a[l] = desc ? lo : hi;
;         }
;       }
; }
; DI void peer_top16(const u16* __restrict__ PQrow, const u16* __restrict__ SK, unsigned (&top)[16], int lr, int hh) {
;     ...
;     for (int ks = 0; ks < 8; ++ks) {
;       bf16x8 a = *(const bf16x8*)(SK + (size_t)(kt * 32 + lr) * 128 + ks * 16 + hh * 8);
;       acc = MFMA32(a, qf[ks], acc);
;     }
; #pragma unroll
;     for (int e = 0; e < 16; ++e) {
;       int kidx = kt * 32 + crow(e, hh);
;       g[kt][e] = (f2ord(acc[e]) & ~127u) | (unsigned)(127 - kidx);
;     }
;     bitonic_sort_desc<4>(g[kt]);
;   }
	v_mfma_f32_32x32x16_bf16 v[128:143], v[152:155], v[184:187], v[128:143]
	s_waitcnt vmcnt(4)
	v_mfma_f32_32x32x16_bf16 v[128:143], v[156:159], v[188:191], v[128:143]
	s_waitcnt vmcnt(3)
	v_mfma_f32_32x32x16_bf16 v[128:143], v[160:163], v[192:195], v[128:143]
	s_waitcnt vmcnt(2)
	v_mfma_f32_32x32x16_bf16 v[128:143], v[164:167], v[196:199], v[128:143]
	s_waitcnt vmcnt(1)
	v_mfma_f32_32x32x16_bf16 v[128:143], v[168:171], v[200:203], v[128:143]
	s_waitcnt vmcnt(0)
	v_mfma_f32_32x32x16_bf16 v[128:143], v[172:175], v[204:207], v[128:143]
	s_add_u32 s4, s0, 57344
	s_addc_u32 s5, s1, 0
	global_load_dwordx4 v[144:147], v238, s[4:5] offset:0
	global_load_dwordx4 v[148:151], v238, s[4:5] offset:32
	global_load_dwordx4 v[152:155], v238, s[4:5] offset:64
	global_load_dwordx4 v[156:159], v238, s[4:5] offset:96
	global_load_dwordx4 v[160:163], v238, s[4:5] offset:128
	global_load_dwordx4 v[164:167], v238, s[4:5] offset:160
	global_load_dwordx4 v[168:171], v238, s[4:5] offset:192
	global_load_dwordx4 v[172:175], v238, s[4:5] offset:224
	s_nop 7
	v_ashrrev_i32_e32 v230, 31, v128
	v_or_b32_e32 v230, 0x80000000, v230
	v_xor_b32_e32 v229, v230, v128
	v_and_b32_e32 v229, 0xffffff80, v229
	v_or_b32_e32 v108, v229, v213
	v_ashrrev_i32_e32 v230, 31, v129
	v_or_b32_e32 v230, 0x80000000, v230
	v_xor_b32_e32 v229, v230, v129
	v_and_b32_e32 v229, 0xffffff80, v229
	v_or_b32_e32 v96, v229, v214
	v_ashrrev_i32_e32 v230, 31, v130
	v_or_b32_e32 v230, 0x80000000, v230
	v_xor_b32_e32 v229, v230, v130
	v_and_b32_e32 v229, 0xffffff80, v229
	v_or_b32_e32 v113, v229, v215
	v_ashrrev_i32_e32 v230, 31, v131
	v_or_b32_e32 v230, 0x80000000, v230
	v_xor_b32_e32 v229, v230, v131
	v_and_b32_e32 v229, 0xffffff80, v229
	v_or_b32_e32 v111, v229, v216
	v_ashrrev_i32_e32 v230, 31, v132
	v_or_b32_e32 v230, 0x80000000, v230
	v_xor_b32_e32 v229, v230, v132
	v_and_b32_e32 v229, 0xffffff80, v229
	v_or_b32_e32 v95, v229, v217
	v_ashrrev_i32_e32 v230, 31, v133
	v_or_b32_e32 v230, 0x80000000, v230
	v_xor_b32_e32 v229, v230, v133
	v_and_b32_e32 v229, 0xffffff80, v229
	v_or_b32_e32 v116, v229, v218
	v_ashrrev_i32_e32 v230, 31, v134
	v_or_b32_e32 v230, 0x80000000, v230
	v_xor_b32_e32 v229, v230, v134
	v_and_b32_e32 v229, 0xffffff80, v229
	v_or_b32_e32 v81, v229, v219
	v_ashrrev_i32_e32 v230, 31, v135
	v_or_b32_e32 v230, 0x80000000, v230
	v_xor_b32_e32 v229, v230, v135
	v_and_b32_e32 v229, 0xffffff80, v229
	v_or_b32_e32 v110, v229, v220
	v_ashrrev_i32_e32 v230, 31, v136
	v_or_b32_e32 v230, 0x80000000, v230
	v_xor_b32_e32 v229, v230, v136
	v_and_b32_e32 v229, 0xffffff80, v229
	v_or_b32_e32 v102, v229, v221
	v_ashrrev_i32_e32 v230, 31, v137
	v_or_b32_e32 v230, 0x80000000, v230
	v_xor_b32_e32 v229, v230, v137
	v_and_b32_e32 v229, 0xffffff80, v229
	v_or_b32_e32 v70, v229, v222
	v_ashrrev_i32_e32 v230, 31, v138
	v_or_b32_e32 v230, 0x80000000, v230
	v_xor_b32_e32 v229, v230, v138
	v_and_b32_e32 v229, 0xffffff80, v229
	v_or_b32_e32 v92, v229, v223
	v_ashrrev_i32_e32 v230, 31, v139
	v_or_b32_e32 v230, 0x80000000, v230
	v_xor_b32_e32 v229, v230, v139
	v_and_b32_e32 v229, 0xffffff80, v229
	v_or_b32_e32 v85, v229, v224
	v_ashrrev_i32_e32 v230, 31, v140
	v_or_b32_e32 v230, 0x80000000, v230
	v_xor_b32_e32 v229, v230, v140
	v_and_b32_e32 v229, 0xffffff80, v229
	v_or_b32_e32 v88, v229, v225
	v_ashrrev_i32_e32 v230, 31, v141
	v_or_b32_e32 v230, 0x80000000, v230
	v_xor_b32_e32 v229, v230, v141
	v_and_b32_e32 v229, 0xffffff80, v229
	v_or_b32_e32 v89, v229, v226
	v_ashrrev_i32_e32 v230, 31, v142
	v_or_b32_e32 v230, 0x80000000, v230
	v_xor_b32_e32 v229, v230, v142
	v_and_b32_e32 v229, 0xffffff80, v229
	v_or_b32_e32 v87, v229, v227
	v_ashrrev_i32_e32 v230, 31, v143
	v_or_b32_e32 v230, 0x80000000, v230
	v_xor_b32_e32 v229, v230, v143
	v_and_b32_e32 v229, 0xffffff80, v229
	v_or_b32_e32 v94, v229, v228
	v_subrev_u32_e32 v213, 32, v213
	v_subrev_u32_e32 v214, 32, v214
	v_subrev_u32_e32 v215, 32, v215
	v_subrev_u32_e32 v216, 32, v216
	v_subrev_u32_e32 v217, 32, v217
	v_subrev_u32_e32 v218, 32, v218
	v_subrev_u32_e32 v219, 32, v219
	v_subrev_u32_e32 v220, 32, v220
	v_subrev_u32_e32 v221, 32, v221
	v_subrev_u32_e32 v222, 32, v222
	v_subrev_u32_e32 v223, 32, v223
	v_subrev_u32_e32 v224, 32, v224
	v_subrev_u32_e32 v225, 32, v225
	v_subrev_u32_e32 v226, 32, v226
	v_subrev_u32_e32 v227, 32, v227
	v_subrev_u32_e32 v228, 32, v228
	v_max_u32_e32 v117, v108, v96
	v_min_u32_e32 v96, v108, v96
	v_min_u32_e32 v108, v113, v111
	v_max_u32_e32 v111, v113, v111
	v_max_u32_e32 v113, v95, v116
	v_min_u32_e32 v116, v95, v116
	v_min_u32_e32 v95, v81, v110
	v_max_u32_e32 v110, v81, v110
	v_max_u32_e32 v81, v102, v70
	v_min_u32_e32 v70, v102, v70
	v_min_u32_e32 v102, v92, v85
	v_max_u32_e32 v85, v92, v85
	v_max_u32_e32 v92, v88, v89
	v_min_u32_e32 v89, v88, v89
	v_min_u32_e32 v88, v87, v94
	v_max_u32_e32 v94, v87, v94
	v_max_u32_e32 v87, v117, v108
	v_min_u32_e32 v108, v117, v108
	v_max_u32_e32 v117, v96, v111
	v_min_u32_e32 v111, v96, v111
	v_min_u32_e32 v96, v113, v95
	v_max_u32_e32 v95, v113, v95
	v_min_u32_e32 v113, v116, v110
	v_max_u32_e32 v110, v116, v110
	v_max_u32_e32 v116, v81, v102
	v_min_u32_e32 v102, v81, v102
	v_max_u32_e32 v81, v70, v85
	v_min_u32_e32 v85, v70, v85
	v_min_u32_e32 v70, v92, v88
	v_max_u32_e32 v88, v92, v88
	v_min_u32_e32 v92, v89, v94
	v_max_u32_e32 v94, v89, v94
	v_max_u32_e32 v89, v87, v117
	v_min_u32_e32 v117, v87, v117
	v_max_u32_e32 v87, v108, v111
	v_min_u32_e32 v111, v108, v111
	v_min_u32_e32 v108, v96, v113
	v_max_u32_e32 v113, v96, v113
	v_min_u32_e32 v96, v95, v110
	v_max_u32_e32 v110, v95, v110
	v_max_u32_e32 v95, v116, v81
	v_min_u32_e32 v81, v116, v81
	v_max_u32_e32 v116, v102, v85
	v_min_u32_e32 v85, v102, v85
; #define MFMA32(a, b, c) __builtin_amdgcn_mfma_f32_32x32x16_bf16((a), (b), (c), 0, 0, 0)
; DI int crow(int i, int hh) { return (i & 3) + 8 * (i >> 2) + 4 * hh; }
; DI void peer_top16(const u16* __restrict__ PQrow, const u16* __restrict__ SK, unsigned (&top)[16], int lr, int hh) {
;   bf16x8 qf[8];
; #pragma unroll
;   for (int ks = 0; ks < 8; ++ks) qf[ks] = *(const bf16x8*)(PQrow + ks * 16 + hh * 8);
;   unsigned g[4][16];
; #pragma unroll
;   for (int kt = 0; kt < 4; ++kt) {
;     f32x16 acc;
; #pragma unroll
;     for (int e = 0; e < 16; ++e) acc[e] = 0.f;
; #pragma unroll
;     for (int ks = 0; ks < 8; ++ks) {
;       bf16x8 a = *(const bf16x8*)(SK + (size_t)(kt * 32 + lr) * 128 + ks * 16 + hh * 8);
;       acc = MFMA32(a, qf[ks], acc);
;     }
; #pragma unroll
;     for (int e = 0; e < 16; ++e) {
;       int kidx = kt * 32 + crow(e, hh);
;       g[kt][e] = (f2ord(acc[e]) & ~127u) | (unsigned)(127 - kidx);
; template <bool STORE>
; DI void peer_item(const Params& p, int item, char* smem) {
;     ...
;   for (int hq = 0; hq < 2; ++hq) {
;     const int hd = wave * 2 + hq;
;     unsigned top1[16], top2[16];
;     const u16* pqrow = PQ + (size_t)(tok0 + lr) * 2048 + hd * 256;
;     peer_top16(pqrow, SUBK + (size_t)(hd * 2 + 0) * 128 * 128, top1, lr, hh);
;     peer_top16(pqrow + 128, SUBK + (size_t)(hd * 2 + 1) * 128 * 128, top2, lr, hh);
	v_min_u32_e32 v102, v70, v92
	v_max_u32_e32 v92, v70, v92
	v_min_u32_e32 v70, v88, v94
	v_max_u32_e32 v94, v88, v94
	v_max_u32_e32 v88, v89, v108
	v_min_u32_e32 v108, v89, v108
	v_max_u32_e32 v89, v117, v113
	v_min_u32_e32 v113, v117, v113
	v_max_u32_e32 v117, v87, v96
	v_min_u32_e32 v96, v87, v96
	v_max_u32_e32 v87, v111, v110
	v_min_u32_e32 v110, v111, v110
	v_min_u32_e32 v111, v95, v102
	v_max_u32_e32 v102, v95, v102
	v_min_u32_e32 v95, v81, v92
	v_max_u32_e32 v92, v81, v92
	v_min_u32_e32 v81, v116, v70
	v_max_u32_e32 v70, v116, v70
	v_min_u32_e32 v116, v85, v94
	v_max_u32_e32 v94, v85, v94
	v_max_u32_e32 v85, v88, v117
	v_min_u32_e32 v117, v88, v117
	v_max_u32_e32 v88, v89, v87
	v_min_u32_e32 v87, v89, v87
	v_max_u32_e32 v89, v108, v96
	v_min_u32_e32 v96, v108, v96
	v_max_u32_e32 v108, v113, v110
	v_min_u32_e32 v110, v113, v110
	v_min_u32_e32 v113, v111, v81
	v_max_u32_e32 v81, v111, v81
	v_min_u32_e32 v111, v95, v116
	v_max_u32_e32 v116, v95, v116
	v_min_u32_e32 v95, v102, v70
	v_max_u32_e32 v70, v102, v70
	v_min_u32_e32 v102, v92, v94
	v_max_u32_e32 v94, v92, v94
	v_max_u32_e32 v92, v85, v88
	v_min_u32_e32 v88, v85, v88
	v_max_u32_e32 v85, v117, v87
	v_min_u32_e32 v87, v117, v87
	v_max_u32_e32 v117, v89, v108
	v_min_u32_e32 v108, v89, v108
	v_max_u32_e32 v89, v96, v110
	v_min_u32_e32 v110, v96, v110
	v_min_u32_e32 v96, v113, v111
	v_max_u32_e32 v111, v113, v111
	v_min_u32_e32 v113, v81, v116
	v_max_u32_e32 v116, v81, v116
	v_min_u32_e32 v81, v95, v102
	v_max_u32_e32 v102, v95, v102
	v_min_u32_e32 v95, v70, v94
	v_max_u32_e32 v94, v70, v94
	v_max_u32_e32 v70, v92, v96
	v_min_u32_e32 v96, v92, v96
	v_max_u32_e32 v92, v88, v111
	v_min_u32_e32 v111, v88, v111
	v_max_u32_e32 v88, v85, v113
	v_min_u32_e32 v113, v85, v113
	v_max_u32_e32 v85, v87, v116
	v_min_u32_e32 v116, v87, v116
	v_max_u32_e32 v87, v117, v81
	v_min_u32_e32 v81, v117, v81
	v_max_u32_e32 v117, v108, v102
	v_min_u32_e32 v102, v108, v102
	v_max_u32_e32 v108, v89, v95
	v_min_u32_e32 v95, v89, v95
	v_max_u32_e32 v89, v110, v94
	v_min_u32_e32 v94, v110, v94
	v_max_u32_e32 v110, v70, v87
	v_min_u32_e32 v87, v70, v87
	v_max_u32_e32 v70, v92, v117
	v_min_u32_e32 v117, v92, v117
	v_max_u32_e32 v92, v88, v108
	v_min_u32_e32 v108, v88, v108
	v_max_u32_e32 v88, v85, v89
	v_min_u32_e32 v89, v85, v89
	v_max_u32_e32 v85, v96, v81
	v_min_u32_e32 v81, v96, v81
	v_max_u32_e32 v96, v111, v102
	v_min_u32_e32 v102, v111, v102
	v_max_u32_e32 v111, v113, v95
	v_min_u32_e32 v95, v113, v95
	v_max_u32_e32 v113, v116, v94
	v_min_u32_e32 v94, v116, v94
	v_max_u32_e32 v116, v110, v92
	v_min_u32_e32 v92, v110, v92
	v_max_u32_e32 v110, v70, v88
	v_min_u32_e32 v88, v70, v88
	v_max_u32_e32 v70, v87, v108
	v_min_u32_e32 v108, v87, v108
	v_max_u32_e32 v87, v117, v89
	v_min_u32_e32 v89, v117, v89
	v_max_u32_e32 v117, v85, v111
	v_min_u32_e32 v111, v85, v111
	v_max_u32_e32 v85, v96, v113
	v_min_u32_e32 v113, v96, v113
	v_max_u32_e32 v96, v81, v95
	v_min_u32_e32 v95, v81, v95
	v_max_u32_e32 v81, v102, v94
	v_min_u32_e32 v94, v102, v94
	v_max_u32_e32 v102, v116, v110
	v_min_u32_e32 v110, v116, v110
	v_max_u32_e32 v116, v92, v88
	v_min_u32_e32 v88, v92, v88
	v_max_u32_e32 v92, v70, v87
	v_min_u32_e32 v87, v70, v87
	v_max_u32_e32 v70, v108, v89
	v_min_u32_e32 v89, v108, v89
	v_max_u32_e32 v108, v117, v85
	v_min_u32_e32 v85, v117, v85
	v_max_u32_e32 v117, v111, v113
	v_min_u32_e32 v113, v111, v113
	v_max_u32_e32 v111, v96, v81
	v_min_u32_e32 v81, v96, v81
	v_max_u32_e32 v96, v95, v94
	v_min_u32_e32 v94, v95, v94
	s_waitcnt vmcnt(7)
	v_mfma_f32_32x32x16_bf16 v[128:143], v[144:147], v[176:179], 0
	s_waitcnt vmcnt(6)
	v_mfma_f32_32x32x16_bf16 v[128:143], v[148:151], v[180:183], v[128:143]
	s_waitcnt vmcnt(5)
	v_mfma_f32_32x32x16_bf16 v[128:143], v[152:155], v[184:187], v[128:143]
	s_waitcnt vmcnt(4)
	v_mfma_f32_32x32x16_bf16 v[128:143], v[156:159], v[188:191], v[128:143]
	s_waitcnt vmcnt(3)
	v_mfma_f32_32x32x16_bf16 v[128:143], v[160:163], v[192:195], v[128:143]
	s_waitcnt vmcnt(2)
	v_mfma_f32_32x32x16_bf16 v[128:143], v[164:167], v[196:199], v[128:143]
	s_waitcnt vmcnt(1)
	v_mfma_f32_32x32x16_bf16 v[128:143], v[168:171], v[200:203], v[128:143]
	s_waitcnt vmcnt(0)
	v_mfma_f32_32x32x16_bf16 v[128:143], v[172:175], v[204:207], v[128:143]
	global_load_dwordx4 v[176:179], v239, s[2:3] offset:512
	global_load_dwordx4 v[180:183], v239, s[2:3] offset:544
	global_load_dwordx4 v[184:187], v239, s[2:3] offset:576
	global_load_dwordx4 v[188:191], v239, s[2:3] offset:608
	global_load_dwordx4 v[192:195], v239, s[2:3] offset:640
	global_load_dwordx4 v[196:199], v239, s[2:3] offset:672
	global_load_dwordx4 v[200:203], v239, s[2:3] offset:704
	global_load_dwordx4 v[204:207], v239, s[2:3] offset:736
	s_add_u32 s4, s0, 65536
	s_addc_u32 s5, s1, 0
	global_load_dwordx4 v[144:147], v238, s[4:5] offset:0
	global_load_dwordx4 v[148:151], v238, s[4:5] offset:32
	global_load_dwordx4 v[152:155], v238, s[4:5] offset:64
	global_load_dwordx4 v[156:159], v238, s[4:5] offset:96
	global_load_dwordx4 v[160:163], v238, s[4:5] offset:128
	global_load_dwordx4 v[164:167], v238, s[4:5] offset:160
	global_load_dwordx4 v[168:171], v238, s[4:5] offset:192
	global_load_dwordx4 v[172:175], v238, s[4:5] offset:224
	s_nop 7
	v_ashrrev_i32_e32 v230, 31, v128
	v_or_b32_e32 v230, 0x80000000, v230
	v_xor_b32_e32 v229, v230, v128
	v_and_b32_e32 v229, 0xffffff80, v229
	v_or_b32_e32 v95, v229, v213
	v_ashrrev_i32_e32 v230, 31, v129
	v_or_b32_e32 v230, 0x80000000, v230
	v_xor_b32_e32 v229, v230, v129
	v_and_b32_e32 v229, 0xffffff80, v229
	v_or_b32_e32 v84, v229, v214
	v_ashrrev_i32_e32 v230, 31, v130
	v_or_b32_e32 v230, 0x80000000, v230
	v_xor_b32_e32 v229, v230, v130
; DI int crow(int i, int hh) { return (i & 3) + 8 * (i >> 2) + 4 * hh; }
; template <int LOGN>
; DI void bitonic_sort_desc(unsigned (&a)[1 << LOGN]) {
;   constexpr int N = 1 << LOGN;
; #pragma unroll
;   for (int ks = 1; ks <= LOGN; ++ks)
; #pragma unroll
;     ...
; #pragma unroll
;       for (int i = 0; i < N; ++i) {
;         const int k = 1 << ks, j = 1 << js, l = i ^ j;
;         if (l > i) {
;           const bool desc = ((i & k) == 0) || (ks == LOGN);
;           const unsigned x = a[i], y = a[l];
;           const unsigned hi = max(x, y), lo = min(x, y);
;           a[i] = desc ? hi : lo;
;           a[l] = desc ? lo : hi;
;         }
;       }
; }
; DI void peer_top16(const u16* __restrict__ PQrow, const u16* __restrict__ SK, unsigned (&top)[16], int lr, int hh) {
;     ...
;     for (int e = 0; e < 16; ++e) {
;       int kidx = kt * 32 + crow(e, hh);
;       g[kt][e] = (f2ord(acc[e]) & ~127u) | (unsigned)(127 - kidx);
;     }
;     bitonic_sort_desc<4>(g[kt]);
	v_and_b32_e32 v229, 0xffffff80, v229
	v_or_b32_e32 v79, v229, v215
	v_ashrrev_i32_e32 v230, 31, v131
	v_or_b32_e32 v230, 0x80000000, v230
	v_xor_b32_e32 v229, v230, v131
	v_and_b32_e32 v229, 0xffffff80, v229
	v_or_b32_e32 v82, v229, v216
	v_ashrrev_i32_e32 v230, 31, v132
	v_or_b32_e32 v230, 0x80000000, v230
	v_xor_b32_e32 v229, v230, v132
	v_and_b32_e32 v229, 0xffffff80, v229
	v_or_b32_e32 v83, v229, v217
	v_ashrrev_i32_e32 v230, 31, v133
	v_or_b32_e32 v230, 0x80000000, v230
	v_xor_b32_e32 v229, v230, v133
	v_and_b32_e32 v229, 0xffffff80, v229
	v_or_b32_e32 v69, v229, v218
	v_ashrrev_i32_e32 v230, 31, v134
	v_or_b32_e32 v230, 0x80000000, v230
	v_xor_b32_e32 v229, v230, v134
	v_and_b32_e32 v229, 0xffffff80, v229
	v_or_b32_e32 v74, v229, v219
	v_ashrrev_i32_e32 v230, 31, v135
	v_or_b32_e32 v230, 0x80000000, v230
	v_xor_b32_e32 v229, v230, v135
	v_and_b32_e32 v229, 0xffffff80, v229
	v_or_b32_e32 v99, v229, v220
	v_ashrrev_i32_e32 v230, 31, v136
	v_or_b32_e32 v230, 0x80000000, v230
	v_xor_b32_e32 v229, v230, v136
	v_and_b32_e32 v229, 0xffffff80, v229
	v_or_b32_e32 v72, v229, v221
	v_ashrrev_i32_e32 v230, 31, v137
	v_or_b32_e32 v230, 0x80000000, v230
	v_xor_b32_e32 v229, v230, v137
	v_and_b32_e32 v229, 0xffffff80, v229
	v_or_b32_e32 v76, v229, v222
	v_ashrrev_i32_e32 v230, 31, v138
	v_or_b32_e32 v230, 0x80000000, v230
	v_xor_b32_e32 v229, v230, v138
	v_and_b32_e32 v229, 0xffffff80, v229
	v_or_b32_e32 v71, v229, v223
	v_ashrrev_i32_e32 v230, 31, v139
	v_or_b32_e32 v230, 0x80000000, v230
	v_xor_b32_e32 v229, v230, v139
	v_and_b32_e32 v229, 0xffffff80, v229
	v_or_b32_e32 v75, v229, v224
	v_ashrrev_i32_e32 v230, 31, v140
	v_or_b32_e32 v230, 0x80000000, v230
	v_xor_b32_e32 v229, v230, v140
	v_and_b32_e32 v229, 0xffffff80, v229
	v_or_b32_e32 v73, v229, v225
	v_ashrrev_i32_e32 v230, 31, v141
	v_or_b32_e32 v230, 0x80000000, v230
	v_xor_b32_e32 v229, v230, v141
	v_and_b32_e32 v229, 0xffffff80, v229
	v_or_b32_e32 v80, v229, v226
	v_ashrrev_i32_e32 v230, 31, v142
	v_or_b32_e32 v230, 0x80000000, v230
	v_xor_b32_e32 v229, v230, v142
	v_and_b32_e32 v229, 0xffffff80, v229
	v_or_b32_e32 v78, v229, v227
	v_ashrrev_i32_e32 v230, 31, v143
	v_or_b32_e32 v230, 0x80000000, v230
	v_xor_b32_e32 v229, v230, v143
	v_and_b32_e32 v229, 0xffffff80, v229
	v_or_b32_e32 v77, v229, v228
	v_max_u32_e32 v93, v95, v84
	v_min_u32_e32 v84, v95, v84
	v_min_u32_e32 v95, v79, v82
	v_max_u32_e32 v82, v79, v82
	v_max_u32_e32 v79, v83, v69
	v_min_u32_e32 v69, v83, v69
	v_min_u32_e32 v83, v74, v99
	v_max_u32_e32 v99, v74, v99
	v_max_u32_e32 v74, v72, v76
	v_min_u32_e32 v76, v72, v76
	v_min_u32_e32 v72, v71, v75
	v_max_u32_e32 v75, v71, v75
	v_max_u32_e32 v71, v73, v80
	v_min_u32_e32 v80, v73, v80
	v_min_u32_e32 v73, v78, v77
	v_max_u32_e32 v77, v78, v77
	v_max_u32_e32 v78, v93, v95
	v_min_u32_e32 v95, v93, v95
	v_max_u32_e32 v93, v84, v82
	v_min_u32_e32 v82, v84, v82
	v_min_u32_e32 v84, v79, v83
	v_max_u32_e32 v83, v79, v83
	v_min_u32_e32 v79, v69, v99
	v_max_u32_e32 v99, v69, v99
	v_max_u32_e32 v69, v74, v72
	v_min_u32_e32 v72, v74, v72
	v_max_u32_e32 v74, v76, v75
	v_min_u32_e32 v75, v76, v75
	v_min_u32_e32 v76, v71, v73
	v_max_u32_e32 v73, v71, v73
	v_min_u32_e32 v71, v80, v77
	v_max_u32_e32 v77, v80, v77
	v_max_u32_e32 v80, v78, v93
	v_min_u32_e32 v93, v78, v93
	v_max_u32_e32 v78, v95, v82
	v_min_u32_e32 v82, v95, v82
	v_min_u32_e32 v95, v84, v79
	v_max_u32_e32 v79, v84, v79
	v_min_u32_e32 v84, v83, v99
	v_max_u32_e32 v99, v83, v99
	v_max_u32_e32 v83, v69, v74
	v_min_u32_e32 v74, v69, v74
	v_max_u32_e32 v69, v72, v75
	v_min_u32_e32 v75, v72, v75
	v_min_u32_e32 v72, v76, v71
	v_max_u32_e32 v71, v76, v71
	v_min_u32_e32 v76, v73, v77
	v_max_u32_e32 v77, v73, v77
	v_max_u32_e32 v73, v80, v95
	v_min_u32_e32 v95, v80, v95
	v_max_u32_e32 v80, v93, v79
	v_min_u32_e32 v79, v93, v79
	v_max_u32_e32 v93, v78, v84
	v_min_u32_e32 v84, v78, v84
	v_max_u32_e32 v78, v82, v99
	v_min_u32_e32 v99, v82, v99
	v_min_u32_e32 v82, v83, v72
	v_max_u32_e32 v72, v83, v72
	v_min_u32_e32 v83, v74, v71
	v_max_u32_e32 v71, v74, v71
	v_min_u32_e32 v74, v69, v76
	v_max_u32_e32 v76, v69, v76
	v_min_u32_e32 v69, v75, v77
	v_max_u32_e32 v77, v75, v77
	v_max_u32_e32 v75, v73, v93
	v_min_u32_e32 v93, v73, v93
	v_max_u32_e32 v73, v80, v78
	v_min_u32_e32 v78, v80, v78
	v_max_u32_e32 v80, v95, v84
	v_min_u32_e32 v84, v95, v84
	v_max_u32_e32 v95, v79, v99
	v_min_u32_e32 v99, v79, v99
	v_min_u32_e32 v79, v82, v74
	v_max_u32_e32 v74, v82, v74
	v_min_u32_e32 v82, v83, v69
	v_max_u32_e32 v69, v83, v69
	v_min_u32_e32 v83, v72, v76
	v_max_u32_e32 v76, v72, v76
	v_min_u32_e32 v72, v71, v77
	v_max_u32_e32 v77, v71, v77
	v_max_u32_e32 v71, v75, v73
	v_min_u32_e32 v73, v75, v73
	v_max_u32_e32 v75, v93, v78
	v_min_u32_e32 v78, v93, v78
	v_max_u32_e32 v93, v80, v95
	v_min_u32_e32 v95, v80, v95
	v_max_u32_e32 v80, v84, v99
	v_min_u32_e32 v99, v84, v99
	v_min_u32_e32 v84, v79, v82
	v_max_u32_e32 v82, v79, v82
	v_min_u32_e32 v79, v74, v69
	v_max_u32_e32 v69, v74, v69
	v_min_u32_e32 v74, v83, v72
	v_max_u32_e32 v72, v83, v72
	v_min_u32_e32 v83, v76, v77
	v_max_u32_e32 v77, v76, v77
	v_max_u32_e32 v76, v71, v84
	v_min_u32_e32 v84, v71, v84
	v_max_u32_e32 v71, v73, v82
	v_min_u32_e32 v82, v73, v82
	v_max_u32_e32 v73, v75, v79
	v_min_u32_e32 v79, v75, v79
	v_max_u32_e32 v75, v78, v69
	v_min_u32_e32 v69, v78, v69
	v_max_u32_e32 v78, v93, v74
	v_min_u32_e32 v74, v93, v74
	v_max_u32_e32 v93, v95, v72
	v_min_u32_e32 v72, v95, v72
	v_max_u32_e32 v95, v80, v83
	v_min_u32_e32 v83, v80, v83
	v_max_u32_e32 v80, v99, v77
	v_min_u32_e32 v77, v99, v77
	v_max_u32_e32 v99, v76, v78
	v_min_u32_e32 v78, v76, v78
	v_max_u32_e32 v76, v71, v93
; template <int LOGN>
; DI void bitonic_sort_desc(unsigned (&a)[1 << LOGN]) {
;   constexpr int N = 1 << LOGN;
; #pragma unroll
;   for (int ks = 1; ks <= LOGN; ++ks)
; #pragma unroll
;     ...
; #pragma unroll
;       for (int i = 0; i < N; ++i) {
;         const int k = 1 << ks, j = 1 << js, l = i ^ j;
;         if (l > i) {
;           const bool desc = ((i & k) == 0) || (ks == LOGN);
;           const unsigned x = a[i], y = a[l];
;           const unsigned hi = max(x, y), lo = min(x, y);
;           a[i] = desc ? hi : lo;
;           a[l] = desc ? lo : hi;
;         }
;       }
; }
; DI void merge_top16(unsigned (&a)[16], const unsigned (&b)[16]) {
; #pragma unroll
;   for (int i = 0; i < 16; ++i) a[i] = max(a[i], b[15 - i]);
; #pragma unroll
;     ...
; #pragma unroll
;     for (int i = 0; i < 16; ++i) {
;       const int j = 1 << js, l = i ^ j;
;       if (l > i) {
;         const unsigned x = a[i], y = a[l];
;         a[i] = max(x, y);
;         a[l] = min(x, y);
;       }
;     }
; }
	v_min_u32_e32 v93, v71, v93
	v_max_u32_e32 v71, v73, v95
	v_min_u32_e32 v95, v73, v95
	v_max_u32_e32 v73, v75, v80
	v_min_u32_e32 v80, v75, v80
	v_max_u32_e32 v75, v84, v74
	v_min_u32_e32 v74, v84, v74
	v_max_u32_e32 v84, v82, v72
	v_min_u32_e32 v72, v82, v72
	v_max_u32_e32 v82, v79, v83
	v_min_u32_e32 v83, v79, v83
	v_max_u32_e32 v79, v69, v77
	v_min_u32_e32 v77, v69, v77
	v_max_u32_e32 v69, v99, v71
	v_min_u32_e32 v71, v99, v71
	v_max_u32_e32 v99, v76, v73
	v_min_u32_e32 v73, v76, v73
	v_max_u32_e32 v76, v78, v95
	v_min_u32_e32 v95, v78, v95
	v_max_u32_e32 v78, v93, v80
	v_min_u32_e32 v80, v93, v80
	v_max_u32_e32 v93, v75, v82
	v_min_u32_e32 v82, v75, v82
	v_max_u32_e32 v75, v84, v79
	v_min_u32_e32 v79, v84, v79
	v_max_u32_e32 v84, v74, v83
	v_min_u32_e32 v83, v74, v83
	v_max_u32_e32 v74, v72, v77
	v_min_u32_e32 v77, v72, v77
	v_max_u32_e32 v72, v69, v99
	v_min_u32_e32 v99, v69, v99
	v_max_u32_e32 v69, v71, v73
	v_min_u32_e32 v73, v71, v73
	v_max_u32_e32 v71, v76, v78
	v_min_u32_e32 v78, v76, v78
	v_max_u32_e32 v76, v95, v80
	v_min_u32_e32 v80, v95, v80
	v_max_u32_e32 v95, v93, v75
	v_min_u32_e32 v75, v93, v75
	v_max_u32_e32 v93, v82, v79
	v_min_u32_e32 v79, v82, v79
	v_max_u32_e32 v82, v84, v74
	v_min_u32_e32 v74, v84, v74
	v_max_u32_e32 v84, v83, v77
	v_min_u32_e32 v77, v83, v77
	v_max_u32_e32 v83, v102, v77
	v_max_u32_e32 v102, v110, v84
	v_max_u32_e32 v110, v116, v74
	v_max_u32_e32 v116, v88, v82
	v_max_u32_e32 v88, v92, v79
	v_max_u32_e32 v92, v87, v93
	v_max_u32_e32 v87, v70, v75
	v_max_u32_e32 v70, v89, v95
	v_max_u32_e32 v89, v108, v80
	v_max_u32_e32 v108, v85, v76
	v_max_u32_e32 v85, v117, v78
	v_max_u32_e32 v117, v113, v71
	v_max_u32_e32 v113, v111, v73
	v_max_u32_e32 v111, v81, v69
	v_max_u32_e32 v81, v96, v99
	v_max_u32_e32 v96, v94, v72
	v_max_u32_e32 v77, v83, v89
	v_min_u32_e32 v89, v83, v89
	v_max_u32_e32 v83, v102, v108
	v_min_u32_e32 v108, v102, v108
	v_max_u32_e32 v102, v110, v85
	v_min_u32_e32 v85, v110, v85
	v_max_u32_e32 v110, v116, v117
	v_min_u32_e32 v117, v116, v117
	v_max_u32_e32 v116, v88, v113
	v_min_u32_e32 v113, v88, v113
	v_max_u32_e32 v88, v92, v111
	v_min_u32_e32 v111, v92, v111
	v_max_u32_e32 v92, v87, v81
	v_min_u32_e32 v81, v87, v81
	v_max_u32_e32 v87, v70, v96
	v_min_u32_e32 v96, v70, v96
	v_max_u32_e32 v70, v77, v116
	v_min_u32_e32 v116, v77, v116
	v_max_u32_e32 v77, v83, v88
	v_min_u32_e32 v88, v83, v88
	v_max_u32_e32 v83, v102, v92
	v_min_u32_e32 v92, v102, v92
	v_max_u32_e32 v102, v110, v87
	v_min_u32_e32 v87, v110, v87
	v_max_u32_e32 v110, v89, v113
	v_min_u32_e32 v113, v89, v113
	v_max_u32_e32 v89, v108, v111
	v_min_u32_e32 v111, v108, v111
	v_max_u32_e32 v108, v85, v81
	v_min_u32_e32 v81, v85, v81
	v_max_u32_e32 v85, v117, v96
	v_min_u32_e32 v96, v117, v96
	v_max_u32_e32 v117, v70, v83
	v_min_u32_e32 v83, v70, v83
	v_max_u32_e32 v70, v77, v102
	v_min_u32_e32 v102, v77, v102
	v_max_u32_e32 v77, v116, v92
	v_min_u32_e32 v92, v116, v92
	v_max_u32_e32 v116, v88, v87
	v_min_u32_e32 v87, v88, v87
	v_max_u32_e32 v88, v110, v108
	v_min_u32_e32 v108, v110, v108
	v_max_u32_e32 v110, v89, v85
	v_min_u32_e32 v85, v89, v85
	v_max_u32_e32 v89, v113, v81
	v_min_u32_e32 v81, v113, v81
	v_max_u32_e32 v113, v111, v96
	v_min_u32_e32 v96, v111, v96
	v_max_u32_e32 v111, v117, v70
	v_min_u32_e32 v70, v117, v70
	v_max_u32_e32 v117, v83, v102
	v_min_u32_e32 v102, v83, v102
	v_max_u32_e32 v83, v77, v116
	v_min_u32_e32 v116, v77, v116
	v_max_u32_e32 v77, v92, v87
	v_min_u32_e32 v87, v92, v87
	v_max_u32_e32 v92, v88, v110
	v_min_u32_e32 v110, v88, v110
	v_max_u32_e32 v88, v108, v85
	v_min_u32_e32 v85, v108, v85
	v_max_u32_e32 v108, v89, v113
	v_min_u32_e32 v113, v89, v113
	v_max_u32_e32 v89, v81, v96
	v_min_u32_e32 v96, v81, v96
	v_max_u32_e32 v81, v107, v96
	v_max_u32_e32 v107, v100, v89
	v_max_u32_e32 v100, v115, v113
	v_max_u32_e32 v115, v112, v108
	v_max_u32_e32 v112, v91, v85
	v_max_u32_e32 v91, v109, v88
	v_max_u32_e32 v109, v98, v110
	v_max_u32_e32 v98, v86, v92
	v_max_u32_e32 v86, v101, v87
	v_max_u32_e32 v101, v97, v77
	v_max_u32_e32 v97, v114, v116
	v_max_u32_e32 v114, v90, v83
	v_max_u32_e32 v90, v104, v102
	v_max_u32_e32 v104, v106, v117
	v_max_u32_e32 v106, v105, v70
	v_max_u32_e32 v105, v103, v111
	v_max_u32_e32 v96, v81, v86
	v_min_u32_e32 v86, v81, v86
	v_max_u32_e32 v81, v107, v101
	v_min_u32_e32 v101, v107, v101
	v_max_u32_e32 v107, v100, v97
	v_min_u32_e32 v97, v100, v97
	v_max_u32_e32 v100, v115, v114
	v_min_u32_e32 v114, v115, v114
	v_max_u32_e32 v115, v112, v90
	v_min_u32_e32 v90, v112, v90
	v_max_u32_e32 v112, v91, v104
	v_min_u32_e32 v104, v91, v104
	v_max_u32_e32 v91, v109, v106
	v_min_u32_e32 v106, v109, v106
	v_max_u32_e32 v109, v98, v105
	v_min_u32_e32 v105, v98, v105
	v_max_u32_e32 v98, v96, v115
	v_min_u32_e32 v115, v96, v115
	v_max_u32_e32 v96, v81, v112
	v_min_u32_e32 v112, v81, v112
	v_max_u32_e32 v81, v107, v91
	v_min_u32_e32 v91, v107, v91
	v_max_u32_e32 v107, v100, v109
	v_min_u32_e32 v109, v100, v109
	v_max_u32_e32 v100, v86, v90
	v_min_u32_e32 v90, v86, v90
	v_max_u32_e32 v86, v101, v104
	v_min_u32_e32 v104, v101, v104
	v_max_u32_e32 v101, v97, v106
	v_min_u32_e32 v106, v97, v106
	v_max_u32_e32 v97, v114, v105
	v_min_u32_e32 v105, v114, v105
	v_max_u32_e32 v114, v98, v81
	v_min_u32_e32 v81, v98, v81
	v_max_u32_e32 v98, v96, v107
	v_min_u32_e32 v107, v96, v107
	v_max_u32_e32 v96, v115, v91
	v_min_u32_e32 v91, v115, v91
	v_max_u32_e32 v115, v112, v109
	v_min_u32_e32 v109, v112, v109
	v_max_u32_e32 v112, v100, v101
	v_min_u32_e32 v101, v100, v101
	v_max_u32_e32 v100, v86, v97
	v_min_u32_e32 v97, v86, v97
	v_max_u32_e32 v86, v90, v106
	v_min_u32_e32 v106, v90, v106
	v_max_u32_e32 v90, v104, v105
; #define MFMA32(a, b, c) __builtin_amdgcn_mfma_f32_32x32x16_bf16((a), (b), (c), 0, 0, 0)
; DI int crow(int i, int hh) { return (i & 3) + 8 * (i >> 2) + 4 * hh; }
; DI void merge_top16(unsigned (&a)[16], const unsigned (&b)[16]) {
; #pragma unroll
;   for (int i = 0; i < 16; ++i) a[i] = max(a[i], b[15 - i]);
; #pragma unroll
;     ...
; #pragma unroll
;     for (int i = 0; i < 16; ++i) {
;       const int j = 1 << js, l = i ^ j;
;       if (l > i) {
;         const unsigned x = a[i], y = a[l];
;         a[i] = max(x, y);
;         a[l] = min(x, y);
;       }
;     }
; }
; DI void peer_top16(const u16* __restrict__ PQrow, const u16* __restrict__ SK, unsigned (&top)[16], int lr, int hh) {
;     ...
;     for (int ks = 0; ks < 8; ++ks) {
;       bf16x8 a = *(const bf16x8*)(SK + (size_t)(kt * 32 + lr) * 128 + ks * 16 + hh * 8);
;       acc = MFMA32(a, qf[ks], acc);
;     }
; #pragma unroll
;     for (int e = 0; e < 16; ++e) {
;       int kidx = kt * 32 + crow(e, hh);
;       g[kt][e] = (f2ord(acc[e]) & ~127u) | (unsigned)(127 - kidx);
;     }
;     bitonic_sort_desc<4>(g[kt]);
;   }
	v_min_u32_e32 v105, v104, v105
	v_max_u32_e32 v104, v114, v98
	v_min_u32_e32 v98, v114, v98
	v_max_u32_e32 v114, v81, v107
	v_min_u32_e32 v107, v81, v107
	v_max_u32_e32 v81, v96, v115
	v_min_u32_e32 v115, v96, v115
	v_max_u32_e32 v96, v91, v109
	v_min_u32_e32 v109, v91, v109
	v_max_u32_e32 v91, v112, v100
	v_min_u32_e32 v100, v112, v100
	v_max_u32_e32 v112, v101, v97
	v_min_u32_e32 v97, v101, v97
	v_max_u32_e32 v101, v86, v90
	v_min_u32_e32 v90, v86, v90
	v_max_u32_e32 v86, v106, v105
	v_min_u32_e32 v105, v106, v105
	v_mov_b32_e32 v16, v104
	v_mov_b32_e32 v17, v98
	v_mov_b32_e32 v18, v114
	v_mov_b32_e32 v19, v107
	v_mov_b32_e32 v20, v81
	v_mov_b32_e32 v21, v115
	v_mov_b32_e32 v22, v96
	v_mov_b32_e32 v23, v109
	v_mov_b32_e32 v24, v91
	v_mov_b32_e32 v25, v100
	v_mov_b32_e32 v26, v112
	v_mov_b32_e32 v27, v97
	v_mov_b32_e32 v28, v101
	v_mov_b32_e32 v29, v90
	v_mov_b32_e32 v30, v86
	v_mov_b32_e32 v31, v105
	v_sub_u32_e32 v213, 127, v245
	v_sub_u32_e32 v214, 126, v245
	v_sub_u32_e32 v215, 125, v245
	v_sub_u32_e32 v216, 124, v245
	v_sub_u32_e32 v217, 119, v245
	v_sub_u32_e32 v218, 118, v245
	v_sub_u32_e32 v219, 117, v245
	v_sub_u32_e32 v220, 116, v245
	v_sub_u32_e32 v221, 111, v245
	v_sub_u32_e32 v222, 110, v245
	v_sub_u32_e32 v223, 109, v245
	v_sub_u32_e32 v224, 108, v245
	v_sub_u32_e32 v225, 103, v245
	v_sub_u32_e32 v226, 102, v245
	v_sub_u32_e32 v227, 101, v245
	v_sub_u32_e32 v228, 100, v245
	s_waitcnt vmcnt(7)
	v_mfma_f32_32x32x16_bf16 v[128:143], v[144:147], v[176:179], 0
	s_waitcnt vmcnt(6)
	v_mfma_f32_32x32x16_bf16 v[128:143], v[148:151], v[180:183], v[128:143]
	s_waitcnt vmcnt(5)
	v_mfma_f32_32x32x16_bf16 v[128:143], v[152:155], v[184:187], v[128:143]
	s_waitcnt vmcnt(4)
	v_mfma_f32_32x32x16_bf16 v[128:143], v[156:159], v[188:191], v[128:143]
	s_waitcnt vmcnt(3)
	v_mfma_f32_32x32x16_bf16 v[128:143], v[160:163], v[192:195], v[128:143]
	s_waitcnt vmcnt(2)
	v_mfma_f32_32x32x16_bf16 v[128:143], v[164:167], v[196:199], v[128:143]
	s_waitcnt vmcnt(1)
	v_mfma_f32_32x32x16_bf16 v[128:143], v[168:171], v[200:203], v[128:143]
	s_waitcnt vmcnt(0)
	v_mfma_f32_32x32x16_bf16 v[128:143], v[172:175], v[204:207], v[128:143]
	s_add_u32 s4, s0, 73728
	s_addc_u32 s5, s1, 0
	global_load_dwordx4 v[144:147], v238, s[4:5] offset:0
	global_load_dwordx4 v[148:151], v238, s[4:5] offset:32
	global_load_dwordx4 v[152:155], v238, s[4:5] offset:64
	global_load_dwordx4 v[156:159], v238, s[4:5] offset:96
	global_load_dwordx4 v[160:163], v238, s[4:5] offset:128
	global_load_dwordx4 v[164:167], v238, s[4:5] offset:160
	global_load_dwordx4 v[168:171], v238, s[4:5] offset:192
	global_load_dwordx4 v[172:175], v238, s[4:5] offset:224
	s_nop 7
	v_ashrrev_i32_e32 v230, 31, v128
	v_or_b32_e32 v230, 0x80000000, v230
	v_xor_b32_e32 v229, v230, v128
	v_and_b32_e32 v229, 0xffffff80, v229
	v_or_b32_e32 v105, v229, v213
	v_ashrrev_i32_e32 v230, 31, v129
	v_or_b32_e32 v230, 0x80000000, v230
	v_xor_b32_e32 v229, v230, v129
	v_and_b32_e32 v229, 0xffffff80, v229
	v_or_b32_e32 v86, v229, v214
	v_ashrrev_i32_e32 v230, 31, v130
	v_or_b32_e32 v230, 0x80000000, v230
	v_xor_b32_e32 v229, v230, v130
	v_and_b32_e32 v229, 0xffffff80, v229
	v_or_b32_e32 v90, v229, v215
	v_ashrrev_i32_e32 v230, 31, v131
	v_or_b32_e32 v230, 0x80000000, v230
	v_xor_b32_e32 v229, v230, v131
	v_and_b32_e32 v229, 0xffffff80, v229
	v_or_b32_e32 v101, v229, v216
	v_ashrrev_i32_e32 v230, 31, v132
	v_or_b32_e32 v230, 0x80000000, v230
	v_xor_b32_e32 v229, v230, v132
	v_and_b32_e32 v229, 0xffffff80, v229
	v_or_b32_e32 v97, v229, v217
	v_ashrrev_i32_e32 v230, 31, v133
	v_or_b32_e32 v230, 0x80000000, v230
	v_xor_b32_e32 v229, v230, v133
	v_and_b32_e32 v229, 0xffffff80, v229
	v_or_b32_e32 v112, v229, v218
	v_ashrrev_i32_e32 v230, 31, v134
	v_or_b32_e32 v230, 0x80000000, v230
	v_xor_b32_e32 v229, v230, v134
	v_and_b32_e32 v229, 0xffffff80, v229
	v_or_b32_e32 v100, v229, v219
	v_ashrrev_i32_e32 v230, 31, v135
	v_or_b32_e32 v230, 0x80000000, v230
	v_xor_b32_e32 v229, v230, v135
	v_and_b32_e32 v229, 0xffffff80, v229
	v_or_b32_e32 v91, v229, v220
	v_ashrrev_i32_e32 v230, 31, v136
	v_or_b32_e32 v230, 0x80000000, v230
	v_xor_b32_e32 v229, v230, v136
	v_and_b32_e32 v229, 0xffffff80, v229
	v_or_b32_e32 v109, v229, v221
	v_ashrrev_i32_e32 v230, 31, v137
	v_or_b32_e32 v230, 0x80000000, v230
	v_xor_b32_e32 v229, v230, v137
	v_and_b32_e32 v229, 0xffffff80, v229
	v_or_b32_e32 v96, v229, v222
	v_ashrrev_i32_e32 v230, 31, v138
	v_or_b32_e32 v230, 0x80000000, v230
	v_xor_b32_e32 v229, v230, v138
	v_and_b32_e32 v229, 0xffffff80, v229
	v_or_b32_e32 v115, v229, v223
	v_ashrrev_i32_e32 v230, 31, v139
	v_or_b32_e32 v230, 0x80000000, v230
	v_xor_b32_e32 v229, v230, v139
	v_and_b32_e32 v229, 0xffffff80, v229
	v_or_b32_e32 v81, v229, v224
	v_ashrrev_i32_e32 v230, 31, v140
	v_or_b32_e32 v230, 0x80000000, v230
	v_xor_b32_e32 v229, v230, v140
	v_and_b32_e32 v229, 0xffffff80, v229
	v_or_b32_e32 v107, v229, v225
	v_ashrrev_i32_e32 v230, 31, v141
	v_or_b32_e32 v230, 0x80000000, v230
	v_xor_b32_e32 v229, v230, v141
	v_and_b32_e32 v229, 0xffffff80, v229
	v_or_b32_e32 v114, v229, v226
	v_ashrrev_i32_e32 v230, 31, v142
	v_or_b32_e32 v230, 0x80000000, v230
	v_xor_b32_e32 v229, v230, v142
	v_and_b32_e32 v229, 0xffffff80, v229
	v_or_b32_e32 v98, v229, v227
	v_ashrrev_i32_e32 v230, 31, v143
	v_or_b32_e32 v230, 0x80000000, v230
	v_xor_b32_e32 v229, v230, v143
	v_and_b32_e32 v229, 0xffffff80, v229
	v_or_b32_e32 v104, v229, v228
	v_subrev_u32_e32 v213, 32, v213
	v_subrev_u32_e32 v214, 32, v214
	v_subrev_u32_e32 v215, 32, v215
	v_subrev_u32_e32 v216, 32, v216
	v_subrev_u32_e32 v217, 32, v217
	v_subrev_u32_e32 v218, 32, v218
	v_subrev_u32_e32 v219, 32, v219
; #define MFMA32(a, b, c) __builtin_amdgcn_mfma_f32_32x32x16_bf16((a), (b), (c), 0, 0, 0)
; template <int LOGN>
; DI void bitonic_sort_desc(unsigned (&a)[1 << LOGN]) {
;   constexpr int N = 1 << LOGN;
; #pragma unroll
;   for (int ks = 1; ks <= LOGN; ++ks)
; #pragma unroll
;     ...
; #pragma unroll
;       for (int i = 0; i < N; ++i) {
;         const int k = 1 << ks, j = 1 << js, l = i ^ j;
;         if (l > i) {
;           const bool desc = ((i & k) == 0) || (ks == LOGN);
;           const unsigned x = a[i], y = a[l];
;           const unsigned hi = max(x, y), lo = min(x, y);
;           a[i] = desc ? hi : lo;
;           a[l] = desc ? lo : hi;
;         }
;       }
; DI void peer_top16(const u16* __restrict__ PQrow, const u16* __restrict__ SK, unsigned (&top)[16], int lr, int hh) {
;     ...
; #pragma unroll
;     for (int ks = 0; ks < 8; ++ks) {
;       bf16x8 a = *(const bf16x8*)(SK + (size_t)(kt * 32 + lr) * 128 + ks * 16 + hh * 8);
;       acc = MFMA32(a, qf[ks], acc);
;     }
	v_subrev_u32_e32 v220, 32, v220
	v_subrev_u32_e32 v221, 32, v221
	v_subrev_u32_e32 v222, 32, v222
	v_subrev_u32_e32 v223, 32, v223
	v_subrev_u32_e32 v224, 32, v224
	v_subrev_u32_e32 v225, 32, v225
	v_subrev_u32_e32 v226, 32, v226
	v_subrev_u32_e32 v227, 32, v227
	v_subrev_u32_e32 v228, 32, v228
	v_max_u32_e32 v106, v105, v86
	v_min_u32_e32 v86, v105, v86
	v_min_u32_e32 v105, v90, v101
	v_max_u32_e32 v101, v90, v101
	v_max_u32_e32 v90, v97, v112
	v_min_u32_e32 v112, v97, v112
	v_min_u32_e32 v97, v100, v91
	v_max_u32_e32 v91, v100, v91
	v_max_u32_e32 v100, v109, v96
	v_min_u32_e32 v96, v109, v96
	v_min_u32_e32 v109, v115, v81
	v_max_u32_e32 v81, v115, v81
	v_max_u32_e32 v115, v107, v114
	v_min_u32_e32 v114, v107, v114
	v_min_u32_e32 v107, v98, v104
	v_max_u32_e32 v104, v98, v104
	v_max_u32_e32 v98, v106, v105
	v_min_u32_e32 v105, v106, v105
	v_max_u32_e32 v106, v86, v101
	v_min_u32_e32 v101, v86, v101
	v_min_u32_e32 v86, v90, v97
	v_max_u32_e32 v97, v90, v97
	v_min_u32_e32 v90, v112, v91
	v_max_u32_e32 v91, v112, v91
	v_max_u32_e32 v112, v100, v109
	v_min_u32_e32 v109, v100, v109
	v_max_u32_e32 v100, v96, v81
	v_min_u32_e32 v81, v96, v81
	v_min_u32_e32 v96, v115, v107
	v_max_u32_e32 v107, v115, v107
	v_min_u32_e32 v115, v114, v104
	v_max_u32_e32 v104, v114, v104
	v_max_u32_e32 v114, v98, v106
	v_min_u32_e32 v106, v98, v106
	v_max_u32_e32 v98, v105, v101
	v_min_u32_e32 v101, v105, v101
	v_min_u32_e32 v105, v86, v90
	v_max_u32_e32 v90, v86, v90
	v_min_u32_e32 v86, v97, v91
	v_max_u32_e32 v91, v97, v91
	v_max_u32_e32 v97, v112, v100
	v_min_u32_e32 v100, v112, v100
	v_max_u32_e32 v112, v109, v81
	v_min_u32_e32 v81, v109, v81
	v_min_u32_e32 v109, v96, v115
	v_max_u32_e32 v115, v96, v115
	v_min_u32_e32 v96, v107, v104
	v_max_u32_e32 v104, v107, v104
	v_max_u32_e32 v107, v114, v105
	v_min_u32_e32 v105, v114, v105
	v_max_u32_e32 v114, v106, v90
	v_min_u32_e32 v90, v106, v90
	v_max_u32_e32 v106, v98, v86
	v_min_u32_e32 v86, v98, v86
	v_max_u32_e32 v98, v101, v91
	v_min_u32_e32 v91, v101, v91
	v_min_u32_e32 v101, v97, v109
	v_max_u32_e32 v109, v97, v109
	v_min_u32_e32 v97, v100, v115
	v_max_u32_e32 v115, v100, v115
	v_min_u32_e32 v100, v112, v96
	v_max_u32_e32 v96, v112, v96
	v_min_u32_e32 v112, v81, v104
	v_max_u32_e32 v104, v81, v104
	v_max_u32_e32 v81, v107, v106
	v_min_u32_e32 v106, v107, v106
	v_max_u32_e32 v107, v114, v98
	v_min_u32_e32 v98, v114, v98
	v_max_u32_e32 v114, v105, v86
	v_min_u32_e32 v86, v105, v86
	v_max_u32_e32 v105, v90, v91
	v_min_u32_e32 v91, v90, v91
	v_min_u32_e32 v90, v101, v100
	v_max_u32_e32 v100, v101, v100
	v_min_u32_e32 v101, v97, v112
	v_max_u32_e32 v112, v97, v112
	v_min_u32_e32 v97, v109, v96
	v_max_u32_e32 v96, v109, v96
	v_min_u32_e32 v109, v115, v104
	v_max_u32_e32 v104, v115, v104
	v_max_u32_e32 v115, v81, v107
	v_min_u32_e32 v107, v81, v107
	v_max_u32_e32 v81, v106, v98
	v_min_u32_e32 v98, v106, v98
	v_max_u32_e32 v106, v114, v105
	v_min_u32_e32 v105, v114, v105
	v_max_u32_e32 v114, v86, v91
	v_min_u32_e32 v91, v86, v91
	v_min_u32_e32 v86, v90, v101
	v_max_u32_e32 v101, v90, v101
	v_min_u32_e32 v90, v100, v112
	v_max_u32_e32 v112, v100, v112
	v_min_u32_e32 v100, v97, v109
	v_max_u32_e32 v109, v97, v109
	v_min_u32_e32 v97, v96, v104
	v_max_u32_e32 v104, v96, v104
	v_max_u32_e32 v96, v115, v86
	v_min_u32_e32 v86, v115, v86
	v_max_u32_e32 v115, v107, v101
	v_min_u32_e32 v101, v107, v101
	v_max_u32_e32 v107, v81, v90
	v_min_u32_e32 v90, v81, v90
	v_max_u32_e32 v81, v98, v112
	v_min_u32_e32 v112, v98, v112
	v_max_u32_e32 v98, v106, v100
	v_min_u32_e32 v100, v106, v100
	v_max_u32_e32 v106, v105, v109
	v_min_u32_e32 v109, v105, v109
	v_max_u32_e32 v105, v114, v97
	v_min_u32_e32 v97, v114, v97
	v_max_u32_e32 v114, v91, v104
	v_min_u32_e32 v104, v91, v104
	v_max_u32_e32 v91, v96, v98
	v_min_u32_e32 v98, v96, v98
	v_max_u32_e32 v96, v115, v106
	v_min_u32_e32 v106, v115, v106
	v_max_u32_e32 v115, v107, v105
	v_min_u32_e32 v105, v107, v105
	v_max_u32_e32 v107, v81, v114
	v_min_u32_e32 v114, v81, v114
	v_max_u32_e32 v81, v86, v100
	v_min_u32_e32 v100, v86, v100
	v_max_u32_e32 v86, v101, v109
	v_min_u32_e32 v109, v101, v109
	v_max_u32_e32 v101, v90, v97
	v_min_u32_e32 v97, v90, v97
	v_max_u32_e32 v90, v112, v104
	v_min_u32_e32 v104, v112, v104
	v_max_u32_e32 v112, v91, v115
	v_min_u32_e32 v115, v91, v115
	v_max_u32_e32 v91, v96, v107
	v_min_u32_e32 v107, v96, v107
	v_max_u32_e32 v96, v98, v105
	v_min_u32_e32 v105, v98, v105
	v_max_u32_e32 v98, v106, v114
	v_min_u32_e32 v114, v106, v114
	v_max_u32_e32 v106, v81, v101
	v_min_u32_e32 v101, v81, v101
	v_max_u32_e32 v81, v86, v90
	v_min_u32_e32 v90, v86, v90
	v_max_u32_e32 v86, v100, v97
	v_min_u32_e32 v97, v100, v97
	v_max_u32_e32 v100, v109, v104
	v_min_u32_e32 v104, v109, v104
	v_max_u32_e32 v109, v112, v91
	v_min_u32_e32 v91, v112, v91
	v_max_u32_e32 v112, v115, v107
	v_min_u32_e32 v107, v115, v107
	v_max_u32_e32 v115, v96, v98
	v_min_u32_e32 v98, v96, v98
	v_max_u32_e32 v96, v105, v114
	v_min_u32_e32 v114, v105, v114
	v_max_u32_e32 v105, v106, v81
	v_min_u32_e32 v81, v106, v81
	v_max_u32_e32 v106, v101, v90
	v_min_u32_e32 v90, v101, v90
	v_max_u32_e32 v101, v86, v100
	v_min_u32_e32 v100, v86, v100
	v_max_u32_e32 v86, v97, v104
	v_min_u32_e32 v104, v97, v104
	s_waitcnt vmcnt(7)
	v_mfma_f32_32x32x16_bf16 v[128:143], v[144:147], v[176:179], 0
	s_waitcnt vmcnt(6)
	v_mfma_f32_32x32x16_bf16 v[128:143], v[148:151], v[180:183], v[128:143]
	s_waitcnt vmcnt(5)
	v_mfma_f32_32x32x16_bf16 v[128:143], v[152:155], v[184:187], v[128:143]
	s_waitcnt vmcnt(4)
	v_mfma_f32_32x32x16_bf16 v[128:143], v[156:159], v[188:191], v[128:143]
	s_waitcnt vmcnt(3)
; #define MFMA32(a, b, c) __builtin_amdgcn_mfma_f32_32x32x16_bf16((a), (b), (c), 0, 0, 0)
; DI int crow(int i, int hh) { return (i & 3) + 8 * (i >> 2) + 4 * hh; }
; template <int LOGN>
; DI void bitonic_sort_desc(unsigned (&a)[1 << LOGN]) {
;   constexpr int N = 1 << LOGN;
; #pragma unroll
;   for (int ks = 1; ks <= LOGN; ++ks)
; #pragma unroll
;     ...
; #pragma unroll
;       for (int i = 0; i < N; ++i) {
;         const int k = 1 << ks, j = 1 << js, l = i ^ j;
;         if (l > i) {
;           const bool desc = ((i & k) == 0) || (ks == LOGN);
;           const unsigned x = a[i], y = a[l];
;           const unsigned hi = max(x, y), lo = min(x, y);
;           a[i] = desc ? hi : lo;
;           a[l] = desc ? lo : hi;
;         }
;       }
; DI void peer_top16(const u16* __restrict__ PQrow, const u16* __restrict__ SK, unsigned (&top)[16], int lr, int hh) {
;     ...
;   for (int kt = 0; kt < 4; ++kt) {
;     f32x16 acc;
; #pragma unroll
;     for (int e = 0; e < 16; ++e) acc[e] = 0.f;
; #pragma unroll
;     for (int ks = 0; ks < 8; ++ks) {
;       bf16x8 a = *(const bf16x8*)(SK + (size_t)(kt * 32 + lr) * 128 + ks * 16 + hh * 8);
;       acc = MFMA32(a, qf[ks], acc);
;     }
; #pragma unroll
;     for (int e = 0; e < 16; ++e) {
;       int kidx = kt * 32 + crow(e, hh);
;       g[kt][e] = (f2ord(acc[e]) & ~127u) | (unsigned)(127 - kidx);
;     }
;     bitonic_sort_desc<4>(g[kt]);
	v_mfma_f32_32x32x16_bf16 v[128:143], v[160:163], v[192:195], v[128:143]
	s_waitcnt vmcnt(2)
	v_mfma_f32_32x32x16_bf16 v[128:143], v[164:167], v[196:199], v[128:143]
	s_waitcnt vmcnt(1)
	v_mfma_f32_32x32x16_bf16 v[128:143], v[168:171], v[200:203], v[128:143]
	s_waitcnt vmcnt(0)
	v_mfma_f32_32x32x16_bf16 v[128:143], v[172:175], v[204:207], v[128:143]
	s_add_u32 s4, s0, 81920
	s_addc_u32 s5, s1, 0
	global_load_dwordx4 v[144:147], v238, s[4:5] offset:0
	global_load_dwordx4 v[148:151], v238, s[4:5] offset:32
	global_load_dwordx4 v[152:155], v238, s[4:5] offset:64
	global_load_dwordx4 v[156:159], v238, s[4:5] offset:96
	global_load_dwordx4 v[160:163], v238, s[4:5] offset:128
	global_load_dwordx4 v[164:167], v238, s[4:5] offset:160
	global_load_dwordx4 v[168:171], v238, s[4:5] offset:192
	global_load_dwordx4 v[172:175], v238, s[4:5] offset:224
	s_nop 7
	v_ashrrev_i32_e32 v230, 31, v128
	v_or_b32_e32 v230, 0x80000000, v230
	v_xor_b32_e32 v229, v230, v128
	v_and_b32_e32 v229, 0xffffff80, v229
	v_or_b32_e32 v97, v229, v213
	v_ashrrev_i32_e32 v230, 31, v129
	v_or_b32_e32 v230, 0x80000000, v230
	v_xor_b32_e32 v229, v230, v129
	v_and_b32_e32 v229, 0xffffff80, v229
	v_or_b32_e32 v89, v229, v214
	v_ashrrev_i32_e32 v230, 31, v130
	v_or_b32_e32 v230, 0x80000000, v230
	v_xor_b32_e32 v229, v230, v130
	v_and_b32_e32 v229, 0xffffff80, v229
	v_or_b32_e32 v113, v229, v215
	v_ashrrev_i32_e32 v230, 31, v131
	v_or_b32_e32 v230, 0x80000000, v230
	v_xor_b32_e32 v229, v230, v131
	v_and_b32_e32 v229, 0xffffff80, v229
	v_or_b32_e32 v108, v229, v216
	v_ashrrev_i32_e32 v230, 31, v132
	v_or_b32_e32 v230, 0x80000000, v230
	v_xor_b32_e32 v229, v230, v132
	v_and_b32_e32 v229, 0xffffff80, v229
	v_or_b32_e32 v85, v229, v217
	v_ashrrev_i32_e32 v230, 31, v133
	v_or_b32_e32 v230, 0x80000000, v230
	v_xor_b32_e32 v229, v230, v133
	v_and_b32_e32 v229, 0xffffff80, v229
	v_or_b32_e32 v88, v229, v218
	v_ashrrev_i32_e32 v230, 31, v134
	v_or_b32_e32 v230, 0x80000000, v230
	v_xor_b32_e32 v229, v230, v134
	v_and_b32_e32 v229, 0xffffff80, v229
	v_or_b32_e32 v110, v229, v219
	v_ashrrev_i32_e32 v230, 31, v135
	v_or_b32_e32 v230, 0x80000000, v230
	v_xor_b32_e32 v229, v230, v135
	v_and_b32_e32 v229, 0xffffff80, v229
	v_or_b32_e32 v92, v229, v220
	v_ashrrev_i32_e32 v230, 31, v136
	v_or_b32_e32 v230, 0x80000000, v230
	v_xor_b32_e32 v229, v230, v136
	v_and_b32_e32 v229, 0xffffff80, v229
	v_or_b32_e32 v87, v229, v221
	v_ashrrev_i32_e32 v230, 31, v137
	v_or_b32_e32 v230, 0x80000000, v230
	v_xor_b32_e32 v229, v230, v137
	v_and_b32_e32 v229, 0xffffff80, v229
	v_or_b32_e32 v77, v229, v222
	v_ashrrev_i32_e32 v230, 31, v138
	v_or_b32_e32 v230, 0x80000000, v230
	v_xor_b32_e32 v229, v230, v138
	v_and_b32_e32 v229, 0xffffff80, v229
	v_or_b32_e32 v116, v229, v223
	v_ashrrev_i32_e32 v230, 31, v139
	v_or_b32_e32 v230, 0x80000000, v230
	v_xor_b32_e32 v229, v230, v139
	v_and_b32_e32 v229, 0xffffff80, v229
	v_or_b32_e32 v83, v229, v224
	v_ashrrev_i32_e32 v230, 31, v140
	v_or_b32_e32 v230, 0x80000000, v230
	v_xor_b32_e32 v229, v230, v140
	v_and_b32_e32 v229, 0xffffff80, v229
	v_or_b32_e32 v102, v229, v225
	v_ashrrev_i32_e32 v230, 31, v141
	v_or_b32_e32 v230, 0x80000000, v230
	v_xor_b32_e32 v229, v230, v141
	v_and_b32_e32 v229, 0xffffff80, v229
	v_or_b32_e32 v117, v229, v226
	v_ashrrev_i32_e32 v230, 31, v142
	v_or_b32_e32 v230, 0x80000000, v230
	v_xor_b32_e32 v229, v230, v142
	v_and_b32_e32 v229, 0xffffff80, v229
	v_or_b32_e32 v70, v229, v227
	v_ashrrev_i32_e32 v230, 31, v143
	v_or_b32_e32 v230, 0x80000000, v230
	v_xor_b32_e32 v229, v230, v143
	v_and_b32_e32 v229, 0xffffff80, v229
	v_or_b32_e32 v111, v229, v228
	v_subrev_u32_e32 v213, 32, v213
	v_subrev_u32_e32 v214, 32, v214
	v_subrev_u32_e32 v215, 32, v215
	v_subrev_u32_e32 v216, 32, v216
	v_subrev_u32_e32 v217, 32, v217
	v_subrev_u32_e32 v218, 32, v218
	v_subrev_u32_e32 v219, 32, v219
	v_subrev_u32_e32 v220, 32, v220
	v_subrev_u32_e32 v221, 32, v221
	v_subrev_u32_e32 v222, 32, v222
	v_subrev_u32_e32 v223, 32, v223
	v_subrev_u32_e32 v224, 32, v224
	v_subrev_u32_e32 v225, 32, v225
	v_subrev_u32_e32 v226, 32, v226
	v_subrev_u32_e32 v227, 32, v227
	v_subrev_u32_e32 v228, 32, v228
	v_max_u32_e32 v103, v97, v89
	v_min_u32_e32 v89, v97, v89
	v_min_u32_e32 v97, v113, v108
	v_max_u32_e32 v108, v113, v108
	v_max_u32_e32 v113, v85, v88
	v_min_u32_e32 v88, v85, v88
	v_min_u32_e32 v85, v110, v92
	v_max_u32_e32 v92, v110, v92
	v_max_u32_e32 v110, v87, v77
	v_min_u32_e32 v77, v87, v77
	v_min_u32_e32 v87, v116, v83
	v_max_u32_e32 v83, v116, v83
	v_max_u32_e32 v116, v102, v117
	v_min_u32_e32 v117, v102, v117
	v_min_u32_e32 v102, v70, v111
	v_max_u32_e32 v111, v70, v111
	v_max_u32_e32 v70, v103, v97
	v_min_u32_e32 v97, v103, v97
	v_max_u32_e32 v103, v89, v108
	v_min_u32_e32 v108, v89, v108
	v_min_u32_e32 v89, v113, v85
	v_max_u32_e32 v85, v113, v85
	v_min_u32_e32 v113, v88, v92
	v_max_u32_e32 v92, v88, v92
	v_max_u32_e32 v88, v110, v87
	v_min_u32_e32 v87, v110, v87
	v_max_u32_e32 v110, v77, v83
	v_min_u32_e32 v83, v77, v83
	v_min_u32_e32 v77, v116, v102
	v_max_u32_e32 v102, v116, v102
	v_min_u32_e32 v116, v117, v111
	v_max_u32_e32 v111, v117, v111
	v_max_u32_e32 v117, v70, v103
	v_min_u32_e32 v103, v70, v103
	v_max_u32_e32 v70, v97, v108
	v_min_u32_e32 v108, v97, v108
	v_min_u32_e32 v97, v89, v113
	v_max_u32_e32 v113, v89, v113
	v_min_u32_e32 v89, v85, v92
	v_max_u32_e32 v92, v85, v92
	v_max_u32_e32 v85, v88, v110
	v_min_u32_e32 v110, v88, v110
	v_max_u32_e32 v88, v87, v83
	v_min_u32_e32 v83, v87, v83
	v_min_u32_e32 v87, v77, v116
	v_max_u32_e32 v116, v77, v116
	v_min_u32_e32 v77, v102, v111
	v_max_u32_e32 v111, v102, v111
	v_max_u32_e32 v102, v117, v97
	v_min_u32_e32 v97, v117, v97
; template <int LOGN>
; DI void bitonic_sort_desc(unsigned (&a)[1 << LOGN]) {
;   constexpr int N = 1 << LOGN;
; #pragma unroll
;   for (int ks = 1; ks <= LOGN; ++ks)
; #pragma unroll
;     ...
; #pragma unroll
;       for (int i = 0; i < N; ++i) {
;         const int k = 1 << ks, j = 1 << js, l = i ^ j;
;         if (l > i) {
;           const bool desc = ((i & k) == 0) || (ks == LOGN);
;           const unsigned x = a[i], y = a[l];
;           const unsigned hi = max(x, y), lo = min(x, y);
;           a[i] = desc ? hi : lo;
;           a[l] = desc ? lo : hi;
;         }
;       }
; }
; DI void merge_top16(unsigned (&a)[16], const unsigned (&b)[16]) {
; #pragma unroll
;   for (int i = 0; i < 16; ++i) a[i] = max(a[i], b[15 - i]);
; #pragma unroll
;     ...
; #pragma unroll
;     for (int i = 0; i < 16; ++i) {
;       const int j = 1 << js, l = i ^ j;
;       if (l > i) {
;         const unsigned x = a[i], y = a[l];
;         a[i] = max(x, y);
;         a[l] = min(x, y);
;       }
;     }
; }
	v_max_u32_e32 v117, v103, v113
	v_min_u32_e32 v113, v103, v113
	v_max_u32_e32 v103, v70, v89
	v_min_u32_e32 v89, v70, v89
	v_max_u32_e32 v70, v108, v92
	v_min_u32_e32 v92, v108, v92
	v_min_u32_e32 v108, v85, v87
	v_max_u32_e32 v87, v85, v87
	v_min_u32_e32 v85, v110, v116
	v_max_u32_e32 v116, v110, v116
	v_min_u32_e32 v110, v88, v77
	v_max_u32_e32 v77, v88, v77
	v_min_u32_e32 v88, v83, v111
	v_max_u32_e32 v111, v83, v111
	v_max_u32_e32 v83, v102, v103
	v_min_u32_e32 v103, v102, v103
	v_max_u32_e32 v102, v117, v70
	v_min_u32_e32 v70, v117, v70
	v_max_u32_e32 v117, v97, v89
	v_min_u32_e32 v89, v97, v89
	v_max_u32_e32 v97, v113, v92
	v_min_u32_e32 v92, v113, v92
	v_min_u32_e32 v113, v108, v110
	v_max_u32_e32 v110, v108, v110
	v_min_u32_e32 v108, v85, v88
	v_max_u32_e32 v88, v85, v88
	v_min_u32_e32 v85, v87, v77
	v_max_u32_e32 v77, v87, v77
	v_min_u32_e32 v87, v116, v111
	v_max_u32_e32 v111, v116, v111
	v_max_u32_e32 v116, v83, v102
	v_min_u32_e32 v102, v83, v102
	v_max_u32_e32 v83, v103, v70
	v_min_u32_e32 v70, v103, v70
	v_max_u32_e32 v103, v117, v97
	v_min_u32_e32 v97, v117, v97
	v_max_u32_e32 v117, v89, v92
	v_min_u32_e32 v92, v89, v92
	v_min_u32_e32 v89, v113, v108
	v_max_u32_e32 v108, v113, v108
	v_min_u32_e32 v113, v110, v88
	v_max_u32_e32 v88, v110, v88
	v_min_u32_e32 v110, v85, v87
	v_max_u32_e32 v87, v85, v87
	v_min_u32_e32 v85, v77, v111
	v_max_u32_e32 v111, v77, v111
	v_max_u32_e32 v77, v116, v89
	v_min_u32_e32 v89, v116, v89
	v_max_u32_e32 v116, v102, v108
	v_min_u32_e32 v108, v102, v108
	v_max_u32_e32 v102, v83, v113
	v_min_u32_e32 v113, v83, v113
	v_max_u32_e32 v83, v70, v88
	v_min_u32_e32 v88, v70, v88
	v_max_u32_e32 v70, v103, v110
	v_min_u32_e32 v110, v103, v110
	v_max_u32_e32 v103, v97, v87
	v_min_u32_e32 v87, v97, v87
	v_max_u32_e32 v97, v117, v85
	v_min_u32_e32 v85, v117, v85
	v_max_u32_e32 v117, v92, v111
	v_min_u32_e32 v111, v92, v111
	v_max_u32_e32 v92, v77, v70
	v_min_u32_e32 v70, v77, v70
	v_max_u32_e32 v77, v116, v103
	v_min_u32_e32 v103, v116, v103
	v_max_u32_e32 v116, v102, v97
	v_min_u32_e32 v97, v102, v97
	v_max_u32_e32 v102, v83, v117
	v_min_u32_e32 v117, v83, v117
	v_max_u32_e32 v83, v89, v110
	v_min_u32_e32 v110, v89, v110
	v_max_u32_e32 v89, v108, v87
	v_min_u32_e32 v87, v108, v87
	v_max_u32_e32 v108, v113, v85
	v_min_u32_e32 v85, v113, v85
	v_max_u32_e32 v113, v88, v111
	v_min_u32_e32 v111, v88, v111
	v_max_u32_e32 v88, v92, v116
	v_min_u32_e32 v116, v92, v116
	v_max_u32_e32 v92, v77, v102
	v_min_u32_e32 v102, v77, v102
	v_max_u32_e32 v77, v70, v97
	v_min_u32_e32 v97, v70, v97
	v_max_u32_e32 v70, v103, v117
	v_min_u32_e32 v117, v103, v117
	v_max_u32_e32 v103, v83, v108
	v_min_u32_e32 v108, v83, v108
	v_max_u32_e32 v83, v89, v113
	v_min_u32_e32 v113, v89, v113
	v_max_u32_e32 v89, v110, v85
	v_min_u32_e32 v85, v110, v85
	v_max_u32_e32 v110, v87, v111
	v_min_u32_e32 v111, v87, v111
	v_max_u32_e32 v87, v88, v92
	v_min_u32_e32 v92, v88, v92
	v_max_u32_e32 v88, v116, v102
	v_min_u32_e32 v102, v116, v102
	v_max_u32_e32 v116, v77, v70
	v_min_u32_e32 v70, v77, v70
	v_max_u32_e32 v77, v97, v117
	v_min_u32_e32 v117, v97, v117
	v_max_u32_e32 v97, v103, v83
	v_min_u32_e32 v83, v103, v83
	v_max_u32_e32 v103, v108, v113
	v_min_u32_e32 v113, v108, v113
	v_max_u32_e32 v108, v89, v110
	v_min_u32_e32 v110, v89, v110
	v_max_u32_e32 v89, v85, v111
	v_min_u32_e32 v111, v85, v111
	v_max_u32_e32 v85, v109, v111
	v_max_u32_e32 v109, v91, v89
	v_max_u32_e32 v91, v112, v110
	v_max_u32_e32 v112, v107, v108
	v_max_u32_e32 v107, v115, v113
	v_max_u32_e32 v115, v98, v103
	v_max_u32_e32 v98, v96, v83
	v_max_u32_e32 v96, v114, v97
	v_max_u32_e32 v114, v105, v117
	v_max_u32_e32 v105, v81, v77
	v_max_u32_e32 v81, v106, v70
	v_max_u32_e32 v106, v90, v116
	v_max_u32_e32 v90, v101, v102
	v_max_u32_e32 v101, v100, v88
	v_max_u32_e32 v100, v86, v92
	v_max_u32_e32 v86, v104, v87
	v_max_u32_e32 v111, v85, v114
	v_min_u32_e32 v114, v85, v114
	v_max_u32_e32 v85, v109, v105
	v_min_u32_e32 v105, v109, v105
	v_max_u32_e32 v109, v91, v81
	v_min_u32_e32 v81, v91, v81
	v_max_u32_e32 v91, v112, v106
	v_min_u32_e32 v106, v112, v106
	v_max_u32_e32 v112, v107, v90
	v_min_u32_e32 v90, v107, v90
	v_max_u32_e32 v107, v115, v101
	v_min_u32_e32 v101, v115, v101
	v_max_u32_e32 v115, v98, v100
	v_min_u32_e32 v100, v98, v100
	v_max_u32_e32 v98, v96, v86
	v_min_u32_e32 v86, v96, v86
	v_max_u32_e32 v96, v111, v112
	v_min_u32_e32 v112, v111, v112
	v_max_u32_e32 v111, v85, v107
	v_min_u32_e32 v107, v85, v107
	v_max_u32_e32 v85, v109, v115
	v_min_u32_e32 v115, v109, v115
	v_max_u32_e32 v109, v91, v98
	v_min_u32_e32 v98, v91, v98
	v_max_u32_e32 v91, v114, v90
	v_min_u32_e32 v90, v114, v90
	v_max_u32_e32 v114, v105, v101
	v_min_u32_e32 v101, v105, v101
	v_max_u32_e32 v105, v81, v100
	v_min_u32_e32 v100, v81, v100
	v_max_u32_e32 v81, v106, v86
	v_min_u32_e32 v86, v106, v86
	v_max_u32_e32 v106, v96, v85
	v_min_u32_e32 v85, v96, v85
	v_max_u32_e32 v96, v111, v109
	v_min_u32_e32 v109, v111, v109
	v_max_u32_e32 v111, v112, v115
	v_min_u32_e32 v115, v112, v115
	v_max_u32_e32 v112, v107, v98
	v_min_u32_e32 v98, v107, v98
	v_max_u32_e32 v107, v91, v105
	v_min_u32_e32 v105, v91, v105
	v_max_u32_e32 v91, v114, v81
	v_min_u32_e32 v81, v114, v81
	v_max_u32_e32 v114, v90, v100
	v_min_u32_e32 v100, v90, v100
	v_max_u32_e32 v90, v101, v86
	v_min_u32_e32 v86, v101, v86
	v_max_u32_e32 v101, v106, v96
	v_min_u32_e32 v96, v106, v96
	v_max_u32_e32 v106, v85, v109
	v_min_u32_e32 v109, v85, v109
	v_max_u32_e32 v85, v111, v112
	v_min_u32_e32 v112, v111, v112
	v_max_u32_e32 v111, v115, v98
	v_min_u32_e32 v98, v115, v98
	v_max_u32_e32 v115, v107, v91
	v_min_u32_e32 v91, v107, v91
	v_max_u32_e32 v107, v105, v81
	v_min_u32_e32 v81, v105, v81
	v_max_u32_e32 v105, v114, v90
	v_min_u32_e32 v90, v114, v90
	v_max_u32_e32 v114, v100, v86
	v_min_u32_e32 v86, v100, v86
	s_waitcnt vmcnt(7)
; #define MFMA32(a, b, c) __builtin_amdgcn_mfma_f32_32x32x16_bf16((a), (b), (c), 0, 0, 0)
; DI int crow(int i, int hh) { return (i & 3) + 8 * (i >> 2) + 4 * hh; }
; template <int LOGN>
; DI void bitonic_sort_desc(unsigned (&a)[1 << LOGN]) {
;   constexpr int N = 1 << LOGN;
; #pragma unroll
;   for (int ks = 1; ks <= LOGN; ++ks)
; #pragma unroll
;     ...
; #pragma unroll
;       for (int i = 0; i < N; ++i) {
;         const int k = 1 << ks, j = 1 << js, l = i ^ j;
;         if (l > i) {
;           const bool desc = ((i & k) == 0) || (ks == LOGN);
;           const unsigned x = a[i], y = a[l];
;           const unsigned hi = max(x, y), lo = min(x, y);
;           a[i] = desc ? hi : lo;
;           a[l] = desc ? lo : hi;
;         }
;       }
; DI void peer_top16(const u16* __restrict__ PQrow, const u16* __restrict__ SK, unsigned (&top)[16], int lr, int hh) {
;     ...
;   for (int kt = 0; kt < 4; ++kt) {
;     f32x16 acc;
; #pragma unroll
;     for (int e = 0; e < 16; ++e) acc[e] = 0.f;
; #pragma unroll
;     for (int ks = 0; ks < 8; ++ks) {
;       bf16x8 a = *(const bf16x8*)(SK + (size_t)(kt * 32 + lr) * 128 + ks * 16 + hh * 8);
;       acc = MFMA32(a, qf[ks], acc);
;     }
; #pragma unroll
;     for (int e = 0; e < 16; ++e) {
;       int kidx = kt * 32 + crow(e, hh);
;       g[kt][e] = (f2ord(acc[e]) & ~127u) | (unsigned)(127 - kidx);
;     }
;     bitonic_sort_desc<4>(g[kt]);
	v_mfma_f32_32x32x16_bf16 v[128:143], v[144:147], v[176:179], 0
	s_waitcnt vmcnt(6)
	v_mfma_f32_32x32x16_bf16 v[128:143], v[148:151], v[180:183], v[128:143]
	s_waitcnt vmcnt(5)
	v_mfma_f32_32x32x16_bf16 v[128:143], v[152:155], v[184:187], v[128:143]
	s_waitcnt vmcnt(4)
	v_mfma_f32_32x32x16_bf16 v[128:143], v[156:159], v[188:191], v[128:143]
	s_waitcnt vmcnt(3)
	v_mfma_f32_32x32x16_bf16 v[128:143], v[160:163], v[192:195], v[128:143]
	s_waitcnt vmcnt(2)
	v_mfma_f32_32x32x16_bf16 v[128:143], v[164:167], v[196:199], v[128:143]
	s_waitcnt vmcnt(1)
	v_mfma_f32_32x32x16_bf16 v[128:143], v[168:171], v[200:203], v[128:143]
	s_waitcnt vmcnt(0)
	v_mfma_f32_32x32x16_bf16 v[128:143], v[172:175], v[204:207], v[128:143]
	s_add_u32 s4, s0, 90112
	s_addc_u32 s5, s1, 0
	global_load_dwordx4 v[144:147], v238, s[4:5] offset:0
	global_load_dwordx4 v[148:151], v238, s[4:5] offset:32
	global_load_dwordx4 v[152:155], v238, s[4:5] offset:64
	global_load_dwordx4 v[156:159], v238, s[4:5] offset:96
	global_load_dwordx4 v[160:163], v238, s[4:5] offset:128
	global_load_dwordx4 v[164:167], v238, s[4:5] offset:160
	global_load_dwordx4 v[168:171], v238, s[4:5] offset:192
	global_load_dwordx4 v[172:175], v238, s[4:5] offset:224
	s_nop 7
	v_ashrrev_i32_e32 v230, 31, v128
	v_or_b32_e32 v230, 0x80000000, v230
	v_xor_b32_e32 v229, v230, v128
	v_and_b32_e32 v229, 0xffffff80, v229
	v_or_b32_e32 v100, v229, v213
	v_ashrrev_i32_e32 v230, 31, v129
	v_or_b32_e32 v230, 0x80000000, v230
	v_xor_b32_e32 v229, v230, v129
	v_and_b32_e32 v229, 0xffffff80, v229
	v_or_b32_e32 v89, v229, v214
	v_ashrrev_i32_e32 v230, 31, v130
	v_or_b32_e32 v230, 0x80000000, v230
	v_xor_b32_e32 v229, v230, v130
	v_and_b32_e32 v229, 0xffffff80, v229
	v_or_b32_e32 v110, v229, v215
	v_ashrrev_i32_e32 v230, 31, v131
	v_or_b32_e32 v230, 0x80000000, v230
	v_xor_b32_e32 v229, v230, v131
	v_and_b32_e32 v229, 0xffffff80, v229
	v_or_b32_e32 v108, v229, v216
	v_ashrrev_i32_e32 v230, 31, v132
	v_or_b32_e32 v230, 0x80000000, v230
	v_xor_b32_e32 v229, v230, v132
	v_and_b32_e32 v229, 0xffffff80, v229
	v_or_b32_e32 v113, v229, v217
	v_ashrrev_i32_e32 v230, 31, v133
	v_or_b32_e32 v230, 0x80000000, v230
	v_xor_b32_e32 v229, v230, v133
	v_and_b32_e32 v229, 0xffffff80, v229
	v_or_b32_e32 v103, v229, v218
	v_ashrrev_i32_e32 v230, 31, v134
	v_or_b32_e32 v230, 0x80000000, v230
	v_xor_b32_e32 v229, v230, v134
	v_and_b32_e32 v229, 0xffffff80, v229
	v_or_b32_e32 v83, v229, v219
	v_ashrrev_i32_e32 v230, 31, v135
	v_or_b32_e32 v230, 0x80000000, v230
	v_xor_b32_e32 v229, v230, v135
	v_and_b32_e32 v229, 0xffffff80, v229
	v_or_b32_e32 v97, v229, v220
	v_ashrrev_i32_e32 v230, 31, v136
	v_or_b32_e32 v230, 0x80000000, v230
	v_xor_b32_e32 v229, v230, v136
	v_and_b32_e32 v229, 0xffffff80, v229
	v_or_b32_e32 v117, v229, v221
	v_ashrrev_i32_e32 v230, 31, v137
	v_or_b32_e32 v230, 0x80000000, v230
	v_xor_b32_e32 v229, v230, v137
	v_and_b32_e32 v229, 0xffffff80, v229
	v_or_b32_e32 v77, v229, v222
	v_ashrrev_i32_e32 v230, 31, v138
	v_or_b32_e32 v230, 0x80000000, v230
	v_xor_b32_e32 v229, v230, v138
	v_and_b32_e32 v229, 0xffffff80, v229
	v_or_b32_e32 v70, v229, v223
	v_ashrrev_i32_e32 v230, 31, v139
	v_or_b32_e32 v230, 0x80000000, v230
	v_xor_b32_e32 v229, v230, v139
	v_and_b32_e32 v229, 0xffffff80, v229
	v_or_b32_e32 v116, v229, v224
	v_ashrrev_i32_e32 v230, 31, v140
	v_or_b32_e32 v230, 0x80000000, v230
	v_xor_b32_e32 v229, v230, v140
	v_and_b32_e32 v229, 0xffffff80, v229
	v_or_b32_e32 v102, v229, v225
	v_ashrrev_i32_e32 v230, 31, v141
	v_or_b32_e32 v230, 0x80000000, v230
	v_xor_b32_e32 v229, v230, v141
	v_and_b32_e32 v229, 0xffffff80, v229
	v_or_b32_e32 v88, v229, v226
	v_ashrrev_i32_e32 v230, 31, v142
	v_or_b32_e32 v230, 0x80000000, v230
	v_xor_b32_e32 v229, v230, v142
	v_and_b32_e32 v229, 0xffffff80, v229
	v_or_b32_e32 v92, v229, v227
	v_ashrrev_i32_e32 v230, 31, v143
	v_or_b32_e32 v230, 0x80000000, v230
	v_xor_b32_e32 v229, v230, v143
	v_and_b32_e32 v229, 0xffffff80, v229
	v_or_b32_e32 v87, v229, v228
	v_subrev_u32_e32 v213, 32, v213
	v_subrev_u32_e32 v214, 32, v214
	v_subrev_u32_e32 v215, 32, v215
	v_subrev_u32_e32 v216, 32, v216
	v_subrev_u32_e32 v217, 32, v217
	v_subrev_u32_e32 v218, 32, v218
	v_subrev_u32_e32 v219, 32, v219
	v_subrev_u32_e32 v220, 32, v220
	v_subrev_u32_e32 v221, 32, v221
	v_subrev_u32_e32 v222, 32, v222
	v_subrev_u32_e32 v223, 32, v223
	v_subrev_u32_e32 v224, 32, v224
	v_subrev_u32_e32 v225, 32, v225
	v_subrev_u32_e32 v226, 32, v226
	v_subrev_u32_e32 v227, 32, v227
	v_subrev_u32_e32 v228, 32, v228
	v_max_u32_e32 v104, v100, v89
	v_min_u32_e32 v89, v100, v89
	v_min_u32_e32 v100, v110, v108
	v_max_u32_e32 v108, v110, v108
	v_max_u32_e32 v110, v113, v103
	v_min_u32_e32 v103, v113, v103
	v_min_u32_e32 v113, v83, v97
	v_max_u32_e32 v97, v83, v97
	v_max_u32_e32 v83, v117, v77
	v_min_u32_e32 v77, v117, v77
	v_min_u32_e32 v117, v70, v116
	v_max_u32_e32 v116, v70, v116
	v_max_u32_e32 v70, v102, v88
	v_min_u32_e32 v88, v102, v88
	v_min_u32_e32 v102, v92, v87
	v_max_u32_e32 v87, v92, v87
	v_max_u32_e32 v92, v104, v100
	v_min_u32_e32 v100, v104, v100
	v_max_u32_e32 v104, v89, v108
	v_min_u32_e32 v108, v89, v108
	v_min_u32_e32 v89, v110, v113
	v_max_u32_e32 v113, v110, v113
	v_min_u32_e32 v110, v103, v97
	v_max_u32_e32 v97, v103, v97
	v_max_u32_e32 v103, v83, v117
	v_min_u32_e32 v117, v83, v117
	v_max_u32_e32 v83, v77, v116
	v_min_u32_e32 v116, v77, v116
	v_min_u32_e32 v77, v70, v102
	v_max_u32_e32 v102, v70, v102
	v_min_u32_e32 v70, v88, v87
	v_max_u32_e32 v87, v88, v87
	v_max_u32_e32 v88, v92, v104
	v_min_u32_e32 v104, v92, v104
	v_max_u32_e32 v92, v100, v108
	v_min_u32_e32 v108, v100, v108
	v_min_u32_e32 v100, v89, v110
; #define MFMA32(a, b, c) __builtin_amdgcn_mfma_f32_32x32x16_bf16((a), (b), (c), 0, 0, 0)
; template <int LOGN>
; DI void bitonic_sort_desc(unsigned (&a)[1 << LOGN]) {
;   constexpr int N = 1 << LOGN;
; #pragma unroll
;   for (int ks = 1; ks <= LOGN; ++ks)
; #pragma unroll
;     ...
; #pragma unroll
;       for (int i = 0; i < N; ++i) {
;         const int k = 1 << ks, j = 1 << js, l = i ^ j;
;         if (l > i) {
;           const bool desc = ((i & k) == 0) || (ks == LOGN);
;           const unsigned x = a[i], y = a[l];
;           const unsigned hi = max(x, y), lo = min(x, y);
;           a[i] = desc ? hi : lo;
;           a[l] = desc ? lo : hi;
;         }
;       }
; DI void peer_top16(const u16* __restrict__ PQrow, const u16* __restrict__ SK, unsigned (&top)[16], int lr, int hh) {
;     ...
; #pragma unroll
;     for (int ks = 0; ks < 8; ++ks) {
;       bf16x8 a = *(const bf16x8*)(SK + (size_t)(kt * 32 + lr) * 128 + ks * 16 + hh * 8);
;       acc = MFMA32(a, qf[ks], acc);
;     }
	v_max_u32_e32 v110, v89, v110
	v_min_u32_e32 v89, v113, v97
	v_max_u32_e32 v97, v113, v97
	v_max_u32_e32 v113, v103, v83
	v_min_u32_e32 v83, v103, v83
	v_max_u32_e32 v103, v117, v116
	v_min_u32_e32 v116, v117, v116
	v_min_u32_e32 v117, v77, v70
	v_max_u32_e32 v70, v77, v70
	v_min_u32_e32 v77, v102, v87
	v_max_u32_e32 v87, v102, v87
	v_max_u32_e32 v102, v88, v100
	v_min_u32_e32 v100, v88, v100
	v_max_u32_e32 v88, v104, v110
	v_min_u32_e32 v110, v104, v110
	v_max_u32_e32 v104, v92, v89
	v_min_u32_e32 v89, v92, v89
	v_max_u32_e32 v92, v108, v97
	v_min_u32_e32 v97, v108, v97
	v_min_u32_e32 v108, v113, v117
	v_max_u32_e32 v117, v113, v117
	v_min_u32_e32 v113, v83, v70
	v_max_u32_e32 v70, v83, v70
	v_min_u32_e32 v83, v103, v77
	v_max_u32_e32 v77, v103, v77
	v_min_u32_e32 v103, v116, v87
	v_max_u32_e32 v87, v116, v87
	v_max_u32_e32 v116, v102, v104
	v_min_u32_e32 v104, v102, v104
	v_max_u32_e32 v102, v88, v92
	v_min_u32_e32 v92, v88, v92
	v_max_u32_e32 v88, v100, v89
	v_min_u32_e32 v89, v100, v89
	v_max_u32_e32 v100, v110, v97
	v_min_u32_e32 v97, v110, v97
	v_min_u32_e32 v110, v108, v83
	v_max_u32_e32 v83, v108, v83
	v_min_u32_e32 v108, v113, v103
	v_max_u32_e32 v103, v113, v103
	v_min_u32_e32 v113, v117, v77
	v_max_u32_e32 v77, v117, v77
	v_min_u32_e32 v117, v70, v87
	v_max_u32_e32 v87, v70, v87
	v_max_u32_e32 v70, v116, v102
	v_min_u32_e32 v102, v116, v102
	v_max_u32_e32 v116, v104, v92
	v_min_u32_e32 v92, v104, v92
	v_max_u32_e32 v104, v88, v100
	v_min_u32_e32 v100, v88, v100
	v_max_u32_e32 v88, v89, v97
	v_min_u32_e32 v97, v89, v97
	v_min_u32_e32 v89, v110, v108
	v_max_u32_e32 v108, v110, v108
	v_min_u32_e32 v110, v83, v103
	v_max_u32_e32 v103, v83, v103
	v_min_u32_e32 v83, v113, v117
	v_max_u32_e32 v117, v113, v117
	v_min_u32_e32 v113, v77, v87
	v_max_u32_e32 v87, v77, v87
	v_max_u32_e32 v77, v70, v89
	v_min_u32_e32 v89, v70, v89
	v_max_u32_e32 v70, v102, v108
	v_min_u32_e32 v108, v102, v108
	v_max_u32_e32 v102, v116, v110
	v_min_u32_e32 v110, v116, v110
	v_max_u32_e32 v116, v92, v103
	v_min_u32_e32 v103, v92, v103
	v_max_u32_e32 v92, v104, v83
	v_min_u32_e32 v83, v104, v83
	v_max_u32_e32 v104, v100, v117
	v_min_u32_e32 v117, v100, v117
	v_max_u32_e32 v100, v88, v113
	v_min_u32_e32 v113, v88, v113
	v_max_u32_e32 v88, v97, v87
	v_min_u32_e32 v87, v97, v87
	v_max_u32_e32 v97, v77, v92
	v_min_u32_e32 v92, v77, v92
	v_max_u32_e32 v77, v70, v104
	v_min_u32_e32 v104, v70, v104
	v_max_u32_e32 v70, v102, v100
	v_min_u32_e32 v100, v102, v100
	v_max_u32_e32 v102, v116, v88
	v_min_u32_e32 v88, v116, v88
	v_max_u32_e32 v116, v89, v83
	v_min_u32_e32 v83, v89, v83
	v_max_u32_e32 v89, v108, v117
	v_min_u32_e32 v117, v108, v117
	v_max_u32_e32 v108, v110, v113
	v_min_u32_e32 v113, v110, v113
	v_max_u32_e32 v110, v103, v87
	v_min_u32_e32 v87, v103, v87
	v_max_u32_e32 v103, v97, v70
	v_min_u32_e32 v70, v97, v70
	v_max_u32_e32 v97, v77, v102
	v_min_u32_e32 v102, v77, v102
	v_max_u32_e32 v77, v92, v100
	v_min_u32_e32 v100, v92, v100
	v_max_u32_e32 v92, v104, v88
	v_min_u32_e32 v88, v104, v88
	v_max_u32_e32 v104, v116, v108
	v_min_u32_e32 v108, v116, v108
	v_max_u32_e32 v116, v89, v110
	v_min_u32_e32 v110, v89, v110
	v_max_u32_e32 v89, v83, v113
	v_min_u32_e32 v113, v83, v113
	v_max_u32_e32 v83, v117, v87
	v_min_u32_e32 v87, v117, v87
	v_max_u32_e32 v117, v103, v97
	v_min_u32_e32 v97, v103, v97
	v_max_u32_e32 v103, v70, v102
	v_min_u32_e32 v102, v70, v102
	v_max_u32_e32 v70, v77, v92
	v_min_u32_e32 v92, v77, v92
	v_max_u32_e32 v77, v100, v88
	v_min_u32_e32 v88, v100, v88
	v_max_u32_e32 v100, v104, v116
	v_min_u32_e32 v116, v104, v116
	v_max_u32_e32 v104, v108, v110
	v_min_u32_e32 v110, v108, v110
	v_max_u32_e32 v108, v89, v83
	v_min_u32_e32 v83, v89, v83
	v_max_u32_e32 v89, v113, v87
	v_min_u32_e32 v87, v113, v87
	s_waitcnt vmcnt(7)
	v_mfma_f32_32x32x16_bf16 v[128:143], v[144:147], v[176:179], 0
	s_waitcnt vmcnt(6)
	v_mfma_f32_32x32x16_bf16 v[128:143], v[148:151], v[180:183], v[128:143]
	s_waitcnt vmcnt(5)
	v_mfma_f32_32x32x16_bf16 v[128:143], v[152:155], v[184:187], v[128:143]
	s_waitcnt vmcnt(4)
	v_mfma_f32_32x32x16_bf16 v[128:143], v[156:159], v[188:191], v[128:143]
	s_waitcnt vmcnt(3)
	v_mfma_f32_32x32x16_bf16 v[128:143], v[160:163], v[192:195], v[128:143]
	s_waitcnt vmcnt(2)
	v_mfma_f32_32x32x16_bf16 v[128:143], v[164:167], v[196:199], v[128:143]
	s_waitcnt vmcnt(1)
	v_mfma_f32_32x32x16_bf16 v[128:143], v[168:171], v[200:203], v[128:143]
	s_waitcnt vmcnt(0)
; #define MFMA32(a, b, c) __builtin_amdgcn_mfma_f32_32x32x16_bf16((a), (b), (c), 0, 0, 0)
; DI int crow(int i, int hh) { return (i & 3) + 8 * (i >> 2) + 4 * hh; }
; DI void peer_top16(const u16* __restrict__ PQrow, const u16* __restrict__ SK, unsigned (&top)[16], int lr, int hh) {
;   bf16x8 qf[8];
; #pragma unroll
;   for (int ks = 0; ks < 8; ++ks) qf[ks] = *(const bf16x8*)(PQrow + ks * 16 + hh * 8);
;   unsigned g[4][16];
; #pragma unroll
;   for (int kt = 0; kt < 4; ++kt) {
;     f32x16 acc;
; #pragma unroll
;     for (int e = 0; e < 16; ++e) acc[e] = 0.f;
; #pragma unroll
;     for (int ks = 0; ks < 8; ++ks) {
;       bf16x8 a = *(const bf16x8*)(SK + (size_t)(kt * 32 + lr) * 128 + ks * 16 + hh * 8);
;       acc = MFMA32(a, qf[ks], acc);
;     }
; #pragma unroll
;     for (int e = 0; e < 16; ++e) {
;       int kidx = kt * 32 + crow(e, hh);
;       g[kt][e] = (f2ord(acc[e]) & ~127u) | (unsigned)(127 - kidx);
;     }
;     bitonic_sort_desc<4>(g[kt]);
	v_mfma_f32_32x32x16_bf16 v[128:143], v[172:175], v[204:207], v[128:143]
	global_load_dwordx4 v[176:179], v239, s[2:3] offset:768
	global_load_dwordx4 v[180:183], v239, s[2:3] offset:800
	global_load_dwordx4 v[184:187], v239, s[2:3] offset:832
	global_load_dwordx4 v[188:191], v239, s[2:3] offset:864
	global_load_dwordx4 v[192:195], v239, s[2:3] offset:896
	global_load_dwordx4 v[196:199], v239, s[2:3] offset:928
	global_load_dwordx4 v[200:203], v239, s[2:3] offset:960
	global_load_dwordx4 v[204:207], v239, s[2:3] offset:992
	s_add_u32 s4, s0, 98304
	s_addc_u32 s5, s1, 0
	global_load_dwordx4 v[144:147], v238, s[4:5] offset:0
	global_load_dwordx4 v[148:151], v238, s[4:5] offset:32
	global_load_dwordx4 v[152:155], v238, s[4:5] offset:64
	global_load_dwordx4 v[156:159], v238, s[4:5] offset:96
	global_load_dwordx4 v[160:163], v238, s[4:5] offset:128
	global_load_dwordx4 v[164:167], v238, s[4:5] offset:160
	global_load_dwordx4 v[168:171], v238, s[4:5] offset:192
	global_load_dwordx4 v[172:175], v238, s[4:5] offset:224
	s_nop 7
	v_ashrrev_i32_e32 v230, 31, v128
	v_or_b32_e32 v230, 0x80000000, v230
	v_xor_b32_e32 v229, v230, v128
	v_and_b32_e32 v229, 0xffffff80, v229
	v_or_b32_e32 v113, v229, v213
	v_ashrrev_i32_e32 v230, 31, v129
	v_or_b32_e32 v230, 0x80000000, v230
	v_xor_b32_e32 v229, v230, v129
	v_and_b32_e32 v229, 0xffffff80, v229
	v_or_b32_e32 v84, v229, v214
	v_ashrrev_i32_e32 v230, 31, v130
	v_or_b32_e32 v230, 0x80000000, v230
	v_xor_b32_e32 v229, v230, v130
	v_and_b32_e32 v229, 0xffffff80, v229
	v_or_b32_e32 v74, v229, v215
	v_ashrrev_i32_e32 v230, 31, v131
	v_or_b32_e32 v230, 0x80000000, v230
	v_xor_b32_e32 v229, v230, v131
	v_and_b32_e32 v229, 0xffffff80, v229
	v_or_b32_e32 v82, v229, v216
	v_ashrrev_i32_e32 v230, 31, v132
	v_or_b32_e32 v230, 0x80000000, v230
	v_xor_b32_e32 v229, v230, v132
	v_and_b32_e32 v229, 0xffffff80, v229
	v_or_b32_e32 v79, v229, v217
	v_ashrrev_i32_e32 v230, 31, v133
	v_or_b32_e32 v230, 0x80000000, v230
	v_xor_b32_e32 v229, v230, v133
	v_and_b32_e32 v229, 0xffffff80, v229
	v_or_b32_e32 v93, v229, v218
	v_ashrrev_i32_e32 v230, 31, v134
	v_or_b32_e32 v230, 0x80000000, v230
	v_xor_b32_e32 v229, v230, v134
	v_and_b32_e32 v229, 0xffffff80, v229
	v_or_b32_e32 v75, v229, v219
	v_ashrrev_i32_e32 v230, 31, v135
	v_or_b32_e32 v230, 0x80000000, v230
	v_xor_b32_e32 v229, v230, v135
	v_and_b32_e32 v229, 0xffffff80, v229
	v_or_b32_e32 v95, v229, v220
	v_ashrrev_i32_e32 v230, 31, v136
	v_or_b32_e32 v230, 0x80000000, v230
	v_xor_b32_e32 v229, v230, v136
	v_and_b32_e32 v229, 0xffffff80, v229
	v_or_b32_e32 v80, v229, v221
	v_ashrrev_i32_e32 v230, 31, v137
	v_or_b32_e32 v230, 0x80000000, v230
	v_xor_b32_e32 v229, v230, v137
	v_and_b32_e32 v229, 0xffffff80, v229
	v_or_b32_e32 v76, v229, v222
	v_ashrrev_i32_e32 v230, 31, v138
	v_or_b32_e32 v230, 0x80000000, v230
	v_xor_b32_e32 v229, v230, v138
	v_and_b32_e32 v229, 0xffffff80, v229
	v_or_b32_e32 v78, v229, v223
	v_ashrrev_i32_e32 v230, 31, v139
	v_or_b32_e32 v230, 0x80000000, v230
	v_xor_b32_e32 v229, v230, v139
	v_and_b32_e32 v229, 0xffffff80, v229
	v_or_b32_e32 v71, v229, v224
	v_ashrrev_i32_e32 v230, 31, v140
	v_or_b32_e32 v230, 0x80000000, v230
	v_xor_b32_e32 v229, v230, v140
	v_and_b32_e32 v229, 0xffffff80, v229
	v_or_b32_e32 v73, v229, v225
	v_ashrrev_i32_e32 v230, 31, v141
	v_or_b32_e32 v230, 0x80000000, v230
	v_xor_b32_e32 v229, v230, v141
	v_and_b32_e32 v229, 0xffffff80, v229
	v_or_b32_e32 v69, v229, v226
	v_ashrrev_i32_e32 v230, 31, v142
	v_or_b32_e32 v230, 0x80000000, v230
	v_xor_b32_e32 v229, v230, v142
	v_and_b32_e32 v229, 0xffffff80, v229
	v_or_b32_e32 v99, v229, v227
	v_ashrrev_i32_e32 v230, 31, v143
	v_or_b32_e32 v230, 0x80000000, v230
	v_xor_b32_e32 v229, v230, v143
	v_and_b32_e32 v229, 0xffffff80, v229
	v_or_b32_e32 v72, v229, v228
	v_max_u32_e32 v94, v113, v84
	v_min_u32_e32 v84, v113, v84
	v_min_u32_e32 v113, v74, v82
	v_max_u32_e32 v82, v74, v82
	v_max_u32_e32 v74, v79, v93
	v_min_u32_e32 v93, v79, v93
	v_min_u32_e32 v79, v75, v95
	v_max_u32_e32 v95, v75, v95
	v_max_u32_e32 v75, v80, v76
	v_min_u32_e32 v76, v80, v76
	v_min_u32_e32 v80, v78, v71
	v_max_u32_e32 v71, v78, v71
	v_max_u32_e32 v78, v73, v69
	v_min_u32_e32 v69, v73, v69
	v_min_u32_e32 v73, v99, v72
	v_max_u32_e32 v72, v99, v72
	v_max_u32_e32 v99, v94, v113
	v_min_u32_e32 v113, v94, v113
	v_max_u32_e32 v94, v84, v82
	v_min_u32_e32 v82, v84, v82
	v_min_u32_e32 v84, v74, v79
	v_max_u32_e32 v79, v74, v79
	v_min_u32_e32 v74, v93, v95
	v_max_u32_e32 v95, v93, v95
	v_max_u32_e32 v93, v75, v80
	v_min_u32_e32 v80, v75, v80
	v_max_u32_e32 v75, v76, v71
	v_min_u32_e32 v71, v76, v71
	v_min_u32_e32 v76, v78, v73
	v_max_u32_e32 v73, v78, v73
	v_min_u32_e32 v78, v69, v72
	v_max_u32_e32 v72, v69, v72
	v_max_u32_e32 v69, v99, v94
	v_min_u32_e32 v94, v99, v94
	v_max_u32_e32 v99, v113, v82
	v_min_u32_e32 v82, v113, v82
	v_min_u32_e32 v113, v84, v74
	v_max_u32_e32 v74, v84, v74
	v_min_u32_e32 v84, v79, v95
	v_max_u32_e32 v95, v79, v95
	v_max_u32_e32 v79, v93, v75
	v_min_u32_e32 v75, v93, v75
	v_max_u32_e32 v93, v80, v71
	v_min_u32_e32 v71, v80, v71
	v_min_u32_e32 v80, v76, v78
	v_max_u32_e32 v78, v76, v78
	v_min_u32_e32 v76, v73, v72
	v_max_u32_e32 v72, v73, v72
	v_max_u32_e32 v73, v69, v113
	v_min_u32_e32 v113, v69, v113
	v_max_u32_e32 v69, v94, v74
	v_min_u32_e32 v74, v94, v74
	v_max_u32_e32 v94, v99, v84
	v_min_u32_e32 v84, v99, v84
	v_max_u32_e32 v99, v82, v95
	v_min_u32_e32 v95, v82, v95
	v_min_u32_e32 v82, v79, v80
	v_max_u32_e32 v80, v79, v80
	v_min_u32_e32 v79, v75, v78
	v_max_u32_e32 v78, v75, v78
	v_min_u32_e32 v75, v93, v76
	v_max_u32_e32 v76, v93, v76
	v_min_u32_e32 v93, v71, v72
	v_max_u32_e32 v72, v71, v72
; template <int LOGN>
; DI void bitonic_sort_desc(unsigned (&a)[1 << LOGN]) {
;   constexpr int N = 1 << LOGN;
; #pragma unroll
;   for (int ks = 1; ks <= LOGN; ++ks)
; #pragma unroll
;     ...
; #pragma unroll
;       for (int i = 0; i < N; ++i) {
;         const int k = 1 << ks, j = 1 << js, l = i ^ j;
;         if (l > i) {
;           const bool desc = ((i & k) == 0) || (ks == LOGN);
;           const unsigned x = a[i], y = a[l];
;           const unsigned hi = max(x, y), lo = min(x, y);
;           a[i] = desc ? hi : lo;
;           a[l] = desc ? lo : hi;
;         }
;       }
; }
; DI void merge_top16(unsigned (&a)[16], const unsigned (&b)[16]) {
; #pragma unroll
;   for (int i = 0; i < 16; ++i) a[i] = max(a[i], b[15 - i]);
; #pragma unroll
;     ...
; #pragma unroll
;     for (int i = 0; i < 16; ++i) {
;       const int j = 1 << js, l = i ^ j;
;       if (l > i) {
;         const unsigned x = a[i], y = a[l];
;         a[i] = max(x, y);
;         a[l] = min(x, y);
;       }
;     }
; }
	v_max_u32_e32 v71, v73, v94
	v_min_u32_e32 v94, v73, v94
	v_max_u32_e32 v73, v69, v99
	v_min_u32_e32 v99, v69, v99
	v_max_u32_e32 v69, v113, v84
	v_min_u32_e32 v84, v113, v84
	v_max_u32_e32 v113, v74, v95
	v_min_u32_e32 v95, v74, v95
	v_min_u32_e32 v74, v82, v75
	v_max_u32_e32 v75, v82, v75
	v_min_u32_e32 v82, v79, v93
	v_max_u32_e32 v93, v79, v93
	v_min_u32_e32 v79, v80, v76
	v_max_u32_e32 v76, v80, v76
	v_min_u32_e32 v80, v78, v72
	v_max_u32_e32 v72, v78, v72
	v_max_u32_e32 v78, v71, v73
	v_min_u32_e32 v73, v71, v73
	v_max_u32_e32 v71, v94, v99
	v_min_u32_e32 v99, v94, v99
	v_max_u32_e32 v94, v69, v113
	v_min_u32_e32 v113, v69, v113
	v_max_u32_e32 v69, v84, v95
	v_min_u32_e32 v95, v84, v95
	v_min_u32_e32 v84, v74, v82
	v_max_u32_e32 v82, v74, v82
	v_min_u32_e32 v74, v75, v93
	v_max_u32_e32 v93, v75, v93
	v_min_u32_e32 v75, v79, v80
	v_max_u32_e32 v80, v79, v80
	v_min_u32_e32 v79, v76, v72
	v_max_u32_e32 v72, v76, v72
	v_max_u32_e32 v76, v78, v84
	v_min_u32_e32 v84, v78, v84
	v_max_u32_e32 v78, v73, v82
	v_min_u32_e32 v82, v73, v82
	v_max_u32_e32 v73, v71, v74
	v_min_u32_e32 v74, v71, v74
	v_max_u32_e32 v71, v99, v93
	v_min_u32_e32 v93, v99, v93
	v_max_u32_e32 v99, v94, v75
	v_min_u32_e32 v75, v94, v75
	v_max_u32_e32 v94, v113, v80
	v_min_u32_e32 v80, v113, v80
	v_max_u32_e32 v113, v69, v79
	v_min_u32_e32 v79, v69, v79
	v_max_u32_e32 v69, v95, v72
	v_min_u32_e32 v72, v95, v72
	v_max_u32_e32 v95, v76, v99
	v_min_u32_e32 v99, v76, v99
	v_max_u32_e32 v76, v78, v94
	v_min_u32_e32 v94, v78, v94
	v_max_u32_e32 v78, v73, v113
	v_min_u32_e32 v113, v73, v113
	v_max_u32_e32 v73, v71, v69
	v_min_u32_e32 v69, v71, v69
	v_max_u32_e32 v71, v84, v75
	v_min_u32_e32 v75, v84, v75
	v_max_u32_e32 v84, v82, v80
	v_min_u32_e32 v80, v82, v80
	v_max_u32_e32 v82, v74, v79
	v_min_u32_e32 v79, v74, v79
	v_max_u32_e32 v74, v93, v72
	v_min_u32_e32 v72, v93, v72
	v_max_u32_e32 v93, v95, v78
	v_min_u32_e32 v78, v95, v78
	v_max_u32_e32 v95, v76, v73
	v_min_u32_e32 v73, v76, v73
	v_max_u32_e32 v76, v99, v113
	v_min_u32_e32 v113, v99, v113
	v_max_u32_e32 v99, v94, v69
	v_min_u32_e32 v69, v94, v69
	v_max_u32_e32 v94, v71, v82
	v_min_u32_e32 v82, v71, v82
	v_max_u32_e32 v71, v84, v74
	v_min_u32_e32 v74, v84, v74
	v_max_u32_e32 v84, v75, v79
	v_min_u32_e32 v79, v75, v79
	v_max_u32_e32 v75, v80, v72
	v_min_u32_e32 v72, v80, v72
	v_max_u32_e32 v80, v93, v95
	v_min_u32_e32 v95, v93, v95
	v_max_u32_e32 v93, v78, v73
	v_min_u32_e32 v73, v78, v73
	v_max_u32_e32 v78, v76, v99
	v_min_u32_e32 v99, v76, v99
	v_max_u32_e32 v76, v113, v69
	v_min_u32_e32 v69, v113, v69
	v_max_u32_e32 v113, v94, v71
	v_min_u32_e32 v71, v94, v71
	v_max_u32_e32 v94, v82, v74
	v_min_u32_e32 v74, v82, v74
	v_max_u32_e32 v82, v84, v75
	v_min_u32_e32 v75, v84, v75
	v_max_u32_e32 v84, v79, v72
	v_min_u32_e32 v72, v79, v72
	v_max_u32_e32 v79, v117, v72
	v_max_u32_e32 v117, v97, v84
	v_max_u32_e32 v97, v103, v75
	v_max_u32_e32 v103, v102, v82
	v_max_u32_e32 v102, v70, v74
	v_max_u32_e32 v70, v92, v94
	v_max_u32_e32 v92, v77, v71
	v_max_u32_e32 v77, v88, v113
	v_max_u32_e32 v88, v100, v69
	v_max_u32_e32 v100, v116, v76
	v_max_u32_e32 v116, v104, v99
	v_max_u32_e32 v104, v110, v78
	v_max_u32_e32 v110, v108, v73
	v_max_u32_e32 v108, v83, v93
	v_max_u32_e32 v83, v89, v95
	v_max_u32_e32 v89, v87, v80
	v_max_u32_e32 v72, v79, v88
	v_min_u32_e32 v88, v79, v88
	v_max_u32_e32 v79, v117, v100
	v_min_u32_e32 v100, v117, v100
	v_max_u32_e32 v117, v97, v116
	v_min_u32_e32 v116, v97, v116
	v_max_u32_e32 v97, v103, v104
	v_min_u32_e32 v104, v103, v104
	v_max_u32_e32 v103, v102, v110
	v_min_u32_e32 v110, v102, v110
	v_max_u32_e32 v102, v70, v108
	v_min_u32_e32 v108, v70, v108
	v_max_u32_e32 v70, v92, v83
	v_min_u32_e32 v83, v92, v83
	v_max_u32_e32 v92, v77, v89
	v_min_u32_e32 v89, v77, v89
	v_max_u32_e32 v77, v72, v103
	v_min_u32_e32 v103, v72, v103
	v_max_u32_e32 v72, v79, v102
	v_min_u32_e32 v102, v79, v102
	v_max_u32_e32 v79, v117, v70
	v_min_u32_e32 v70, v117, v70
	v_max_u32_e32 v117, v97, v92
	v_min_u32_e32 v92, v97, v92
	v_max_u32_e32 v97, v88, v110
	v_min_u32_e32 v110, v88, v110
	v_max_u32_e32 v88, v100, v108
	v_min_u32_e32 v108, v100, v108
	v_max_u32_e32 v100, v116, v83
	v_min_u32_e32 v83, v116, v83
	v_max_u32_e32 v116, v104, v89
	v_min_u32_e32 v89, v104, v89
	v_max_u32_e32 v104, v77, v79
	v_min_u32_e32 v79, v77, v79
	v_max_u32_e32 v77, v72, v117
	v_min_u32_e32 v117, v72, v117
	v_max_u32_e32 v72, v103, v70
	v_min_u32_e32 v70, v103, v70
	v_max_u32_e32 v103, v102, v92
	v_min_u32_e32 v92, v102, v92
	v_max_u32_e32 v102, v97, v100
	v_min_u32_e32 v100, v97, v100
	v_max_u32_e32 v97, v88, v116
	v_min_u32_e32 v116, v88, v116
	v_max_u32_e32 v88, v110, v83
	v_min_u32_e32 v83, v110, v83
	v_max_u32_e32 v110, v108, v89
	v_min_u32_e32 v89, v108, v89
	v_max_u32_e32 v108, v104, v77
	v_min_u32_e32 v77, v104, v77
	v_max_u32_e32 v104, v79, v117
	v_min_u32_e32 v117, v79, v117
	v_max_u32_e32 v79, v72, v103
	v_min_u32_e32 v103, v72, v103
	v_max_u32_e32 v72, v70, v92
	v_min_u32_e32 v92, v70, v92
	v_max_u32_e32 v70, v102, v97
	v_min_u32_e32 v97, v102, v97
	v_max_u32_e32 v102, v100, v116
	v_min_u32_e32 v116, v100, v116
	v_max_u32_e32 v100, v88, v110
	v_min_u32_e32 v110, v88, v110
	v_max_u32_e32 v88, v83, v89
	v_min_u32_e32 v89, v83, v89
	v_max_u32_e32 v83, v101, v89
	v_max_u32_e32 v101, v96, v88
	v_max_u32_e32 v96, v106, v110
	v_max_u32_e32 v106, v109, v100
	v_max_u32_e32 v109, v85, v116
	v_max_u32_e32 v85, v112, v102
	v_max_u32_e32 v112, v111, v97
	v_max_u32_e32 v111, v98, v70
	v_max_u32_e32 v98, v115, v92
	v_max_u32_e32 v115, v91, v72
	v_max_u32_e32 v91, v107, v103
	v_max_u32_e32 v107, v81, v79
	v_max_u32_e32 v81, v105, v117
; #define MFMA32(a, b, c) __builtin_amdgcn_mfma_f32_32x32x16_bf16((a), (b), (c), 0, 0, 0)
; DI int crow(int i, int hh) { return (i & 3) + 8 * (i >> 2) + 4 * hh; }
; DI void peer_top16(const u16* __restrict__ PQrow, const u16* __restrict__ SK, unsigned (&top)[16], int lr, int hh) {
;     ...
;   for (int kt = 0; kt < 4; ++kt) {
;     f32x16 acc;
; #pragma unroll
;     for (int e = 0; e < 16; ++e) acc[e] = 0.f;
; #pragma unroll
;     for (int ks = 0; ks < 8; ++ks) {
;       bf16x8 a = *(const bf16x8*)(SK + (size_t)(kt * 32 + lr) * 128 + ks * 16 + hh * 8);
;       acc = MFMA32(a, qf[ks], acc);
;     }
; #pragma unroll
;     for (int e = 0; e < 16; ++e) {
;       int kidx = kt * 32 + crow(e, hh);
;       g[kt][e] = (f2ord(acc[e]) & ~127u) | (unsigned)(127 - kidx);
;     }
;     bitonic_sort_desc<4>(g[kt]);
;   }
;   merge_top16(g[0], g[1]);
;   merge_top16(g[2], g[3]);
;   merge_top16(g[0], g[2]);
	v_max_u32_e32 v105, v90, v104
	v_max_u32_e32 v90, v114, v77
	v_max_u32_e32 v114, v86, v108
	v_max_u32_e32 v89, v83, v98
	v_min_u32_e32 v98, v83, v98
	v_max_u32_e32 v83, v101, v115
	v_min_u32_e32 v115, v101, v115
	v_max_u32_e32 v101, v96, v91
	v_min_u32_e32 v91, v96, v91
	v_max_u32_e32 v96, v106, v107
	v_min_u32_e32 v107, v106, v107
	v_max_u32_e32 v106, v109, v81
	v_min_u32_e32 v81, v109, v81
	v_max_u32_e32 v109, v85, v105
	v_min_u32_e32 v105, v85, v105
	v_max_u32_e32 v85, v112, v90
	v_min_u32_e32 v90, v112, v90
	v_max_u32_e32 v112, v111, v114
	v_min_u32_e32 v114, v111, v114
	v_max_u32_e32 v111, v89, v106
	v_min_u32_e32 v106, v89, v106
	v_max_u32_e32 v89, v83, v109
	v_min_u32_e32 v109, v83, v109
	v_max_u32_e32 v83, v101, v85
	v_min_u32_e32 v85, v101, v85
	v_max_u32_e32 v101, v96, v112
	v_min_u32_e32 v112, v96, v112
	v_max_u32_e32 v96, v98, v81
	v_min_u32_e32 v81, v98, v81
	v_max_u32_e32 v98, v115, v105
	v_min_u32_e32 v105, v115, v105
	v_max_u32_e32 v115, v91, v90
	v_min_u32_e32 v90, v91, v90
	v_max_u32_e32 v91, v107, v114
	v_min_u32_e32 v114, v107, v114
	v_max_u32_e32 v107, v111, v83
	v_min_u32_e32 v83, v111, v83
	v_max_u32_e32 v111, v89, v101
	v_min_u32_e32 v101, v89, v101
	v_max_u32_e32 v89, v106, v85
	v_min_u32_e32 v85, v106, v85
	v_max_u32_e32 v106, v109, v112
	v_min_u32_e32 v112, v109, v112
	v_max_u32_e32 v109, v96, v115
	v_min_u32_e32 v115, v96, v115
	v_max_u32_e32 v96, v98, v91
	v_min_u32_e32 v91, v98, v91
	v_max_u32_e32 v98, v81, v90
	v_min_u32_e32 v90, v81, v90
	v_max_u32_e32 v81, v105, v114
	v_min_u32_e32 v114, v105, v114
	v_max_u32_e32 v105, v107, v111
	v_min_u32_e32 v111, v107, v111
	v_max_u32_e32 v107, v83, v101
	v_min_u32_e32 v101, v83, v101
	v_max_u32_e32 v83, v89, v106
	v_min_u32_e32 v106, v89, v106
	v_max_u32_e32 v89, v85, v112
	v_min_u32_e32 v112, v85, v112
	v_max_u32_e32 v85, v109, v96
	v_min_u32_e32 v96, v109, v96
	v_max_u32_e32 v109, v115, v91
	v_min_u32_e32 v91, v115, v91
	v_max_u32_e32 v115, v98, v81
	v_min_u32_e32 v81, v98, v81
	v_max_u32_e32 v98, v90, v114
	v_min_u32_e32 v114, v90, v114
	v_mov_b32_e32 v32, v105
	v_mov_b32_e32 v33, v111
	v_mov_b32_e32 v34, v107
	v_mov_b32_e32 v35, v101
	v_mov_b32_e32 v36, v83
	v_mov_b32_e32 v37, v106
	v_mov_b32_e32 v38, v89
	v_mov_b32_e32 v39, v112
	v_mov_b32_e32 v40, v85
	v_mov_b32_e32 v41, v96
	v_mov_b32_e32 v42, v109
	v_mov_b32_e32 v43, v91
	v_mov_b32_e32 v44, v115
	v_mov_b32_e32 v45, v81
	v_mov_b32_e32 v46, v98
	v_mov_b32_e32 v47, v114
	v_sub_u32_e32 v213, 127, v245
	v_sub_u32_e32 v214, 126, v245
	v_sub_u32_e32 v215, 125, v245
	v_sub_u32_e32 v216, 124, v245
	v_sub_u32_e32 v217, 119, v245
	v_sub_u32_e32 v218, 118, v245
	v_sub_u32_e32 v219, 117, v245
	v_sub_u32_e32 v220, 116, v245
	v_sub_u32_e32 v221, 111, v245
	v_sub_u32_e32 v222, 110, v245
	v_sub_u32_e32 v223, 109, v245
	v_sub_u32_e32 v224, 108, v245
	v_sub_u32_e32 v225, 103, v245
	v_sub_u32_e32 v226, 102, v245
	v_sub_u32_e32 v227, 101, v245
	v_sub_u32_e32 v228, 100, v245
	s_waitcnt vmcnt(7)
	v_mfma_f32_32x32x16_bf16 v[128:143], v[144:147], v[176:179], 0
	s_waitcnt vmcnt(6)
	v_mfma_f32_32x32x16_bf16 v[128:143], v[148:151], v[180:183], v[128:143]
	s_waitcnt vmcnt(5)
	v_mfma_f32_32x32x16_bf16 v[128:143], v[152:155], v[184:187], v[128:143]
	s_waitcnt vmcnt(4)
	v_mfma_f32_32x32x16_bf16 v[128:143], v[156:159], v[188:191], v[128:143]
	s_waitcnt vmcnt(3)
	v_mfma_f32_32x32x16_bf16 v[128:143], v[160:163], v[192:195], v[128:143]
	s_waitcnt vmcnt(2)
	v_mfma_f32_32x32x16_bf16 v[128:143], v[164:167], v[196:199], v[128:143]
	s_waitcnt vmcnt(1)
	v_mfma_f32_32x32x16_bf16 v[128:143], v[168:171], v[200:203], v[128:143]
	s_waitcnt vmcnt(0)
	v_mfma_f32_32x32x16_bf16 v[128:143], v[172:175], v[204:207], v[128:143]
	s_add_u32 s4, s0, 106496
	s_addc_u32 s5, s1, 0
	global_load_dwordx4 v[144:147], v238, s[4:5] offset:0
	global_load_dwordx4 v[148:151], v238, s[4:5] offset:32
	global_load_dwordx4 v[152:155], v238, s[4:5] offset:64
	global_load_dwordx4 v[156:159], v238, s[4:5] offset:96
	global_load_dwordx4 v[160:163], v238, s[4:5] offset:128
	global_load_dwordx4 v[164:167], v238, s[4:5] offset:160
	global_load_dwordx4 v[168:171], v238, s[4:5] offset:192
	global_load_dwordx4 v[172:175], v238, s[4:5] offset:224
	s_nop 7
	v_ashrrev_i32_e32 v230, 31, v128
	v_or_b32_e32 v230, 0x80000000, v230
	v_xor_b32_e32 v229, v230, v128
	v_and_b32_e32 v229, 0xffffff80, v229
	v_or_b32_e32 v114, v229, v213
	v_ashrrev_i32_e32 v230, 31, v129
	v_or_b32_e32 v230, 0x80000000, v230
	v_xor_b32_e32 v229, v230, v129
	v_and_b32_e32 v229, 0xffffff80, v229
	v_or_b32_e32 v98, v229, v214
	v_ashrrev_i32_e32 v230, 31, v130
	v_or_b32_e32 v230, 0x80000000, v230
	v_xor_b32_e32 v229, v230, v130
	v_and_b32_e32 v229, 0xffffff80, v229
	v_or_b32_e32 v81, v229, v215
	v_ashrrev_i32_e32 v230, 31, v131
	v_or_b32_e32 v230, 0x80000000, v230
	v_xor_b32_e32 v229, v230, v131
	v_and_b32_e32 v229, 0xffffff80, v229
	v_or_b32_e32 v115, v229, v216
	v_ashrrev_i32_e32 v230, 31, v132
	v_or_b32_e32 v230, 0x80000000, v230
	v_xor_b32_e32 v229, v230, v132
	v_and_b32_e32 v229, 0xffffff80, v229
	v_or_b32_e32 v91, v229, v217
	v_ashrrev_i32_e32 v230, 31, v133
	v_or_b32_e32 v230, 0x80000000, v230
	v_xor_b32_e32 v229, v230, v133
	v_and_b32_e32 v229, 0xffffff80, v229
	v_or_b32_e32 v109, v229, v218
	v_ashrrev_i32_e32 v230, 31, v134
	v_or_b32_e32 v230, 0x80000000, v230
	v_xor_b32_e32 v229, v230, v134
	v_and_b32_e32 v229, 0xffffff80, v229
	v_or_b32_e32 v96, v229, v219
	v_ashrrev_i32_e32 v230, 31, v135
	v_or_b32_e32 v230, 0x80000000, v230
	v_xor_b32_e32 v229, v230, v135
	v_and_b32_e32 v229, 0xffffff80, v229
	v_or_b32_e32 v85, v229, v220
	v_ashrrev_i32_e32 v230, 31, v136
	v_or_b32_e32 v230, 0x80000000, v230
	v_xor_b32_e32 v229, v230, v136
; DI int crow(int i, int hh) { return (i & 3) + 8 * (i >> 2) + 4 * hh; }
; template <int LOGN>
; DI void bitonic_sort_desc(unsigned (&a)[1 << LOGN]) {
;   constexpr int N = 1 << LOGN;
; #pragma unroll
;   for (int ks = 1; ks <= LOGN; ++ks)
; #pragma unroll
;     ...
; #pragma unroll
;       for (int i = 0; i < N; ++i) {
;         const int k = 1 << ks, j = 1 << js, l = i ^ j;
;         if (l > i) {
;           const bool desc = ((i & k) == 0) || (ks == LOGN);
;           const unsigned x = a[i], y = a[l];
;           const unsigned hi = max(x, y), lo = min(x, y);
;           a[i] = desc ? hi : lo;
;           a[l] = desc ? lo : hi;
;         }
;       }
; DI void peer_top16(const u16* __restrict__ PQrow, const u16* __restrict__ SK, unsigned (&top)[16], int lr, int hh) {
;     ...
;     for (int e = 0; e < 16; ++e) {
;       int kidx = kt * 32 + crow(e, hh);
;       g[kt][e] = (f2ord(acc[e]) & ~127u) | (unsigned)(127 - kidx);
;     }
;     bitonic_sort_desc<4>(g[kt]);
	v_and_b32_e32 v229, 0xffffff80, v229
	v_or_b32_e32 v112, v229, v221
	v_ashrrev_i32_e32 v230, 31, v137
	v_or_b32_e32 v230, 0x80000000, v230
	v_xor_b32_e32 v229, v230, v137
	v_and_b32_e32 v229, 0xffffff80, v229
	v_or_b32_e32 v89, v229, v222
	v_ashrrev_i32_e32 v230, 31, v138
	v_or_b32_e32 v230, 0x80000000, v230
	v_xor_b32_e32 v229, v230, v138
	v_and_b32_e32 v229, 0xffffff80, v229
	v_or_b32_e32 v106, v229, v223
	v_ashrrev_i32_e32 v230, 31, v139
	v_or_b32_e32 v230, 0x80000000, v230
	v_xor_b32_e32 v229, v230, v139
	v_and_b32_e32 v229, 0xffffff80, v229
	v_or_b32_e32 v83, v229, v224
	v_ashrrev_i32_e32 v230, 31, v140
	v_or_b32_e32 v230, 0x80000000, v230
	v_xor_b32_e32 v229, v230, v140
	v_and_b32_e32 v229, 0xffffff80, v229
	v_or_b32_e32 v101, v229, v225
	v_ashrrev_i32_e32 v230, 31, v141
	v_or_b32_e32 v230, 0x80000000, v230
	v_xor_b32_e32 v229, v230, v141
	v_and_b32_e32 v229, 0xffffff80, v229
	v_or_b32_e32 v107, v229, v226
	v_ashrrev_i32_e32 v230, 31, v142
	v_or_b32_e32 v230, 0x80000000, v230
	v_xor_b32_e32 v229, v230, v142
	v_and_b32_e32 v229, 0xffffff80, v229
	v_or_b32_e32 v111, v229, v227
	v_ashrrev_i32_e32 v230, 31, v143
	v_or_b32_e32 v230, 0x80000000, v230
	v_xor_b32_e32 v229, v230, v143
	v_and_b32_e32 v229, 0xffffff80, v229
	v_or_b32_e32 v105, v229, v228
	v_subrev_u32_e32 v213, 32, v213
	v_subrev_u32_e32 v214, 32, v214
	v_subrev_u32_e32 v215, 32, v215
	v_subrev_u32_e32 v216, 32, v216
	v_subrev_u32_e32 v217, 32, v217
	v_subrev_u32_e32 v218, 32, v218
	v_subrev_u32_e32 v219, 32, v219
	v_subrev_u32_e32 v220, 32, v220
	v_subrev_u32_e32 v221, 32, v221
	v_subrev_u32_e32 v222, 32, v222
	v_subrev_u32_e32 v223, 32, v223
	v_subrev_u32_e32 v224, 32, v224
	v_subrev_u32_e32 v225, 32, v225
	v_subrev_u32_e32 v226, 32, v226
	v_subrev_u32_e32 v227, 32, v227
	v_subrev_u32_e32 v228, 32, v228
	v_max_u32_e32 v90, v114, v98
	v_min_u32_e32 v98, v114, v98
	v_min_u32_e32 v114, v81, v115
	v_max_u32_e32 v115, v81, v115
	v_max_u32_e32 v81, v91, v109
	v_min_u32_e32 v109, v91, v109
	v_min_u32_e32 v91, v96, v85
	v_max_u32_e32 v85, v96, v85
	v_max_u32_e32 v96, v112, v89
	v_min_u32_e32 v89, v112, v89
	v_min_u32_e32 v112, v106, v83
	v_max_u32_e32 v83, v106, v83
	v_max_u32_e32 v106, v101, v107
	v_min_u32_e32 v107, v101, v107
	v_min_u32_e32 v101, v111, v105
	v_max_u32_e32 v105, v111, v105
	v_max_u32_e32 v111, v90, v114
	v_min_u32_e32 v114, v90, v114
	v_max_u32_e32 v90, v98, v115
	v_min_u32_e32 v115, v98, v115
	v_min_u32_e32 v98, v81, v91
	v_max_u32_e32 v91, v81, v91
	v_min_u32_e32 v81, v109, v85
	v_max_u32_e32 v85, v109, v85
	v_max_u32_e32 v109, v96, v112
	v_min_u32_e32 v112, v96, v112
	v_max_u32_e32 v96, v89, v83
	v_min_u32_e32 v83, v89, v83
	v_min_u32_e32 v89, v106, v101
	v_max_u32_e32 v101, v106, v101
	v_min_u32_e32 v106, v107, v105
	v_max_u32_e32 v105, v107, v105
	v_max_u32_e32 v107, v111, v90
	v_min_u32_e32 v90, v111, v90
	v_max_u32_e32 v111, v114, v115
	v_min_u32_e32 v115, v114, v115
	v_min_u32_e32 v114, v98, v81
	v_max_u32_e32 v81, v98, v81
	v_min_u32_e32 v98, v91, v85
	v_max_u32_e32 v85, v91, v85
	v_max_u32_e32 v91, v109, v96
	v_min_u32_e32 v96, v109, v96
	v_max_u32_e32 v109, v112, v83
	v_min_u32_e32 v83, v112, v83
	v_min_u32_e32 v112, v89, v106
	v_max_u32_e32 v106, v89, v106
	v_min_u32_e32 v89, v101, v105
	v_max_u32_e32 v105, v101, v105
	v_max_u32_e32 v101, v107, v114
	v_min_u32_e32 v114, v107, v114
	v_max_u32_e32 v107, v90, v81
	v_min_u32_e32 v81, v90, v81
	v_max_u32_e32 v90, v111, v98
	v_min_u32_e32 v98, v111, v98
	v_max_u32_e32 v111, v115, v85
	v_min_u32_e32 v85, v115, v85
	v_min_u32_e32 v115, v91, v112
	v_max_u32_e32 v112, v91, v112
	v_min_u32_e32 v91, v96, v106
	v_max_u32_e32 v106, v96, v106
	v_min_u32_e32 v96, v109, v89
	v_max_u32_e32 v89, v109, v89
	v_min_u32_e32 v109, v83, v105
	v_max_u32_e32 v105, v83, v105
	v_max_u32_e32 v83, v101, v90
	v_min_u32_e32 v90, v101, v90
	v_max_u32_e32 v101, v107, v111
	v_min_u32_e32 v111, v107, v111
	v_max_u32_e32 v107, v114, v98
	v_min_u32_e32 v98, v114, v98
	v_max_u32_e32 v114, v81, v85
	v_min_u32_e32 v85, v81, v85
	v_min_u32_e32 v81, v115, v96
	v_max_u32_e32 v96, v115, v96
	v_min_u32_e32 v115, v91, v109
	v_max_u32_e32 v109, v91, v109
	v_min_u32_e32 v91, v112, v89
	v_max_u32_e32 v89, v112, v89
	v_min_u32_e32 v112, v106, v105
	v_max_u32_e32 v105, v106, v105
	v_max_u32_e32 v106, v83, v101
	v_min_u32_e32 v101, v83, v101
	v_max_u32_e32 v83, v90, v111
	v_min_u32_e32 v111, v90, v111
	v_max_u32_e32 v90, v107, v114
	v_min_u32_e32 v114, v107, v114
	v_max_u32_e32 v107, v98, v85
	v_min_u32_e32 v85, v98, v85
	v_min_u32_e32 v98, v81, v115
	v_max_u32_e32 v115, v81, v115
	v_min_u32_e32 v81, v96, v109
	v_max_u32_e32 v109, v96, v109
	v_min_u32_e32 v96, v91, v112
	v_max_u32_e32 v112, v91, v112
	v_min_u32_e32 v91, v89, v105
	v_max_u32_e32 v105, v89, v105
	v_max_u32_e32 v89, v106, v98
	v_min_u32_e32 v98, v106, v98
	v_max_u32_e32 v106, v101, v115
	v_min_u32_e32 v115, v101, v115
	v_max_u32_e32 v101, v83, v81
	v_min_u32_e32 v81, v83, v81
	v_max_u32_e32 v83, v111, v109
	v_min_u32_e32 v109, v111, v109
	v_max_u32_e32 v111, v90, v96
	v_min_u32_e32 v96, v90, v96
	v_max_u32_e32 v90, v114, v112
	v_min_u32_e32 v112, v114, v112
	v_max_u32_e32 v114, v107, v91
	v_min_u32_e32 v91, v107, v91
	v_max_u32_e32 v107, v85, v105
	v_min_u32_e32 v105, v85, v105
	v_max_u32_e32 v85, v89, v111
	v_min_u32_e32 v111, v89, v111
	v_max_u32_e32 v89, v106, v90
	v_min_u32_e32 v90, v106, v90
	v_max_u32_e32 v106, v101, v114
	v_min_u32_e32 v114, v101, v114
	v_max_u32_e32 v101, v83, v107
	v_min_u32_e32 v107, v83, v107
	v_max_u32_e32 v83, v98, v96
	v_min_u32_e32 v96, v98, v96
	v_max_u32_e32 v98, v115, v112
	v_min_u32_e32 v112, v115, v112
	v_max_u32_e32 v115, v81, v91
	v_min_u32_e32 v91, v81, v91
	v_max_u32_e32 v81, v109, v105
	v_min_u32_e32 v105, v109, v105
	v_max_u32_e32 v109, v85, v106
	v_min_u32_e32 v106, v85, v106
	v_max_u32_e32 v85, v89, v101
	v_min_u32_e32 v101, v89, v101
	v_max_u32_e32 v89, v111, v114
	v_min_u32_e32 v114, v111, v114
	v_max_u32_e32 v111, v90, v107
	v_min_u32_e32 v107, v90, v107
	v_max_u32_e32 v90, v83, v115
	v_min_u32_e32 v115, v83, v115
	v_max_u32_e32 v83, v98, v81
	v_min_u32_e32 v81, v98, v81
	v_max_u32_e32 v98, v96, v91
	v_min_u32_e32 v91, v96, v91
	v_max_u32_e32 v96, v112, v105
	v_min_u32_e32 v105, v112, v105
	v_max_u32_e32 v112, v109, v85
	v_min_u32_e32 v85, v109, v85
	v_max_u32_e32 v109, v106, v101
	v_min_u32_e32 v101, v106, v101
	v_max_u32_e32 v106, v89, v111
	v_min_u32_e32 v111, v89, v111
	v_max_u32_e32 v89, v114, v107
	v_min_u32_e32 v107, v114, v107
	v_max_u32_e32 v114, v90, v83
	v_min_u32_e32 v83, v90, v83
	v_max_u32_e32 v90, v115, v81
	v_min_u32_e32 v81, v115, v81
	v_max_u32_e32 v115, v98, v96
	v_min_u32_e32 v96, v98, v96
	v_max_u32_e32 v98, v91, v105
	v_min_u32_e32 v105, v91, v105
	s_waitcnt vmcnt(7)
; #define MFMA32(a, b, c) __builtin_amdgcn_mfma_f32_32x32x16_bf16((a), (b), (c), 0, 0, 0)
; DI int crow(int i, int hh) { return (i & 3) + 8 * (i >> 2) + 4 * hh; }
; template <int LOGN>
; DI void bitonic_sort_desc(unsigned (&a)[1 << LOGN]) {
;   constexpr int N = 1 << LOGN;
; #pragma unroll
;   for (int ks = 1; ks <= LOGN; ++ks)
; #pragma unroll
;     ...
; #pragma unroll
;       for (int i = 0; i < N; ++i) {
;         const int k = 1 << ks, j = 1 << js, l = i ^ j;
;         if (l > i) {
;           const bool desc = ((i & k) == 0) || (ks == LOGN);
;           const unsigned x = a[i], y = a[l];
;           const unsigned hi = max(x, y), lo = min(x, y);
;           a[i] = desc ? hi : lo;
;           a[l] = desc ? lo : hi;
;         }
;       }
; DI void peer_top16(const u16* __restrict__ PQrow, const u16* __restrict__ SK, unsigned (&top)[16], int lr, int hh) {
;     ...
;   for (int kt = 0; kt < 4; ++kt) {
;     f32x16 acc;
; #pragma unroll
;     for (int e = 0; e < 16; ++e) acc[e] = 0.f;
; #pragma unroll
;     for (int ks = 0; ks < 8; ++ks) {
;       bf16x8 a = *(const bf16x8*)(SK + (size_t)(kt * 32 + lr) * 128 + ks * 16 + hh * 8);
;       acc = MFMA32(a, qf[ks], acc);
;     }
; #pragma unroll
;     for (int e = 0; e < 16; ++e) {
;       int kidx = kt * 32 + crow(e, hh);
;       g[kt][e] = (f2ord(acc[e]) & ~127u) | (unsigned)(127 - kidx);
;     }
;     bitonic_sort_desc<4>(g[kt]);
	v_mfma_f32_32x32x16_bf16 v[128:143], v[144:147], v[176:179], 0
	s_waitcnt vmcnt(6)
	v_mfma_f32_32x32x16_bf16 v[128:143], v[148:151], v[180:183], v[128:143]
	s_waitcnt vmcnt(5)
	v_mfma_f32_32x32x16_bf16 v[128:143], v[152:155], v[184:187], v[128:143]
	s_waitcnt vmcnt(4)
	v_mfma_f32_32x32x16_bf16 v[128:143], v[156:159], v[188:191], v[128:143]
	s_waitcnt vmcnt(3)
	v_mfma_f32_32x32x16_bf16 v[128:143], v[160:163], v[192:195], v[128:143]
	s_waitcnt vmcnt(2)
	v_mfma_f32_32x32x16_bf16 v[128:143], v[164:167], v[196:199], v[128:143]
	s_waitcnt vmcnt(1)
	v_mfma_f32_32x32x16_bf16 v[128:143], v[168:171], v[200:203], v[128:143]
	s_waitcnt vmcnt(0)
	v_mfma_f32_32x32x16_bf16 v[128:143], v[172:175], v[204:207], v[128:143]
	s_add_u32 s4, s0, 114688
	s_addc_u32 s5, s1, 0
	global_load_dwordx4 v[144:147], v238, s[4:5] offset:0
	global_load_dwordx4 v[148:151], v238, s[4:5] offset:32
	global_load_dwordx4 v[152:155], v238, s[4:5] offset:64
	global_load_dwordx4 v[156:159], v238, s[4:5] offset:96
	global_load_dwordx4 v[160:163], v238, s[4:5] offset:128
	global_load_dwordx4 v[164:167], v238, s[4:5] offset:160
	global_load_dwordx4 v[168:171], v238, s[4:5] offset:192
	global_load_dwordx4 v[172:175], v238, s[4:5] offset:224
	s_nop 7
	v_ashrrev_i32_e32 v230, 31, v128
	v_or_b32_e32 v230, 0x80000000, v230
	v_xor_b32_e32 v229, v230, v128
	v_and_b32_e32 v229, 0xffffff80, v229
	v_or_b32_e32 v91, v229, v213
	v_ashrrev_i32_e32 v230, 31, v129
	v_or_b32_e32 v230, 0x80000000, v230
	v_xor_b32_e32 v229, v230, v129
	v_and_b32_e32 v229, 0xffffff80, v229
	v_or_b32_e32 v88, v229, v214
	v_ashrrev_i32_e32 v230, 31, v130
	v_or_b32_e32 v230, 0x80000000, v230
	v_xor_b32_e32 v229, v230, v130
	v_and_b32_e32 v229, 0xffffff80, v229
	v_or_b32_e32 v110, v229, v215
	v_ashrrev_i32_e32 v230, 31, v131
	v_or_b32_e32 v230, 0x80000000, v230
	v_xor_b32_e32 v229, v230, v131
	v_and_b32_e32 v229, 0xffffff80, v229
	v_or_b32_e32 v100, v229, v216
	v_ashrrev_i32_e32 v230, 31, v132
	v_or_b32_e32 v230, 0x80000000, v230
	v_xor_b32_e32 v229, v230, v132
	v_and_b32_e32 v229, 0xffffff80, v229
	v_or_b32_e32 v116, v229, v217
	v_ashrrev_i32_e32 v230, 31, v133
	v_or_b32_e32 v230, 0x80000000, v230
	v_xor_b32_e32 v229, v230, v133
	v_and_b32_e32 v229, 0xffffff80, v229
	v_or_b32_e32 v102, v229, v218
	v_ashrrev_i32_e32 v230, 31, v134
	v_or_b32_e32 v230, 0x80000000, v230
	v_xor_b32_e32 v229, v230, v134
	v_and_b32_e32 v229, 0xffffff80, v229
	v_or_b32_e32 v97, v229, v219
	v_ashrrev_i32_e32 v230, 31, v135
	v_or_b32_e32 v230, 0x80000000, v230
	v_xor_b32_e32 v229, v230, v135
	v_and_b32_e32 v229, 0xffffff80, v229
	v_or_b32_e32 v70, v229, v220
	v_ashrrev_i32_e32 v230, 31, v136
	v_or_b32_e32 v230, 0x80000000, v230
	v_xor_b32_e32 v229, v230, v136
	v_and_b32_e32 v229, 0xffffff80, v229
	v_or_b32_e32 v92, v229, v221
	v_ashrrev_i32_e32 v230, 31, v137
	v_or_b32_e32 v230, 0x80000000, v230
	v_xor_b32_e32 v229, v230, v137
	v_and_b32_e32 v229, 0xffffff80, v229
	v_or_b32_e32 v72, v229, v222
	v_ashrrev_i32_e32 v230, 31, v138
	v_or_b32_e32 v230, 0x80000000, v230
	v_xor_b32_e32 v229, v230, v138
	v_and_b32_e32 v229, 0xffffff80, v229
	v_or_b32_e32 v103, v229, v223
	v_ashrrev_i32_e32 v230, 31, v139
	v_or_b32_e32 v230, 0x80000000, v230
	v_xor_b32_e32 v229, v230, v139
	v_and_b32_e32 v229, 0xffffff80, v229
	v_or_b32_e32 v79, v229, v224
	v_ashrrev_i32_e32 v230, 31, v140
	v_or_b32_e32 v230, 0x80000000, v230
	v_xor_b32_e32 v229, v230, v140
	v_and_b32_e32 v229, 0xffffff80, v229
	v_or_b32_e32 v117, v229, v225
	v_ashrrev_i32_e32 v230, 31, v141
	v_or_b32_e32 v230, 0x80000000, v230
	v_xor_b32_e32 v229, v230, v141
	v_and_b32_e32 v229, 0xffffff80, v229
	v_or_b32_e32 v104, v229, v226
	v_ashrrev_i32_e32 v230, 31, v142
	v_or_b32_e32 v230, 0x80000000, v230
	v_xor_b32_e32 v229, v230, v142
	v_and_b32_e32 v229, 0xffffff80, v229
	v_or_b32_e32 v77, v229, v227
	v_ashrrev_i32_e32 v230, 31, v143
	v_or_b32_e32 v230, 0x80000000, v230
	v_xor_b32_e32 v229, v230, v143
	v_and_b32_e32 v229, 0xffffff80, v229
	v_or_b32_e32 v108, v229, v228
	v_subrev_u32_e32 v213, 32, v213
	v_subrev_u32_e32 v214, 32, v214
	v_subrev_u32_e32 v215, 32, v215
	v_subrev_u32_e32 v216, 32, v216
	v_subrev_u32_e32 v217, 32, v217
	v_subrev_u32_e32 v218, 32, v218
	v_subrev_u32_e32 v219, 32, v219
	v_subrev_u32_e32 v220, 32, v220
	v_subrev_u32_e32 v221, 32, v221
	v_subrev_u32_e32 v222, 32, v222
	v_subrev_u32_e32 v223, 32, v223
	v_subrev_u32_e32 v224, 32, v224
	v_subrev_u32_e32 v225, 32, v225
	v_subrev_u32_e32 v226, 32, v226
	v_subrev_u32_e32 v227, 32, v227
	v_subrev_u32_e32 v228, 32, v228
	v_max_u32_e32 v86, v91, v88
	v_min_u32_e32 v88, v91, v88
	v_min_u32_e32 v91, v110, v100
	v_max_u32_e32 v100, v110, v100
	v_max_u32_e32 v110, v116, v102
	v_min_u32_e32 v102, v116, v102
	v_min_u32_e32 v116, v97, v70
	v_max_u32_e32 v70, v97, v70
	v_max_u32_e32 v97, v92, v72
	v_min_u32_e32 v72, v92, v72
	v_min_u32_e32 v92, v103, v79
	v_max_u32_e32 v79, v103, v79
	v_max_u32_e32 v103, v117, v104
	v_min_u32_e32 v104, v117, v104
	v_min_u32_e32 v117, v77, v108
	v_max_u32_e32 v108, v77, v108
	v_max_u32_e32 v77, v86, v91
	v_min_u32_e32 v91, v86, v91
	v_max_u32_e32 v86, v88, v100
	v_min_u32_e32 v100, v88, v100
	v_min_u32_e32 v88, v110, v116
	v_max_u32_e32 v116, v110, v116
	v_min_u32_e32 v110, v102, v70
	v_max_u32_e32 v70, v102, v70
	v_max_u32_e32 v102, v97, v92
	v_min_u32_e32 v92, v97, v92
	v_max_u32_e32 v97, v72, v79
	v_min_u32_e32 v79, v72, v79
	v_min_u32_e32 v72, v103, v117
	v_max_u32_e32 v117, v103, v117
	v_min_u32_e32 v103, v104, v108
	v_max_u32_e32 v108, v104, v108
	v_max_u32_e32 v104, v77, v86
	v_min_u32_e32 v86, v77, v86
	v_max_u32_e32 v77, v91, v100
	v_min_u32_e32 v100, v91, v100
	v_min_u32_e32 v91, v88, v110
	v_max_u32_e32 v110, v88, v110
; template <int LOGN>
; DI void bitonic_sort_desc(unsigned (&a)[1 << LOGN]) {
;   constexpr int N = 1 << LOGN;
; #pragma unroll
;   for (int ks = 1; ks <= LOGN; ++ks)
; #pragma unroll
;     ...
; #pragma unroll
;       for (int i = 0; i < N; ++i) {
;         const int k = 1 << ks, j = 1 << js, l = i ^ j;
;         if (l > i) {
;           const bool desc = ((i & k) == 0) || (ks == LOGN);
;           const unsigned x = a[i], y = a[l];
;           const unsigned hi = max(x, y), lo = min(x, y);
;           a[i] = desc ? hi : lo;
;           a[l] = desc ? lo : hi;
;         }
;       }
; }
; DI void merge_top16(unsigned (&a)[16], const unsigned (&b)[16]) {
; #pragma unroll
;   for (int i = 0; i < 16; ++i) a[i] = max(a[i], b[15 - i]);
; #pragma unroll
;     ...
; #pragma unroll
;     for (int i = 0; i < 16; ++i) {
;       const int j = 1 << js, l = i ^ j;
;       if (l > i) {
;         const unsigned x = a[i], y = a[l];
;         a[i] = max(x, y);
;         a[l] = min(x, y);
;       }
;     }
; }
	v_min_u32_e32 v88, v116, v70
	v_max_u32_e32 v70, v116, v70
	v_max_u32_e32 v116, v102, v97
	v_min_u32_e32 v97, v102, v97
	v_max_u32_e32 v102, v92, v79
	v_min_u32_e32 v79, v92, v79
	v_min_u32_e32 v92, v72, v103
	v_max_u32_e32 v103, v72, v103
	v_min_u32_e32 v72, v117, v108
	v_max_u32_e32 v108, v117, v108
	v_max_u32_e32 v117, v104, v91
	v_min_u32_e32 v91, v104, v91
	v_max_u32_e32 v104, v86, v110
	v_min_u32_e32 v110, v86, v110
	v_max_u32_e32 v86, v77, v88
	v_min_u32_e32 v88, v77, v88
	v_max_u32_e32 v77, v100, v70
	v_min_u32_e32 v70, v100, v70
	v_min_u32_e32 v100, v116, v92
	v_max_u32_e32 v92, v116, v92
	v_min_u32_e32 v116, v97, v103
	v_max_u32_e32 v103, v97, v103
	v_min_u32_e32 v97, v102, v72
	v_max_u32_e32 v72, v102, v72
	v_min_u32_e32 v102, v79, v108
	v_max_u32_e32 v108, v79, v108
	v_max_u32_e32 v79, v117, v86
	v_min_u32_e32 v86, v117, v86
	v_max_u32_e32 v117, v104, v77
	v_min_u32_e32 v77, v104, v77
	v_max_u32_e32 v104, v91, v88
	v_min_u32_e32 v88, v91, v88
	v_max_u32_e32 v91, v110, v70
	v_min_u32_e32 v70, v110, v70
	v_min_u32_e32 v110, v100, v97
	v_max_u32_e32 v97, v100, v97
	v_min_u32_e32 v100, v116, v102
	v_max_u32_e32 v102, v116, v102
	v_min_u32_e32 v116, v92, v72
	v_max_u32_e32 v72, v92, v72
	v_min_u32_e32 v92, v103, v108
	v_max_u32_e32 v108, v103, v108
	v_max_u32_e32 v103, v79, v117
	v_min_u32_e32 v117, v79, v117
	v_max_u32_e32 v79, v86, v77
	v_min_u32_e32 v77, v86, v77
	v_max_u32_e32 v86, v104, v91
	v_min_u32_e32 v91, v104, v91
	v_max_u32_e32 v104, v88, v70
	v_min_u32_e32 v70, v88, v70
	v_min_u32_e32 v88, v110, v100
	v_max_u32_e32 v100, v110, v100
	v_min_u32_e32 v110, v97, v102
	v_max_u32_e32 v102, v97, v102
	v_min_u32_e32 v97, v116, v92
	v_max_u32_e32 v92, v116, v92
	v_min_u32_e32 v116, v72, v108
	v_max_u32_e32 v108, v72, v108
	v_max_u32_e32 v72, v103, v88
	v_min_u32_e32 v88, v103, v88
	v_max_u32_e32 v103, v117, v100
	v_min_u32_e32 v100, v117, v100
	v_max_u32_e32 v117, v79, v110
	v_min_u32_e32 v110, v79, v110
	v_max_u32_e32 v79, v77, v102
	v_min_u32_e32 v102, v77, v102
	v_max_u32_e32 v77, v86, v97
	v_min_u32_e32 v97, v86, v97
	v_max_u32_e32 v86, v91, v92
	v_min_u32_e32 v92, v91, v92
	v_max_u32_e32 v91, v104, v116
	v_min_u32_e32 v116, v104, v116
	v_max_u32_e32 v104, v70, v108
	v_min_u32_e32 v108, v70, v108
	v_max_u32_e32 v70, v72, v77
	v_min_u32_e32 v77, v72, v77
	v_max_u32_e32 v72, v103, v86
	v_min_u32_e32 v86, v103, v86
	v_max_u32_e32 v103, v117, v91
	v_min_u32_e32 v91, v117, v91
	v_max_u32_e32 v117, v79, v104
	v_min_u32_e32 v104, v79, v104
	v_max_u32_e32 v79, v88, v97
	v_min_u32_e32 v97, v88, v97
	v_max_u32_e32 v88, v100, v92
	v_min_u32_e32 v92, v100, v92
	v_max_u32_e32 v100, v110, v116
	v_min_u32_e32 v116, v110, v116
	v_max_u32_e32 v110, v102, v108
	v_min_u32_e32 v108, v102, v108
	v_max_u32_e32 v102, v70, v103
	v_min_u32_e32 v103, v70, v103
	v_max_u32_e32 v70, v72, v117
	v_min_u32_e32 v117, v72, v117
	v_max_u32_e32 v72, v77, v91
	v_min_u32_e32 v91, v77, v91
	v_max_u32_e32 v77, v86, v104
	v_min_u32_e32 v104, v86, v104
	v_max_u32_e32 v86, v79, v100
	v_min_u32_e32 v100, v79, v100
	v_max_u32_e32 v79, v88, v110
	v_min_u32_e32 v110, v88, v110
	v_max_u32_e32 v88, v97, v116
	v_min_u32_e32 v116, v97, v116
	v_max_u32_e32 v97, v92, v108
	v_min_u32_e32 v108, v92, v108
	v_max_u32_e32 v92, v102, v70
	v_min_u32_e32 v70, v102, v70
	v_max_u32_e32 v102, v103, v117
	v_min_u32_e32 v117, v103, v117
	v_max_u32_e32 v103, v72, v77
	v_min_u32_e32 v77, v72, v77
	v_max_u32_e32 v72, v91, v104
	v_min_u32_e32 v104, v91, v104
	v_max_u32_e32 v91, v86, v79
	v_min_u32_e32 v79, v86, v79
	v_max_u32_e32 v86, v100, v110
	v_min_u32_e32 v110, v100, v110
	v_max_u32_e32 v100, v88, v97
	v_min_u32_e32 v97, v88, v97
	v_max_u32_e32 v88, v116, v108
	v_min_u32_e32 v108, v116, v108
	v_max_u32_e32 v116, v112, v108
	v_max_u32_e32 v112, v85, v88
	v_max_u32_e32 v85, v109, v97
	v_max_u32_e32 v109, v101, v100
	v_max_u32_e32 v101, v106, v110
	v_max_u32_e32 v106, v111, v86
	v_max_u32_e32 v111, v89, v79
	v_max_u32_e32 v89, v107, v91
	v_max_u32_e32 v107, v114, v104
	v_max_u32_e32 v114, v83, v72
	v_max_u32_e32 v83, v90, v77
	v_max_u32_e32 v90, v81, v103
	v_max_u32_e32 v81, v115, v117
	v_max_u32_e32 v115, v96, v102
	v_max_u32_e32 v96, v98, v70
	v_max_u32_e32 v98, v105, v92
	v_max_u32_e32 v108, v116, v107
	v_min_u32_e32 v107, v116, v107
	v_max_u32_e32 v116, v112, v114
	v_min_u32_e32 v114, v112, v114
	v_max_u32_e32 v112, v85, v83
	v_min_u32_e32 v83, v85, v83
	v_max_u32_e32 v85, v109, v90
	v_min_u32_e32 v90, v109, v90
	v_max_u32_e32 v109, v101, v81
	v_min_u32_e32 v81, v101, v81
	v_max_u32_e32 v101, v106, v115
	v_min_u32_e32 v115, v106, v115
	v_max_u32_e32 v106, v111, v96
	v_min_u32_e32 v96, v111, v96
	v_max_u32_e32 v111, v89, v98
	v_min_u32_e32 v98, v89, v98
	v_max_u32_e32 v89, v108, v109
	v_min_u32_e32 v109, v108, v109
	v_max_u32_e32 v108, v116, v101
	v_min_u32_e32 v101, v116, v101
	v_max_u32_e32 v116, v112, v106
	v_min_u32_e32 v106, v112, v106
	v_max_u32_e32 v112, v85, v111
	v_min_u32_e32 v111, v85, v111
	v_max_u32_e32 v85, v107, v81
	v_min_u32_e32 v81, v107, v81
	v_max_u32_e32 v107, v114, v115
	v_min_u32_e32 v115, v114, v115
	v_max_u32_e32 v114, v83, v96
	v_min_u32_e32 v96, v83, v96
	v_max_u32_e32 v83, v90, v98
	v_min_u32_e32 v98, v90, v98
	v_max_u32_e32 v90, v89, v116
	v_min_u32_e32 v116, v89, v116
	v_max_u32_e32 v89, v108, v112
	v_min_u32_e32 v112, v108, v112
	v_max_u32_e32 v108, v109, v106
	v_min_u32_e32 v106, v109, v106
	v_max_u32_e32 v109, v101, v111
	v_min_u32_e32 v111, v101, v111
	v_max_u32_e32 v101, v85, v114
	v_min_u32_e32 v114, v85, v114
	v_max_u32_e32 v85, v107, v83
	v_min_u32_e32 v83, v107, v83
	v_max_u32_e32 v107, v81, v96
	v_min_u32_e32 v96, v81, v96
	v_max_u32_e32 v81, v115, v98
	v_min_u32_e32 v98, v115, v98
	v_max_u32_e32 v115, v90, v89
	v_min_u32_e32 v89, v90, v89
	v_max_u32_e32 v90, v116, v112
	v_min_u32_e32 v112, v116, v112
	v_max_u32_e32 v116, v108, v109
	v_min_u32_e32 v109, v108, v109
	v_max_u32_e32 v108, v106, v111
	v_min_u32_e32 v111, v106, v111
	v_max_u32_e32 v106, v101, v85
	v_min_u32_e32 v85, v101, v85
	v_max_u32_e32 v101, v114, v83
	v_min_u32_e32 v83, v114, v83
	v_max_u32_e32 v114, v107, v81
	v_min_u32_e32 v81, v107, v81
	v_max_u32_e32 v107, v96, v98
	v_min_u32_e32 v98, v96, v98
	s_waitcnt vmcnt(7)
; #define MFMA32(a, b, c) __builtin_amdgcn_mfma_f32_32x32x16_bf16((a), (b), (c), 0, 0, 0)
; DI int crow(int i, int hh) { return (i & 3) + 8 * (i >> 2) + 4 * hh; }
; template <int LOGN>
; DI void bitonic_sort_desc(unsigned (&a)[1 << LOGN]) {
;   constexpr int N = 1 << LOGN;
; #pragma unroll
;   for (int ks = 1; ks <= LOGN; ++ks)
; #pragma unroll
;     ...
; #pragma unroll
;       for (int i = 0; i < N; ++i) {
;         const int k = 1 << ks, j = 1 << js, l = i ^ j;
;         if (l > i) {
;           const bool desc = ((i & k) == 0) || (ks == LOGN);
;           const unsigned x = a[i], y = a[l];
;           const unsigned hi = max(x, y), lo = min(x, y);
;           a[i] = desc ? hi : lo;
;           a[l] = desc ? lo : hi;
;         }
;       }
; DI void peer_top16(const u16* __restrict__ PQrow, const u16* __restrict__ SK, unsigned (&top)[16], int lr, int hh) {
;     ...
;   for (int kt = 0; kt < 4; ++kt) {
;     f32x16 acc;
; #pragma unroll
;     for (int e = 0; e < 16; ++e) acc[e] = 0.f;
; #pragma unroll
;     for (int ks = 0; ks < 8; ++ks) {
;       bf16x8 a = *(const bf16x8*)(SK + (size_t)(kt * 32 + lr) * 128 + ks * 16 + hh * 8);
;       acc = MFMA32(a, qf[ks], acc);
;     }
; #pragma unroll
;     for (int e = 0; e < 16; ++e) {
;       int kidx = kt * 32 + crow(e, hh);
;       g[kt][e] = (f2ord(acc[e]) & ~127u) | (unsigned)(127 - kidx);
;     }
;     bitonic_sort_desc<4>(g[kt]);
	v_mfma_f32_32x32x16_bf16 v[128:143], v[144:147], v[176:179], 0
	s_waitcnt vmcnt(6)
	v_mfma_f32_32x32x16_bf16 v[128:143], v[148:151], v[180:183], v[128:143]
	s_waitcnt vmcnt(5)
	v_mfma_f32_32x32x16_bf16 v[128:143], v[152:155], v[184:187], v[128:143]
	s_waitcnt vmcnt(4)
	v_mfma_f32_32x32x16_bf16 v[128:143], v[156:159], v[188:191], v[128:143]
	s_waitcnt vmcnt(3)
	v_mfma_f32_32x32x16_bf16 v[128:143], v[160:163], v[192:195], v[128:143]
	s_waitcnt vmcnt(2)
	v_mfma_f32_32x32x16_bf16 v[128:143], v[164:167], v[196:199], v[128:143]
	s_waitcnt vmcnt(1)
	v_mfma_f32_32x32x16_bf16 v[128:143], v[168:171], v[200:203], v[128:143]
	s_waitcnt vmcnt(0)
	v_mfma_f32_32x32x16_bf16 v[128:143], v[172:175], v[204:207], v[128:143]
	s_add_u32 s4, s0, 122880
	s_addc_u32 s5, s1, 0
	global_load_dwordx4 v[144:147], v238, s[4:5] offset:0
	global_load_dwordx4 v[148:151], v238, s[4:5] offset:32
	global_load_dwordx4 v[152:155], v238, s[4:5] offset:64
	global_load_dwordx4 v[156:159], v238, s[4:5] offset:96
	global_load_dwordx4 v[160:163], v238, s[4:5] offset:128
	global_load_dwordx4 v[164:167], v238, s[4:5] offset:160
	global_load_dwordx4 v[168:171], v238, s[4:5] offset:192
	global_load_dwordx4 v[172:175], v238, s[4:5] offset:224
	s_nop 7
	v_ashrrev_i32_e32 v230, 31, v128
	v_or_b32_e32 v230, 0x80000000, v230
	v_xor_b32_e32 v229, v230, v128
	v_and_b32_e32 v229, 0xffffff80, v229
	v_or_b32_e32 v96, v229, v213
	v_ashrrev_i32_e32 v230, 31, v129
	v_or_b32_e32 v230, 0x80000000, v230
	v_xor_b32_e32 v229, v230, v129
	v_and_b32_e32 v229, 0xffffff80, v229
	v_or_b32_e32 v88, v229, v214
	v_ashrrev_i32_e32 v230, 31, v130
	v_or_b32_e32 v230, 0x80000000, v230
	v_xor_b32_e32 v229, v230, v130
	v_and_b32_e32 v229, 0xffffff80, v229
	v_or_b32_e32 v97, v229, v215
	v_ashrrev_i32_e32 v230, 31, v131
	v_or_b32_e32 v230, 0x80000000, v230
	v_xor_b32_e32 v229, v230, v131
	v_and_b32_e32 v229, 0xffffff80, v229
	v_or_b32_e32 v100, v229, v216
	v_ashrrev_i32_e32 v230, 31, v132
	v_or_b32_e32 v230, 0x80000000, v230
	v_xor_b32_e32 v229, v230, v132
	v_and_b32_e32 v229, 0xffffff80, v229
	v_or_b32_e32 v110, v229, v217
	v_ashrrev_i32_e32 v230, 31, v133
	v_or_b32_e32 v230, 0x80000000, v230
	v_xor_b32_e32 v229, v230, v133
	v_and_b32_e32 v229, 0xffffff80, v229
	v_or_b32_e32 v86, v229, v218
	v_ashrrev_i32_e32 v230, 31, v134
	v_or_b32_e32 v230, 0x80000000, v230
	v_xor_b32_e32 v229, v230, v134
	v_and_b32_e32 v229, 0xffffff80, v229
	v_or_b32_e32 v79, v229, v219
	v_ashrrev_i32_e32 v230, 31, v135
	v_or_b32_e32 v230, 0x80000000, v230
	v_xor_b32_e32 v229, v230, v135
	v_and_b32_e32 v229, 0xffffff80, v229
	v_or_b32_e32 v91, v229, v220
	v_ashrrev_i32_e32 v230, 31, v136
	v_or_b32_e32 v230, 0x80000000, v230
	v_xor_b32_e32 v229, v230, v136
	v_and_b32_e32 v229, 0xffffff80, v229
	v_or_b32_e32 v104, v229, v221
	v_ashrrev_i32_e32 v230, 31, v137
	v_or_b32_e32 v230, 0x80000000, v230
	v_xor_b32_e32 v229, v230, v137
	v_and_b32_e32 v229, 0xffffff80, v229
	v_or_b32_e32 v72, v229, v222
	v_ashrrev_i32_e32 v230, 31, v138
	v_or_b32_e32 v230, 0x80000000, v230
	v_xor_b32_e32 v229, v230, v138
	v_and_b32_e32 v229, 0xffffff80, v229
	v_or_b32_e32 v77, v229, v223
	v_ashrrev_i32_e32 v230, 31, v139
	v_or_b32_e32 v230, 0x80000000, v230
	v_xor_b32_e32 v229, v230, v139
	v_and_b32_e32 v229, 0xffffff80, v229
	v_or_b32_e32 v103, v229, v224
	v_ashrrev_i32_e32 v230, 31, v140
	v_or_b32_e32 v230, 0x80000000, v230
	v_xor_b32_e32 v229, v230, v140
	v_and_b32_e32 v229, 0xffffff80, v229
	v_or_b32_e32 v117, v229, v225
	v_ashrrev_i32_e32 v230, 31, v141
	v_or_b32_e32 v230, 0x80000000, v230
	v_xor_b32_e32 v229, v230, v141
	v_and_b32_e32 v229, 0xffffff80, v229
	v_or_b32_e32 v102, v229, v226
	v_ashrrev_i32_e32 v230, 31, v142
	v_or_b32_e32 v230, 0x80000000, v230
	v_xor_b32_e32 v229, v230, v142
	v_and_b32_e32 v229, 0xffffff80, v229
	v_or_b32_e32 v70, v229, v227
	v_ashrrev_i32_e32 v230, 31, v143
	v_or_b32_e32 v230, 0x80000000, v230
	v_xor_b32_e32 v229, v230, v143
	v_and_b32_e32 v229, 0xffffff80, v229
	v_or_b32_e32 v92, v229, v228
	v_subrev_u32_e32 v213, 32, v213
	v_subrev_u32_e32 v214, 32, v214
	v_subrev_u32_e32 v215, 32, v215
	v_subrev_u32_e32 v216, 32, v216
	v_subrev_u32_e32 v217, 32, v217
	v_subrev_u32_e32 v218, 32, v218
	v_subrev_u32_e32 v219, 32, v219
	v_subrev_u32_e32 v220, 32, v220
	v_subrev_u32_e32 v221, 32, v221
	v_subrev_u32_e32 v222, 32, v222
	v_subrev_u32_e32 v223, 32, v223
	v_subrev_u32_e32 v224, 32, v224
	v_subrev_u32_e32 v225, 32, v225
	v_subrev_u32_e32 v226, 32, v226
	v_subrev_u32_e32 v227, 32, v227
	v_subrev_u32_e32 v228, 32, v228
	v_max_u32_e32 v105, v96, v88
	v_min_u32_e32 v88, v96, v88
	v_min_u32_e32 v96, v97, v100
	v_max_u32_e32 v100, v97, v100
	v_max_u32_e32 v97, v110, v86
	v_min_u32_e32 v86, v110, v86
	v_min_u32_e32 v110, v79, v91
	v_max_u32_e32 v91, v79, v91
	v_max_u32_e32 v79, v104, v72
	v_min_u32_e32 v72, v104, v72
	v_min_u32_e32 v104, v77, v103
	v_max_u32_e32 v103, v77, v103
	v_max_u32_e32 v77, v117, v102
	v_min_u32_e32 v102, v117, v102
	v_min_u32_e32 v117, v70, v92
	v_max_u32_e32 v92, v70, v92
	v_max_u32_e32 v70, v105, v96
	v_min_u32_e32 v96, v105, v96
	v_max_u32_e32 v105, v88, v100
	v_min_u32_e32 v100, v88, v100
	v_min_u32_e32 v88, v97, v110
	v_max_u32_e32 v110, v97, v110
	v_min_u32_e32 v97, v86, v91
	v_max_u32_e32 v91, v86, v91
	v_max_u32_e32 v86, v79, v104
	v_min_u32_e32 v104, v79, v104
	v_max_u32_e32 v79, v72, v103
	v_min_u32_e32 v103, v72, v103
	v_min_u32_e32 v72, v77, v117
	v_max_u32_e32 v117, v77, v117
	v_min_u32_e32 v77, v102, v92
	v_max_u32_e32 v92, v102, v92
	v_max_u32_e32 v102, v70, v105
	v_min_u32_e32 v105, v70, v105
	v_max_u32_e32 v70, v96, v100
	v_min_u32_e32 v100, v96, v100
	v_min_u32_e32 v96, v88, v97
	v_max_u32_e32 v97, v88, v97
; #define MFMA32(a, b, c) __builtin_amdgcn_mfma_f32_32x32x16_bf16((a), (b), (c), 0, 0, 0)
; template <int LOGN>
; DI void bitonic_sort_desc(unsigned (&a)[1 << LOGN]) {
;   constexpr int N = 1 << LOGN;
; #pragma unroll
;   for (int ks = 1; ks <= LOGN; ++ks)
; #pragma unroll
;     ...
; #pragma unroll
;       for (int i = 0; i < N; ++i) {
;         const int k = 1 << ks, j = 1 << js, l = i ^ j;
;         if (l > i) {
;           const bool desc = ((i & k) == 0) || (ks == LOGN);
;           const unsigned x = a[i], y = a[l];
;           const unsigned hi = max(x, y), lo = min(x, y);
;           a[i] = desc ? hi : lo;
;           a[l] = desc ? lo : hi;
;         }
;       }
; DI void peer_top16(const u16* __restrict__ PQrow, const u16* __restrict__ SK, unsigned (&top)[16], int lr, int hh) {
;     ...
; #pragma unroll
;     for (int ks = 0; ks < 8; ++ks) {
;       bf16x8 a = *(const bf16x8*)(SK + (size_t)(kt * 32 + lr) * 128 + ks * 16 + hh * 8);
;       acc = MFMA32(a, qf[ks], acc);
;     }
	v_min_u32_e32 v88, v110, v91
	v_max_u32_e32 v91, v110, v91
	v_max_u32_e32 v110, v86, v79
	v_min_u32_e32 v79, v86, v79
	v_max_u32_e32 v86, v104, v103
	v_min_u32_e32 v103, v104, v103
	v_min_u32_e32 v104, v72, v77
	v_max_u32_e32 v77, v72, v77
	v_min_u32_e32 v72, v117, v92
	v_max_u32_e32 v92, v117, v92
	v_max_u32_e32 v117, v102, v96
	v_min_u32_e32 v96, v102, v96
	v_max_u32_e32 v102, v105, v97
	v_min_u32_e32 v97, v105, v97
	v_max_u32_e32 v105, v70, v88
	v_min_u32_e32 v88, v70, v88
	v_max_u32_e32 v70, v100, v91
	v_min_u32_e32 v91, v100, v91
	v_min_u32_e32 v100, v110, v104
	v_max_u32_e32 v104, v110, v104
	v_min_u32_e32 v110, v79, v77
	v_max_u32_e32 v77, v79, v77
	v_min_u32_e32 v79, v86, v72
	v_max_u32_e32 v72, v86, v72
	v_min_u32_e32 v86, v103, v92
	v_max_u32_e32 v92, v103, v92
	v_max_u32_e32 v103, v117, v105
	v_min_u32_e32 v105, v117, v105
	v_max_u32_e32 v117, v102, v70
	v_min_u32_e32 v70, v102, v70
	v_max_u32_e32 v102, v96, v88
	v_min_u32_e32 v88, v96, v88
	v_max_u32_e32 v96, v97, v91
	v_min_u32_e32 v91, v97, v91
	v_min_u32_e32 v97, v100, v79
	v_max_u32_e32 v79, v100, v79
	v_min_u32_e32 v100, v110, v86
	v_max_u32_e32 v86, v110, v86
	v_min_u32_e32 v110, v104, v72
	v_max_u32_e32 v72, v104, v72
	v_min_u32_e32 v104, v77, v92
	v_max_u32_e32 v92, v77, v92
	v_max_u32_e32 v77, v103, v117
	v_min_u32_e32 v117, v103, v117
	v_max_u32_e32 v103, v105, v70
	v_min_u32_e32 v70, v105, v70
	v_max_u32_e32 v105, v102, v96
	v_min_u32_e32 v96, v102, v96
	v_max_u32_e32 v102, v88, v91
	v_min_u32_e32 v91, v88, v91
	v_min_u32_e32 v88, v97, v100
	v_max_u32_e32 v100, v97, v100
	v_min_u32_e32 v97, v79, v86
	v_max_u32_e32 v86, v79, v86
	v_min_u32_e32 v79, v110, v104
	v_max_u32_e32 v104, v110, v104
	v_min_u32_e32 v110, v72, v92
	v_max_u32_e32 v92, v72, v92
	v_max_u32_e32 v72, v77, v88
	v_min_u32_e32 v88, v77, v88
	v_max_u32_e32 v77, v117, v100
	v_min_u32_e32 v100, v117, v100
	v_max_u32_e32 v117, v103, v97
	v_min_u32_e32 v97, v103, v97
	v_max_u32_e32 v103, v70, v86
	v_min_u32_e32 v86, v70, v86
	v_max_u32_e32 v70, v105, v79
	v_min_u32_e32 v79, v105, v79
	v_max_u32_e32 v105, v96, v104
	v_min_u32_e32 v104, v96, v104
	v_max_u32_e32 v96, v102, v110
	v_min_u32_e32 v110, v102, v110
	v_max_u32_e32 v102, v91, v92
	v_min_u32_e32 v92, v91, v92
	v_max_u32_e32 v91, v72, v70
	v_min_u32_e32 v70, v72, v70
	v_max_u32_e32 v72, v77, v105
	v_min_u32_e32 v105, v77, v105
	v_max_u32_e32 v77, v117, v96
	v_min_u32_e32 v96, v117, v96
	v_max_u32_e32 v117, v103, v102
	v_min_u32_e32 v102, v103, v102
	v_max_u32_e32 v103, v88, v79
	v_min_u32_e32 v79, v88, v79
	v_max_u32_e32 v88, v100, v104
	v_min_u32_e32 v104, v100, v104
	v_max_u32_e32 v100, v97, v110
	v_min_u32_e32 v110, v97, v110
	v_max_u32_e32 v97, v86, v92
	v_min_u32_e32 v92, v86, v92
	v_max_u32_e32 v86, v91, v77
	v_min_u32_e32 v77, v91, v77
	v_max_u32_e32 v91, v72, v117
	v_min_u32_e32 v117, v72, v117
	v_max_u32_e32 v72, v70, v96
	v_min_u32_e32 v96, v70, v96
	v_max_u32_e32 v70, v105, v102
	v_min_u32_e32 v102, v105, v102
	v_max_u32_e32 v105, v103, v100
	v_min_u32_e32 v100, v103, v100
	v_max_u32_e32 v103, v88, v97
	v_min_u32_e32 v97, v88, v97
	v_max_u32_e32 v88, v79, v110
	v_min_u32_e32 v110, v79, v110
	v_max_u32_e32 v79, v104, v92
	v_min_u32_e32 v92, v104, v92
	v_max_u32_e32 v104, v86, v91
	v_min_u32_e32 v91, v86, v91
	v_max_u32_e32 v86, v77, v117
	v_min_u32_e32 v117, v77, v117
	v_max_u32_e32 v77, v72, v70
	v_min_u32_e32 v70, v72, v70
	v_max_u32_e32 v72, v96, v102
	v_min_u32_e32 v102, v96, v102
	v_max_u32_e32 v96, v105, v103
	v_min_u32_e32 v103, v105, v103
	v_max_u32_e32 v105, v100, v97
	v_min_u32_e32 v97, v100, v97
	v_max_u32_e32 v100, v88, v79
	v_min_u32_e32 v79, v88, v79
	v_max_u32_e32 v88, v110, v92
	v_min_u32_e32 v92, v110, v92
	s_waitcnt vmcnt(7)
	v_mfma_f32_32x32x16_bf16 v[128:143], v[144:147], v[176:179], 0
	s_waitcnt vmcnt(6)
	v_mfma_f32_32x32x16_bf16 v[128:143], v[148:151], v[180:183], v[128:143]
	s_waitcnt vmcnt(5)
	v_mfma_f32_32x32x16_bf16 v[128:143], v[152:155], v[184:187], v[128:143]
	s_waitcnt vmcnt(4)
	v_mfma_f32_32x32x16_bf16 v[128:143], v[156:159], v[188:191], v[128:143]
	s_waitcnt vmcnt(3)
	v_mfma_f32_32x32x16_bf16 v[128:143], v[160:163], v[192:195], v[128:143]
	s_waitcnt vmcnt(2)
	v_mfma_f32_32x32x16_bf16 v[128:143], v[164:167], v[196:199], v[128:143]
	s_waitcnt vmcnt(1)
	v_mfma_f32_32x32x16_bf16 v[128:143], v[168:171], v[200:203], v[128:143]
	s_waitcnt vmcnt(0)
; #define MFMA32(a, b, c) __builtin_amdgcn_mfma_f32_32x32x16_bf16((a), (b), (c), 0, 0, 0)
; DI int crow(int i, int hh) { return (i & 3) + 8 * (i >> 2) + 4 * hh; }
; template <int LOGN>
; DI void bitonic_sort_desc(unsigned (&a)[1 << LOGN]) {
;   constexpr int N = 1 << LOGN;
; #pragma unroll
;   for (int ks = 1; ks <= LOGN; ++ks)
; #pragma unroll
;     ...
; #pragma unroll
;       for (int i = 0; i < N; ++i) {
;         const int k = 1 << ks, j = 1 << js, l = i ^ j;
;         if (l > i) {
;           const bool desc = ((i & k) == 0) || (ks == LOGN);
;           const unsigned x = a[i], y = a[l];
;           const unsigned hi = max(x, y), lo = min(x, y);
;           a[i] = desc ? hi : lo;
;           a[l] = desc ? lo : hi;
;         }
;       }
; DI void peer_top16(const u16* __restrict__ PQrow, const u16* __restrict__ SK, unsigned (&top)[16], int lr, int hh) {
;     ...
;   for (int kt = 0; kt < 4; ++kt) {
;     f32x16 acc;
; #pragma unroll
;     for (int e = 0; e < 16; ++e) acc[e] = 0.f;
; #pragma unroll
;     for (int ks = 0; ks < 8; ++ks) {
;       bf16x8 a = *(const bf16x8*)(SK + (size_t)(kt * 32 + lr) * 128 + ks * 16 + hh * 8);
;       acc = MFMA32(a, qf[ks], acc);
;     }
; #pragma unroll
;     for (int e = 0; e < 16; ++e) {
;       int kidx = kt * 32 + crow(e, hh);
;       g[kt][e] = (f2ord(acc[e]) & ~127u) | (unsigned)(127 - kidx);
;     }
;     bitonic_sort_desc<4>(g[kt]);
	v_mfma_f32_32x32x16_bf16 v[128:143], v[172:175], v[204:207], v[128:143]
	s_nop 7
	v_ashrrev_i32_e32 v230, 31, v128
	v_or_b32_e32 v230, 0x80000000, v230
	v_xor_b32_e32 v229, v230, v128
	v_and_b32_e32 v229, 0xffffff80, v229
	v_or_b32_e32 v110, v229, v213
	v_ashrrev_i32_e32 v230, 31, v129
	v_or_b32_e32 v230, 0x80000000, v230
	v_xor_b32_e32 v229, v230, v129
	v_and_b32_e32 v229, 0xffffff80, v229
	v_or_b32_e32 v84, v229, v214
	v_ashrrev_i32_e32 v230, 31, v130
	v_or_b32_e32 v230, 0x80000000, v230
	v_xor_b32_e32 v229, v230, v130
	v_and_b32_e32 v229, 0xffffff80, v229
	v_or_b32_e32 v75, v229, v215
	v_ashrrev_i32_e32 v230, 31, v131
	v_or_b32_e32 v230, 0x80000000, v230
	v_xor_b32_e32 v229, v230, v131
	v_and_b32_e32 v229, 0xffffff80, v229
	v_or_b32_e32 v82, v229, v216
	v_ashrrev_i32_e32 v230, 31, v132
	v_or_b32_e32 v230, 0x80000000, v230
	v_xor_b32_e32 v229, v230, v132
	v_and_b32_e32 v229, 0xffffff80, v229
	v_or_b32_e32 v74, v229, v217
	v_ashrrev_i32_e32 v230, 31, v133
	v_or_b32_e32 v230, 0x80000000, v230
	v_xor_b32_e32 v229, v230, v133
	v_and_b32_e32 v229, 0xffffff80, v229
	v_or_b32_e32 v94, v229, v218
	v_ashrrev_i32_e32 v230, 31, v134
	v_or_b32_e32 v230, 0x80000000, v230
	v_xor_b32_e32 v229, v230, v134
	v_and_b32_e32 v229, 0xffffff80, v229
	v_or_b32_e32 v71, v229, v219
	v_ashrrev_i32_e32 v230, 31, v135
	v_or_b32_e32 v230, 0x80000000, v230
	v_xor_b32_e32 v229, v230, v135
	v_and_b32_e32 v229, 0xffffff80, v229
	v_or_b32_e32 v113, v229, v220
	v_ashrrev_i32_e32 v230, 31, v136
	v_or_b32_e32 v230, 0x80000000, v230
	v_xor_b32_e32 v229, v230, v136
	v_and_b32_e32 v229, 0xffffff80, v229
	v_or_b32_e32 v69, v229, v221
	v_ashrrev_i32_e32 v230, 31, v137
	v_or_b32_e32 v230, 0x80000000, v230
	v_xor_b32_e32 v229, v230, v137
	v_and_b32_e32 v229, 0xffffff80, v229
	v_or_b32_e32 v76, v229, v222
	v_ashrrev_i32_e32 v230, 31, v138
	v_or_b32_e32 v230, 0x80000000, v230
	v_xor_b32_e32 v229, v230, v138
	v_and_b32_e32 v229, 0xffffff80, v229
	v_or_b32_e32 v99, v229, v223
	v_ashrrev_i32_e32 v230, 31, v139
	v_or_b32_e32 v230, 0x80000000, v230
	v_xor_b32_e32 v229, v230, v139
	v_and_b32_e32 v229, 0xffffff80, v229
	v_or_b32_e32 v78, v229, v224
	v_ashrrev_i32_e32 v230, 31, v140
	v_or_b32_e32 v230, 0x80000000, v230
	v_xor_b32_e32 v229, v230, v140
	v_and_b32_e32 v229, 0xffffff80, v229
	v_or_b32_e32 v73, v229, v225
	v_ashrrev_i32_e32 v230, 31, v141
	v_or_b32_e32 v230, 0x80000000, v230
	v_xor_b32_e32 v229, v230, v141
	v_and_b32_e32 v229, 0xffffff80, v229
	v_or_b32_e32 v93, v229, v226
	v_ashrrev_i32_e32 v230, 31, v142
	v_or_b32_e32 v230, 0x80000000, v230
	v_xor_b32_e32 v229, v230, v142
	v_and_b32_e32 v229, 0xffffff80, v229
	v_or_b32_e32 v95, v229, v227
	v_ashrrev_i32_e32 v230, 31, v143
	v_or_b32_e32 v230, 0x80000000, v230
	v_xor_b32_e32 v229, v230, v143
	v_and_b32_e32 v229, 0xffffff80, v229
	v_or_b32_e32 v80, v229, v228
	v_max_u32_e32 v87, v110, v84
	v_min_u32_e32 v84, v110, v84
	v_min_u32_e32 v110, v75, v82
	v_max_u32_e32 v82, v75, v82
	v_max_u32_e32 v75, v74, v94
	v_min_u32_e32 v94, v74, v94
	v_min_u32_e32 v74, v71, v113
	v_max_u32_e32 v113, v71, v113
	v_max_u32_e32 v71, v69, v76
	v_min_u32_e32 v76, v69, v76
	v_min_u32_e32 v69, v99, v78
	v_max_u32_e32 v78, v99, v78
	v_max_u32_e32 v99, v73, v93
	v_min_u32_e32 v93, v73, v93
	v_min_u32_e32 v73, v95, v80
	v_max_u32_e32 v80, v95, v80
	v_max_u32_e32 v95, v87, v110
	v_min_u32_e32 v110, v87, v110
	v_max_u32_e32 v87, v84, v82
	v_min_u32_e32 v82, v84, v82
	v_min_u32_e32 v84, v75, v74
	v_max_u32_e32 v74, v75, v74
	v_min_u32_e32 v75, v94, v113
	v_max_u32_e32 v113, v94, v113
	v_max_u32_e32 v94, v71, v69
	v_min_u32_e32 v69, v71, v69
	v_max_u32_e32 v71, v76, v78
	v_min_u32_e32 v78, v76, v78
	v_min_u32_e32 v76, v99, v73
	v_max_u32_e32 v73, v99, v73
	v_min_u32_e32 v99, v93, v80
	v_max_u32_e32 v80, v93, v80
	v_max_u32_e32 v93, v95, v87
	v_min_u32_e32 v87, v95, v87
	v_max_u32_e32 v95, v110, v82
	v_min_u32_e32 v82, v110, v82
	v_min_u32_e32 v110, v84, v75
	v_max_u32_e32 v75, v84, v75
	v_min_u32_e32 v84, v74, v113
	v_max_u32_e32 v113, v74, v113
	v_max_u32_e32 v74, v94, v71
	v_min_u32_e32 v71, v94, v71
	v_max_u32_e32 v94, v69, v78
	v_min_u32_e32 v78, v69, v78
	v_min_u32_e32 v69, v76, v99
	v_max_u32_e32 v99, v76, v99
	v_min_u32_e32 v76, v73, v80
	v_max_u32_e32 v80, v73, v80
	v_max_u32_e32 v73, v93, v110
	v_min_u32_e32 v110, v93, v110
	v_max_u32_e32 v93, v87, v75
	v_min_u32_e32 v75, v87, v75
	v_max_u32_e32 v87, v95, v84
	v_min_u32_e32 v84, v95, v84
	v_max_u32_e32 v95, v82, v113
	v_min_u32_e32 v113, v82, v113
	v_min_u32_e32 v82, v74, v69
	v_max_u32_e32 v69, v74, v69
	v_min_u32_e32 v74, v71, v99
	v_max_u32_e32 v99, v71, v99
	v_min_u32_e32 v71, v94, v76
	v_max_u32_e32 v76, v94, v76
	v_min_u32_e32 v94, v78, v80
	v_max_u32_e32 v80, v78, v80
	v_max_u32_e32 v78, v73, v87
	v_min_u32_e32 v87, v73, v87
	v_max_u32_e32 v73, v93, v95
	v_min_u32_e32 v95, v93, v95
	v_max_u32_e32 v93, v110, v84
	v_min_u32_e32 v84, v110, v84
	v_max_u32_e32 v110, v75, v113
	v_min_u32_e32 v113, v75, v113
	v_min_u32_e32 v75, v82, v71
	v_max_u32_e32 v71, v82, v71
	v_min_u32_e32 v82, v74, v94
	v_max_u32_e32 v94, v74, v94
	v_min_u32_e32 v74, v69, v76
	v_max_u32_e32 v76, v69, v76
	v_min_u32_e32 v69, v99, v80
	v_max_u32_e32 v80, v99, v80
	v_max_u32_e32 v99, v78, v73
	v_min_u32_e32 v73, v78, v73
	v_max_u32_e32 v78, v87, v95
	v_min_u32_e32 v95, v87, v95
	v_max_u32_e32 v87, v93, v110
	v_min_u32_e32 v110, v93, v110
	v_max_u32_e32 v93, v84, v113
	v_min_u32_e32 v113, v84, v113
	v_min_u32_e32 v84, v75, v82
	v_max_u32_e32 v82, v75, v82
	v_min_u32_e32 v75, v71, v94
	v_max_u32_e32 v94, v71, v94
	v_min_u32_e32 v71, v74, v69
	v_max_u32_e32 v69, v74, v69
	v_min_u32_e32 v74, v76, v80
	v_max_u32_e32 v80, v76, v80
; template <int LOGN>
; DI void bitonic_sort_desc(unsigned (&a)[1 << LOGN]) {
;   constexpr int N = 1 << LOGN;
; #pragma unroll
;   for (int ks = 1; ks <= LOGN; ++ks)
; #pragma unroll
;     ...
; #pragma unroll
;       for (int i = 0; i < N; ++i) {
;         const int k = 1 << ks, j = 1 << js, l = i ^ j;
;         if (l > i) {
;           const bool desc = ((i & k) == 0) || (ks == LOGN);
;           const unsigned x = a[i], y = a[l];
;           const unsigned hi = max(x, y), lo = min(x, y);
;           a[i] = desc ? hi : lo;
;           a[l] = desc ? lo : hi;
;         }
;       }
; }
; DI void merge_top16(unsigned (&a)[16], const unsigned (&b)[16]) {
; #pragma unroll
;   for (int i = 0; i < 16; ++i) a[i] = max(a[i], b[15 - i]);
; #pragma unroll
;     ...
; #pragma unroll
;     for (int i = 0; i < 16; ++i) {
;       const int j = 1 << js, l = i ^ j;
;       if (l > i) {
;         const unsigned x = a[i], y = a[l];
;         a[i] = max(x, y);
;         a[l] = min(x, y);
;       }
;     }
; }
	v_max_u32_e32 v76, v99, v84
	v_min_u32_e32 v84, v99, v84
	v_max_u32_e32 v99, v73, v82
	v_min_u32_e32 v82, v73, v82
	v_max_u32_e32 v73, v78, v75
	v_min_u32_e32 v75, v78, v75
	v_max_u32_e32 v78, v95, v94
	v_min_u32_e32 v94, v95, v94
	v_max_u32_e32 v95, v87, v71
	v_min_u32_e32 v71, v87, v71
	v_max_u32_e32 v87, v110, v69
	v_min_u32_e32 v69, v110, v69
	v_max_u32_e32 v110, v93, v74
	v_min_u32_e32 v74, v93, v74
	v_max_u32_e32 v93, v113, v80
	v_min_u32_e32 v80, v113, v80
	v_max_u32_e32 v113, v76, v95
	v_min_u32_e32 v95, v76, v95
	v_max_u32_e32 v76, v99, v87
	v_min_u32_e32 v87, v99, v87
	v_max_u32_e32 v99, v73, v110
	v_min_u32_e32 v110, v73, v110
	v_max_u32_e32 v73, v78, v93
	v_min_u32_e32 v93, v78, v93
	v_max_u32_e32 v78, v84, v71
	v_min_u32_e32 v71, v84, v71
	v_max_u32_e32 v84, v82, v69
	v_min_u32_e32 v69, v82, v69
	v_max_u32_e32 v82, v75, v74
	v_min_u32_e32 v74, v75, v74
	v_max_u32_e32 v75, v94, v80
	v_min_u32_e32 v80, v94, v80
	v_max_u32_e32 v94, v113, v99
	v_min_u32_e32 v99, v113, v99
	v_max_u32_e32 v113, v76, v73
	v_min_u32_e32 v73, v76, v73
	v_max_u32_e32 v76, v95, v110
	v_min_u32_e32 v110, v95, v110
	v_max_u32_e32 v95, v87, v93
	v_min_u32_e32 v93, v87, v93
	v_max_u32_e32 v87, v78, v82
	v_min_u32_e32 v82, v78, v82
	v_max_u32_e32 v78, v84, v75
	v_min_u32_e32 v75, v84, v75
	v_max_u32_e32 v84, v71, v74
	v_min_u32_e32 v74, v71, v74
	v_max_u32_e32 v71, v69, v80
	v_min_u32_e32 v80, v69, v80
	v_max_u32_e32 v69, v94, v113
	v_min_u32_e32 v113, v94, v113
	v_max_u32_e32 v94, v99, v73
	v_min_u32_e32 v73, v99, v73
	v_max_u32_e32 v99, v76, v95
	v_min_u32_e32 v95, v76, v95
	v_max_u32_e32 v76, v110, v93
	v_min_u32_e32 v93, v110, v93
	v_max_u32_e32 v110, v87, v78
	v_min_u32_e32 v78, v87, v78
	v_max_u32_e32 v87, v82, v75
	v_min_u32_e32 v75, v82, v75
	v_max_u32_e32 v82, v84, v71
	v_min_u32_e32 v71, v84, v71
	v_max_u32_e32 v84, v74, v80
	v_min_u32_e32 v80, v74, v80
	v_max_u32_e32 v74, v104, v80
	v_max_u32_e32 v104, v91, v84
	v_max_u32_e32 v91, v86, v71
	v_max_u32_e32 v86, v117, v82
	v_max_u32_e32 v117, v77, v75
	v_max_u32_e32 v77, v70, v87
	v_max_u32_e32 v70, v72, v78
	v_max_u32_e32 v72, v102, v110
	v_max_u32_e32 v102, v96, v93
	v_max_u32_e32 v96, v103, v76
	v_max_u32_e32 v103, v105, v95
	v_max_u32_e32 v105, v97, v99
	v_max_u32_e32 v97, v100, v73
	v_max_u32_e32 v100, v79, v94
	v_max_u32_e32 v79, v88, v113
	v_max_u32_e32 v88, v92, v69
	v_max_u32_e32 v80, v74, v102
	v_min_u32_e32 v102, v74, v102
	v_max_u32_e32 v74, v104, v96
	v_min_u32_e32 v96, v104, v96
	v_max_u32_e32 v104, v91, v103
	v_min_u32_e32 v103, v91, v103
	v_max_u32_e32 v91, v86, v105
	v_min_u32_e32 v105, v86, v105
	v_max_u32_e32 v86, v117, v97
	v_min_u32_e32 v97, v117, v97
	v_max_u32_e32 v117, v77, v100
	v_min_u32_e32 v100, v77, v100
	v_max_u32_e32 v77, v70, v79
	v_min_u32_e32 v79, v70, v79
	v_max_u32_e32 v70, v72, v88
	v_min_u32_e32 v88, v72, v88
	v_max_u32_e32 v72, v80, v86
	v_min_u32_e32 v86, v80, v86
	v_max_u32_e32 v80, v74, v117
	v_min_u32_e32 v117, v74, v117
	v_max_u32_e32 v74, v104, v77
	v_min_u32_e32 v77, v104, v77
	v_max_u32_e32 v104, v91, v70
	v_min_u32_e32 v70, v91, v70
	v_max_u32_e32 v91, v102, v97
	v_min_u32_e32 v97, v102, v97
	v_max_u32_e32 v102, v96, v100
	v_min_u32_e32 v100, v96, v100
	v_max_u32_e32 v96, v103, v79
	v_min_u32_e32 v79, v103, v79
	v_max_u32_e32 v103, v105, v88
	v_min_u32_e32 v88, v105, v88
	v_max_u32_e32 v105, v72, v74
	v_min_u32_e32 v74, v72, v74
	v_max_u32_e32 v72, v80, v104
	v_min_u32_e32 v104, v80, v104
	v_max_u32_e32 v80, v86, v77
	v_min_u32_e32 v77, v86, v77
	v_max_u32_e32 v86, v117, v70
	v_min_u32_e32 v70, v117, v70
	v_max_u32_e32 v117, v91, v96
	v_min_u32_e32 v96, v91, v96
	v_max_u32_e32 v91, v102, v103
	v_min_u32_e32 v103, v102, v103
	v_max_u32_e32 v102, v97, v79
	v_min_u32_e32 v79, v97, v79
	v_max_u32_e32 v97, v100, v88
	v_min_u32_e32 v88, v100, v88
	v_max_u32_e32 v100, v105, v72
	v_min_u32_e32 v72, v105, v72
	v_max_u32_e32 v105, v74, v104
	v_min_u32_e32 v104, v74, v104
	v_max_u32_e32 v74, v80, v86
	v_min_u32_e32 v86, v80, v86
	v_max_u32_e32 v80, v77, v70
	v_min_u32_e32 v70, v77, v70
	v_max_u32_e32 v77, v117, v91
	v_min_u32_e32 v91, v117, v91
	v_max_u32_e32 v117, v96, v103
	v_min_u32_e32 v103, v96, v103
	v_max_u32_e32 v96, v102, v97
	v_min_u32_e32 v97, v102, v97
	v_max_u32_e32 v102, v79, v88
	v_min_u32_e32 v88, v79, v88
	v_max_u32_e32 v79, v115, v88
	v_max_u32_e32 v115, v89, v102
	v_max_u32_e32 v89, v90, v97
	v_max_u32_e32 v90, v112, v96
	v_max_u32_e32 v112, v116, v103
	v_max_u32_e32 v116, v109, v117
	v_max_u32_e32 v109, v108, v91
	v_max_u32_e32 v108, v111, v77
	v_max_u32_e32 v111, v106, v70
	v_max_u32_e32 v106, v85, v80
	v_max_u32_e32 v85, v101, v86
	v_max_u32_e32 v101, v83, v74
	v_max_u32_e32 v83, v114, v104
	v_max_u32_e32 v114, v81, v105
	v_max_u32_e32 v81, v107, v72
	v_max_u32_e32 v107, v98, v100
	v_max_u32_e32 v88, v79, v111
	v_min_u32_e32 v111, v79, v111
	v_max_u32_e32 v79, v115, v106
	v_min_u32_e32 v106, v115, v106
	v_max_u32_e32 v115, v89, v85
	v_min_u32_e32 v85, v89, v85
	v_max_u32_e32 v89, v90, v101
	v_min_u32_e32 v101, v90, v101
	v_max_u32_e32 v90, v112, v83
	v_min_u32_e32 v83, v112, v83
	v_max_u32_e32 v112, v116, v114
	v_min_u32_e32 v114, v116, v114
	v_max_u32_e32 v116, v109, v81
	v_min_u32_e32 v81, v109, v81
	v_max_u32_e32 v109, v108, v107
	v_min_u32_e32 v107, v108, v107
	v_max_u32_e32 v108, v88, v90
	v_min_u32_e32 v90, v88, v90
	v_max_u32_e32 v88, v79, v112
	v_min_u32_e32 v112, v79, v112
	v_max_u32_e32 v79, v115, v116
	v_min_u32_e32 v116, v115, v116
	v_max_u32_e32 v115, v89, v109
	v_min_u32_e32 v109, v89, v109
	v_max_u32_e32 v89, v111, v83
	v_min_u32_e32 v83, v111, v83
	v_max_u32_e32 v111, v106, v114
	v_min_u32_e32 v114, v106, v114
; DI void merge_top16(unsigned (&a)[16], const unsigned (&b)[16]) {
; #pragma unroll
;   for (int i = 0; i < 16; ++i) a[i] = max(a[i], b[15 - i]);
; #pragma unroll
;     ...
; #pragma unroll
;     for (int i = 0; i < 16; ++i) {
;       const int j = 1 << js, l = i ^ j;
;       if (l > i) {
;         const unsigned x = a[i], y = a[l];
;         a[i] = max(x, y);
;         a[l] = min(x, y);
;       }
;     }
; }
; DI void peer_top16(const u16* __restrict__ PQrow, const u16* __restrict__ SK, unsigned (&top)[16], int lr, int hh) {
;     ...
;   merge_top16(g[0], g[1]);
;   merge_top16(g[2], g[3]);
;   merge_top16(g[0], g[2]);
;   unsigned other[16];
; #pragma unroll
;   for (int i = 0; i < 16; ++i) other[i] = (unsigned)__shfl_xor((int)g[0][i], 32);
;   merge_top16(g[0], other);
; #pragma unroll
;   for (int i = 0; i < 16; ++i) top[i] = g[0][i];
	v_max_u32_e32 v106, v85, v81
	v_min_u32_e32 v81, v85, v81
	v_max_u32_e32 v85, v101, v107
	v_min_u32_e32 v107, v101, v107
	v_max_u32_e32 v101, v108, v79
	v_min_u32_e32 v79, v108, v79
	v_max_u32_e32 v108, v88, v115
	v_min_u32_e32 v115, v88, v115
	v_max_u32_e32 v88, v90, v116
	v_min_u32_e32 v116, v90, v116
	v_max_u32_e32 v90, v112, v109
	v_min_u32_e32 v109, v112, v109
	v_max_u32_e32 v112, v89, v106
	v_min_u32_e32 v106, v89, v106
	v_max_u32_e32 v89, v111, v85
	v_min_u32_e32 v85, v111, v85
	v_max_u32_e32 v111, v83, v81
	v_min_u32_e32 v81, v83, v81
	v_max_u32_e32 v83, v114, v107
	v_min_u32_e32 v107, v114, v107
	v_max_u32_e32 v114, v101, v108
	v_min_u32_e32 v108, v101, v108
	v_max_u32_e32 v101, v79, v115
	v_min_u32_e32 v115, v79, v115
	v_max_u32_e32 v79, v88, v90
	v_min_u32_e32 v90, v88, v90
	v_max_u32_e32 v88, v116, v109
	v_min_u32_e32 v109, v116, v109
	v_max_u32_e32 v116, v112, v89
	v_min_u32_e32 v89, v112, v89
	v_max_u32_e32 v112, v106, v85
	v_min_u32_e32 v85, v106, v85
	v_max_u32_e32 v106, v111, v83
	v_min_u32_e32 v83, v111, v83
	v_max_u32_e32 v111, v81, v107
	v_min_u32_e32 v107, v81, v107
	v_mov_b32_e32 v48, v114
	v_mov_b32_e32 v49, v108
	v_mov_b32_e32 v50, v101
	v_mov_b32_e32 v51, v115
	v_mov_b32_e32 v52, v79
	v_mov_b32_e32 v53, v90
	v_mov_b32_e32 v54, v88
	v_mov_b32_e32 v55, v109
	v_mov_b32_e32 v56, v116
	v_mov_b32_e32 v57, v89
	v_mov_b32_e32 v58, v112
	v_mov_b32_e32 v59, v85
	v_mov_b32_e32 v60, v106
	v_mov_b32_e32 v61, v83
	v_mov_b32_e32 v62, v111
	v_mov_b32_e32 v63, v107
	s_nop 1
	v_permlane32_swap_b32_e32 v0, v32
	v_permlane32_swap_b32_e32 v1, v33
	v_permlane32_swap_b32_e32 v2, v34
	v_permlane32_swap_b32_e32 v3, v35
	v_permlane32_swap_b32_e32 v4, v36
	v_permlane32_swap_b32_e32 v5, v37
	v_permlane32_swap_b32_e32 v6, v38
	v_permlane32_swap_b32_e32 v7, v39
	v_permlane32_swap_b32_e32 v8, v40
	v_permlane32_swap_b32_e32 v9, v41
	v_permlane32_swap_b32_e32 v10, v42
	v_permlane32_swap_b32_e32 v11, v43
	v_permlane32_swap_b32_e32 v12, v44
	v_permlane32_swap_b32_e32 v13, v45
	v_permlane32_swap_b32_e32 v14, v46
	v_permlane32_swap_b32_e32 v15, v47
	v_permlane32_swap_b32_e32 v16, v48
	v_permlane32_swap_b32_e32 v17, v49
	v_permlane32_swap_b32_e32 v18, v50
	v_permlane32_swap_b32_e32 v19, v51
	v_permlane32_swap_b32_e32 v20, v52
	v_permlane32_swap_b32_e32 v21, v53
	v_permlane32_swap_b32_e32 v22, v54
	v_permlane32_swap_b32_e32 v23, v55
	v_permlane32_swap_b32_e32 v24, v56
	v_permlane32_swap_b32_e32 v25, v57
	v_permlane32_swap_b32_e32 v26, v58
	v_permlane32_swap_b32_e32 v27, v59
	v_permlane32_swap_b32_e32 v28, v60
	v_permlane32_swap_b32_e32 v29, v61
	v_permlane32_swap_b32_e32 v30, v62
	v_permlane32_swap_b32_e32 v31, v63
	v_max_u32_e32 v107, v0, v47
	v_max_u32_e32 v0, v1, v46
	v_max_u32_e32 v1, v2, v45
	v_max_u32_e32 v2, v3, v44
	v_max_u32_e32 v3, v4, v43
	v_max_u32_e32 v4, v5, v42
	v_max_u32_e32 v5, v6, v41
	v_max_u32_e32 v6, v7, v40
	v_max_u32_e32 v7, v8, v39
	v_max_u32_e32 v8, v9, v38
	v_max_u32_e32 v9, v10, v37
	v_max_u32_e32 v10, v11, v36
	v_max_u32_e32 v11, v12, v35
	v_max_u32_e32 v12, v13, v34
	v_max_u32_e32 v13, v14, v33
	v_max_u32_e32 v14, v15, v32
	v_max_u32_e32 v47, v107, v7
	v_min_u32_e32 v7, v107, v7
	v_max_u32_e32 v107, v0, v8
	v_min_u32_e32 v8, v0, v8
	v_max_u32_e32 v0, v1, v9
	v_min_u32_e32 v9, v1, v9
	v_max_u32_e32 v1, v2, v10
	v_min_u32_e32 v10, v2, v10
	v_max_u32_e32 v2, v3, v11
	v_min_u32_e32 v11, v3, v11
	v_max_u32_e32 v3, v4, v12
	v_min_u32_e32 v12, v4, v12
	v_max_u32_e32 v4, v5, v13
	v_min_u32_e32 v13, v5, v13
	v_max_u32_e32 v5, v6, v14
	v_min_u32_e32 v14, v6, v14
	v_max_u32_e32 v6, v47, v2
	v_min_u32_e32 v2, v47, v2
	v_max_u32_e32 v47, v107, v3
	v_min_u32_e32 v3, v107, v3
	v_max_u32_e32 v107, v0, v4
	v_min_u32_e32 v4, v0, v4
	v_max_u32_e32 v0, v1, v5
	v_min_u32_e32 v5, v1, v5
	v_max_u32_e32 v1, v7, v11
	v_min_u32_e32 v11, v7, v11
	v_max_u32_e32 v7, v8, v12
	v_min_u32_e32 v12, v8, v12
	v_max_u32_e32 v8, v9, v13
	v_min_u32_e32 v13, v9, v13
	v_max_u32_e32 v9, v10, v14
	v_min_u32_e32 v14, v10, v14
	v_max_u32_e32 v10, v6, v107
	v_min_u32_e32 v107, v6, v107
	v_max_u32_e32 v6, v47, v0
	v_min_u32_e32 v0, v47, v0
	v_max_u32_e32 v47, v2, v4
	v_min_u32_e32 v4, v2, v4
	v_max_u32_e32 v2, v3, v5
	v_min_u32_e32 v5, v3, v5
	v_max_u32_e32 v3, v1, v8
	v_min_u32_e32 v8, v1, v8
	v_max_u32_e32 v1, v7, v9
	v_min_u32_e32 v9, v7, v9
	v_max_u32_e32 v7, v11, v13
	v_min_u32_e32 v13, v11, v13
	v_max_u32_e32 v11, v12, v14
	v_min_u32_e32 v14, v12, v14
	v_max_u32_e32 v12, v10, v6
	v_min_u32_e32 v6, v10, v6
	v_max_u32_e32 v10, v107, v0
	v_min_u32_e32 v0, v107, v0
	v_max_u32_e32 v107, v47, v2
	v_min_u32_e32 v2, v47, v2
	v_max_u32_e32 v47, v4, v5
	v_min_u32_e32 v5, v4, v5
	v_max_u32_e32 v4, v3, v1
	v_min_u32_e32 v1, v3, v1
	v_max_u32_e32 v3, v8, v9
	v_min_u32_e32 v9, v8, v9
	v_max_u32_e32 v8, v7, v11
	v_min_u32_e32 v11, v7, v11
	v_max_u32_e32 v7, v13, v14
	v_min_u32_e32 v14, v13, v14
	v_max_u32_e32 v13, v16, v63
	v_max_u32_e32 v16, v17, v62
	v_max_u32_e32 v17, v18, v61
	v_max_u32_e32 v18, v19, v60
	v_max_u32_e32 v19, v20, v59
	v_max_u32_e32 v20, v21, v58
	v_max_u32_e32 v21, v22, v57
	v_max_u32_e32 v22, v23, v56
	v_max_u32_e32 v23, v24, v55
	v_max_u32_e32 v24, v25, v54
	v_max_u32_e32 v25, v26, v53
	v_max_u32_e32 v26, v27, v52
	v_max_u32_e32 v27, v28, v51
	v_max_u32_e32 v28, v29, v50
	v_max_u32_e32 v29, v30, v49
	v_max_u32_e32 v30, v31, v48
	v_max_u32_e32 v63, v13, v23
	v_min_u32_e32 v23, v13, v23
	v_max_u32_e32 v13, v16, v24
	v_min_u32_e32 v24, v16, v24
	v_max_u32_e32 v16, v17, v25
	v_min_u32_e32 v25, v17, v25
	v_max_u32_e32 v17, v18, v26
	v_min_u32_e32 v26, v18, v26
	v_max_u32_e32 v18, v19, v27
	v_min_u32_e32 v27, v19, v27
	v_max_u32_e32 v19, v20, v28
; DI float ord2f(unsigned u) { return __uint_as_float((u & 0x80000000u) ? (u ^ 0x80000000u) : ~u); }
; template <bool STORE>
; DI void peer_item(const Params& p, int item, char* smem) {
;     ...
;     for (int a = 0; a < 16; ++a)
; #pragma unroll
;       for (int bq = 0; bq < 16; ++bq)
;         if ((a + 1) * (bq + 1) <= 16)
;           ckey[a][bq] = (f2ord(ord2f(top1[a] & ~127u) + ord2f(top2[bq] & ~127u)) & ~255u) | (unsigned)(255 - (a * 16 + bq));
;     unsigned wkey[16];
;     int we[16];
; #pragma unroll
;     for (int r = 0; r < 16; ++r) {
;       unsigned mx = 0u;
; #pragma unroll
;       for (int a = 0; a < 16; ++a)
; #pragma unroll
;         for (int bq = 0; bq < 16; ++bq)
;           if ((a + 1) * (bq + 1) <= 16) mx = max(mx, ckey[a][bq]);
; #pragma unroll
;       for (int a = 0; a < 16; ++a)
; #pragma unroll
;         for (int bq = 0; bq < 16; ++bq)
;           if ((a + 1) * (bq + 1) <= 16) ckey[a][bq] = (ckey[a][bq] == mx) ? 0u : ckey[a][bq];
;       wkey[r] = mx;
;       const int cidx = 255 - (int)(mx & 255u);
;       const int wa = cidx >> 4, wb = cidx & 15;
;       unsigned t1 = top1[0], t2 = top2[0];
; #pragma unroll
;       for (int a = 1; a < 16; ++a) { t1 = (wa == a) ? top1[a] : t1; t2 = (wb == a) ? top2[a] : t2; }
;       we[r] = (127 - (int)(t1 & 127u)) * 128 + (127 - (int)(t2 & 127u));
	v_min_u32_e32 v28, v20, v28
	v_max_u32_e32 v20, v21, v29
	v_min_u32_e32 v29, v21, v29
	v_max_u32_e32 v21, v22, v30
	v_min_u32_e32 v30, v22, v30
	v_max_u32_e32 v22, v63, v18
	v_min_u32_e32 v18, v63, v18
	v_max_u32_e32 v63, v13, v19
	v_min_u32_e32 v19, v13, v19
	v_max_u32_e32 v13, v16, v20
	v_min_u32_e32 v20, v16, v20
	v_max_u32_e32 v16, v17, v21
	v_min_u32_e32 v21, v17, v21
	v_max_u32_e32 v17, v23, v27
	v_min_u32_e32 v27, v23, v27
	v_max_u32_e32 v23, v24, v28
	v_min_u32_e32 v28, v24, v28
	v_max_u32_e32 v24, v25, v29
	v_min_u32_e32 v29, v25, v29
	v_max_u32_e32 v25, v26, v30
	v_min_u32_e32 v30, v26, v30
	v_max_u32_e32 v26, v22, v13
	v_min_u32_e32 v13, v22, v13
	v_max_u32_e32 v22, v63, v16
	v_min_u32_e32 v16, v63, v16
	v_max_u32_e32 v63, v18, v20
	v_min_u32_e32 v20, v18, v20
	v_max_u32_e32 v18, v19, v21
	v_min_u32_e32 v21, v19, v21
	v_max_u32_e32 v19, v17, v24
	v_min_u32_e32 v24, v17, v24
	v_max_u32_e32 v17, v23, v25
	v_min_u32_e32 v25, v23, v25
	v_max_u32_e32 v23, v27, v29
	v_min_u32_e32 v29, v27, v29
	v_max_u32_e32 v27, v28, v30
	v_min_u32_e32 v30, v28, v30
	v_max_u32_e32 v28, v26, v22
	v_min_u32_e32 v22, v26, v22
	v_max_u32_e32 v26, v13, v16
	v_min_u32_e32 v16, v13, v16
	v_max_u32_e32 v13, v63, v18
	v_min_u32_e32 v18, v63, v18
	v_max_u32_e32 v63, v20, v21
	v_min_u32_e32 v21, v20, v21
	v_max_u32_e32 v20, v19, v17
	v_min_u32_e32 v17, v19, v17
	v_max_u32_e32 v19, v24, v25
	v_min_u32_e32 v25, v24, v25
	v_max_u32_e32 v24, v23, v27
	v_min_u32_e32 v27, v23, v27
	v_max_u32_e32 v23, v29, v30
	v_min_u32_e32 v30, v29, v30
	v_xor_b32_e32 v229, 0x7f, v12
	v_and_b32_e32 v229, 0x7f, v229
	v_mov_b32_e32 v29, v229
	v_xor_b32_e32 v229, 0x7f, v6
	v_and_b32_e32 v229, 0x7f, v229
	v_lshl_or_b32 v29, v229, 8, v29
	v_xor_b32_e32 v229, 0x7f, v10
	v_and_b32_e32 v229, 0x7f, v229
	v_lshl_or_b32 v29, v229, 16, v29
	v_xor_b32_e32 v229, 0x7f, v0
	v_and_b32_e32 v229, 0x7f, v229
	v_lshl_or_b32 v29, v229, 24, v29
	v_xor_b32_e32 v229, 0x7f, v107
	v_and_b32_e32 v229, 0x7f, v229
	v_mov_b32_e32 v62, v229
	v_xor_b32_e32 v229, 0x7f, v2
	v_and_b32_e32 v229, 0x7f, v229
	v_lshl_or_b32 v62, v229, 8, v62
	v_xor_b32_e32 v229, 0x7f, v47
	v_and_b32_e32 v229, 0x7f, v229
	v_lshl_or_b32 v62, v229, 16, v62
	v_xor_b32_e32 v229, 0x7f, v5
	v_and_b32_e32 v229, 0x7f, v229
	v_lshl_or_b32 v62, v229, 24, v62
	v_xor_b32_e32 v229, 0x7f, v4
	v_and_b32_e32 v229, 0x7f, v229
	v_mov_b32_e32 v61, v229
	v_xor_b32_e32 v229, 0x7f, v1
	v_and_b32_e32 v229, 0x7f, v229
	v_lshl_or_b32 v61, v229, 8, v61
	v_xor_b32_e32 v229, 0x7f, v3
	v_and_b32_e32 v229, 0x7f, v229
	v_lshl_or_b32 v61, v229, 16, v61
	v_xor_b32_e32 v229, 0x7f, v9
	v_and_b32_e32 v229, 0x7f, v229
	v_lshl_or_b32 v61, v229, 24, v61
	v_xor_b32_e32 v229, 0x7f, v8
	v_and_b32_e32 v229, 0x7f, v229
	v_mov_b32_e32 v60, v229
	v_xor_b32_e32 v229, 0x7f, v11
	v_and_b32_e32 v229, 0x7f, v229
	v_lshl_or_b32 v60, v229, 8, v60
	v_xor_b32_e32 v229, 0x7f, v7
	v_and_b32_e32 v229, 0x7f, v229
	v_lshl_or_b32 v60, v229, 16, v60
	v_xor_b32_e32 v229, 0x7f, v14
	v_and_b32_e32 v229, 0x7f, v229
	v_lshl_or_b32 v60, v229, 24, v60
	v_xor_b32_e32 v229, 0x7f, v28
	v_and_b32_e32 v229, 0x7f, v229
	v_mov_b32_e32 v59, v229
	v_xor_b32_e32 v229, 0x7f, v22
	v_and_b32_e32 v229, 0x7f, v229
	v_lshl_or_b32 v59, v229, 8, v59
	v_xor_b32_e32 v229, 0x7f, v26
	v_and_b32_e32 v229, 0x7f, v229
	v_lshl_or_b32 v59, v229, 16, v59
	v_xor_b32_e32 v229, 0x7f, v16
	v_and_b32_e32 v229, 0x7f, v229
	v_lshl_or_b32 v59, v229, 24, v59
	v_xor_b32_e32 v229, 0x7f, v13
	v_and_b32_e32 v229, 0x7f, v229
	v_mov_b32_e32 v58, v229
	v_xor_b32_e32 v229, 0x7f, v18
	v_and_b32_e32 v229, 0x7f, v229
	v_lshl_or_b32 v58, v229, 8, v58
	v_xor_b32_e32 v229, 0x7f, v63
	v_and_b32_e32 v229, 0x7f, v229
	v_lshl_or_b32 v58, v229, 16, v58
	v_xor_b32_e32 v229, 0x7f, v21
	v_and_b32_e32 v229, 0x7f, v229
	v_lshl_or_b32 v58, v229, 24, v58
	v_xor_b32_e32 v229, 0x7f, v20
	v_and_b32_e32 v229, 0x7f, v229
	v_mov_b32_e32 v57, v229
	v_xor_b32_e32 v229, 0x7f, v17
	v_and_b32_e32 v229, 0x7f, v229
	v_lshl_or_b32 v57, v229, 8, v57
	v_xor_b32_e32 v229, 0x7f, v19
	v_and_b32_e32 v229, 0x7f, v229
	v_lshl_or_b32 v57, v229, 16, v57
	v_xor_b32_e32 v229, 0x7f, v25
	v_and_b32_e32 v229, 0x7f, v229
	v_lshl_or_b32 v57, v229, 24, v57
	v_xor_b32_e32 v229, 0x7f, v24
	v_and_b32_e32 v229, 0x7f, v229
	v_mov_b32_e32 v56, v229
	v_xor_b32_e32 v229, 0x7f, v27
	v_and_b32_e32 v229, 0x7f, v229
	v_lshl_or_b32 v56, v229, 8, v56
	v_xor_b32_e32 v229, 0x7f, v23
	v_and_b32_e32 v229, 0x7f, v229
	v_lshl_or_b32 v56, v229, 16, v56
	v_xor_b32_e32 v229, 0x7f, v30
	v_and_b32_e32 v229, 0x7f, v229
	v_lshl_or_b32 v56, v229, 24, v56
	ds_write_b32 v241, v29 offset:0
	ds_write_b32 v241, v62 offset:4
	ds_write_b32 v241, v61 offset:8
	ds_write_b32 v241, v60 offset:12
	ds_write_b32 v241, v59 offset:16
	ds_write_b32 v241, v58 offset:20
	ds_write_b32 v241, v57 offset:24
	ds_write_b32 v241, v56 offset:28
	v_and_b32_e32 v229, 0xffffff80, v12
	v_ashrrev_i32_e32 v230, 31, v229
	v_not_b32_e32 v230, v230
	v_or_b32_e32 v230, 0x80000000, v230
	v_xor_b32_e32 v56, v230, v229
	v_and_b32_e32 v229, 0xffffff80, v6
	v_ashrrev_i32_e32 v230, 31, v229
	v_not_b32_e32 v230, v230
	v_or_b32_e32 v230, 0x80000000, v230
	v_xor_b32_e32 v57, v230, v229
	v_and_b32_e32 v229, 0xffffff80, v10
	v_ashrrev_i32_e32 v230, 31, v229
	v_not_b32_e32 v230, v230
	v_or_b32_e32 v230, 0x80000000, v230
	v_xor_b32_e32 v58, v230, v229
	v_and_b32_e32 v229, 0xffffff80, v0
	v_ashrrev_i32_e32 v230, 31, v229
	v_not_b32_e32 v230, v230
	v_or_b32_e32 v230, 0x80000000, v230
	v_xor_b32_e32 v59, v230, v229
	v_and_b32_e32 v229, 0xffffff80, v107
	v_ashrrev_i32_e32 v230, 31, v229
	v_not_b32_e32 v230, v230
	v_or_b32_e32 v230, 0x80000000, v230
	v_xor_b32_e32 v60, v230, v229
; DI float ord2f(unsigned u) { return __uint_as_float((u & 0x80000000u) ? (u ^ 0x80000000u) : ~u); }
; template <bool STORE>
; DI void peer_item(const Params& p, int item, char* smem) {
;     ...
;     for (int a = 0; a < 16; ++a)
; #pragma unroll
;       for (int bq = 0; bq < 16; ++bq)
;         if ((a + 1) * (bq + 1) <= 16)
;           ckey[a][bq] = (f2ord(ord2f(top1[a] & ~127u) + ord2f(top2[bq] & ~127u)) & ~255u) | (unsigned)(255 - (a * 16 + bq));
	v_and_b32_e32 v229, 0xffffff80, v2
	v_ashrrev_i32_e32 v230, 31, v229
	v_not_b32_e32 v230, v230
	v_or_b32_e32 v230, 0x80000000, v230
	v_xor_b32_e32 v61, v230, v229
	v_and_b32_e32 v229, 0xffffff80, v47
	v_ashrrev_i32_e32 v230, 31, v229
	v_not_b32_e32 v230, v230
	v_or_b32_e32 v230, 0x80000000, v230
	v_xor_b32_e32 v62, v230, v229
	v_and_b32_e32 v229, 0xffffff80, v5
	v_ashrrev_i32_e32 v230, 31, v229
	v_not_b32_e32 v230, v230
	v_or_b32_e32 v230, 0x80000000, v230
	v_xor_b32_e32 v29, v230, v229
	v_and_b32_e32 v229, 0xffffff80, v4
	v_ashrrev_i32_e32 v230, 31, v229
	v_not_b32_e32 v230, v230
	v_or_b32_e32 v230, 0x80000000, v230
	v_xor_b32_e32 v55, v230, v229
	v_and_b32_e32 v229, 0xffffff80, v1
	v_ashrrev_i32_e32 v230, 31, v229
	v_not_b32_e32 v230, v230
	v_or_b32_e32 v230, 0x80000000, v230
	v_xor_b32_e32 v54, v230, v229
	v_and_b32_e32 v229, 0xffffff80, v3
	v_ashrrev_i32_e32 v230, 31, v229
	v_not_b32_e32 v230, v230
	v_or_b32_e32 v230, 0x80000000, v230
	v_xor_b32_e32 v53, v230, v229
	v_and_b32_e32 v229, 0xffffff80, v9
	v_ashrrev_i32_e32 v230, 31, v229
	v_not_b32_e32 v230, v230
	v_or_b32_e32 v230, 0x80000000, v230
	v_xor_b32_e32 v52, v230, v229
	v_and_b32_e32 v229, 0xffffff80, v8
	v_ashrrev_i32_e32 v230, 31, v229
	v_not_b32_e32 v230, v230
	v_or_b32_e32 v230, 0x80000000, v230
	v_xor_b32_e32 v51, v230, v229
	v_and_b32_e32 v229, 0xffffff80, v11
	v_ashrrev_i32_e32 v230, 31, v229
	v_not_b32_e32 v230, v230
	v_or_b32_e32 v230, 0x80000000, v230
	v_xor_b32_e32 v50, v230, v229
	v_and_b32_e32 v229, 0xffffff80, v7
	v_ashrrev_i32_e32 v230, 31, v229
	v_not_b32_e32 v230, v230
	v_or_b32_e32 v230, 0x80000000, v230
	v_xor_b32_e32 v49, v230, v229
	v_and_b32_e32 v229, 0xffffff80, v14
	v_ashrrev_i32_e32 v230, 31, v229
	v_not_b32_e32 v230, v230
	v_or_b32_e32 v230, 0x80000000, v230
	v_xor_b32_e32 v48, v230, v229
	v_and_b32_e32 v229, 0xffffff80, v28
	v_ashrrev_i32_e32 v230, 31, v229
	v_not_b32_e32 v230, v230
	v_or_b32_e32 v230, 0x80000000, v230
	v_xor_b32_e32 v31, v230, v229
	v_and_b32_e32 v229, 0xffffff80, v22
	v_ashrrev_i32_e32 v230, 31, v229
	v_not_b32_e32 v230, v230
	v_or_b32_e32 v230, 0x80000000, v230
	v_xor_b32_e32 v46, v230, v229
	v_and_b32_e32 v229, 0xffffff80, v26
	v_ashrrev_i32_e32 v230, 31, v229
	v_not_b32_e32 v230, v230
	v_or_b32_e32 v230, 0x80000000, v230
	v_xor_b32_e32 v45, v230, v229
	v_and_b32_e32 v229, 0xffffff80, v16
	v_ashrrev_i32_e32 v230, 31, v229
	v_not_b32_e32 v230, v230
	v_or_b32_e32 v230, 0x80000000, v230
	v_xor_b32_e32 v44, v230, v229
	v_and_b32_e32 v229, 0xffffff80, v13
	v_ashrrev_i32_e32 v230, 31, v229
	v_not_b32_e32 v230, v230
	v_or_b32_e32 v230, 0x80000000, v230
	v_xor_b32_e32 v43, v230, v229
	v_and_b32_e32 v229, 0xffffff80, v18
	v_ashrrev_i32_e32 v230, 31, v229
	v_not_b32_e32 v230, v230
	v_or_b32_e32 v230, 0x80000000, v230
	v_xor_b32_e32 v42, v230, v229
	v_and_b32_e32 v229, 0xffffff80, v63
	v_ashrrev_i32_e32 v230, 31, v229
	v_not_b32_e32 v230, v230
	v_or_b32_e32 v230, 0x80000000, v230
	v_xor_b32_e32 v41, v230, v229
	v_and_b32_e32 v229, 0xffffff80, v21
	v_ashrrev_i32_e32 v230, 31, v229
	v_not_b32_e32 v230, v230
	v_or_b32_e32 v230, 0x80000000, v230
	v_xor_b32_e32 v40, v230, v229
	v_and_b32_e32 v229, 0xffffff80, v20
	v_ashrrev_i32_e32 v230, 31, v229
	v_not_b32_e32 v230, v230
	v_or_b32_e32 v230, 0x80000000, v230
	v_xor_b32_e32 v39, v230, v229
	v_and_b32_e32 v229, 0xffffff80, v17
	v_ashrrev_i32_e32 v230, 31, v229
	v_not_b32_e32 v230, v230
	v_or_b32_e32 v230, 0x80000000, v230
	v_xor_b32_e32 v38, v230, v229
	v_and_b32_e32 v229, 0xffffff80, v19
	v_ashrrev_i32_e32 v230, 31, v229
	v_not_b32_e32 v230, v230
	v_or_b32_e32 v230, 0x80000000, v230
	v_xor_b32_e32 v37, v230, v229
	v_and_b32_e32 v229, 0xffffff80, v25
	v_ashrrev_i32_e32 v230, 31, v229
	v_not_b32_e32 v230, v230
	v_or_b32_e32 v230, 0x80000000, v230
	v_xor_b32_e32 v36, v230, v229
	v_and_b32_e32 v229, 0xffffff80, v24
	v_ashrrev_i32_e32 v230, 31, v229
	v_not_b32_e32 v230, v230
	v_or_b32_e32 v230, 0x80000000, v230
	v_xor_b32_e32 v35, v230, v229
	v_and_b32_e32 v229, 0xffffff80, v27
	v_ashrrev_i32_e32 v230, 31, v229
	v_not_b32_e32 v230, v230
	v_or_b32_e32 v230, 0x80000000, v230
	v_xor_b32_e32 v34, v230, v229
	v_and_b32_e32 v229, 0xffffff80, v23
	v_ashrrev_i32_e32 v230, 31, v229
	v_not_b32_e32 v230, v230
	v_or_b32_e32 v230, 0x80000000, v230
	v_xor_b32_e32 v33, v230, v229
	v_and_b32_e32 v229, 0xffffff80, v30
	v_ashrrev_i32_e32 v230, 31, v229
	v_not_b32_e32 v230, v230
	v_or_b32_e32 v230, 0x80000000, v230
	v_xor_b32_e32 v32, v230, v229
	v_add_f32_e32 v229, v56, v31
	v_ashrrev_i32_e32 v230, 31, v229
	v_or_b32_e32 v230, 0x80000000, v230
	v_xor_b32_e32 v231, v230, v229
	v_and_b32_e32 v231, 0xffffff00, v231
	v_or_b32_e32 v15, 0xff, v231
	v_add_f32_e32 v229, v56, v46
	v_ashrrev_i32_e32 v230, 31, v229
	v_or_b32_e32 v230, 0x80000000, v230
	v_xor_b32_e32 v231, v230, v229
	v_and_b32_e32 v231, 0xffffff00, v231
	v_or_b32_e32 v111, 0xfe, v231
	v_add_f32_e32 v229, v56, v45
	v_ashrrev_i32_e32 v230, 31, v229
	v_or_b32_e32 v230, 0x80000000, v230
	v_xor_b32_e32 v231, v230, v229
	v_and_b32_e32 v231, 0xffffff00, v231
	v_or_b32_e32 v83, 0xfd, v231
	v_add_f32_e32 v229, v56, v44
	v_ashrrev_i32_e32 v230, 31, v229
	v_or_b32_e32 v230, 0x80000000, v230
	v_xor_b32_e32 v231, v230, v229
	v_and_b32_e32 v231, 0xffffff00, v231
	v_or_b32_e32 v106, 0xfc, v231
	v_add_f32_e32 v229, v56, v43
	v_ashrrev_i32_e32 v230, 31, v229
	v_or_b32_e32 v230, 0x80000000, v230
	v_xor_b32_e32 v231, v230, v229
	v_and_b32_e32 v231, 0xffffff00, v231
	v_or_b32_e32 v85, 0xfb, v231
	v_add_f32_e32 v229, v56, v42
	v_ashrrev_i32_e32 v230, 31, v229
	v_or_b32_e32 v230, 0x80000000, v230
	v_xor_b32_e32 v231, v230, v229
	v_and_b32_e32 v231, 0xffffff00, v231
; DI float ord2f(unsigned u) { return __uint_as_float((u & 0x80000000u) ? (u ^ 0x80000000u) : ~u); }
; template <bool STORE>
; DI void peer_item(const Params& p, int item, char* smem) {
;     ...
;     for (int a = 0; a < 16; ++a)
; #pragma unroll
;       for (int bq = 0; bq < 16; ++bq)
;         if ((a + 1) * (bq + 1) <= 16)
;           ckey[a][bq] = (f2ord(ord2f(top1[a] & ~127u) + ord2f(top2[bq] & ~127u)) & ~255u) | (unsigned)(255 - (a * 16 + bq));
;     unsigned wkey[16];
;     int we[16];
; #pragma unroll
;     for (int r = 0; r < 16; ++r) {
;       unsigned mx = 0u;
; #pragma unroll
;       for (int a = 0; a < 16; ++a)
; #pragma unroll
;         for (int bq = 0; bq < 16; ++bq)
;           if ((a + 1) * (bq + 1) <= 16) mx = max(mx, ckey[a][bq]);
; #pragma unroll
;       for (int a = 0; a < 16; ++a)
; #pragma unroll
;         for (int bq = 0; bq < 16; ++bq)
;           if ((a + 1) * (bq + 1) <= 16) ckey[a][bq] = (ckey[a][bq] == mx) ? 0u : ckey[a][bq];
;       wkey[r] = mx;
	v_or_b32_e32 v112, 0xfa, v231
	v_add_f32_e32 v229, v56, v41
	v_ashrrev_i32_e32 v230, 31, v229
	v_or_b32_e32 v230, 0x80000000, v230
	v_xor_b32_e32 v231, v230, v229
	v_and_b32_e32 v231, 0xffffff00, v231
	v_or_b32_e32 v89, 0xf9, v231
	v_add_f32_e32 v229, v56, v40
	v_ashrrev_i32_e32 v230, 31, v229
	v_or_b32_e32 v230, 0x80000000, v230
	v_xor_b32_e32 v231, v230, v229
	v_and_b32_e32 v231, 0xffffff00, v231
	v_or_b32_e32 v116, 0xf8, v231
	v_add_f32_e32 v229, v56, v39
	v_ashrrev_i32_e32 v230, 31, v229
	v_or_b32_e32 v230, 0x80000000, v230
	v_xor_b32_e32 v231, v230, v229
	v_and_b32_e32 v231, 0xffffff00, v231
	v_or_b32_e32 v109, 0xf7, v231
	v_add_f32_e32 v229, v56, v38
	v_ashrrev_i32_e32 v230, 31, v229
	v_or_b32_e32 v230, 0x80000000, v230
	v_xor_b32_e32 v231, v230, v229
	v_and_b32_e32 v231, 0xffffff00, v231
	v_or_b32_e32 v88, 0xf6, v231
	v_add_f32_e32 v229, v56, v37
	v_ashrrev_i32_e32 v230, 31, v229
	v_or_b32_e32 v230, 0x80000000, v230
	v_xor_b32_e32 v231, v230, v229
	v_and_b32_e32 v231, 0xffffff00, v231
	v_or_b32_e32 v90, 0xf5, v231
	v_add_f32_e32 v229, v56, v36
	v_ashrrev_i32_e32 v230, 31, v229
	v_or_b32_e32 v230, 0x80000000, v230
	v_xor_b32_e32 v231, v230, v229
	v_and_b32_e32 v231, 0xffffff00, v231
	v_or_b32_e32 v79, 0xf4, v231
	v_add_f32_e32 v229, v56, v35
	v_ashrrev_i32_e32 v230, 31, v229
	v_or_b32_e32 v230, 0x80000000, v230
	v_xor_b32_e32 v231, v230, v229
	v_and_b32_e32 v231, 0xffffff00, v231
	v_or_b32_e32 v115, 0xf3, v231
	v_add_f32_e32 v229, v56, v34
	v_ashrrev_i32_e32 v230, 31, v229
	v_or_b32_e32 v230, 0x80000000, v230
	v_xor_b32_e32 v231, v230, v229
	v_and_b32_e32 v231, 0xffffff00, v231
	v_or_b32_e32 v101, 0xf2, v231
	v_add_f32_e32 v229, v56, v33
	v_ashrrev_i32_e32 v230, 31, v229
	v_or_b32_e32 v230, 0x80000000, v230
	v_xor_b32_e32 v231, v230, v229
	v_and_b32_e32 v231, 0xffffff00, v231
	v_or_b32_e32 v108, 0xf1, v231
	v_add_f32_e32 v229, v56, v32
	v_ashrrev_i32_e32 v230, 31, v229
	v_or_b32_e32 v230, 0x80000000, v230
	v_xor_b32_e32 v231, v230, v229
	v_and_b32_e32 v231, 0xffffff00, v231
	v_or_b32_e32 v114, 0xf0, v231
	v_add_f32_e32 v229, v57, v31
	v_ashrrev_i32_e32 v230, 31, v229
	v_or_b32_e32 v230, 0x80000000, v230
	v_xor_b32_e32 v231, v230, v229
	v_and_b32_e32 v231, 0xffffff00, v231
	v_or_b32_e32 v81, 0xef, v231
	v_add_f32_e32 v229, v57, v46
	v_ashrrev_i32_e32 v230, 31, v229
	v_or_b32_e32 v230, 0x80000000, v230
	v_xor_b32_e32 v231, v230, v229
	v_and_b32_e32 v231, 0xffffff00, v231
	v_or_b32_e32 v102, 0xee, v231
	v_add_f32_e32 v229, v57, v45
	v_ashrrev_i32_e32 v230, 31, v229
	v_or_b32_e32 v230, 0x80000000, v230
	v_xor_b32_e32 v231, v230, v229
	v_and_b32_e32 v231, 0xffffff00, v231
	v_or_b32_e32 v97, 0xed, v231
	v_add_f32_e32 v229, v57, v44
	v_ashrrev_i32_e32 v230, 31, v229
	v_or_b32_e32 v230, 0x80000000, v230
	v_xor_b32_e32 v231, v230, v229
	v_and_b32_e32 v231, 0xffffff00, v231
	v_or_b32_e32 v96, 0xec, v231
	v_add_f32_e32 v229, v57, v43
	v_ashrrev_i32_e32 v230, 31, v229
	v_or_b32_e32 v230, 0x80000000, v230
	v_xor_b32_e32 v231, v230, v229
	v_and_b32_e32 v231, 0xffffff00, v231
	v_or_b32_e32 v103, 0xeb, v231
	v_add_f32_e32 v229, v57, v42
	v_ashrrev_i32_e32 v230, 31, v229
	v_or_b32_e32 v230, 0x80000000, v230
	v_xor_b32_e32 v231, v230, v229
	v_and_b32_e32 v231, 0xffffff00, v231
	v_or_b32_e32 v117, 0xea, v231
	v_add_f32_e32 v229, v57, v41
	v_ashrrev_i32_e32 v230, 31, v229
	v_or_b32_e32 v230, 0x80000000, v230
	v_xor_b32_e32 v231, v230, v229
	v_and_b32_e32 v231, 0xffffff00, v231
	v_or_b32_e32 v91, 0xe9, v231
	v_add_f32_e32 v229, v57, v40
	v_ashrrev_i32_e32 v230, 31, v229
	v_or_b32_e32 v230, 0x80000000, v230
	v_xor_b32_e32 v231, v230, v229
	v_and_b32_e32 v231, 0xffffff00, v231
	v_or_b32_e32 v77, 0xe8, v231
	v_add_f32_e32 v229, v58, v31
	v_ashrrev_i32_e32 v230, 31, v229
	v_or_b32_e32 v230, 0x80000000, v230
	v_xor_b32_e32 v231, v230, v229
	v_and_b32_e32 v231, 0xffffff00, v231
	v_or_b32_e32 v70, 0xdf, v231
	v_add_f32_e32 v229, v58, v46
	v_ashrrev_i32_e32 v230, 31, v229
	v_or_b32_e32 v230, 0x80000000, v230
	v_xor_b32_e32 v231, v230, v229
	v_and_b32_e32 v231, 0xffffff00, v231
	v_or_b32_e32 v80, 0xde, v231
	v_add_f32_e32 v229, v58, v45
	v_ashrrev_i32_e32 v230, 31, v229
	v_or_b32_e32 v230, 0x80000000, v230
	v_xor_b32_e32 v231, v230, v229
	v_and_b32_e32 v231, 0xffffff00, v231
	v_or_b32_e32 v86, 0xdd, v231
	v_add_f32_e32 v229, v58, v44
	v_ashrrev_i32_e32 v230, 31, v229
	v_or_b32_e32 v230, 0x80000000, v230
	v_xor_b32_e32 v231, v230, v229
	v_and_b32_e32 v231, 0xffffff00, v231
	v_or_b32_e32 v74, 0xdc, v231
	v_add_f32_e32 v229, v58, v43
	v_ashrrev_i32_e32 v230, 31, v229
	v_or_b32_e32 v230, 0x80000000, v230
	v_xor_b32_e32 v231, v230, v229
	v_and_b32_e32 v231, 0xffffff00, v231
	v_or_b32_e32 v104, 0xdb, v231
	v_add_f32_e32 v229, v59, v31
	v_ashrrev_i32_e32 v230, 31, v229
	v_or_b32_e32 v230, 0x80000000, v230
	v_xor_b32_e32 v231, v230, v229
	v_and_b32_e32 v231, 0xffffff00, v231
	v_or_b32_e32 v105, 0xcf, v231
	v_add_f32_e32 v229, v59, v46
	v_ashrrev_i32_e32 v230, 31, v229
	v_or_b32_e32 v230, 0x80000000, v230
	v_xor_b32_e32 v231, v230, v229
	v_and_b32_e32 v231, 0xffffff00, v231
	v_or_b32_e32 v72, 0xce, v231
	v_add_f32_e32 v229, v59, v45
	v_ashrrev_i32_e32 v230, 31, v229
	v_or_b32_e32 v230, 0x80000000, v230
	v_xor_b32_e32 v231, v230, v229
	v_and_b32_e32 v231, 0xffffff00, v231
	v_or_b32_e32 v100, 0xcd, v231
	v_max_u32_e32 v98, v81, v102
	v_min_u32_e32 v102, v81, v102
	v_min_u32_e32 v81, v97, v96
	v_max_u32_e32 v96, v97, v96
	v_max_u32_e32 v97, v103, v117
	v_min_u32_e32 v117, v103, v117
	v_min_u32_e32 v103, v91, v77
	v_max_u32_e32 v77, v91, v77
	v_max_u32_e32 v91, v70, v80
	v_min_u32_e32 v80, v70, v80
	v_min_u32_e32 v70, v86, v74
	v_max_u32_e32 v74, v86, v74
; template <int LOGN>
; DI void bitonic_sort_desc(unsigned (&a)[1 << LOGN]) {
;   constexpr int N = 1 << LOGN;
; #pragma unroll
;   for (int ks = 1; ks <= LOGN; ++ks)
; #pragma unroll
;     ...
; #pragma unroll
;       for (int i = 0; i < N; ++i) {
;         const int k = 1 << ks, j = 1 << js, l = i ^ j;
;         if (l > i) {
;           const bool desc = ((i & k) == 0) || (ks == LOGN);
;           const unsigned x = a[i], y = a[l];
;           const unsigned hi = max(x, y), lo = min(x, y);
;           a[i] = desc ? hi : lo;
;           a[l] = desc ? lo : hi;
;         }
;       }
; }
; DI void merge_top16(unsigned (&a)[16], const unsigned (&b)[16]) {
; #pragma unroll
;   for (int i = 0; i < 16; ++i) a[i] = max(a[i], b[15 - i]);
; #pragma unroll
;     ...
; #pragma unroll
;     for (int i = 0; i < 16; ++i) {
;       const int j = 1 << js, l = i ^ j;
;       if (l > i) {
;         const unsigned x = a[i], y = a[l];
;         a[i] = max(x, y);
;         a[l] = min(x, y);
;       }
;     }
; }
	v_max_u32_e32 v86, v104, v105
	v_min_u32_e32 v105, v104, v105
	v_min_u32_e32 v104, v72, v100
	v_max_u32_e32 v100, v72, v100
	v_max_u32_e32 v72, v98, v81
	v_min_u32_e32 v81, v98, v81
	v_max_u32_e32 v98, v102, v96
	v_min_u32_e32 v96, v102, v96
	v_min_u32_e32 v102, v97, v103
	v_max_u32_e32 v103, v97, v103
	v_min_u32_e32 v97, v117, v77
	v_max_u32_e32 v77, v117, v77
	v_max_u32_e32 v117, v91, v70
	v_min_u32_e32 v70, v91, v70
	v_max_u32_e32 v91, v80, v74
	v_min_u32_e32 v74, v80, v74
	v_min_u32_e32 v80, v86, v104
	v_max_u32_e32 v104, v86, v104
	v_min_u32_e32 v86, v105, v100
	v_max_u32_e32 v100, v105, v100
	v_max_u32_e32 v105, v72, v98
	v_min_u32_e32 v98, v72, v98
	v_max_u32_e32 v72, v81, v96
	v_min_u32_e32 v96, v81, v96
	v_min_u32_e32 v81, v102, v97
	v_max_u32_e32 v97, v102, v97
	v_min_u32_e32 v102, v103, v77
	v_max_u32_e32 v77, v103, v77
	v_max_u32_e32 v103, v117, v91
	v_min_u32_e32 v91, v117, v91
	v_max_u32_e32 v117, v70, v74
	v_min_u32_e32 v74, v70, v74
	v_min_u32_e32 v70, v80, v86
	v_max_u32_e32 v86, v80, v86
	v_min_u32_e32 v80, v104, v100
	v_max_u32_e32 v100, v104, v100
	v_max_u32_e32 v104, v105, v81
	v_min_u32_e32 v81, v105, v81
	v_max_u32_e32 v105, v98, v97
	v_min_u32_e32 v97, v98, v97
	v_max_u32_e32 v98, v72, v102
	v_min_u32_e32 v102, v72, v102
	v_max_u32_e32 v72, v96, v77
	v_min_u32_e32 v77, v96, v77
	v_min_u32_e32 v96, v103, v70
	v_max_u32_e32 v70, v103, v70
	v_min_u32_e32 v103, v91, v86
	v_max_u32_e32 v86, v91, v86
	v_min_u32_e32 v91, v117, v80
	v_max_u32_e32 v80, v117, v80
	v_min_u32_e32 v117, v74, v100
	v_max_u32_e32 v100, v74, v100
	v_max_u32_e32 v74, v104, v98
	v_min_u32_e32 v98, v104, v98
	v_max_u32_e32 v104, v105, v72
	v_min_u32_e32 v72, v105, v72
	v_max_u32_e32 v105, v81, v102
	v_min_u32_e32 v102, v81, v102
	v_max_u32_e32 v81, v97, v77
	v_min_u32_e32 v77, v97, v77
	v_min_u32_e32 v97, v96, v91
	v_max_u32_e32 v91, v96, v91
	v_min_u32_e32 v96, v103, v117
	v_max_u32_e32 v117, v103, v117
	v_min_u32_e32 v103, v70, v80
	v_max_u32_e32 v80, v70, v80
	v_min_u32_e32 v70, v86, v100
	v_max_u32_e32 v100, v86, v100
	v_max_u32_e32 v86, v74, v104
	v_min_u32_e32 v104, v74, v104
	v_max_u32_e32 v74, v98, v72
	v_min_u32_e32 v72, v98, v72
	v_max_u32_e32 v98, v105, v81
	v_min_u32_e32 v81, v105, v81
	v_max_u32_e32 v105, v102, v77
	v_min_u32_e32 v77, v102, v77
	v_min_u32_e32 v102, v97, v96
	v_max_u32_e32 v96, v97, v96
	v_min_u32_e32 v97, v91, v117
	v_max_u32_e32 v117, v91, v117
	v_min_u32_e32 v91, v103, v70
	v_max_u32_e32 v70, v103, v70
	v_min_u32_e32 v103, v80, v100
	v_max_u32_e32 v100, v80, v100
	v_max_u32_e32 v80, v86, v102
	v_min_u32_e32 v102, v86, v102
	v_max_u32_e32 v86, v104, v96
	v_min_u32_e32 v96, v104, v96
	v_max_u32_e32 v104, v74, v97
	v_min_u32_e32 v97, v74, v97
	v_max_u32_e32 v74, v72, v117
	v_min_u32_e32 v117, v72, v117
	v_max_u32_e32 v72, v98, v91
	v_min_u32_e32 v91, v98, v91
	v_max_u32_e32 v98, v81, v70
	v_min_u32_e32 v70, v81, v70
	v_max_u32_e32 v81, v105, v103
	v_min_u32_e32 v103, v105, v103
	v_max_u32_e32 v105, v77, v100
	v_min_u32_e32 v100, v77, v100
	v_max_u32_e32 v77, v80, v72
	v_min_u32_e32 v72, v80, v72
	v_max_u32_e32 v80, v86, v98
	v_min_u32_e32 v98, v86, v98
	v_max_u32_e32 v86, v104, v81
	v_min_u32_e32 v81, v104, v81
	v_max_u32_e32 v104, v74, v105
	v_min_u32_e32 v105, v74, v105
	v_max_u32_e32 v74, v102, v91
	v_min_u32_e32 v91, v102, v91
	v_max_u32_e32 v102, v96, v70
	v_min_u32_e32 v70, v96, v70
	v_max_u32_e32 v96, v97, v103
	v_min_u32_e32 v103, v97, v103
	v_max_u32_e32 v97, v117, v100
	v_min_u32_e32 v100, v117, v100
	v_max_u32_e32 v117, v77, v86
	v_min_u32_e32 v86, v77, v86
	v_max_u32_e32 v77, v80, v104
	v_min_u32_e32 v104, v80, v104
	v_max_u32_e32 v80, v72, v81
	v_min_u32_e32 v81, v72, v81
	v_max_u32_e32 v72, v98, v105
	v_min_u32_e32 v105, v98, v105
	v_max_u32_e32 v98, v74, v96
	v_min_u32_e32 v96, v74, v96
	v_max_u32_e32 v74, v102, v97
	v_min_u32_e32 v97, v102, v97
	v_max_u32_e32 v102, v91, v103
	v_min_u32_e32 v103, v91, v103
	v_max_u32_e32 v91, v70, v100
	v_min_u32_e32 v100, v70, v100
	v_max_u32_e32 v70, v117, v77
	v_min_u32_e32 v77, v117, v77
	v_max_u32_e32 v117, v86, v104
	v_min_u32_e32 v104, v86, v104
	v_max_u32_e32 v86, v80, v72
	v_min_u32_e32 v72, v80, v72
	v_max_u32_e32 v80, v81, v105
	v_min_u32_e32 v105, v81, v105
	v_max_u32_e32 v81, v98, v74
	v_min_u32_e32 v74, v98, v74
	v_max_u32_e32 v98, v96, v97
	v_min_u32_e32 v97, v96, v97
	v_max_u32_e32 v96, v102, v91
	v_min_u32_e32 v91, v102, v91
	v_max_u32_e32 v102, v103, v100
	v_min_u32_e32 v100, v103, v100
	v_max_u32_e32 v103, v15, v100
	v_max_u32_e32 v15, v111, v102
	v_max_u32_e32 v111, v83, v91
	v_max_u32_e32 v83, v106, v96
	v_max_u32_e32 v106, v85, v97
	v_max_u32_e32 v85, v112, v98
	v_max_u32_e32 v112, v89, v74
	v_max_u32_e32 v89, v116, v81
	v_max_u32_e32 v116, v109, v105
	v_max_u32_e32 v109, v88, v80
	v_max_u32_e32 v88, v90, v72
	v_max_u32_e32 v90, v79, v86
	v_max_u32_e32 v79, v115, v104
	v_max_u32_e32 v115, v101, v117
	v_max_u32_e32 v101, v108, v77
	v_max_u32_e32 v108, v114, v70
	v_max_u32_e32 v100, v103, v116
	v_min_u32_e32 v116, v103, v116
	v_max_u32_e32 v103, v15, v109
	v_min_u32_e32 v109, v15, v109
	v_max_u32_e32 v15, v111, v88
	v_min_u32_e32 v88, v111, v88
	v_max_u32_e32 v111, v83, v90
	v_min_u32_e32 v90, v83, v90
	v_max_u32_e32 v83, v106, v79
	v_min_u32_e32 v79, v106, v79
	v_max_u32_e32 v106, v85, v115
	v_min_u32_e32 v115, v85, v115
	v_max_u32_e32 v85, v112, v101
	v_min_u32_e32 v101, v112, v101
	v_max_u32_e32 v112, v89, v108
	v_min_u32_e32 v108, v89, v108
	v_max_u32_e32 v89, v100, v83
	v_min_u32_e32 v83, v100, v83
	v_max_u32_e32 v100, v103, v106
	v_min_u32_e32 v106, v103, v106
	v_max_u32_e32 v103, v15, v85
	v_min_u32_e32 v85, v15, v85
	v_max_u32_e32 v15, v111, v112
; DI float ord2f(unsigned u) { return __uint_as_float((u & 0x80000000u) ? (u ^ 0x80000000u) : ~u); }
; DI void merge_top16(unsigned (&a)[16], const unsigned (&b)[16]) {
; #pragma unroll
;   for (int i = 0; i < 16; ++i) a[i] = max(a[i], b[15 - i]);
; #pragma unroll
;     ...
; #pragma unroll
;     for (int i = 0; i < 16; ++i) {
;       const int j = 1 << js, l = i ^ j;
;       if (l > i) {
;         const unsigned x = a[i], y = a[l];
;         a[i] = max(x, y);
;         a[l] = min(x, y);
;       }
;     }
; }
; template <bool STORE>
; DI void peer_item(const Params& p, int item, char* smem) {
;     ...
;     for (int a = 0; a < 16; ++a)
; #pragma unroll
;       for (int bq = 0; bq < 16; ++bq)
;         if ((a + 1) * (bq + 1) <= 16)
;           ckey[a][bq] = (f2ord(ord2f(top1[a] & ~127u) + ord2f(top2[bq] & ~127u)) & ~255u) | (unsigned)(255 - (a * 16 + bq));
;     unsigned wkey[16];
;     int we[16];
; #pragma unroll
;     for (int r = 0; r < 16; ++r) {
;       unsigned mx = 0u;
; #pragma unroll
;       for (int a = 0; a < 16; ++a)
; #pragma unroll
;         for (int bq = 0; bq < 16; ++bq)
;           if ((a + 1) * (bq + 1) <= 16) mx = max(mx, ckey[a][bq]);
; #pragma unroll
;       for (int a = 0; a < 16; ++a)
; #pragma unroll
;         for (int bq = 0; bq < 16; ++bq)
;           if ((a + 1) * (bq + 1) <= 16) ckey[a][bq] = (ckey[a][bq] == mx) ? 0u : ckey[a][bq];
;       wkey[r] = mx;
	v_min_u32_e32 v112, v111, v112
	v_max_u32_e32 v111, v116, v79
	v_min_u32_e32 v79, v116, v79
	v_max_u32_e32 v116, v109, v115
	v_min_u32_e32 v115, v109, v115
	v_max_u32_e32 v109, v88, v101
	v_min_u32_e32 v101, v88, v101
	v_max_u32_e32 v88, v90, v108
	v_min_u32_e32 v108, v90, v108
	v_max_u32_e32 v90, v89, v103
	v_min_u32_e32 v103, v89, v103
	v_max_u32_e32 v89, v100, v15
	v_min_u32_e32 v15, v100, v15
	v_max_u32_e32 v100, v83, v85
	v_min_u32_e32 v85, v83, v85
	v_max_u32_e32 v83, v106, v112
	v_min_u32_e32 v112, v106, v112
	v_max_u32_e32 v106, v111, v109
	v_min_u32_e32 v109, v111, v109
	v_max_u32_e32 v111, v116, v88
	v_min_u32_e32 v88, v116, v88
	v_max_u32_e32 v116, v79, v101
	v_min_u32_e32 v101, v79, v101
	v_max_u32_e32 v79, v115, v108
	v_min_u32_e32 v108, v115, v108
	v_max_u32_e32 v115, v90, v89
	v_min_u32_e32 v89, v90, v89
	v_max_u32_e32 v90, v103, v15
	v_min_u32_e32 v15, v103, v15
	v_max_u32_e32 v103, v100, v83
	v_min_u32_e32 v83, v100, v83
	v_max_u32_e32 v100, v85, v112
	v_min_u32_e32 v112, v85, v112
	v_max_u32_e32 v85, v106, v111
	v_min_u32_e32 v111, v106, v111
	v_max_u32_e32 v106, v109, v88
	v_min_u32_e32 v88, v109, v88
	v_max_u32_e32 v109, v116, v79
	v_min_u32_e32 v79, v116, v79
	v_max_u32_e32 v116, v101, v108
	v_min_u32_e32 v108, v101, v108
	v_add_f32_e32 v229, v59, v44
	v_ashrrev_i32_e32 v230, 31, v229
	v_or_b32_e32 v230, 0x80000000, v230
	v_xor_b32_e32 v231, v230, v229
	v_and_b32_e32 v231, 0xffffff00, v231
	v_or_b32_e32 v101, 0xcc, v231
	v_add_f32_e32 v229, v60, v31
	v_ashrrev_i32_e32 v230, 31, v229
	v_or_b32_e32 v230, 0x80000000, v230
	v_xor_b32_e32 v231, v230, v229
	v_and_b32_e32 v231, 0xffffff00, v231
	v_or_b32_e32 v102, 0xbf, v231
	v_add_f32_e32 v229, v60, v46
	v_ashrrev_i32_e32 v230, 31, v229
	v_or_b32_e32 v230, 0x80000000, v230
	v_xor_b32_e32 v231, v230, v229
	v_and_b32_e32 v231, 0xffffff00, v231
	v_or_b32_e32 v91, 0xbe, v231
	v_add_f32_e32 v229, v60, v45
	v_ashrrev_i32_e32 v230, 31, v229
	v_or_b32_e32 v230, 0x80000000, v230
	v_xor_b32_e32 v231, v230, v229
	v_and_b32_e32 v231, 0xffffff00, v231
	v_or_b32_e32 v96, 0xbd, v231
	v_add_f32_e32 v229, v61, v31
	v_ashrrev_i32_e32 v230, 31, v229
	v_or_b32_e32 v230, 0x80000000, v230
	v_xor_b32_e32 v231, v230, v229
	v_and_b32_e32 v231, 0xffffff00, v231
	v_or_b32_e32 v97, 0xaf, v231
	v_add_f32_e32 v229, v61, v46
	v_ashrrev_i32_e32 v230, 31, v229
	v_or_b32_e32 v230, 0x80000000, v230
	v_xor_b32_e32 v231, v230, v229
	v_and_b32_e32 v231, 0xffffff00, v231
	v_or_b32_e32 v98, 0xae, v231
	v_add_f32_e32 v229, v62, v31
	v_ashrrev_i32_e32 v230, 31, v229
	v_or_b32_e32 v230, 0x80000000, v230
	v_xor_b32_e32 v231, v230, v229
	v_and_b32_e32 v231, 0xffffff00, v231
	v_or_b32_e32 v74, 0x9f, v231
	v_add_f32_e32 v229, v62, v46
	v_ashrrev_i32_e32 v230, 31, v229
	v_or_b32_e32 v230, 0x80000000, v230
	v_xor_b32_e32 v231, v230, v229
	v_and_b32_e32 v231, 0xffffff00, v231
	v_or_b32_e32 v81, 0x9e, v231
	v_add_f32_e32 v229, v29, v31
	v_ashrrev_i32_e32 v230, 31, v229
	v_or_b32_e32 v230, 0x80000000, v230
	v_xor_b32_e32 v231, v230, v229
	v_and_b32_e32 v231, 0xffffff00, v231
	v_or_b32_e32 v105, 0x8f, v231
	v_add_f32_e32 v229, v29, v46
	v_ashrrev_i32_e32 v230, 31, v229
	v_or_b32_e32 v230, 0x80000000, v230
	v_xor_b32_e32 v231, v230, v229
	v_and_b32_e32 v231, 0xffffff00, v231
	v_or_b32_e32 v80, 0x8e, v231
	v_add_f32_e32 v229, v55, v31
	v_ashrrev_i32_e32 v230, 31, v229
	v_or_b32_e32 v230, 0x80000000, v230
	v_xor_b32_e32 v231, v230, v229
	v_and_b32_e32 v231, 0xffffff00, v231
	v_or_b32_e32 v72, 0x7f, v231
	v_add_f32_e32 v229, v54, v31
	v_ashrrev_i32_e32 v230, 31, v229
	v_or_b32_e32 v230, 0x80000000, v230
	v_xor_b32_e32 v231, v230, v229
	v_and_b32_e32 v231, 0xffffff00, v231
	v_or_b32_e32 v86, 0x6f, v231
	v_add_f32_e32 v229, v53, v31
	v_ashrrev_i32_e32 v230, 31, v229
	v_or_b32_e32 v230, 0x80000000, v230
	v_xor_b32_e32 v231, v230, v229
	v_and_b32_e32 v231, 0xffffff00, v231
	v_or_b32_e32 v104, 0x5f, v231
	v_add_f32_e32 v229, v52, v31
	v_ashrrev_i32_e32 v230, 31, v229
	v_or_b32_e32 v230, 0x80000000, v230
	v_xor_b32_e32 v231, v230, v229
	v_and_b32_e32 v231, 0xffffff00, v231
	v_or_b32_e32 v117, 0x4f, v231
	v_add_f32_e32 v229, v51, v31
	v_ashrrev_i32_e32 v230, 31, v229
	v_or_b32_e32 v230, 0x80000000, v230
	v_xor_b32_e32 v231, v230, v229
	v_and_b32_e32 v231, 0xffffff00, v231
	v_or_b32_e32 v77, 0x3f, v231
	v_add_f32_e32 v229, v50, v31
	v_ashrrev_i32_e32 v230, 31, v229
	v_or_b32_e32 v230, 0x80000000, v230
	v_xor_b32_e32 v231, v230, v229
	v_and_b32_e32 v231, 0xffffff00, v231
	v_or_b32_e32 v70, 0x2f, v231
	v_max_u32_e32 v114, v101, v102
	v_min_u32_e32 v102, v101, v102
	v_min_u32_e32 v101, v91, v96
	v_max_u32_e32 v96, v91, v96
	v_max_u32_e32 v91, v97, v98
	v_min_u32_e32 v98, v97, v98
	v_min_u32_e32 v97, v74, v81
	v_max_u32_e32 v81, v74, v81
	v_max_u32_e32 v74, v105, v80
	v_min_u32_e32 v80, v105, v80
	v_min_u32_e32 v105, v72, v86
	v_max_u32_e32 v86, v72, v86
	v_max_u32_e32 v72, v104, v117
	v_min_u32_e32 v117, v104, v117
	v_min_u32_e32 v104, v77, v70
	v_max_u32_e32 v70, v77, v70
	v_max_u32_e32 v77, v114, v101
	v_min_u32_e32 v101, v114, v101
	v_max_u32_e32 v114, v102, v96
	v_min_u32_e32 v96, v102, v96
	v_min_u32_e32 v102, v91, v97
	v_max_u32_e32 v97, v91, v97
	v_min_u32_e32 v91, v98, v81
	v_max_u32_e32 v81, v98, v81
	v_max_u32_e32 v98, v74, v105
	v_min_u32_e32 v105, v74, v105
	v_max_u32_e32 v74, v80, v86
	v_min_u32_e32 v86, v80, v86
	v_min_u32_e32 v80, v72, v104
	v_max_u32_e32 v104, v72, v104
	v_min_u32_e32 v72, v117, v70
	v_max_u32_e32 v70, v117, v70
	v_max_u32_e32 v117, v77, v114
	v_min_u32_e32 v114, v77, v114
	v_max_u32_e32 v77, v101, v96
	v_min_u32_e32 v96, v101, v96
	v_min_u32_e32 v101, v102, v91
	v_max_u32_e32 v91, v102, v91
; DI float ord2f(unsigned u) { return __uint_as_float((u & 0x80000000u) ? (u ^ 0x80000000u) : ~u); }
; DI void merge_top16(unsigned (&a)[16], const unsigned (&b)[16]) {
; #pragma unroll
;   for (int i = 0; i < 16; ++i) a[i] = max(a[i], b[15 - i]);
; #pragma unroll
;     ...
; #pragma unroll
;     for (int i = 0; i < 16; ++i) {
;       const int j = 1 << js, l = i ^ j;
;       if (l > i) {
;         const unsigned x = a[i], y = a[l];
;         a[i] = max(x, y);
;         a[l] = min(x, y);
;       }
;     }
; }
; template <bool STORE>
; DI void peer_item(const Params& p, int item, char* smem) {
;     ...
;     for (int a = 0; a < 16; ++a)
; #pragma unroll
;       for (int bq = 0; bq < 16; ++bq)
;         if ((a + 1) * (bq + 1) <= 16)
;           ckey[a][bq] = (f2ord(ord2f(top1[a] & ~127u) + ord2f(top2[bq] & ~127u)) & ~255u) | (unsigned)(255 - (a * 16 + bq));
;     unsigned wkey[16];
;     int we[16];
; #pragma unroll
;     for (int r = 0; r < 16; ++r) {
;       unsigned mx = 0u;
; #pragma unroll
;       for (int a = 0; a < 16; ++a)
; #pragma unroll
;         for (int bq = 0; bq < 16; ++bq)
;           if ((a + 1) * (bq + 1) <= 16) mx = max(mx, ckey[a][bq]);
; #pragma unroll
;       for (int a = 0; a < 16; ++a)
; #pragma unroll
;         for (int bq = 0; bq < 16; ++bq)
;           if ((a + 1) * (bq + 1) <= 16) ckey[a][bq] = (ckey[a][bq] == mx) ? 0u : ckey[a][bq];
;       wkey[r] = mx;
	v_min_u32_e32 v102, v97, v81
	v_max_u32_e32 v81, v97, v81
	v_max_u32_e32 v97, v98, v74
	v_min_u32_e32 v74, v98, v74
	v_max_u32_e32 v98, v105, v86
	v_min_u32_e32 v86, v105, v86
	v_min_u32_e32 v105, v80, v72
	v_max_u32_e32 v72, v80, v72
	v_min_u32_e32 v80, v104, v70
	v_max_u32_e32 v70, v104, v70
	v_max_u32_e32 v104, v117, v101
	v_min_u32_e32 v101, v117, v101
	v_max_u32_e32 v117, v114, v91
	v_min_u32_e32 v91, v114, v91
	v_max_u32_e32 v114, v77, v102
	v_min_u32_e32 v102, v77, v102
	v_max_u32_e32 v77, v96, v81
	v_min_u32_e32 v81, v96, v81
	v_min_u32_e32 v96, v97, v105
	v_max_u32_e32 v105, v97, v105
	v_min_u32_e32 v97, v74, v72
	v_max_u32_e32 v72, v74, v72
	v_min_u32_e32 v74, v98, v80
	v_max_u32_e32 v80, v98, v80
	v_min_u32_e32 v98, v86, v70
	v_max_u32_e32 v70, v86, v70
	v_max_u32_e32 v86, v104, v114
	v_min_u32_e32 v114, v104, v114
	v_max_u32_e32 v104, v117, v77
	v_min_u32_e32 v77, v117, v77
	v_max_u32_e32 v117, v101, v102
	v_min_u32_e32 v102, v101, v102
	v_max_u32_e32 v101, v91, v81
	v_min_u32_e32 v81, v91, v81
	v_min_u32_e32 v91, v96, v74
	v_max_u32_e32 v74, v96, v74
	v_min_u32_e32 v96, v97, v98
	v_max_u32_e32 v98, v97, v98
	v_min_u32_e32 v97, v105, v80
	v_max_u32_e32 v80, v105, v80
	v_min_u32_e32 v105, v72, v70
	v_max_u32_e32 v70, v72, v70
	v_max_u32_e32 v72, v86, v104
	v_min_u32_e32 v104, v86, v104
	v_max_u32_e32 v86, v114, v77
	v_min_u32_e32 v77, v114, v77
	v_max_u32_e32 v114, v117, v101
	v_min_u32_e32 v101, v117, v101
	v_max_u32_e32 v117, v102, v81
	v_min_u32_e32 v81, v102, v81
	v_min_u32_e32 v102, v91, v96
	v_max_u32_e32 v96, v91, v96
	v_min_u32_e32 v91, v74, v98
	v_max_u32_e32 v98, v74, v98
	v_min_u32_e32 v74, v97, v105
	v_max_u32_e32 v105, v97, v105
	v_min_u32_e32 v97, v80, v70
	v_max_u32_e32 v70, v80, v70
	v_max_u32_e32 v80, v72, v102
	v_min_u32_e32 v102, v72, v102
	v_max_u32_e32 v72, v104, v96
	v_min_u32_e32 v96, v104, v96
	v_max_u32_e32 v104, v86, v91
	v_min_u32_e32 v91, v86, v91
	v_max_u32_e32 v86, v77, v98
	v_min_u32_e32 v98, v77, v98
	v_max_u32_e32 v77, v114, v74
	v_min_u32_e32 v74, v114, v74
	v_max_u32_e32 v114, v101, v105
	v_min_u32_e32 v105, v101, v105
	v_max_u32_e32 v101, v117, v97
	v_min_u32_e32 v97, v117, v97
	v_max_u32_e32 v117, v81, v70
	v_min_u32_e32 v70, v81, v70
	v_max_u32_e32 v81, v80, v77
	v_min_u32_e32 v77, v80, v77
	v_max_u32_e32 v80, v72, v114
	v_min_u32_e32 v114, v72, v114
	v_max_u32_e32 v72, v104, v101
	v_min_u32_e32 v101, v104, v101
	v_max_u32_e32 v104, v86, v117
	v_min_u32_e32 v117, v86, v117
	v_max_u32_e32 v86, v102, v74
	v_min_u32_e32 v74, v102, v74
	v_max_u32_e32 v102, v96, v105
	v_min_u32_e32 v105, v96, v105
	v_max_u32_e32 v96, v91, v97
	v_min_u32_e32 v97, v91, v97
	v_max_u32_e32 v91, v98, v70
	v_min_u32_e32 v70, v98, v70
	v_max_u32_e32 v98, v81, v72
	v_min_u32_e32 v72, v81, v72
	v_max_u32_e32 v81, v80, v104
	v_min_u32_e32 v104, v80, v104
	v_max_u32_e32 v80, v77, v101
	v_min_u32_e32 v101, v77, v101
	v_max_u32_e32 v77, v114, v117
	v_min_u32_e32 v117, v114, v117
	v_max_u32_e32 v114, v86, v96
	v_min_u32_e32 v96, v86, v96
	v_max_u32_e32 v86, v102, v91
	v_min_u32_e32 v91, v102, v91
	v_max_u32_e32 v102, v74, v97
	v_min_u32_e32 v97, v74, v97
	v_max_u32_e32 v74, v105, v70
	v_min_u32_e32 v70, v105, v70
	v_max_u32_e32 v105, v98, v81
	v_min_u32_e32 v81, v98, v81
	v_max_u32_e32 v98, v72, v104
	v_min_u32_e32 v104, v72, v104
	v_max_u32_e32 v72, v80, v77
	v_min_u32_e32 v77, v80, v77
	v_max_u32_e32 v80, v101, v117
	v_min_u32_e32 v117, v101, v117
	v_max_u32_e32 v101, v114, v86
	v_min_u32_e32 v86, v114, v86
	v_max_u32_e32 v114, v96, v91
	v_min_u32_e32 v91, v96, v91
	v_max_u32_e32 v96, v102, v74
	v_min_u32_e32 v74, v102, v74
	v_max_u32_e32 v102, v97, v70
	v_min_u32_e32 v70, v97, v70
	v_add_f32_e32 v229, v49, v31
	v_ashrrev_i32_e32 v230, 31, v229
	v_or_b32_e32 v230, 0x80000000, v230
	v_xor_b32_e32 v231, v230, v229
	v_and_b32_e32 v231, 0xffffff00, v231
	v_or_b32_e32 v97, 0x1f, v231
	v_add_f32_e32 v229, v48, v31
	v_ashrrev_i32_e32 v230, 31, v229
	v_or_b32_e32 v230, 0x80000000, v230
	v_xor_b32_e32 v231, v230, v229
	v_and_b32_e32 v231, 0xffffff00, v231
	v_or_b32_e32 v84, 0xf, v231
	v_mov_b32_e32 v71, 0
	v_mov_b32_e32 v82, 0
	v_mov_b32_e32 v75, 0
	v_mov_b32_e32 v87, 0
	v_mov_b32_e32 v78, 0
	v_mov_b32_e32 v110, 0
	v_mov_b32_e32 v93, 0
	v_mov_b32_e32 v76, 0
	v_mov_b32_e32 v95, 0
	v_mov_b32_e32 v99, 0
	v_mov_b32_e32 v73, 0
	v_mov_b32_e32 v94, 0
	v_mov_b32_e32 v113, 0
	v_mov_b32_e32 v69, 0
	v_max_u32_e32 v92, v97, v84
	v_min_u32_e32 v84, v97, v84
	v_max_u32_e32 v97, v105, v69
	v_max_u32_e32 v105, v81, v113
	v_max_u32_e32 v81, v98, v94
	v_max_u32_e32 v98, v104, v73
	v_max_u32_e32 v104, v72, v99
	v_max_u32_e32 v72, v77, v95
	v_max_u32_e32 v77, v80, v76
	v_max_u32_e32 v80, v117, v93
	v_max_u32_e32 v117, v101, v110
	v_max_u32_e32 v101, v86, v78
	v_max_u32_e32 v86, v114, v87
	v_max_u32_e32 v114, v91, v75
	v_max_u32_e32 v91, v96, v82
	v_max_u32_e32 v96, v74, v71
	v_max_u32_e32 v74, v102, v84
	v_max_u32_e32 v102, v70, v92
	v_max_u32_e32 v69, v97, v117
	v_min_u32_e32 v117, v97, v117
	v_max_u32_e32 v97, v105, v101
	v_min_u32_e32 v101, v105, v101
	v_max_u32_e32 v105, v81, v86
	v_min_u32_e32 v86, v81, v86
	v_max_u32_e32 v81, v98, v114
	v_min_u32_e32 v114, v98, v114
	v_max_u32_e32 v98, v104, v91
	v_min_u32_e32 v91, v104, v91
	v_max_u32_e32 v104, v72, v96
	v_min_u32_e32 v96, v72, v96
	v_max_u32_e32 v72, v77, v74
	v_min_u32_e32 v74, v77, v74
	v_max_u32_e32 v77, v80, v102
	v_min_u32_e32 v102, v80, v102
	v_max_u32_e32 v80, v69, v98
	v_min_u32_e32 v98, v69, v98
	v_max_u32_e32 v69, v97, v104
	v_min_u32_e32 v104, v97, v104
	v_max_u32_e32 v97, v105, v72
	v_min_u32_e32 v72, v105, v72
	v_max_u32_e32 v105, v81, v77
	v_min_u32_e32 v77, v81, v77
; DI void merge_top16(unsigned (&a)[16], const unsigned (&b)[16]) {
; #pragma unroll
;   for (int i = 0; i < 16; ++i) a[i] = max(a[i], b[15 - i]);
; #pragma unroll
;     ...
; #pragma unroll
;     for (int i = 0; i < 16; ++i) {
;       const int j = 1 << js, l = i ^ j;
;       if (l > i) {
;         const unsigned x = a[i], y = a[l];
;         a[i] = max(x, y);
;         a[l] = min(x, y);
;       }
;     }
; }
; template <bool STORE>
; DI void peer_item(const Params& p, int item, char* smem) {
;     ...
;       const int cidx = 255 - (int)(mx & 255u);
;       const int wa = cidx >> 4, wb = cidx & 15;
;       unsigned t1 = top1[0], t2 = top2[0];
; #pragma unroll
;       for (int a = 1; a < 16; ++a) { t1 = (wa == a) ? top1[a] : t1; t2 = (wb == a) ? top2[a] : t2; }
;       we[r] = (127 - (int)(t1 & 127u)) * 128 + (127 - (int)(t2 & 127u));
	v_max_u32_e32 v81, v117, v91
	v_min_u32_e32 v91, v117, v91
	v_max_u32_e32 v117, v101, v96
	v_min_u32_e32 v96, v101, v96
	v_max_u32_e32 v101, v86, v74
	v_min_u32_e32 v74, v86, v74
	v_max_u32_e32 v86, v114, v102
	v_min_u32_e32 v102, v114, v102
	v_max_u32_e32 v114, v80, v97
	v_min_u32_e32 v97, v80, v97
	v_max_u32_e32 v80, v69, v105
	v_min_u32_e32 v105, v69, v105
	v_max_u32_e32 v69, v98, v72
	v_min_u32_e32 v72, v98, v72
	v_max_u32_e32 v98, v104, v77
	v_min_u32_e32 v77, v104, v77
	v_max_u32_e32 v104, v81, v101
	v_min_u32_e32 v101, v81, v101
	v_max_u32_e32 v81, v117, v86
	v_min_u32_e32 v86, v117, v86
	v_max_u32_e32 v117, v91, v74
	v_min_u32_e32 v74, v91, v74
	v_max_u32_e32 v91, v96, v102
	v_min_u32_e32 v102, v96, v102
	v_max_u32_e32 v96, v114, v80
	v_min_u32_e32 v80, v114, v80
	v_max_u32_e32 v114, v97, v105
	v_min_u32_e32 v105, v97, v105
	v_max_u32_e32 v97, v69, v98
	v_min_u32_e32 v98, v69, v98
	v_max_u32_e32 v69, v72, v77
	v_min_u32_e32 v77, v72, v77
	v_max_u32_e32 v72, v104, v81
	v_min_u32_e32 v81, v104, v81
	v_max_u32_e32 v104, v101, v86
	v_min_u32_e32 v86, v101, v86
	v_max_u32_e32 v101, v117, v91
	v_min_u32_e32 v91, v117, v91
	v_max_u32_e32 v117, v74, v102
	v_min_u32_e32 v102, v74, v102
	v_max_u32_e32 v74, v115, v102
	v_max_u32_e32 v115, v89, v117
	v_max_u32_e32 v89, v90, v91
	v_max_u32_e32 v90, v15, v101
	v_max_u32_e32 v15, v103, v86
	v_max_u32_e32 v103, v83, v104
	v_max_u32_e32 v83, v100, v81
	v_max_u32_e32 v100, v112, v72
	v_max_u32_e32 v112, v85, v77
	v_max_u32_e32 v85, v111, v69
	v_max_u32_e32 v111, v106, v98
	v_max_u32_e32 v106, v88, v97
	v_max_u32_e32 v88, v109, v105
	v_max_u32_e32 v109, v79, v114
	v_max_u32_e32 v79, v116, v80
	v_max_u32_e32 v116, v108, v96
	v_max_u32_e32 v102, v74, v112
	v_min_u32_e32 v112, v74, v112
	v_max_u32_e32 v74, v115, v85
	v_min_u32_e32 v85, v115, v85
	v_max_u32_e32 v115, v89, v111
	v_min_u32_e32 v111, v89, v111
	v_max_u32_e32 v89, v90, v106
	v_min_u32_e32 v106, v90, v106
	v_max_u32_e32 v90, v15, v88
	v_min_u32_e32 v88, v15, v88
	v_max_u32_e32 v15, v103, v109
	v_min_u32_e32 v109, v103, v109
	v_max_u32_e32 v103, v83, v79
	v_min_u32_e32 v79, v83, v79
	v_max_u32_e32 v83, v100, v116
	v_min_u32_e32 v116, v100, v116
	v_max_u32_e32 v100, v102, v90
	v_min_u32_e32 v90, v102, v90
	v_max_u32_e32 v102, v74, v15
	v_min_u32_e32 v15, v74, v15
	v_max_u32_e32 v74, v115, v103
	v_min_u32_e32 v103, v115, v103
	v_max_u32_e32 v115, v89, v83
	v_min_u32_e32 v83, v89, v83
	v_max_u32_e32 v89, v112, v88
	v_min_u32_e32 v88, v112, v88
	v_max_u32_e32 v112, v85, v109
	v_min_u32_e32 v109, v85, v109
	v_max_u32_e32 v85, v111, v79
	v_min_u32_e32 v79, v111, v79
	v_max_u32_e32 v111, v106, v116
	v_min_u32_e32 v116, v106, v116
	v_max_u32_e32 v106, v100, v74
	v_min_u32_e32 v74, v100, v74
	v_max_u32_e32 v100, v102, v115
	v_min_u32_e32 v115, v102, v115
	v_max_u32_e32 v102, v90, v103
	v_min_u32_e32 v103, v90, v103
	v_max_u32_e32 v90, v15, v83
	v_min_u32_e32 v83, v15, v83
	v_max_u32_e32 v15, v89, v85
	v_min_u32_e32 v85, v89, v85
	v_max_u32_e32 v89, v112, v111
	v_min_u32_e32 v111, v112, v111
	v_max_u32_e32 v112, v88, v79
	v_min_u32_e32 v79, v88, v79
	v_max_u32_e32 v88, v109, v116
	v_min_u32_e32 v116, v109, v116
	v_max_u32_e32 v109, v106, v100
	v_min_u32_e32 v100, v106, v100
	v_max_u32_e32 v106, v74, v115
	v_min_u32_e32 v115, v74, v115
	v_max_u32_e32 v74, v102, v90
	v_min_u32_e32 v90, v102, v90
	v_max_u32_e32 v102, v103, v83
	v_min_u32_e32 v83, v103, v83
	v_max_u32_e32 v103, v15, v89
	v_min_u32_e32 v89, v15, v89
	v_max_u32_e32 v15, v85, v111
	v_min_u32_e32 v111, v85, v111
	v_max_u32_e32 v85, v112, v88
	v_min_u32_e32 v88, v112, v88
	v_max_u32_e32 v112, v79, v116
	v_min_u32_e32 v116, v79, v116
	s_waitcnt lgkmcnt(0)
	v_not_b32_e32 v229, v109
	v_bfe_u32 v230, v229, 4, 4
	v_and_b32_e32 v231, 15, v229
	v_add_u32_e32 v230, v241, v230
	v_add_u32_e32 v231, v241, v231
	ds_read_u8 v79, v230
	ds_read_u8 v108, v231 offset:16
	v_not_b32_e32 v229, v100
	v_bfe_u32 v230, v229, 4, 4
	v_and_b32_e32 v231, 15, v229
	v_add_u32_e32 v230, v241, v230
	v_add_u32_e32 v231, v241, v231
	ds_read_u8 v117, v230
	ds_read_u8 v113, v231 offset:16
	v_not_b32_e32 v229, v106
	v_bfe_u32 v230, v229, 4, 4
	v_and_b32_e32 v231, 15, v229
	v_add_u32_e32 v230, v241, v230
	v_add_u32_e32 v231, v241, v231
	ds_read_u8 v91, v230
	ds_read_u8 v94, v231 offset:16
	v_not_b32_e32 v229, v115
	v_bfe_u32 v230, v229, 4, 4
	v_and_b32_e32 v231, 15, v229
	v_add_u32_e32 v230, v241, v230
	v_add_u32_e32 v231, v241, v231
	ds_read_u8 v101, v230
	ds_read_u8 v73, v231 offset:16
	v_not_b32_e32 v229, v74
	v_bfe_u32 v230, v229, 4, 4
	v_and_b32_e32 v231, 15, v229
	v_add_u32_e32 v230, v241, v230
	v_add_u32_e32 v231, v241, v231
	ds_read_u8 v86, v230
	ds_read_u8 v99, v231 offset:16
	v_not_b32_e32 v229, v90
	v_bfe_u32 v230, v229, 4, 4
	v_and_b32_e32 v231, 15, v229
	v_add_u32_e32 v230, v241, v230
	v_add_u32_e32 v231, v241, v231
	ds_read_u8 v104, v230
	ds_read_u8 v95, v231 offset:16
	v_not_b32_e32 v229, v102
	v_bfe_u32 v230, v229, 4, 4
	v_and_b32_e32 v231, 15, v229
	v_add_u32_e32 v230, v241, v230
	v_add_u32_e32 v231, v241, v231
	ds_read_u8 v81, v230
	ds_read_u8 v76, v231 offset:16
	v_not_b32_e32 v229, v83
	v_bfe_u32 v230, v229, 4, 4
	v_and_b32_e32 v231, 15, v229
	v_add_u32_e32 v230, v241, v230
	v_add_u32_e32 v231, v241, v231
	ds_read_u8 v72, v230
	ds_read_u8 v93, v231 offset:16
	v_not_b32_e32 v229, v103
	v_bfe_u32 v230, v229, 4, 4
	v_and_b32_e32 v231, 15, v229
	v_add_u32_e32 v230, v241, v230
	v_add_u32_e32 v231, v241, v231
	ds_read_u8 v77, v230
	ds_read_u8 v110, v231 offset:16
	v_not_b32_e32 v229, v89
	v_bfe_u32 v230, v229, 4, 4
	v_and_b32_e32 v231, 15, v229
	v_add_u32_e32 v230, v241, v230
	v_add_u32_e32 v231, v241, v231
; DI float ord2f(unsigned u) { return __uint_as_float((u & 0x80000000u) ? (u ^ 0x80000000u) : ~u); }
; template <bool STORE>
; DI void peer_item(const Params& p, int item, char* smem) {
;     ...
;       const int wa = cidx >> 4, wb = cidx & 15;
;       unsigned t1 = top1[0], t2 = top2[0];
; #pragma unroll
;       for (int a = 1; a < 16; ++a) { t1 = (wa == a) ? top1[a] : t1; t2 = (wb == a) ? top2[a] : t2; }
;       we[r] = (127 - (int)(t1 & 127u)) * 128 + (127 - (int)(t2 & 127u));
;     }
;     float cs0 = ord2f(wkey[0] & ~255u);
;     float ex[16], sum = 0.f;
; #pragma unroll
;     for (int r = 0; r < 16; ++r) { ex[r] = __expf(ord2f(wkey[r] & ~255u) - cs0); sum += ex[r]; }
;     float inv = 1.f / sum;
	ds_read_u8 v69, v230
	ds_read_u8 v78, v231 offset:16
	v_not_b32_e32 v229, v15
	v_bfe_u32 v230, v229, 4, 4
	v_and_b32_e32 v231, 15, v229
	v_add_u32_e32 v230, v241, v230
	v_add_u32_e32 v231, v241, v231
	ds_read_u8 v98, v230
	ds_read_u8 v87, v231 offset:16
	v_not_b32_e32 v229, v111
	v_bfe_u32 v230, v229, 4, 4
	v_and_b32_e32 v231, 15, v229
	v_add_u32_e32 v230, v241, v230
	v_add_u32_e32 v231, v241, v231
	ds_read_u8 v97, v230
	ds_read_u8 v75, v231 offset:16
	v_not_b32_e32 v229, v85
	v_bfe_u32 v230, v229, 4, 4
	v_and_b32_e32 v231, 15, v229
	v_add_u32_e32 v230, v241, v230
	v_add_u32_e32 v231, v241, v231
	ds_read_u8 v105, v230
	ds_read_u8 v82, v231 offset:16
	v_not_b32_e32 v229, v88
	v_bfe_u32 v230, v229, 4, 4
	v_and_b32_e32 v231, 15, v229
	v_add_u32_e32 v230, v241, v230
	v_add_u32_e32 v231, v241, v231
	ds_read_u8 v114, v230
	ds_read_u8 v71, v231 offset:16
	v_not_b32_e32 v229, v112
	v_bfe_u32 v230, v229, 4, 4
	v_and_b32_e32 v231, 15, v229
	v_add_u32_e32 v230, v241, v230
	v_add_u32_e32 v231, v241, v231
	ds_read_u8 v80, v230
	ds_read_u8 v84, v231 offset:16
	v_not_b32_e32 v229, v116
	v_bfe_u32 v230, v229, 4, 4
	v_and_b32_e32 v231, 15, v229
	v_add_u32_e32 v230, v241, v230
	v_add_u32_e32 v231, v241, v231
	ds_read_u8 v96, v230
	ds_read_u8 v92, v231 offset:16
	v_and_b32_e32 v229, 0xffffff00, v109
	v_ashrrev_i32_e32 v230, 31, v229
	v_not_b32_e32 v230, v230
	v_or_b32_e32 v230, 0x80000000, v230
	v_xor_b32_e32 v48, v230, v229
	v_and_b32_e32 v229, 0xffffff00, v100
	v_ashrrev_i32_e32 v230, 31, v229
	v_not_b32_e32 v230, v230
	v_or_b32_e32 v230, 0x80000000, v230
	v_xor_b32_e32 v49, v230, v229
	v_and_b32_e32 v229, 0xffffff00, v106
	v_ashrrev_i32_e32 v230, 31, v229
	v_not_b32_e32 v230, v230
	v_or_b32_e32 v230, 0x80000000, v230
	v_xor_b32_e32 v50, v230, v229
	v_and_b32_e32 v229, 0xffffff00, v115
	v_ashrrev_i32_e32 v230, 31, v229
	v_not_b32_e32 v230, v230
	v_or_b32_e32 v230, 0x80000000, v230
	v_xor_b32_e32 v51, v230, v229
	v_and_b32_e32 v229, 0xffffff00, v74
	v_ashrrev_i32_e32 v230, 31, v229
	v_not_b32_e32 v230, v230
	v_or_b32_e32 v230, 0x80000000, v230
	v_xor_b32_e32 v52, v230, v229
	v_and_b32_e32 v229, 0xffffff00, v90
	v_ashrrev_i32_e32 v230, 31, v229
	v_not_b32_e32 v230, v230
	v_or_b32_e32 v230, 0x80000000, v230
	v_xor_b32_e32 v53, v230, v229
	v_and_b32_e32 v229, 0xffffff00, v102
	v_ashrrev_i32_e32 v230, 31, v229
	v_not_b32_e32 v230, v230
	v_or_b32_e32 v230, 0x80000000, v230
	v_xor_b32_e32 v54, v230, v229
	v_and_b32_e32 v229, 0xffffff00, v83
	v_ashrrev_i32_e32 v230, 31, v229
	v_not_b32_e32 v230, v230
	v_or_b32_e32 v230, 0x80000000, v230
	v_xor_b32_e32 v55, v230, v229
	v_and_b32_e32 v229, 0xffffff00, v103
	v_ashrrev_i32_e32 v230, 31, v229
	v_not_b32_e32 v230, v230
	v_or_b32_e32 v230, 0x80000000, v230
	v_xor_b32_e32 v29, v230, v229
	v_and_b32_e32 v229, 0xffffff00, v89
	v_ashrrev_i32_e32 v230, 31, v229
	v_not_b32_e32 v230, v230
	v_or_b32_e32 v230, 0x80000000, v230
	v_xor_b32_e32 v62, v230, v229
	v_and_b32_e32 v229, 0xffffff00, v15
	v_ashrrev_i32_e32 v230, 31, v229
	v_not_b32_e32 v230, v230
	v_or_b32_e32 v230, 0x80000000, v230
	v_xor_b32_e32 v61, v230, v229
	v_and_b32_e32 v229, 0xffffff00, v111
	v_ashrrev_i32_e32 v230, 31, v229
	v_not_b32_e32 v230, v230
	v_or_b32_e32 v230, 0x80000000, v230
	v_xor_b32_e32 v60, v230, v229
	v_and_b32_e32 v229, 0xffffff00, v85
	v_ashrrev_i32_e32 v230, 31, v229
	v_not_b32_e32 v230, v230
	v_or_b32_e32 v230, 0x80000000, v230
	v_xor_b32_e32 v59, v230, v229
	v_and_b32_e32 v229, 0xffffff00, v88
	v_ashrrev_i32_e32 v230, 31, v229
	v_not_b32_e32 v230, v230
	v_or_b32_e32 v230, 0x80000000, v230
	v_xor_b32_e32 v58, v230, v229
	v_and_b32_e32 v229, 0xffffff00, v112
	v_ashrrev_i32_e32 v230, 31, v229
	v_not_b32_e32 v230, v230
	v_or_b32_e32 v230, 0x80000000, v230
	v_xor_b32_e32 v57, v230, v229
	v_and_b32_e32 v229, 0xffffff00, v116
	v_ashrrev_i32_e32 v230, 31, v229
	v_not_b32_e32 v230, v230
	v_or_b32_e32 v230, 0x80000000, v230
	v_xor_b32_e32 v56, v230, v229
	v_sub_f32_e32 v56, v56, v48
	v_sub_f32_e32 v57, v57, v48
	v_sub_f32_e32 v58, v58, v48
	v_sub_f32_e32 v59, v59, v48
	v_sub_f32_e32 v60, v60, v48
	v_sub_f32_e32 v61, v61, v48
	v_sub_f32_e32 v62, v62, v48
	v_sub_f32_e32 v29, v29, v48
	v_sub_f32_e32 v55, v55, v48
	v_sub_f32_e32 v54, v54, v48
	v_sub_f32_e32 v53, v53, v48
	v_sub_f32_e32 v52, v52, v48
	v_sub_f32_e32 v51, v51, v48
	v_sub_f32_e32 v50, v50, v48
	v_sub_f32_e32 v49, v49, v48
	v_sub_f32_e32 v48, v48, v48
	v_mul_f32_e32 v48, 0x3fb8aa3b, v48
	v_mul_f32_e32 v49, 0x3fb8aa3b, v49
	v_mul_f32_e32 v50, 0x3fb8aa3b, v50
	v_mul_f32_e32 v51, 0x3fb8aa3b, v51
	v_mul_f32_e32 v52, 0x3fb8aa3b, v52
	v_mul_f32_e32 v53, 0x3fb8aa3b, v53
	v_mul_f32_e32 v54, 0x3fb8aa3b, v54
	v_mul_f32_e32 v55, 0x3fb8aa3b, v55
	v_mul_f32_e32 v29, 0x3fb8aa3b, v29
	v_mul_f32_e32 v62, 0x3fb8aa3b, v62
	v_mul_f32_e32 v61, 0x3fb8aa3b, v61
	v_mul_f32_e32 v60, 0x3fb8aa3b, v60
	v_mul_f32_e32 v59, 0x3fb8aa3b, v59
	v_mul_f32_e32 v58, 0x3fb8aa3b, v58
	v_mul_f32_e32 v57, 0x3fb8aa3b, v57
	v_mul_f32_e32 v56, 0x3fb8aa3b, v56
	v_exp_f32_e32 v48, v48
	v_exp_f32_e32 v49, v49
	v_exp_f32_e32 v50, v50
	v_exp_f32_e32 v51, v51
	v_exp_f32_e32 v52, v52
	v_exp_f32_e32 v53, v53
	v_exp_f32_e32 v54, v54
	v_exp_f32_e32 v55, v55
	v_exp_f32_e32 v29, v29
	v_exp_f32_e32 v62, v62
	v_exp_f32_e32 v61, v61
	v_exp_f32_e32 v60, v60
	v_exp_f32_e32 v59, v59
	v_exp_f32_e32 v58, v58
	v_exp_f32_e32 v57, v57
	v_exp_f32_e32 v56, v56
	s_nop 0
	v_add_f32_e32 v232, v48, v49
	v_add_f32_e32 v232, v232, v50
	v_add_f32_e32 v232, v232, v51
	v_add_f32_e32 v232, v232, v52
	v_add_f32_e32 v232, v232, v53
	v_add_f32_e32 v232, v232, v54
	v_add_f32_e32 v232, v232, v55
	v_add_f32_e32 v232, v232, v29
	v_add_f32_e32 v232, v232, v62
	v_add_f32_e32 v232, v232, v61
	v_add_f32_e32 v232, v232, v60
	v_add_f32_e32 v232, v232, v59
	v_add_f32_e32 v232, v232, v58
	v_add_f32_e32 v232, v232, v57
	v_add_f32_e32 v232, v232, v56
	v_div_scale_f32 v246, s[8:9], v232, v232, 1.0
	v_rcp_f32_e32 v247, v246
	s_nop 0
	v_fma_f32 v248, -v246, v247, 1.0
	v_fmac_f32_e32 v247, v248, v247
	v_div_scale_f32 v249, vcc, 1.0, v232, 1.0
	v_mul_f32_e32 v250, v249, v247
	v_fma_f32 v251, -v246, v250, v249
	v_fmac_f32_e32 v250, v251, v247
	v_fma_f32 v246, -v246, v250, v249
	s_nop 1
	v_div_fmas_f32 v246, v246, v247, v250
	v_div_fixup_f32 v247, v246, v232, 1.0
	v_mul_f32_e32 v48, v48, v247
	v_mul_f32_e32 v49, v49, v247
	v_mul_f32_e32 v50, v50, v247
	v_mul_f32_e32 v51, v51, v247
	v_mul_f32_e32 v52, v52, v247
	v_mul_f32_e32 v53, v53, v247
	v_mul_f32_e32 v54, v54, v247
	v_mul_f32_e32 v55, v55, v247
	v_mul_f32_e32 v29, v29, v247
	v_mul_f32_e32 v62, v62, v247
	v_mul_f32_e32 v61, v61, v247
	v_mul_f32_e32 v60, v60, v247
	v_mul_f32_e32 v59, v59, v247
	v_mul_f32_e32 v58, v58, v247
	v_mul_f32_e32 v57, v57, v247
	v_mul_f32_e32 v56, v56, v247
	s_waitcnt lgkmcnt(0)
; DI float ord2f(unsigned u) { return __uint_as_float((u & 0x80000000u) ? (u ^ 0x80000000u) : ~u); }
; template <bool STORE>
; DI void peer_item(const Params& p, int item, char* smem) {
;     ...
;       we[r] = (127 - (int)(t1 & 127u)) * 128 + (127 - (int)(t2 & 127u));
;     }
;     float cs0 = ord2f(wkey[0] & ~255u);
;     float ex[16], sum = 0.f;
; #pragma unroll
;     for (int r = 0; r < 16; ++r) { ex[r] = __expf(ord2f(wkey[r] & ~255u) - cs0); sum += ex[r]; }
;     float inv = 1.f / sum;
;     if (hh == 0) {
; #pragma unroll
;       for (int r = 0; r < 16; ++r) {
;         e_s[lr * 128 + hd * 16 + r] = we[r];
;         g_s[lr * 128 + hd * 16 + r] = ex[r] * inv;
;       }
;     }
	v_lshl_or_b32 v32, v79, 7, v108
	v_lshl_or_b32 v33, v117, 7, v113
	v_lshl_or_b32 v34, v91, 7, v94
	v_lshl_or_b32 v35, v101, 7, v73
	v_lshl_or_b32 v36, v86, 7, v99
	v_lshl_or_b32 v37, v104, 7, v95
	v_lshl_or_b32 v38, v81, 7, v76
	v_lshl_or_b32 v39, v72, 7, v93
	v_lshl_or_b32 v40, v77, 7, v110
	v_lshl_or_b32 v41, v69, 7, v78
	v_lshl_or_b32 v42, v98, 7, v87
	v_lshl_or_b32 v43, v97, 7, v75
	v_lshl_or_b32 v44, v105, 7, v82
	v_lshl_or_b32 v45, v114, 7, v71
	v_lshl_or_b32 v46, v80, 7, v84
	v_lshl_or_b32 v31, v96, 7, v92
	ds_write_b32 v242, v32 offset:0
	ds_write_b32 v242, v48 offset:16384
	ds_write_b32 v242, v33 offset:4
	ds_write_b32 v242, v49 offset:16388
	ds_write_b32 v242, v34 offset:8
	ds_write_b32 v242, v50 offset:16392
	ds_write_b32 v242, v35 offset:12
	ds_write_b32 v242, v51 offset:16396
	ds_write_b32 v242, v36 offset:16
	ds_write_b32 v242, v52 offset:16400
	ds_write_b32 v242, v37 offset:20
	ds_write_b32 v242, v53 offset:16404
	ds_write_b32 v242, v38 offset:24
	ds_write_b32 v242, v54 offset:16408
	ds_write_b32 v242, v39 offset:28
	ds_write_b32 v242, v55 offset:16412
	ds_write_b32 v242, v40 offset:32
	ds_write_b32 v242, v29 offset:16416
	ds_write_b32 v242, v41 offset:36
	ds_write_b32 v242, v62 offset:16420
	ds_write_b32 v242, v42 offset:40
	ds_write_b32 v242, v61 offset:16424
	ds_write_b32 v242, v43 offset:44
	ds_write_b32 v242, v60 offset:16428
	ds_write_b32 v242, v44 offset:48
	ds_write_b32 v242, v59 offset:16432
	ds_write_b32 v242, v45 offset:52
	ds_write_b32 v242, v58 offset:16436
	ds_write_b32 v242, v46 offset:56
	ds_write_b32 v242, v57 offset:16440
	ds_write_b32 v242, v31 offset:60
	ds_write_b32 v242, v56 offset:16444
	ds_read_b32 v3, v240 offset:512
	ds_read_b32 v53, v240 offset:768
	ds_read_b32 v64, v240 offset:1024
	ds_read_b32 v65, v240 offset:1280
	ds_read_b32 v66, v240 offset:1536
	ds_read_b32 v67, v240 offset:1792
	ds_read_b32 v68, v240 offset:2048
	ds_read_b32 v69, v240 offset:2304
	ds_read_b32 v70, v240 offset:2560
	ds_read_b32 v71, v240 offset:2816
	ds_read_b32 v72, v240 offset:3072
	ds_read_b32 v73, v240 offset:3328
	ds_read_b32 v74, v240 offset:3584
	ds_read_b32 v75, v240 offset:3840
	ds_read_b32 v76, v240 offset:4096
	ds_read_b32 v77, v240 offset:4352
	ds_read_b32 v78, v240 offset:4608
	ds_read_b32 v79, v240 offset:4864
	ds_read_b32 v80, v240 offset:5120
	ds_read_b32 v81, v240 offset:5376
	ds_read_b32 v82, v240 offset:5632
	ds_read_b32 v83, v240 offset:5888
	ds_read_b32 v84, v240 offset:6144
	ds_read_b32 v96, v240 offset:6400
	v_readlane_b32 s6, v254, 0
	v_readlane_b32 s7, v254, 1
	v_readlane_b32 s12, v254, 2
	v_readlane_b32 s13, v254, 3
	v_readlane_b32 s14, v254, 4
	v_readlane_b32 s15, v254, 5
	v_readlane_b32 s16, v254, 6
	v_readlane_b32 s17, v254, 7
	v_readlane_b32 s18, v254, 8
	v_readlane_b32 s19, v254, 9
	v_readlane_b32 s20, v254, 10
	v_readlane_b32 s21, v254, 11
	v_readlane_b32 s22, v254, 12
	v_readlane_b32 s23, v254, 13
	v_readlane_b32 s24, v254, 14
	v_readlane_b32 s25, v254, 15
	v_readlane_b32 s26, v254, 16
	v_readlane_b32 s27, v254, 17
	v_readlane_b32 s28, v254, 18
	v_readlane_b32 s29, v254, 19
	v_readlane_b32 s30, v254, 20
	v_readlane_b32 s31, v254, 21
	v_readlane_b32 s33, v254, 22
	v_readlane_b32 s34, v254, 23
	v_readlane_b32 s35, v254, 24
	v_readlane_b32 s36, v254, 25
	v_readlane_b32 s37, v254, 26
	v_readlane_b32 s38, v254, 27
	v_readlane_b32 s39, v254, 28
	v_readlane_b32 s40, v254, 29
	v_readlane_b32 s41, v254, 30
	v_readlane_b32 s42, v254, 31
	v_readlane_b32 s44, v254, 32
	v_readlane_b32 s45, v254, 33
	v_readlane_b32 s48, v254, 34
	v_readlane_b32 s49, v254, 35
	v_readlane_b32 s50, v254, 36
	v_readlane_b32 s51, v254, 37
	v_readlane_b32 s52, v254, 38
	v_readlane_b32 s53, v254, 39
	v_readlane_b32 s55, v254, 40
	v_readlane_b32 s60, v254, 41
	v_readlane_b32 s61, v254, 42
	v_readlane_b32 s62, v254, 43
	v_readlane_b32 s63, v254, 44
	v_readlane_b32 s66, v254, 45
	v_readlane_b32 s67, v254, 46
	v_readlane_b32 s68, v254, 47
	v_readlane_b32 s69, v254, 48
	v_readlane_b32 s74, v254, 49
	v_readlane_b32 s75, v254, 50
	v_readlane_b32 s76, v254, 51
	v_readlane_b32 s77, v254, 52
	v_readlane_b32 s78, v254, 53
	v_readlane_b32 s79, v254, 54
	v_readlane_b32 s88, v254, 55
	s_waitcnt vmcnt(0) lgkmcnt(0)
	s_nop 3
